# GEMM k-loops role split: waves 0-3 (priority 1) issue the LDS-DMA for themselves and their partner wave, waves 4-7 issue none
# speedup vs baseline: 1.0134x; 1.0018x over previous
.LBB0_22:
	s_add_i32 s2, s7, s8
	s_cmpk_gt_i32 s2, 0x1ff
	s_mov_b64 s[0:1], -1
	s_cbranch_scc1 .LBB0_21
	s_ashr_i32 s0, s2, 31
	s_lshr_b32 s0, s0, 27
	s_add_i32 s0, s2, s0
	s_and_b32 s1, s0, 0xffffffe0
	s_sub_i32 s1, s2, s1
	s_ashr_i32 s2, s1, 31
	s_lshr_b32 s2, s2, 29
	s_add_i32 s2, s1, s2
	s_and_b32 s3, s2, 0xfffff8
	s_sub_i32 s1, s1, s3
	s_lshl_b32 s0, s0, 6
	s_and_b32 s0, s0, 0xfffff800
	s_lshl_b32 s1, s1, 8
	s_add_i32 s0, s1, s0
	s_ashr_i32 s1, s0, 31
	s_lshl_b64 s[4:5], s[0:1], 12
	s_lshl_b32 s1, s2, 5
	s_and_b32 s2, s1, 0xffffff00
	s_ashr_i32 s3, s2, 31
	s_lshl_b64 s[10:11], s[2:3], 12
	s_add_u32 s12, s64, s4
	v_mov_b32_e32 v0, v138
	s_addc_u32 s13, s65, s5
	s_barrier
	v_readlane_b32 s14, v251, 22
	v_lshl_add_u64 v[2:3], v[0:1], 1, s[12:13]
	v_add_u32_e32 v0, 32, v139
	v_readlane_b32 s15, v251, 23
	v_readfirstlane_b32 s1, v0
	s_mov_b32 m0, s1
	v_mov_b32_e32 v0, v140
	global_load_lds_dwordx4 v[2:3], off
	s_add_u32 s14, s14, s10
	v_lshl_add_u64 v[2:3], v[0:1], 1, s[12:13]
	v_add_u32_e32 v0, 32, v141
	s_addc_u32 s15, s15, s11
	v_readfirstlane_b32 s1, v0
	s_mov_b32 m0, s1
	v_mov_b32_e32 v0, v142
	global_load_lds_dwordx4 v[2:3], off
	v_readlane_b32 s3, v254, 3
	v_lshl_add_u64 v[2:3], v[0:1], 1, s[12:13]
	v_add_u32_e32 v0, 32, v143
	s_mov_b32 s27, s51
	v_readfirstlane_b32 s1, v0
	s_mov_b32 m0, s1
	v_mov_b32_e32 v0, v144
	global_load_lds_dwordx4 v[2:3], off
	s_nop 0
	v_lshl_add_u64 v[2:3], v[0:1], 1, s[12:13]
	v_add_u32_e32 v0, 32, v145
	s_nop 0
	v_readfirstlane_b32 s1, v0
	s_mov_b32 m0, s1
	v_mov_b32_e32 v0, v138
	global_load_lds_dwordx4 v[2:3], off
	s_nop 0
	v_lshl_add_u64 v[2:3], v[0:1], 1, s[14:15]
	v_add_u32_e32 v0, s3, v139
	s_nop 0
	v_readfirstlane_b32 s1, v0
	s_mov_b32 m0, s1
	v_mov_b32_e32 v0, v140
	global_load_lds_dwordx4 v[2:3], off
	s_nop 0
	v_lshl_add_u64 v[2:3], v[0:1], 1, s[14:15]
	v_add_u32_e32 v0, s3, v141
	s_nop 0
	v_readfirstlane_b32 s1, v0
	s_mov_b32 m0, s1
	v_mov_b32_e32 v0, v142
	global_load_lds_dwordx4 v[2:3], off
	s_nop 0
	v_lshl_add_u64 v[2:3], v[0:1], 1, s[14:15]
	v_add_u32_e32 v0, s3, v143
	s_nop 0
	v_readfirstlane_b32 s1, v0
	s_mov_b32 m0, s1
	v_mov_b32_e32 v0, v144
	global_load_lds_dwordx4 v[2:3], off
	s_nop 0
	v_lshl_add_u64 v[2:3], v[0:1], 1, s[14:15]
	v_add_u32_e32 v0, s3, v145
	v_readlane_b32 s3, v253, 26
	v_readfirstlane_b32 s1, v0
	s_mov_b32 m0, s1
	v_readlane_b32 s1, v253, 25
	global_load_lds_dwordx4 v[2:3], off
	s_add_u32 s1, s1, s4
	s_waitcnt vmcnt(0)
	s_addc_u32 s3, s3, s5
	v_readlane_b32 s4, v253, 27
	s_add_u32 s9, s4, s10
	v_readlane_b32 s4, v253, 28
	v_mov_b32_e32 v2, 0
	s_addc_u32 s10, s4, s11
	s_mov_b64 s[4:5], 0
	s_mov_b32 s11, 0
	v_mov_b32_e32 v3, v2
	v_mov_b32_e32 v4, v2
	v_mov_b32_e32 v5, v2
	v_mov_b32_e32 v6, v2
	v_mov_b32_e32 v7, v2
	v_mov_b32_e32 v8, v2
	v_mov_b32_e32 v9, v2
	v_mov_b32_e32 v10, v2
	v_mov_b32_e32 v11, v2
	v_mov_b32_e32 v12, v2
	v_mov_b32_e32 v13, v2
	s_waitcnt vmcnt(0)
	v_mov_b32_e32 v14, v2
	v_mov_b32_e32 v15, v2
	v_mov_b32_e32 v16, v2
	v_mov_b32_e32 v17, v2
	v_mov_b32_e32 v18, v2
	v_mov_b32_e32 v19, v2
	v_mov_b32_e32 v20, v2
	v_mov_b32_e32 v21, v2
	v_mov_b32_e32 v22, v2
	v_mov_b32_e32 v23, v2
	v_mov_b32_e32 v24, v2
	v_mov_b32_e32 v25, v2
	v_mov_b32_e32 v26, v2
	v_mov_b32_e32 v27, v2
	v_mov_b32_e32 v28, v2
	v_mov_b32_e32 v29, v2
	v_mov_b32_e32 v30, v2
	v_mov_b32_e32 v31, v2
	v_mov_b32_e32 v32, v2
	v_mov_b32_e32 v33, v2
	v_mov_b32_e32 v34, v2
	v_mov_b32_e32 v35, v2
	v_mov_b32_e32 v36, v2
	v_mov_b32_e32 v37, v2
	v_mov_b32_e32 v38, v2
	v_mov_b32_e32 v39, v2
	v_mov_b32_e32 v40, v2
	v_mov_b32_e32 v41, v2
	v_mov_b32_e32 v42, v2
	v_mov_b32_e32 v43, v2
	v_mov_b32_e32 v44, v2
	v_mov_b32_e32 v45, v2
	v_mov_b32_e32 v46, v2
	v_mov_b32_e32 v47, v2
	v_mov_b32_e32 v48, v2
	v_mov_b32_e32 v49, v2
	v_mov_b32_e32 v50, v2
	v_mov_b32_e32 v51, v2
	v_mov_b32_e32 v52, v2
	v_mov_b32_e32 v53, v2
	v_mov_b32_e32 v54, v2
	v_mov_b32_e32 v55, v2
	v_mov_b32_e32 v56, v2
	v_mov_b32_e32 v57, v2
	v_mov_b32_e32 v58, v2
	v_mov_b32_e32 v59, v2
	v_mov_b32_e32 v60, v2
	v_mov_b32_e32 v61, v2
	v_mov_b32_e32 v62, v2
	v_mov_b32_e32 v63, v2
	v_mov_b32_e32 v64, v2
	v_mov_b32_e32 v65, v2
	v_mov_b32_e32 v66, v2
	v_mov_b32_e32 v67, v2
	v_mov_b32_e32 v68, v2
	v_mov_b32_e32 v69, v2
	v_mov_b32_e32 v70, v2
	v_mov_b32_e32 v71, v2
	v_mov_b32_e32 v72, v2
	v_mov_b32_e32 v73, v2
	v_mov_b32_e32 v74, v2
	v_mov_b32_e32 v75, v2
	v_mov_b32_e32 v76, v2
	v_mov_b32_e32 v77, v2
	v_mov_b32_e32 v78, v2
	v_mov_b32_e32 v79, v2
	v_mov_b32_e32 v80, v2
	v_mov_b32_e32 v81, v2
	v_mov_b32_e32 v82, v2
	v_mov_b32_e32 v83, v2
	v_mov_b32_e32 v84, v2
	v_mov_b32_e32 v85, v2
	v_mov_b32_e32 v86, v2
	v_mov_b32_e32 v87, v2
	v_mov_b32_e32 v88, v2
	v_mov_b32_e32 v89, v2
	v_mov_b32_e32 v90, v2
	v_mov_b32_e32 v91, v2
	v_mov_b32_e32 v92, v2
	v_mov_b32_e32 v93, v2
	v_mov_b32_e32 v94, v2
	v_mov_b32_e32 v95, v2
	v_mov_b32_e32 v96, v2
	v_mov_b32_e32 v97, v2
	v_mov_b32_e32 v98, v2
	v_mov_b32_e32 v99, v2
	v_mov_b32_e32 v100, v2
	v_mov_b32_e32 v101, v2
	v_mov_b32_e32 v102, v2
	v_mov_b32_e32 v103, v2
	v_mov_b32_e32 v104, v2
	v_mov_b32_e32 v105, v2
	v_mov_b32_e32 v106, v2
	v_mov_b32_e32 v107, v2
	v_mov_b32_e32 v108, v2
	v_mov_b32_e32 v109, v2
	v_mov_b32_e32 v110, v2
	v_mov_b32_e32 v111, v2
	v_mov_b32_e32 v112, v2
	v_mov_b32_e32 v113, v2
	v_mov_b32_e32 v114, v2
	v_mov_b32_e32 v115, v2
	v_mov_b32_e32 v116, v2
	v_mov_b32_e32 v117, v2
	v_mov_b32_e32 v118, v2
	v_mov_b32_e32 v119, v2
	v_mov_b32_e32 v120, v2
	v_mov_b32_e32 v121, v2
	v_mov_b32_e32 v122, v2
	v_mov_b32_e32 v123, v2
	v_mov_b32_e32 v124, v2
	v_mov_b32_e32 v125, v2
	v_mov_b32_e32 v126, v2
	v_mov_b32_e32 v127, v2
	v_mov_b32_e32 v128, v2
	v_mov_b32_e32 v129, v2
	s_waitcnt vmcnt(0) lgkmcnt(0)
	s_barrier
	v_readfirstlane_b32 s66, v179
	s_cmp_lt_u32 s66, 0x100
	s_cbranch_scc0 .Lgl24_entry
	s_setprio 1
	v_lshlrev_b32_e32 v155, 1, v138
	v_readfirstlane_b32 s14, v139
	v_add_u32_e32 v177, v146, v148
	v_add_u32_e32 v207, v147, v148
	v_add_u32_e32 v204, v146, v152
	v_add_u32_e32 v208, v147, v152
	v_add_u32_e32 v205, v146, v153
	v_add_u32_e32 v209, v147, v153
	v_add_u32_e32 v206, v146, v154
	v_add_u32_e32 v210, v147, v154
	s_mov_b32 s11, 15
	s_add_u32 m0, s14, 0x8020
	s_add_u32 s12, s1, s4
	s_addc_u32 s13, s3, s5
	global_load_lds_dwordx4 v155, s[12:13]
	s_add_u32 m0, s14, 0x9020
	s_add_u32 s68, s12, 0x20000
	s_addc_u32 s69, s13, 0
	global_load_lds_dwordx4 v155, s[68:69]
	s_add_u32 m0, s14, 0xa020
	s_add_u32 s12, s12, 0x40000
	s_addc_u32 s13, s13, 0
	global_load_lds_dwordx4 v155, s[12:13]
	s_add_u32 m0, s14, 0xb020
	s_add_u32 s68, s12, 0x20000
	s_addc_u32 s69, s13, 0
	global_load_lds_dwordx4 v155, s[68:69]
	s_add_u32 m0, s14, 0xc020
	s_add_u32 s12, s12, 0x40000
	s_addc_u32 s13, s13, 0
	global_load_lds_dwordx4 v155, s[12:13]
	s_add_u32 m0, s14, 0xd020
	s_add_u32 s68, s12, 0x20000
	s_addc_u32 s69, s13, 0
	global_load_lds_dwordx4 v155, s[68:69]
	s_add_u32 m0, s14, 0xe020
	s_add_u32 s12, s12, 0x40000
	s_addc_u32 s13, s13, 0
	global_load_lds_dwordx4 v155, s[12:13]
	s_add_u32 m0, s14, 0xf020
	s_add_u32 s68, s12, 0x20000
	s_addc_u32 s69, s13, 0
	global_load_lds_dwordx4 v155, s[68:69]
	s_add_u32 m0, s14, 0x18020
	s_add_u32 s12, s9, s4
	s_addc_u32 s13, s10, s5
	global_load_lds_dwordx4 v155, s[12:13]
	s_add_u32 m0, s14, 0x19020
	s_add_u32 s68, s12, 0x20000
	s_addc_u32 s69, s13, 0
	global_load_lds_dwordx4 v155, s[68:69]
	ds_read_b128 v[130:133], v177 offset:0
	ds_read_b128 v[164:167], v207 offset:0
	ds_read_b128 v[168:171], v207 offset:4096
	ds_read_b128 v[134:137], v177 offset:4096
	ds_read_b128 v[156:159], v177 offset:8192
	ds_read_b128 v[160:163], v177 offset:12288
.Lg24_loop:
	s_waitcnt lgkmcnt(4)
	v_mfma_f32_32x32x16_bf16 v[114:129], v[130:133], v[164:167], v[114:129]
	ds_read_b128 v[172:175], v204 offset:0
	s_waitcnt lgkmcnt(4)
	v_mfma_f32_32x32x16_bf16 v[98:113], v[130:133], v[168:171], v[98:113]
	ds_read_b128 v[192:195], v208 offset:0
	s_add_u32 m0, s14, 0x1a020
	s_add_u32 s12, s12, 0x40000
	s_addc_u32 s13, s13, 0
	global_load_lds_dwordx4 v155, s[12:13]
	s_add_u32 m0, s14, 0x1b020
	s_add_u32 s68, s12, 0x20000
	s_addc_u32 s69, s13, 0
	global_load_lds_dwordx4 v155, s[68:69]
	s_waitcnt lgkmcnt(4)
	v_mfma_f32_32x32x16_bf16 v[82:97], v[134:137], v[164:167], v[82:97]
	ds_read_b128 v[200:203], v208 offset:4096
	v_mfma_f32_32x32x16_bf16 v[66:81], v[134:137], v[168:171], v[66:81]
	ds_read_b128 v[180:183], v204 offset:4096
	s_add_u32 m0, s14, 0x1c020
	s_add_u32 s12, s12, 0x40000
	s_addc_u32 s13, s13, 0
	global_load_lds_dwordx4 v155, s[12:13]
	s_add_u32 m0, s14, 0x1d020
	s_add_u32 s68, s12, 0x20000
	s_addc_u32 s69, s13, 0
	global_load_lds_dwordx4 v155, s[68:69]
	s_waitcnt lgkmcnt(5)
	v_mfma_f32_32x32x16_bf16 v[50:65], v[156:159], v[164:167], v[50:65]
	ds_read_b128 v[184:187], v204 offset:8192
	v_mfma_f32_32x32x16_bf16 v[34:49], v[156:159], v[168:171], v[34:49]
	ds_read_b128 v[188:191], v204 offset:12288
	s_add_u32 m0, s14, 0x1e020
	s_add_u32 s12, s12, 0x40000
	s_addc_u32 s13, s13, 0
	global_load_lds_dwordx4 v155, s[12:13]
	s_add_u32 m0, s14, 0x1f020
	s_add_u32 s68, s12, 0x20000
	s_addc_u32 s69, s13, 0
	global_load_lds_dwordx4 v155, s[68:69]
	s_add_u32 s4, s4, 0x80
	s_addc_u32 s5, s5, 0
	s_waitcnt lgkmcnt(6)
	v_mfma_f32_32x32x16_bf16 v[18:33], v[160:163], v[164:167], v[18:33]
	v_mfma_f32_32x32x16_bf16 v[2:17], v[160:163], v[168:171], v[2:17]
	s_waitcnt lgkmcnt(4)
	v_mfma_f32_32x32x16_bf16 v[114:129], v[172:175], v[192:195], v[114:129]
	ds_read_b128 v[130:133], v205 offset:0
	s_waitcnt lgkmcnt(4)
	v_mfma_f32_32x32x16_bf16 v[98:113], v[172:175], v[200:203], v[98:113]
	ds_read_b128 v[164:167], v209 offset:0
	s_waitcnt lgkmcnt(4)
	v_mfma_f32_32x32x16_bf16 v[82:97], v[180:183], v[192:195], v[82:97]
	ds_read_b128 v[168:171], v209 offset:4096
	v_mfma_f32_32x32x16_bf16 v[66:81], v[180:183], v[200:203], v[66:81]
	ds_read_b128 v[134:137], v205 offset:4096
	s_waitcnt lgkmcnt(5)
	v_mfma_f32_32x32x16_bf16 v[50:65], v[184:187], v[192:195], v[50:65]
	ds_read_b128 v[156:159], v205 offset:8192
	v_mfma_f32_32x32x16_bf16 v[34:49], v[184:187], v[200:203], v[34:49]
	ds_read_b128 v[160:163], v205 offset:12288
	s_waitcnt lgkmcnt(6)
	v_mfma_f32_32x32x16_bf16 v[18:33], v[188:191], v[192:195], v[18:33]
	v_mfma_f32_32x32x16_bf16 v[2:17], v[188:191], v[200:203], v[2:17]
	s_waitcnt lgkmcnt(4)
	v_mfma_f32_32x32x16_bf16 v[114:129], v[130:133], v[164:167], v[114:129]
	ds_read_b128 v[172:175], v206 offset:0
	ds_read_b128 v[192:195], v210 offset:0
	s_waitcnt lgkmcnt(5)
	v_mfma_f32_32x32x16_bf16 v[98:113], v[130:133], v[168:171], v[98:113]
	ds_read_b128 v[200:203], v210 offset:4096
	ds_read_b128 v[180:183], v206 offset:4096
	s_waitcnt lgkmcnt(6)
	v_mfma_f32_32x32x16_bf16 v[82:97], v[134:137], v[164:167], v[82:97]
	ds_read_b128 v[184:187], v206 offset:8192
	ds_read_b128 v[188:191], v206 offset:12288
	v_mfma_f32_32x32x16_bf16 v[66:81], v[134:137], v[168:171], v[66:81]
	s_waitcnt lgkmcnt(7)
	v_mfma_f32_32x32x16_bf16 v[50:65], v[156:159], v[164:167], v[50:65]
	v_mfma_f32_32x32x16_bf16 v[34:49], v[156:159], v[168:171], v[34:49]
	s_waitcnt lgkmcnt(6)
	v_mfma_f32_32x32x16_bf16 v[18:33], v[160:163], v[164:167], v[18:33]
	v_mfma_f32_32x32x16_bf16 v[2:17], v[160:163], v[168:171], v[2:17]
	s_waitcnt vmcnt(0) lgkmcnt(0)
	s_barrier
	v_mfma_f32_32x32x16_bf16 v[114:129], v[172:175], v[192:195], v[114:129]
	ds_read_b128 v[130:133], v177 offset:32768
	s_add_u32 m0, s14, 0x20
	s_add_u32 s12, s1, s4
	s_addc_u32 s13, s3, s5
	global_load_lds_dwordx4 v155, s[12:13]
	s_add_u32 m0, s14, 0x1020
	s_add_u32 s68, s12, 0x20000
	s_addc_u32 s69, s13, 0
	global_load_lds_dwordx4 v155, s[68:69]
	v_mfma_f32_32x32x16_bf16 v[98:113], v[172:175], v[200:203], v[98:113]
	ds_read_b128 v[164:167], v207 offset:32768
	s_add_u32 m0, s14, 0x2020
	s_add_u32 s12, s12, 0x40000
	s_addc_u32 s13, s13, 0
	global_load_lds_dwordx4 v155, s[12:13]
	s_add_u32 m0, s14, 0x3020
	s_add_u32 s68, s12, 0x20000
	s_addc_u32 s69, s13, 0
	global_load_lds_dwordx4 v155, s[68:69]
	v_mfma_f32_32x32x16_bf16 v[82:97], v[180:183], v[192:195], v[82:97]
	ds_read_b128 v[168:171], v207 offset:36864
	s_add_u32 m0, s14, 0x4020
	s_add_u32 s12, s12, 0x40000
	s_addc_u32 s13, s13, 0
	global_load_lds_dwordx4 v155, s[12:13]
	s_add_u32 m0, s14, 0x5020
	s_add_u32 s68, s12, 0x20000
	s_addc_u32 s69, s13, 0
	global_load_lds_dwordx4 v155, s[68:69]
	v_mfma_f32_32x32x16_bf16 v[66:81], v[180:183], v[200:203], v[66:81]
	ds_read_b128 v[134:137], v177 offset:36864
	s_add_u32 m0, s14, 0x6020
	s_add_u32 s12, s12, 0x40000
	s_addc_u32 s13, s13, 0
	global_load_lds_dwordx4 v155, s[12:13]
	s_add_u32 m0, s14, 0x7020
	s_add_u32 s68, s12, 0x20000
	s_addc_u32 s69, s13, 0
	global_load_lds_dwordx4 v155, s[68:69]
	v_mfma_f32_32x32x16_bf16 v[50:65], v[184:187], v[192:195], v[50:65]
	ds_read_b128 v[156:159], v177 offset:40960
	s_add_u32 m0, s14, 0x10020
	s_add_u32 s12, s9, s4
	s_addc_u32 s13, s10, s5
	global_load_lds_dwordx4 v155, s[12:13]
	s_add_u32 m0, s14, 0x11020
	s_add_u32 s68, s12, 0x20000
	s_addc_u32 s69, s13, 0
	global_load_lds_dwordx4 v155, s[68:69]
	v_mfma_f32_32x32x16_bf16 v[34:49], v[184:187], v[200:203], v[34:49]
	ds_read_b128 v[160:163], v177 offset:45056
	v_mfma_f32_32x32x16_bf16 v[18:33], v[188:191], v[192:195], v[18:33]
	v_mfma_f32_32x32x16_bf16 v[2:17], v[188:191], v[200:203], v[2:17]
	s_waitcnt lgkmcnt(4)
	v_mfma_f32_32x32x16_bf16 v[114:129], v[130:133], v[164:167], v[114:129]
	ds_read_b128 v[172:175], v204 offset:32768
	s_waitcnt lgkmcnt(4)
	v_mfma_f32_32x32x16_bf16 v[98:113], v[130:133], v[168:171], v[98:113]
	ds_read_b128 v[192:195], v208 offset:32768
	s_add_u32 m0, s14, 0x12020
	s_add_u32 s12, s12, 0x40000
	s_addc_u32 s13, s13, 0
	global_load_lds_dwordx4 v155, s[12:13]
	s_add_u32 m0, s14, 0x13020
	s_add_u32 s68, s12, 0x20000
	s_addc_u32 s69, s13, 0
	global_load_lds_dwordx4 v155, s[68:69]
	s_waitcnt lgkmcnt(4)
	v_mfma_f32_32x32x16_bf16 v[82:97], v[134:137], v[164:167], v[82:97]
	ds_read_b128 v[200:203], v208 offset:36864
	v_mfma_f32_32x32x16_bf16 v[66:81], v[134:137], v[168:171], v[66:81]
	ds_read_b128 v[180:183], v204 offset:36864
	s_add_u32 m0, s14, 0x14020
	s_add_u32 s12, s12, 0x40000
	s_addc_u32 s13, s13, 0
	global_load_lds_dwordx4 v155, s[12:13]
	s_add_u32 m0, s14, 0x15020
	s_add_u32 s68, s12, 0x20000
	s_addc_u32 s69, s13, 0
	global_load_lds_dwordx4 v155, s[68:69]
	s_waitcnt lgkmcnt(5)
	v_mfma_f32_32x32x16_bf16 v[50:65], v[156:159], v[164:167], v[50:65]
	ds_read_b128 v[184:187], v204 offset:40960
	v_mfma_f32_32x32x16_bf16 v[34:49], v[156:159], v[168:171], v[34:49]
	ds_read_b128 v[188:191], v204 offset:45056
	s_add_u32 m0, s14, 0x16020
	s_add_u32 s12, s12, 0x40000
	s_addc_u32 s13, s13, 0
	global_load_lds_dwordx4 v155, s[12:13]
	s_add_u32 m0, s14, 0x17020
	s_add_u32 s68, s12, 0x20000
	s_addc_u32 s69, s13, 0
	global_load_lds_dwordx4 v155, s[68:69]
	s_add_u32 s4, s4, 0x80
	s_addc_u32 s5, s5, 0
	s_waitcnt lgkmcnt(6)
	v_mfma_f32_32x32x16_bf16 v[18:33], v[160:163], v[164:167], v[18:33]
	v_mfma_f32_32x32x16_bf16 v[2:17], v[160:163], v[168:171], v[2:17]
	s_waitcnt lgkmcnt(4)
	v_mfma_f32_32x32x16_bf16 v[114:129], v[172:175], v[192:195], v[114:129]
	ds_read_b128 v[130:133], v205 offset:32768
	s_waitcnt lgkmcnt(4)
	v_mfma_f32_32x32x16_bf16 v[98:113], v[172:175], v[200:203], v[98:113]
	ds_read_b128 v[164:167], v209 offset:32768
	s_waitcnt lgkmcnt(4)
	v_mfma_f32_32x32x16_bf16 v[82:97], v[180:183], v[192:195], v[82:97]
	ds_read_b128 v[168:171], v209 offset:36864
	v_mfma_f32_32x32x16_bf16 v[66:81], v[180:183], v[200:203], v[66:81]
	ds_read_b128 v[134:137], v205 offset:36864
	s_waitcnt lgkmcnt(5)
	v_mfma_f32_32x32x16_bf16 v[50:65], v[184:187], v[192:195], v[50:65]
	ds_read_b128 v[156:159], v205 offset:40960
	v_mfma_f32_32x32x16_bf16 v[34:49], v[184:187], v[200:203], v[34:49]
	ds_read_b128 v[160:163], v205 offset:45056
	s_waitcnt lgkmcnt(6)
	v_mfma_f32_32x32x16_bf16 v[18:33], v[188:191], v[192:195], v[18:33]
	v_mfma_f32_32x32x16_bf16 v[2:17], v[188:191], v[200:203], v[2:17]
	s_waitcnt lgkmcnt(4)
	v_mfma_f32_32x32x16_bf16 v[114:129], v[130:133], v[164:167], v[114:129]
	ds_read_b128 v[172:175], v206 offset:32768
	ds_read_b128 v[192:195], v210 offset:32768
	s_waitcnt lgkmcnt(5)
	v_mfma_f32_32x32x16_bf16 v[98:113], v[130:133], v[168:171], v[98:113]
	ds_read_b128 v[200:203], v210 offset:36864
	ds_read_b128 v[180:183], v206 offset:36864
	s_waitcnt lgkmcnt(6)
	v_mfma_f32_32x32x16_bf16 v[82:97], v[134:137], v[164:167], v[82:97]
	ds_read_b128 v[184:187], v206 offset:40960
	ds_read_b128 v[188:191], v206 offset:45056
	v_mfma_f32_32x32x16_bf16 v[66:81], v[134:137], v[168:171], v[66:81]
	s_waitcnt lgkmcnt(7)
	v_mfma_f32_32x32x16_bf16 v[50:65], v[156:159], v[164:167], v[50:65]
	v_mfma_f32_32x32x16_bf16 v[34:49], v[156:159], v[168:171], v[34:49]
	s_waitcnt lgkmcnt(6)
	v_mfma_f32_32x32x16_bf16 v[18:33], v[160:163], v[164:167], v[18:33]
	v_mfma_f32_32x32x16_bf16 v[2:17], v[160:163], v[168:171], v[2:17]
	s_waitcnt vmcnt(0) lgkmcnt(0)
	s_barrier
	v_mfma_f32_32x32x16_bf16 v[114:129], v[172:175], v[192:195], v[114:129]
	ds_read_b128 v[130:133], v177 offset:0
	s_add_u32 m0, s14, 0x8020
	s_add_u32 s12, s1, s4
	s_addc_u32 s13, s3, s5
	global_load_lds_dwordx4 v155, s[12:13]
	s_add_u32 m0, s14, 0x9020
	s_add_u32 s68, s12, 0x20000
	s_addc_u32 s69, s13, 0
	global_load_lds_dwordx4 v155, s[68:69]
	v_mfma_f32_32x32x16_bf16 v[98:113], v[172:175], v[200:203], v[98:113]
	ds_read_b128 v[164:167], v207 offset:0
	s_add_u32 m0, s14, 0xa020
	s_add_u32 s12, s12, 0x40000
	s_addc_u32 s13, s13, 0
	global_load_lds_dwordx4 v155, s[12:13]
	s_add_u32 m0, s14, 0xb020
	s_add_u32 s68, s12, 0x20000
	s_addc_u32 s69, s13, 0
	global_load_lds_dwordx4 v155, s[68:69]
	v_mfma_f32_32x32x16_bf16 v[82:97], v[180:183], v[192:195], v[82:97]
	ds_read_b128 v[168:171], v207 offset:4096
	s_add_u32 m0, s14, 0xc020
	s_add_u32 s12, s12, 0x40000
	s_addc_u32 s13, s13, 0
	global_load_lds_dwordx4 v155, s[12:13]
	s_add_u32 m0, s14, 0xd020
	s_add_u32 s68, s12, 0x20000
	s_addc_u32 s69, s13, 0
	global_load_lds_dwordx4 v155, s[68:69]
	v_mfma_f32_32x32x16_bf16 v[66:81], v[180:183], v[200:203], v[66:81]
	ds_read_b128 v[134:137], v177 offset:4096
	s_add_u32 m0, s14, 0xe020
	s_add_u32 s12, s12, 0x40000
	s_addc_u32 s13, s13, 0
	global_load_lds_dwordx4 v155, s[12:13]
	s_add_u32 m0, s14, 0xf020
	s_add_u32 s68, s12, 0x20000
	s_addc_u32 s69, s13, 0
	global_load_lds_dwordx4 v155, s[68:69]
	v_mfma_f32_32x32x16_bf16 v[50:65], v[184:187], v[192:195], v[50:65]
	ds_read_b128 v[156:159], v177 offset:8192
	s_add_u32 m0, s14, 0x18020
	s_add_u32 s12, s9, s4
	s_addc_u32 s13, s10, s5
	global_load_lds_dwordx4 v155, s[12:13]
	s_add_u32 m0, s14, 0x19020
	s_add_u32 s68, s12, 0x20000
	s_addc_u32 s69, s13, 0
	global_load_lds_dwordx4 v155, s[68:69]
	v_mfma_f32_32x32x16_bf16 v[34:49], v[184:187], v[200:203], v[34:49]
	ds_read_b128 v[160:163], v177 offset:12288
	v_mfma_f32_32x32x16_bf16 v[18:33], v[188:191], v[192:195], v[18:33]
	v_mfma_f32_32x32x16_bf16 v[2:17], v[188:191], v[200:203], v[2:17]
	s_sub_u32 s11, s11, 1
	s_cmp_lg_u32 s11, 0
	s_cbranch_scc1 .Lg24_loop
	s_waitcnt lgkmcnt(4)
	v_mfma_f32_32x32x16_bf16 v[114:129], v[130:133], v[164:167], v[114:129]
	ds_read_b128 v[172:175], v204 offset:0
	s_waitcnt lgkmcnt(4)
	v_mfma_f32_32x32x16_bf16 v[98:113], v[130:133], v[168:171], v[98:113]
	ds_read_b128 v[192:195], v208 offset:0
	s_add_u32 m0, s14, 0x1a020
	s_add_u32 s12, s12, 0x40000
	s_addc_u32 s13, s13, 0
	global_load_lds_dwordx4 v155, s[12:13]
	s_add_u32 m0, s14, 0x1b020
	s_add_u32 s68, s12, 0x20000
	s_addc_u32 s69, s13, 0
	global_load_lds_dwordx4 v155, s[68:69]
	s_waitcnt lgkmcnt(4)
	v_mfma_f32_32x32x16_bf16 v[82:97], v[134:137], v[164:167], v[82:97]
	ds_read_b128 v[200:203], v208 offset:4096
	v_mfma_f32_32x32x16_bf16 v[66:81], v[134:137], v[168:171], v[66:81]
	ds_read_b128 v[180:183], v204 offset:4096
	s_add_u32 m0, s14, 0x1c020
	s_add_u32 s12, s12, 0x40000
	s_addc_u32 s13, s13, 0
	global_load_lds_dwordx4 v155, s[12:13]
	s_add_u32 m0, s14, 0x1d020
	s_add_u32 s68, s12, 0x20000
	s_addc_u32 s69, s13, 0
	global_load_lds_dwordx4 v155, s[68:69]
	s_waitcnt lgkmcnt(5)
	v_mfma_f32_32x32x16_bf16 v[50:65], v[156:159], v[164:167], v[50:65]
	ds_read_b128 v[184:187], v204 offset:8192
	v_mfma_f32_32x32x16_bf16 v[34:49], v[156:159], v[168:171], v[34:49]
	ds_read_b128 v[188:191], v204 offset:12288
	s_add_u32 m0, s14, 0x1e020
	s_add_u32 s12, s12, 0x40000
	s_addc_u32 s13, s13, 0
	global_load_lds_dwordx4 v155, s[12:13]
	s_add_u32 m0, s14, 0x1f020
	s_add_u32 s68, s12, 0x20000
	s_addc_u32 s69, s13, 0
	global_load_lds_dwordx4 v155, s[68:69]
	s_add_u32 s4, s4, 0x80
	s_addc_u32 s5, s5, 0
	s_waitcnt lgkmcnt(6)
	v_mfma_f32_32x32x16_bf16 v[18:33], v[160:163], v[164:167], v[18:33]
	v_mfma_f32_32x32x16_bf16 v[2:17], v[160:163], v[168:171], v[2:17]
	s_waitcnt lgkmcnt(4)
	v_mfma_f32_32x32x16_bf16 v[114:129], v[172:175], v[192:195], v[114:129]
	ds_read_b128 v[130:133], v205 offset:0
	s_waitcnt lgkmcnt(4)
	v_mfma_f32_32x32x16_bf16 v[98:113], v[172:175], v[200:203], v[98:113]
	ds_read_b128 v[164:167], v209 offset:0
	s_waitcnt lgkmcnt(4)
	v_mfma_f32_32x32x16_bf16 v[82:97], v[180:183], v[192:195], v[82:97]
	ds_read_b128 v[168:171], v209 offset:4096
	v_mfma_f32_32x32x16_bf16 v[66:81], v[180:183], v[200:203], v[66:81]
	ds_read_b128 v[134:137], v205 offset:4096
	s_waitcnt lgkmcnt(5)
	v_mfma_f32_32x32x16_bf16 v[50:65], v[184:187], v[192:195], v[50:65]
	ds_read_b128 v[156:159], v205 offset:8192
	v_mfma_f32_32x32x16_bf16 v[34:49], v[184:187], v[200:203], v[34:49]
	ds_read_b128 v[160:163], v205 offset:12288
	s_waitcnt lgkmcnt(6)
	v_mfma_f32_32x32x16_bf16 v[18:33], v[188:191], v[192:195], v[18:33]
	v_mfma_f32_32x32x16_bf16 v[2:17], v[188:191], v[200:203], v[2:17]
	s_waitcnt lgkmcnt(4)
	v_mfma_f32_32x32x16_bf16 v[114:129], v[130:133], v[164:167], v[114:129]
	ds_read_b128 v[172:175], v206 offset:0
	ds_read_b128 v[192:195], v210 offset:0
	s_waitcnt lgkmcnt(5)
	v_mfma_f32_32x32x16_bf16 v[98:113], v[130:133], v[168:171], v[98:113]
	ds_read_b128 v[200:203], v210 offset:4096
	ds_read_b128 v[180:183], v206 offset:4096
	s_waitcnt lgkmcnt(6)
	v_mfma_f32_32x32x16_bf16 v[82:97], v[134:137], v[164:167], v[82:97]
	ds_read_b128 v[184:187], v206 offset:8192
	ds_read_b128 v[188:191], v206 offset:12288
	v_mfma_f32_32x32x16_bf16 v[66:81], v[134:137], v[168:171], v[66:81]
	s_waitcnt lgkmcnt(7)
	v_mfma_f32_32x32x16_bf16 v[50:65], v[156:159], v[164:167], v[50:65]
	v_mfma_f32_32x32x16_bf16 v[34:49], v[156:159], v[168:171], v[34:49]
	s_waitcnt lgkmcnt(6)
	v_mfma_f32_32x32x16_bf16 v[18:33], v[160:163], v[164:167], v[18:33]
	v_mfma_f32_32x32x16_bf16 v[2:17], v[160:163], v[168:171], v[2:17]
	s_waitcnt vmcnt(0) lgkmcnt(0)
	s_barrier
	v_mfma_f32_32x32x16_bf16 v[114:129], v[172:175], v[192:195], v[114:129]
	ds_read_b128 v[130:133], v177 offset:32768
	v_mfma_f32_32x32x16_bf16 v[98:113], v[172:175], v[200:203], v[98:113]
	ds_read_b128 v[164:167], v207 offset:32768
	v_mfma_f32_32x32x16_bf16 v[82:97], v[180:183], v[192:195], v[82:97]
	ds_read_b128 v[168:171], v207 offset:36864
	v_mfma_f32_32x32x16_bf16 v[66:81], v[180:183], v[200:203], v[66:81]
	ds_read_b128 v[134:137], v177 offset:36864
	v_mfma_f32_32x32x16_bf16 v[50:65], v[184:187], v[192:195], v[50:65]
	ds_read_b128 v[156:159], v177 offset:40960
	v_mfma_f32_32x32x16_bf16 v[34:49], v[184:187], v[200:203], v[34:49]
	ds_read_b128 v[160:163], v177 offset:45056
	v_mfma_f32_32x32x16_bf16 v[18:33], v[188:191], v[192:195], v[18:33]
	v_mfma_f32_32x32x16_bf16 v[2:17], v[188:191], v[200:203], v[2:17]
	s_waitcnt lgkmcnt(4)
	v_mfma_f32_32x32x16_bf16 v[114:129], v[130:133], v[164:167], v[114:129]
	ds_read_b128 v[172:175], v204 offset:32768
	s_waitcnt lgkmcnt(4)
	v_mfma_f32_32x32x16_bf16 v[98:113], v[130:133], v[168:171], v[98:113]
	ds_read_b128 v[192:195], v208 offset:32768
	s_waitcnt lgkmcnt(4)
	v_mfma_f32_32x32x16_bf16 v[82:97], v[134:137], v[164:167], v[82:97]
	ds_read_b128 v[200:203], v208 offset:36864
	v_mfma_f32_32x32x16_bf16 v[66:81], v[134:137], v[168:171], v[66:81]
	ds_read_b128 v[180:183], v204 offset:36864
	s_waitcnt lgkmcnt(5)
	v_mfma_f32_32x32x16_bf16 v[50:65], v[156:159], v[164:167], v[50:65]
	ds_read_b128 v[184:187], v204 offset:40960
	v_mfma_f32_32x32x16_bf16 v[34:49], v[156:159], v[168:171], v[34:49]
	ds_read_b128 v[188:191], v204 offset:45056
	s_waitcnt lgkmcnt(6)
	v_mfma_f32_32x32x16_bf16 v[18:33], v[160:163], v[164:167], v[18:33]
	v_mfma_f32_32x32x16_bf16 v[2:17], v[160:163], v[168:171], v[2:17]
	s_waitcnt lgkmcnt(4)
	v_mfma_f32_32x32x16_bf16 v[114:129], v[172:175], v[192:195], v[114:129]
	ds_read_b128 v[130:133], v205 offset:32768
	s_waitcnt lgkmcnt(4)
	v_mfma_f32_32x32x16_bf16 v[98:113], v[172:175], v[200:203], v[98:113]
	ds_read_b128 v[164:167], v209 offset:32768
	s_waitcnt lgkmcnt(4)
	v_mfma_f32_32x32x16_bf16 v[82:97], v[180:183], v[192:195], v[82:97]
	ds_read_b128 v[168:171], v209 offset:36864
	v_mfma_f32_32x32x16_bf16 v[66:81], v[180:183], v[200:203], v[66:81]
	ds_read_b128 v[134:137], v205 offset:36864
	s_waitcnt lgkmcnt(5)
	v_mfma_f32_32x32x16_bf16 v[50:65], v[184:187], v[192:195], v[50:65]
	ds_read_b128 v[156:159], v205 offset:40960
	v_mfma_f32_32x32x16_bf16 v[34:49], v[184:187], v[200:203], v[34:49]
	ds_read_b128 v[160:163], v205 offset:45056
	s_waitcnt lgkmcnt(6)
	v_mfma_f32_32x32x16_bf16 v[18:33], v[188:191], v[192:195], v[18:33]
	v_mfma_f32_32x32x16_bf16 v[2:17], v[188:191], v[200:203], v[2:17]
	s_waitcnt lgkmcnt(4)
	v_mfma_f32_32x32x16_bf16 v[114:129], v[130:133], v[164:167], v[114:129]
	ds_read_b128 v[172:175], v206 offset:32768
	ds_read_b128 v[192:195], v210 offset:32768
	s_waitcnt lgkmcnt(5)
	v_mfma_f32_32x32x16_bf16 v[98:113], v[130:133], v[168:171], v[98:113]
	ds_read_b128 v[200:203], v210 offset:36864
	ds_read_b128 v[180:183], v206 offset:36864
	s_waitcnt lgkmcnt(6)
	v_mfma_f32_32x32x16_bf16 v[82:97], v[134:137], v[164:167], v[82:97]
	ds_read_b128 v[184:187], v206 offset:40960
	ds_read_b128 v[188:191], v206 offset:45056
	v_mfma_f32_32x32x16_bf16 v[66:81], v[134:137], v[168:171], v[66:81]
	s_waitcnt lgkmcnt(7)
	v_mfma_f32_32x32x16_bf16 v[50:65], v[156:159], v[164:167], v[50:65]
	v_mfma_f32_32x32x16_bf16 v[34:49], v[156:159], v[168:171], v[34:49]
	s_waitcnt lgkmcnt(6)
	v_mfma_f32_32x32x16_bf16 v[18:33], v[160:163], v[164:167], v[18:33]
	v_mfma_f32_32x32x16_bf16 v[2:17], v[160:163], v[168:171], v[2:17]
	s_waitcnt vmcnt(0) lgkmcnt(0)
	s_barrier
	v_mfma_f32_32x32x16_bf16 v[114:129], v[172:175], v[192:195], v[114:129]
	v_mfma_f32_32x32x16_bf16 v[98:113], v[172:175], v[200:203], v[98:113]
	v_mfma_f32_32x32x16_bf16 v[82:97], v[180:183], v[192:195], v[82:97]
	v_mfma_f32_32x32x16_bf16 v[66:81], v[180:183], v[200:203], v[66:81]
	v_mfma_f32_32x32x16_bf16 v[50:65], v[184:187], v[192:195], v[50:65]
	v_mfma_f32_32x32x16_bf16 v[34:49], v[184:187], v[200:203], v[34:49]
	v_mfma_f32_32x32x16_bf16 v[18:33], v[188:191], v[192:195], v[18:33]
	v_mfma_f32_32x32x16_bf16 v[2:17], v[188:191], v[200:203], v[2:17]
	s_branch .Lg24_end
.Lgl24_entry:
	v_lshlrev_b32_e32 v155, 1, v138
	v_readfirstlane_b32 s14, v139
	v_add_u32_e32 v177, v146, v148
	v_add_u32_e32 v207, v147, v148
	v_add_u32_e32 v204, v146, v152
	v_add_u32_e32 v208, v147, v152
	v_add_u32_e32 v205, v146, v153
	v_add_u32_e32 v209, v147, v153
	v_add_u32_e32 v206, v146, v154
	v_add_u32_e32 v210, v147, v154
	s_mov_b32 s11, 15
	ds_read_b128 v[130:133], v177 offset:0
	ds_read_b128 v[164:167], v207 offset:0
	ds_read_b128 v[168:171], v207 offset:4096
	ds_read_b128 v[134:137], v177 offset:4096
	ds_read_b128 v[156:159], v177 offset:8192
	ds_read_b128 v[160:163], v177 offset:12288
.Lgl24_loop:
	s_waitcnt lgkmcnt(4)
	v_mfma_f32_32x32x16_bf16 v[114:129], v[130:133], v[164:167], v[114:129]
	ds_read_b128 v[172:175], v204 offset:0
	s_waitcnt lgkmcnt(4)
	v_mfma_f32_32x32x16_bf16 v[98:113], v[130:133], v[168:171], v[98:113]
	ds_read_b128 v[192:195], v208 offset:0
	s_waitcnt lgkmcnt(4)
	v_mfma_f32_32x32x16_bf16 v[82:97], v[134:137], v[164:167], v[82:97]
	ds_read_b128 v[200:203], v208 offset:4096
	v_mfma_f32_32x32x16_bf16 v[66:81], v[134:137], v[168:171], v[66:81]
	ds_read_b128 v[180:183], v204 offset:4096
	s_waitcnt lgkmcnt(5)
	v_mfma_f32_32x32x16_bf16 v[50:65], v[156:159], v[164:167], v[50:65]
	ds_read_b128 v[184:187], v204 offset:8192
	v_mfma_f32_32x32x16_bf16 v[34:49], v[156:159], v[168:171], v[34:49]
	ds_read_b128 v[188:191], v204 offset:12288
	s_add_u32 s4, s4, 0x80
	s_addc_u32 s5, s5, 0
	s_waitcnt lgkmcnt(6)
	v_mfma_f32_32x32x16_bf16 v[18:33], v[160:163], v[164:167], v[18:33]
	v_mfma_f32_32x32x16_bf16 v[2:17], v[160:163], v[168:171], v[2:17]
	s_waitcnt lgkmcnt(4)
	v_mfma_f32_32x32x16_bf16 v[114:129], v[172:175], v[192:195], v[114:129]
	ds_read_b128 v[130:133], v205 offset:0
	s_waitcnt lgkmcnt(4)
	v_mfma_f32_32x32x16_bf16 v[98:113], v[172:175], v[200:203], v[98:113]
	ds_read_b128 v[164:167], v209 offset:0
	s_waitcnt lgkmcnt(4)
	v_mfma_f32_32x32x16_bf16 v[82:97], v[180:183], v[192:195], v[82:97]
	ds_read_b128 v[168:171], v209 offset:4096
	v_mfma_f32_32x32x16_bf16 v[66:81], v[180:183], v[200:203], v[66:81]
	ds_read_b128 v[134:137], v205 offset:4096
	s_waitcnt lgkmcnt(5)
	v_mfma_f32_32x32x16_bf16 v[50:65], v[184:187], v[192:195], v[50:65]
	ds_read_b128 v[156:159], v205 offset:8192
	v_mfma_f32_32x32x16_bf16 v[34:49], v[184:187], v[200:203], v[34:49]
	ds_read_b128 v[160:163], v205 offset:12288
	s_waitcnt lgkmcnt(6)
	v_mfma_f32_32x32x16_bf16 v[18:33], v[188:191], v[192:195], v[18:33]
	v_mfma_f32_32x32x16_bf16 v[2:17], v[188:191], v[200:203], v[2:17]
	s_waitcnt lgkmcnt(4)
	v_mfma_f32_32x32x16_bf16 v[114:129], v[130:133], v[164:167], v[114:129]
	ds_read_b128 v[172:175], v206 offset:0
	ds_read_b128 v[192:195], v210 offset:0
	s_waitcnt lgkmcnt(5)
	v_mfma_f32_32x32x16_bf16 v[98:113], v[130:133], v[168:171], v[98:113]
	ds_read_b128 v[200:203], v210 offset:4096
	ds_read_b128 v[180:183], v206 offset:4096
	s_waitcnt lgkmcnt(6)
	v_mfma_f32_32x32x16_bf16 v[82:97], v[134:137], v[164:167], v[82:97]
	ds_read_b128 v[184:187], v206 offset:8192
	ds_read_b128 v[188:191], v206 offset:12288
	v_mfma_f32_32x32x16_bf16 v[66:81], v[134:137], v[168:171], v[66:81]
	s_waitcnt lgkmcnt(7)
	v_mfma_f32_32x32x16_bf16 v[50:65], v[156:159], v[164:167], v[50:65]
	v_mfma_f32_32x32x16_bf16 v[34:49], v[156:159], v[168:171], v[34:49]
	s_waitcnt lgkmcnt(6)
	v_mfma_f32_32x32x16_bf16 v[18:33], v[160:163], v[164:167], v[18:33]
	v_mfma_f32_32x32x16_bf16 v[2:17], v[160:163], v[168:171], v[2:17]
	s_waitcnt vmcnt(0) lgkmcnt(0)
	s_barrier
	v_mfma_f32_32x32x16_bf16 v[114:129], v[172:175], v[192:195], v[114:129]
	ds_read_b128 v[130:133], v177 offset:32768
	v_mfma_f32_32x32x16_bf16 v[98:113], v[172:175], v[200:203], v[98:113]
	ds_read_b128 v[164:167], v207 offset:32768
	v_mfma_f32_32x32x16_bf16 v[82:97], v[180:183], v[192:195], v[82:97]
	ds_read_b128 v[168:171], v207 offset:36864
	v_mfma_f32_32x32x16_bf16 v[66:81], v[180:183], v[200:203], v[66:81]
	ds_read_b128 v[134:137], v177 offset:36864
	v_mfma_f32_32x32x16_bf16 v[50:65], v[184:187], v[192:195], v[50:65]
	ds_read_b128 v[156:159], v177 offset:40960
	v_mfma_f32_32x32x16_bf16 v[34:49], v[184:187], v[200:203], v[34:49]
	ds_read_b128 v[160:163], v177 offset:45056
	v_mfma_f32_32x32x16_bf16 v[18:33], v[188:191], v[192:195], v[18:33]
	v_mfma_f32_32x32x16_bf16 v[2:17], v[188:191], v[200:203], v[2:17]
	s_waitcnt lgkmcnt(4)
	v_mfma_f32_32x32x16_bf16 v[114:129], v[130:133], v[164:167], v[114:129]
	ds_read_b128 v[172:175], v204 offset:32768
	s_waitcnt lgkmcnt(4)
	v_mfma_f32_32x32x16_bf16 v[98:113], v[130:133], v[168:171], v[98:113]
	ds_read_b128 v[192:195], v208 offset:32768
	s_waitcnt lgkmcnt(4)
	v_mfma_f32_32x32x16_bf16 v[82:97], v[134:137], v[164:167], v[82:97]
	ds_read_b128 v[200:203], v208 offset:36864
	v_mfma_f32_32x32x16_bf16 v[66:81], v[134:137], v[168:171], v[66:81]
	ds_read_b128 v[180:183], v204 offset:36864
	s_waitcnt lgkmcnt(5)
	v_mfma_f32_32x32x16_bf16 v[50:65], v[156:159], v[164:167], v[50:65]
	ds_read_b128 v[184:187], v204 offset:40960
	v_mfma_f32_32x32x16_bf16 v[34:49], v[156:159], v[168:171], v[34:49]
	ds_read_b128 v[188:191], v204 offset:45056
	s_add_u32 s4, s4, 0x80
	s_addc_u32 s5, s5, 0
	s_waitcnt lgkmcnt(6)
	v_mfma_f32_32x32x16_bf16 v[18:33], v[160:163], v[164:167], v[18:33]
	v_mfma_f32_32x32x16_bf16 v[2:17], v[160:163], v[168:171], v[2:17]
	s_waitcnt lgkmcnt(4)
	v_mfma_f32_32x32x16_bf16 v[114:129], v[172:175], v[192:195], v[114:129]
	ds_read_b128 v[130:133], v205 offset:32768
	s_waitcnt lgkmcnt(4)
	v_mfma_f32_32x32x16_bf16 v[98:113], v[172:175], v[200:203], v[98:113]
	ds_read_b128 v[164:167], v209 offset:32768
	s_waitcnt lgkmcnt(4)
	v_mfma_f32_32x32x16_bf16 v[82:97], v[180:183], v[192:195], v[82:97]
	ds_read_b128 v[168:171], v209 offset:36864
	v_mfma_f32_32x32x16_bf16 v[66:81], v[180:183], v[200:203], v[66:81]
	ds_read_b128 v[134:137], v205 offset:36864
	s_waitcnt lgkmcnt(5)
	v_mfma_f32_32x32x16_bf16 v[50:65], v[184:187], v[192:195], v[50:65]
	ds_read_b128 v[156:159], v205 offset:40960
	v_mfma_f32_32x32x16_bf16 v[34:49], v[184:187], v[200:203], v[34:49]
	ds_read_b128 v[160:163], v205 offset:45056
	s_waitcnt lgkmcnt(6)
	v_mfma_f32_32x32x16_bf16 v[18:33], v[188:191], v[192:195], v[18:33]
	v_mfma_f32_32x32x16_bf16 v[2:17], v[188:191], v[200:203], v[2:17]
	s_waitcnt lgkmcnt(4)
	v_mfma_f32_32x32x16_bf16 v[114:129], v[130:133], v[164:167], v[114:129]
	ds_read_b128 v[172:175], v206 offset:32768
	ds_read_b128 v[192:195], v210 offset:32768
	s_waitcnt lgkmcnt(5)
	v_mfma_f32_32x32x16_bf16 v[98:113], v[130:133], v[168:171], v[98:113]
	ds_read_b128 v[200:203], v210 offset:36864
	ds_read_b128 v[180:183], v206 offset:36864
	s_waitcnt lgkmcnt(6)
	v_mfma_f32_32x32x16_bf16 v[82:97], v[134:137], v[164:167], v[82:97]
	ds_read_b128 v[184:187], v206 offset:40960
	ds_read_b128 v[188:191], v206 offset:45056
	v_mfma_f32_32x32x16_bf16 v[66:81], v[134:137], v[168:171], v[66:81]
	s_waitcnt lgkmcnt(7)
	v_mfma_f32_32x32x16_bf16 v[50:65], v[156:159], v[164:167], v[50:65]
	v_mfma_f32_32x32x16_bf16 v[34:49], v[156:159], v[168:171], v[34:49]
	s_waitcnt lgkmcnt(6)
	v_mfma_f32_32x32x16_bf16 v[18:33], v[160:163], v[164:167], v[18:33]
	v_mfma_f32_32x32x16_bf16 v[2:17], v[160:163], v[168:171], v[2:17]
	s_waitcnt vmcnt(0) lgkmcnt(0)
	s_barrier
	v_mfma_f32_32x32x16_bf16 v[114:129], v[172:175], v[192:195], v[114:129]
	ds_read_b128 v[130:133], v177 offset:0
	v_mfma_f32_32x32x16_bf16 v[98:113], v[172:175], v[200:203], v[98:113]
	ds_read_b128 v[164:167], v207 offset:0
	v_mfma_f32_32x32x16_bf16 v[82:97], v[180:183], v[192:195], v[82:97]
	ds_read_b128 v[168:171], v207 offset:4096
	v_mfma_f32_32x32x16_bf16 v[66:81], v[180:183], v[200:203], v[66:81]
	ds_read_b128 v[134:137], v177 offset:4096
	v_mfma_f32_32x32x16_bf16 v[50:65], v[184:187], v[192:195], v[50:65]
	ds_read_b128 v[156:159], v177 offset:8192
	v_mfma_f32_32x32x16_bf16 v[34:49], v[184:187], v[200:203], v[34:49]
	ds_read_b128 v[160:163], v177 offset:12288
	v_mfma_f32_32x32x16_bf16 v[18:33], v[188:191], v[192:195], v[18:33]
	v_mfma_f32_32x32x16_bf16 v[2:17], v[188:191], v[200:203], v[2:17]
	s_sub_u32 s11, s11, 1
	s_cmp_lg_u32 s11, 0
	s_cbranch_scc1 .Lgl24_loop
	s_waitcnt lgkmcnt(4)
	v_mfma_f32_32x32x16_bf16 v[114:129], v[130:133], v[164:167], v[114:129]
	ds_read_b128 v[172:175], v204 offset:0
	s_waitcnt lgkmcnt(4)
	v_mfma_f32_32x32x16_bf16 v[98:113], v[130:133], v[168:171], v[98:113]
	ds_read_b128 v[192:195], v208 offset:0
	s_waitcnt lgkmcnt(4)
	v_mfma_f32_32x32x16_bf16 v[82:97], v[134:137], v[164:167], v[82:97]
	ds_read_b128 v[200:203], v208 offset:4096
	v_mfma_f32_32x32x16_bf16 v[66:81], v[134:137], v[168:171], v[66:81]
	ds_read_b128 v[180:183], v204 offset:4096
	s_waitcnt lgkmcnt(5)
	v_mfma_f32_32x32x16_bf16 v[50:65], v[156:159], v[164:167], v[50:65]
	ds_read_b128 v[184:187], v204 offset:8192
	v_mfma_f32_32x32x16_bf16 v[34:49], v[156:159], v[168:171], v[34:49]
	ds_read_b128 v[188:191], v204 offset:12288
	s_add_u32 s4, s4, 0x80
	s_addc_u32 s5, s5, 0
	s_waitcnt lgkmcnt(6)
	v_mfma_f32_32x32x16_bf16 v[18:33], v[160:163], v[164:167], v[18:33]
	v_mfma_f32_32x32x16_bf16 v[2:17], v[160:163], v[168:171], v[2:17]
	s_waitcnt lgkmcnt(4)
	v_mfma_f32_32x32x16_bf16 v[114:129], v[172:175], v[192:195], v[114:129]
	ds_read_b128 v[130:133], v205 offset:0
	s_waitcnt lgkmcnt(4)
	v_mfma_f32_32x32x16_bf16 v[98:113], v[172:175], v[200:203], v[98:113]
	ds_read_b128 v[164:167], v209 offset:0
	s_waitcnt lgkmcnt(4)
	v_mfma_f32_32x32x16_bf16 v[82:97], v[180:183], v[192:195], v[82:97]
	ds_read_b128 v[168:171], v209 offset:4096
	v_mfma_f32_32x32x16_bf16 v[66:81], v[180:183], v[200:203], v[66:81]
	ds_read_b128 v[134:137], v205 offset:4096
	s_waitcnt lgkmcnt(5)
	v_mfma_f32_32x32x16_bf16 v[50:65], v[184:187], v[192:195], v[50:65]
	ds_read_b128 v[156:159], v205 offset:8192
	v_mfma_f32_32x32x16_bf16 v[34:49], v[184:187], v[200:203], v[34:49]
	ds_read_b128 v[160:163], v205 offset:12288
	s_waitcnt lgkmcnt(6)
	v_mfma_f32_32x32x16_bf16 v[18:33], v[188:191], v[192:195], v[18:33]
	v_mfma_f32_32x32x16_bf16 v[2:17], v[188:191], v[200:203], v[2:17]
	s_waitcnt lgkmcnt(4)
	v_mfma_f32_32x32x16_bf16 v[114:129], v[130:133], v[164:167], v[114:129]
	ds_read_b128 v[172:175], v206 offset:0
	ds_read_b128 v[192:195], v210 offset:0
	s_waitcnt lgkmcnt(5)
	v_mfma_f32_32x32x16_bf16 v[98:113], v[130:133], v[168:171], v[98:113]
	ds_read_b128 v[200:203], v210 offset:4096
	ds_read_b128 v[180:183], v206 offset:4096
	s_waitcnt lgkmcnt(6)
	v_mfma_f32_32x32x16_bf16 v[82:97], v[134:137], v[164:167], v[82:97]
	ds_read_b128 v[184:187], v206 offset:8192
	ds_read_b128 v[188:191], v206 offset:12288
	v_mfma_f32_32x32x16_bf16 v[66:81], v[134:137], v[168:171], v[66:81]
	s_waitcnt lgkmcnt(7)
	v_mfma_f32_32x32x16_bf16 v[50:65], v[156:159], v[164:167], v[50:65]
	v_mfma_f32_32x32x16_bf16 v[34:49], v[156:159], v[168:171], v[34:49]
	s_waitcnt lgkmcnt(6)
	v_mfma_f32_32x32x16_bf16 v[18:33], v[160:163], v[164:167], v[18:33]
	v_mfma_f32_32x32x16_bf16 v[2:17], v[160:163], v[168:171], v[2:17]
	s_waitcnt vmcnt(0) lgkmcnt(0)
	s_barrier
	v_mfma_f32_32x32x16_bf16 v[114:129], v[172:175], v[192:195], v[114:129]
	ds_read_b128 v[130:133], v177 offset:32768
	v_mfma_f32_32x32x16_bf16 v[98:113], v[172:175], v[200:203], v[98:113]
	ds_read_b128 v[164:167], v207 offset:32768
	v_mfma_f32_32x32x16_bf16 v[82:97], v[180:183], v[192:195], v[82:97]
	ds_read_b128 v[168:171], v207 offset:36864
	v_mfma_f32_32x32x16_bf16 v[66:81], v[180:183], v[200:203], v[66:81]
	ds_read_b128 v[134:137], v177 offset:36864
	v_mfma_f32_32x32x16_bf16 v[50:65], v[184:187], v[192:195], v[50:65]
	ds_read_b128 v[156:159], v177 offset:40960
	v_mfma_f32_32x32x16_bf16 v[34:49], v[184:187], v[200:203], v[34:49]
	ds_read_b128 v[160:163], v177 offset:45056
	v_mfma_f32_32x32x16_bf16 v[18:33], v[188:191], v[192:195], v[18:33]
	v_mfma_f32_32x32x16_bf16 v[2:17], v[188:191], v[200:203], v[2:17]
	s_waitcnt lgkmcnt(4)
	v_mfma_f32_32x32x16_bf16 v[114:129], v[130:133], v[164:167], v[114:129]
	ds_read_b128 v[172:175], v204 offset:32768
	s_waitcnt lgkmcnt(4)
	v_mfma_f32_32x32x16_bf16 v[98:113], v[130:133], v[168:171], v[98:113]
	ds_read_b128 v[192:195], v208 offset:32768
	s_waitcnt lgkmcnt(4)
	v_mfma_f32_32x32x16_bf16 v[82:97], v[134:137], v[164:167], v[82:97]
	ds_read_b128 v[200:203], v208 offset:36864
	v_mfma_f32_32x32x16_bf16 v[66:81], v[134:137], v[168:171], v[66:81]
	ds_read_b128 v[180:183], v204 offset:36864
	s_waitcnt lgkmcnt(5)
	v_mfma_f32_32x32x16_bf16 v[50:65], v[156:159], v[164:167], v[50:65]
	ds_read_b128 v[184:187], v204 offset:40960
	v_mfma_f32_32x32x16_bf16 v[34:49], v[156:159], v[168:171], v[34:49]
	ds_read_b128 v[188:191], v204 offset:45056
	s_waitcnt lgkmcnt(6)
	v_mfma_f32_32x32x16_bf16 v[18:33], v[160:163], v[164:167], v[18:33]
	v_mfma_f32_32x32x16_bf16 v[2:17], v[160:163], v[168:171], v[2:17]
	s_waitcnt lgkmcnt(4)
	v_mfma_f32_32x32x16_bf16 v[114:129], v[172:175], v[192:195], v[114:129]
	ds_read_b128 v[130:133], v205 offset:32768
	s_waitcnt lgkmcnt(4)
	v_mfma_f32_32x32x16_bf16 v[98:113], v[172:175], v[200:203], v[98:113]
	ds_read_b128 v[164:167], v209 offset:32768
	s_waitcnt lgkmcnt(4)
	v_mfma_f32_32x32x16_bf16 v[82:97], v[180:183], v[192:195], v[82:97]
	ds_read_b128 v[168:171], v209 offset:36864
	v_mfma_f32_32x32x16_bf16 v[66:81], v[180:183], v[200:203], v[66:81]
	ds_read_b128 v[134:137], v205 offset:36864
	s_waitcnt lgkmcnt(5)
	v_mfma_f32_32x32x16_bf16 v[50:65], v[184:187], v[192:195], v[50:65]
	ds_read_b128 v[156:159], v205 offset:40960
	v_mfma_f32_32x32x16_bf16 v[34:49], v[184:187], v[200:203], v[34:49]
	ds_read_b128 v[160:163], v205 offset:45056
	s_waitcnt lgkmcnt(6)
	v_mfma_f32_32x32x16_bf16 v[18:33], v[188:191], v[192:195], v[18:33]
	v_mfma_f32_32x32x16_bf16 v[2:17], v[188:191], v[200:203], v[2:17]
	s_waitcnt lgkmcnt(4)
	v_mfma_f32_32x32x16_bf16 v[114:129], v[130:133], v[164:167], v[114:129]
	ds_read_b128 v[172:175], v206 offset:32768
	ds_read_b128 v[192:195], v210 offset:32768
	s_waitcnt lgkmcnt(5)
	v_mfma_f32_32x32x16_bf16 v[98:113], v[130:133], v[168:171], v[98:113]
	ds_read_b128 v[200:203], v210 offset:36864
	ds_read_b128 v[180:183], v206 offset:36864
	s_waitcnt lgkmcnt(6)
	v_mfma_f32_32x32x16_bf16 v[82:97], v[134:137], v[164:167], v[82:97]
	ds_read_b128 v[184:187], v206 offset:40960
	ds_read_b128 v[188:191], v206 offset:45056
	v_mfma_f32_32x32x16_bf16 v[66:81], v[134:137], v[168:171], v[66:81]
	s_waitcnt lgkmcnt(7)
	v_mfma_f32_32x32x16_bf16 v[50:65], v[156:159], v[164:167], v[50:65]
	v_mfma_f32_32x32x16_bf16 v[34:49], v[156:159], v[168:171], v[34:49]
	s_waitcnt lgkmcnt(6)
	v_mfma_f32_32x32x16_bf16 v[18:33], v[160:163], v[164:167], v[18:33]
	v_mfma_f32_32x32x16_bf16 v[2:17], v[160:163], v[168:171], v[2:17]
	s_waitcnt vmcnt(0) lgkmcnt(0)
	s_barrier
	v_mfma_f32_32x32x16_bf16 v[114:129], v[172:175], v[192:195], v[114:129]
	v_mfma_f32_32x32x16_bf16 v[98:113], v[172:175], v[200:203], v[98:113]
	v_mfma_f32_32x32x16_bf16 v[82:97], v[180:183], v[192:195], v[82:97]
	v_mfma_f32_32x32x16_bf16 v[66:81], v[180:183], v[200:203], v[66:81]
	v_mfma_f32_32x32x16_bf16 v[50:65], v[184:187], v[192:195], v[50:65]
	v_mfma_f32_32x32x16_bf16 v[34:49], v[184:187], v[200:203], v[34:49]
	v_mfma_f32_32x32x16_bf16 v[18:33], v[188:191], v[192:195], v[18:33]
	v_mfma_f32_32x32x16_bf16 v[2:17], v[188:191], v[200:203], v[2:17]
.Lg24_end:
	s_setprio 0
	v_add_u32_e32 v130, s0, v149
	v_ashrrev_i32_e32 v131, 31, v130
	v_lshrrev_b32_e32 v155, 18, v131
	v_add_u32_e32 v0, v130, v155
	v_ashrrev_i32_e32 v0, 14, v0
	v_mul_i32_i24_e32 v133, 0x4000, v0
	v_sub_u32_e32 v133, v130, v133
	v_add_u32_e32 v156, 0x100, v133
	v_mul_hi_i32_i24_e32 v137, 0x4100, v0
	v_mul_i32_i24_e32 v136, 0x4100, v0
	v_ashrrev_i32_e32 v157, 31, v156
	v_lshl_add_u64 v[136:137], v[136:137], 0, v[156:157]
	v_mov_b32_e32 v156, v179
	s_waitcnt vmcnt(0)
	s_barrier
	v_mul_i32_i24_e32 v134, 0xc00, v0
	v_readlane_b32 s40, v251, 2
	v_and_b32_e32 v0, 31, v156
	v_bfe_u32 v133, v156, 5, 1
	v_mul_u32_u24_e32 v133, 0x240, v133
	v_lshlrev_b32_e32 v0, 2, v0
	v_add3_u32 v0, v151, v133, v0
	ds_write2_b32 v0, v114, v115 offset1:36
	ds_write2_b32 v0, v116, v117 offset0:72 offset1:108
	v_add_u32_e32 v114, 0x400, v0
	v_or_b32_e32 v132, s2, v150
	ds_write2_b32 v114, v118, v119 offset0:32 offset1:68
	ds_write2_b32 v114, v120, v121 offset0:104 offset1:140
	v_add_u32_e32 v114, 0x800, v0
	v_add_u32_e32 v0, 0xc00, v0
	v_readlane_b32 s41, v251, 3
	v_readlane_b32 s42, v251, 4
	v_readlane_b32 s43, v251, 5
	v_readlane_b32 s44, v251, 6
	v_readlane_b32 s45, v251, 7
	v_readlane_b32 s46, v251, 8
	v_readlane_b32 s47, v251, 9
	v_readlane_b32 s48, v251, 10
	v_readlane_b32 s49, v251, 11
	v_readlane_b32 s50, v251, 12
	v_readlane_b32 s51, v251, 13
	v_readlane_b32 s0, v251, 26
	v_ashrrev_i32_e32 v135, 31, v134
	v_lshlrev_b64 v[136:137], 11, v[136:137]
	ds_write2_b32 v114, v122, v123 offset0:64 offset1:100
	ds_write2_b32 v114, v124, v125 offset0:136 offset1:172
	ds_write2_b32 v0, v126, v127 offset0:96 offset1:132
	ds_write2_b32 v0, v128, v129 offset0:168 offset1:204
	v_readlane_b32 s54, v251, 16
	v_readlane_b32 s55, v251, 17
	v_ashrrev_i32_e32 v133, 31, v132
	v_readlane_b32 s1, v251, 27
	v_readlane_b32 s36, v253, 47
	v_lshlrev_b32_e32 v0, 2, v156
	v_readlane_b32 s52, v251, 14
	v_readlane_b32 s53, v251, 15
	v_lshl_add_u64 v[114:115], v[134:135], 2, s[54:55]
	s_mov_b64 s[2:3], 0x1b0b000
	v_lshl_add_u64 v[118:119], s[0:1], 0, v[136:137]
	v_lshlrev_b64 v[116:117], 1, v[132:133]
	v_lshlrev_b64 v[122:123], 12, v[130:131]
	v_readlane_b32 s37, v253, 48
	v_and_b32_e32 v128, 28, v0
	v_lshl_add_u64 v[120:121], v[114:115], 0, s[2:3]
	v_lshlrev_b64 v[114:115], 2, v[132:133]
	v_lshl_add_u64 v[118:119], v[118:119], 0, v[116:117]
	v_lshl_add_u64 v[124:125], s[36:37], 0, v[122:123]
	v_lshl_add_u64 v[122:123], s[52:53], 0, v[122:123]
	v_lshlrev_b32_e32 v0, 2, v128
	v_lshlrev_b32_e32 v128, 1, v128
	v_mov_b32_e32 v129, v1
	v_bfe_u32 v133, v156, 3, 3
	v_lshl_add_u64 v[126:127], v[120:121], 0, v[114:115]
	v_lshl_add_u64 v[124:125], v[124:125], 0, v[114:115]
	v_lshl_add_u64 v[122:123], v[122:123], 0, v[114:115]
	v_lshl_add_u64 v[134:135], v[118:119], 0, v[128:129]
	v_mul_u32_u24_e32 v131, 0x90, v133
	v_lshlrev_b32_e32 v156, 11, v133
	v_mov_b32_e32 v157, v1
	s_waitcnt lgkmcnt(0)
	v_lshl_add_u64 v[126:127], v[126:127], 0, v[0:1]
	v_lshl_add_u64 v[136:137], v[124:125], 0, v[0:1]
	v_lshl_add_u64 v[128:129], v[122:123], 0, v[0:1]
	v_add3_u32 v131, v151, v0, v131
	v_lshlrev_b32_e32 v0, 12, v133
	v_lshl_add_u64 v[156:157], v[134:135], 0, v[156:157]
	v_lshl_add_u64 v[164:165], v[136:137], 0, v[0:1]
	global_load_dwordx4 v[180:183], v[126:127], off
	v_mov_b32_e32 v212, v133
	v_lshlrev_b32_e32 v184, 11, v212
	v_mov_b32_e32 v185, v1
	v_lshl_add_u64 v[184:185], v[134:135], 0, v[184:185]
	global_load_dwordx2 v[184:185], v[184:185], off
	v_lshlrev_b32_e32 v192, 12, v212
	v_mov_b32_e32 v193, v1
	v_lshl_add_u64 v[192:193], v[136:137], 0, v[192:193]
	global_load_dwordx4 v[192:195], v[192:193], off
	v_or_b32_e32 v212, 8, v133
	v_lshlrev_b32_e32 v186, 11, v212
	v_mov_b32_e32 v187, v1
	v_lshl_add_u64 v[186:187], v[134:135], 0, v[186:187]
	global_load_dwordx2 v[186:187], v[186:187], off
	v_lshlrev_b32_e32 v200, 12, v212
	v_mov_b32_e32 v201, v1
	v_lshl_add_u64 v[200:201], v[136:137], 0, v[200:201]
	global_load_dwordx4 v[200:203], v[200:201], off
	v_or_b32_e32 v212, 16, v133
	v_lshlrev_b32_e32 v188, 11, v212
	v_mov_b32_e32 v189, v1
	v_lshl_add_u64 v[188:189], v[134:135], 0, v[188:189]
	global_load_dwordx2 v[188:189], v[188:189], off
	v_lshlrev_b32_e32 v204, 12, v212
	v_mov_b32_e32 v205, v1
	v_lshl_add_u64 v[204:205], v[136:137], 0, v[204:205]
	global_load_dwordx4 v[204:207], v[204:205], off
	v_or_b32_e32 v212, 24, v133
	v_lshlrev_b32_e32 v190, 11, v212
	v_mov_b32_e32 v191, v1
	v_lshl_add_u64 v[190:191], v[134:135], 0, v[190:191]
	global_load_dwordx2 v[190:191], v[190:191], off
	v_lshlrev_b32_e32 v208, 12, v212
	v_mov_b32_e32 v209, v1
	v_lshl_add_u64 v[208:209], v[136:137], 0, v[208:209]
	global_load_dwordx4 v[208:211], v[208:209], off
	s_waitcnt vmcnt(6)
	v_mov_b32_e32 v168, v184
	v_mov_b32_e32 v169, v185
	ds_read_b128 v[156:159], v131
	v_mov_b32_e32 v160, v180
	v_mov_b32_e32 v161, v181
	v_mov_b32_e32 v162, v182
	v_mov_b32_e32 v163, v183
	s_nop 0
	v_mov_b32_e32 v164, v192
	v_mov_b32_e32 v165, v193
	v_mov_b32_e32 v166, v194
	v_mov_b32_e32 v167, v195
	v_lshl_add_u64 v[170:171], v[128:129], 0, v[0:1]
	v_readlane_b32 s38, v253, 49
	v_readlane_b32 s39, v253, 50
	v_readlane_b32 s42, v253, 53
	v_readlane_b32 s43, v253, 54
	v_readlane_b32 s44, v253, 55
	v_readlane_b32 s45, v253, 56
	v_readlane_b32 s46, v253, 57
	v_readlane_b32 s47, v253, 58
	v_readlane_b32 s48, v253, 59
	v_readlane_b32 s49, v253, 60
	v_readlane_b32 s51, v253, 62
	v_readlane_b32 s40, v253, 51
	v_readlane_b32 s41, v253, 52
	v_readlane_b32 s50, v253, 61
	v_and_b32_e32 v173, 0xffff0000, v168
	v_lshlrev_b32_e32 v172, 16, v168
	v_pk_add_f32 v[164:165], v[164:165], v[172:173]
	s_waitcnt lgkmcnt(0)
	v_pk_fma_f32 v[156:157], v[156:157], v[160:161], v[164:165]
	v_and_b32_e32 v161, 0xffff0000, v169
	v_lshlrev_b32_e32 v160, 16, v169
	v_pk_add_f32 v[160:161], v[166:167], v[160:161]
	s_nop 0
	v_pk_fma_f32 v[158:159], v[158:159], v[162:163], v[160:161]
	global_store_dwordx4 v[170:171], v[156:159], off
	s_nop 1
	v_or_b32_e32 v156, 8, v133
	v_lshlrev_b32_e32 v0, 12, v156
	v_lshlrev_b32_e32 v156, 11, v156
	v_mov_b32_e32 v157, v1
	v_lshl_add_u64 v[156:157], v[134:135], 0, v[156:157]
	v_lshl_add_u64 v[164:165], v[136:137], 0, v[0:1]
	s_waitcnt vmcnt(5)
	v_mov_b32_e32 v168, v186
	v_mov_b32_e32 v169, v187
	ds_read_b128 v[156:159], v131 offset:1152
	v_mov_b32_e32 v160, v180
	v_mov_b32_e32 v161, v181
	v_mov_b32_e32 v162, v182
	v_mov_b32_e32 v163, v183
	s_nop 0
	v_mov_b32_e32 v164, v200
	v_mov_b32_e32 v165, v201
	v_mov_b32_e32 v166, v202
	v_mov_b32_e32 v167, v203
	v_lshl_add_u64 v[170:171], v[128:129], 0, v[0:1]
	v_or_b32_e32 v0, 16, v133
	v_and_b32_e32 v173, 0xffff0000, v168
	v_lshlrev_b32_e32 v172, 16, v168
	v_pk_add_f32 v[164:165], v[164:165], v[172:173]
	s_waitcnt lgkmcnt(0)
	v_pk_fma_f32 v[156:157], v[156:157], v[160:161], v[164:165]
	v_and_b32_e32 v161, 0xffff0000, v169
	v_lshlrev_b32_e32 v160, 16, v169
	v_pk_add_f32 v[160:161], v[166:167], v[160:161]
	s_nop 0
	v_pk_fma_f32 v[158:159], v[158:159], v[162:163], v[160:161]
	global_store_dwordx4 v[170:171], v[156:159], off
	s_nop 1
	v_lshlrev_b32_e32 v158, 11, v0
	v_mov_b32_e32 v159, v1
	v_lshlrev_b32_e32 v156, 12, v0
	v_mov_b32_e32 v157, v1
	v_lshl_add_u64 v[158:159], v[134:135], 0, v[158:159]
	v_lshl_add_u64 v[164:165], v[136:137], 0, v[156:157]
	s_waitcnt vmcnt(4)
	v_mov_b32_e32 v168, v188
	v_mov_b32_e32 v169, v189
	v_lshl_add_u64 v[170:171], v[128:129], 0, v[156:157]
	ds_read_b128 v[156:159], v131 offset:2304
	v_mov_b32_e32 v160, v180
	v_mov_b32_e32 v161, v181
	v_mov_b32_e32 v162, v182
	v_mov_b32_e32 v163, v183
	s_nop 0
	v_mov_b32_e32 v164, v204
	v_mov_b32_e32 v165, v205
	v_mov_b32_e32 v166, v206
	v_mov_b32_e32 v167, v207
	v_or_b32_e32 v0, 24, v133
	v_and_b32_e32 v173, 0xffff0000, v168
	v_lshlrev_b32_e32 v172, 16, v168
	v_pk_add_f32 v[164:165], v[164:165], v[172:173]
	s_waitcnt lgkmcnt(0)
	v_pk_fma_f32 v[156:157], v[156:157], v[160:161], v[164:165]
	v_and_b32_e32 v161, 0xffff0000, v169
	v_lshlrev_b32_e32 v160, 16, v169
	v_pk_add_f32 v[160:161], v[166:167], v[160:161]
	s_nop 0
	v_pk_fma_f32 v[158:159], v[158:159], v[162:163], v[160:161]
	global_store_dwordx4 v[170:171], v[156:159], off
	s_nop 1
	v_lshlrev_b32_e32 v156, 12, v0
	v_mov_b32_e32 v157, v1
	v_lshl_add_u64 v[158:159], v[136:137], 0, v[156:157]
	v_lshlrev_b32_e32 v136, 11, v0
	v_mov_b32_e32 v137, v1
	v_lshl_add_u64 v[134:135], v[134:135], 0, v[136:137]
	s_waitcnt vmcnt(3)
	v_mov_b32_e32 v160, v190
	v_mov_b32_e32 v161, v191
	v_lshl_add_u64 v[162:163], v[128:129], 0, v[156:157]
	ds_read_b128 v[134:137], v131 offset:3456
	v_mov_b32_e32 v126, v180
	v_mov_b32_e32 v127, v181
	v_mov_b32_e32 v128, v182
	v_mov_b32_e32 v129, v183
	s_nop 0
	v_mov_b32_e32 v156, v208
	v_mov_b32_e32 v157, v209
	v_mov_b32_e32 v158, v210
	v_mov_b32_e32 v159, v211
	v_and_b32_e32 v165, 0xffff0000, v160
	v_lshlrev_b32_e32 v164, 16, v160
	v_pk_add_f32 v[156:157], v[156:157], v[164:165]
	s_waitcnt lgkmcnt(0)
	v_pk_fma_f32 v[126:127], v[134:135], v[126:127], v[156:157]
	v_and_b32_e32 v135, 0xffff0000, v161
	v_lshlrev_b32_e32 v134, 16, v161
	v_pk_add_f32 v[134:135], v[158:159], v[134:135]
	s_nop 0
	v_pk_fma_f32 v[128:129], v[136:137], v[128:129], v[134:135]
	global_store_dwordx4 v[162:163], v[126:129], off
	v_mov_b32_e32 v0, v179
	s_nop 0
	v_or_b32_e32 v126, 32, v132
	v_and_b32_e32 v127, 31, v0
	v_bfe_u32 v128, v0, 5, 1
	v_mul_u32_u24_e32 v128, 0x240, v128
	v_lshlrev_b32_e32 v127, 2, v127
	v_add3_u32 v127, v151, v128, v127
	ds_write2_b32 v127, v98, v99 offset1:36
	ds_write2_b32 v127, v100, v101 offset0:72 offset1:108
	v_add_u32_e32 v98, 0x400, v127
	ds_write2_b32 v98, v102, v103 offset0:32 offset1:68
	ds_write2_b32 v98, v104, v105 offset0:104 offset1:140
	v_add_u32_e32 v98, 0x800, v127
	ds_write2_b32 v98, v106, v107 offset0:64 offset1:100
	ds_write2_b32 v98, v108, v109 offset0:136 offset1:172
	v_add_u32_e32 v98, 0xc00, v127
	ds_write2_b32 v98, v110, v111 offset0:96 offset1:132
	ds_write2_b32 v98, v112, v113 offset0:168 offset1:204
	v_lshlrev_b32_e32 v98, 2, v0
	v_and_b32_e32 v102, 28, v98
	v_lshlrev_b32_e32 v108, 2, v102
	v_lshlrev_b32_e32 v102, 1, v102
	v_mov_b32_e32 v103, v1
	v_bfe_u32 v131, v0, 3, 3
	v_ashrrev_i32_e32 v127, 31, v126
	v_mov_b32_e32 v109, v1
	v_lshl_add_u64 v[104:105], v[118:119], 0, v[102:103]
	v_lshlrev_b32_e32 v110, 11, v131
	v_mov_b32_e32 v111, v1
	s_waitcnt lgkmcnt(0)
	v_lshl_add_u64 v[100:101], v[120:121], 0, v[108:109]
	v_lshlrev_b64 v[98:99], 2, v[126:127]
	v_mul_u32_u24_e32 v0, 0x90, v131
	v_lshl_add_u64 v[110:111], v[104:105], 0, v[110:111]
	v_lshl_add_u64 v[100:101], v[100:101], 0, v[98:99]
	v_lshl_add_u64 v[106:107], v[124:125], 0, v[108:109]
	v_lshl_add_u64 v[102:103], v[122:123], 0, v[108:109]
	v_add3_u32 v0, v151, v108, v0
	v_lshlrev_b32_e32 v108, 12, v131
	global_load_dwordx4 v[180:183], v[100:101], off
	v_mov_b32_e32 v212, v131
	v_lshlrev_b32_e32 v184, 11, v212
	v_mov_b32_e32 v185, v1
	v_lshl_add_u64 v[184:185], v[104:105], 0, v[184:185]
	global_load_dwordx2 v[184:185], v[184:185], off offset:64
	v_lshlrev_b32_e32 v192, 12, v212
	v_mov_b32_e32 v193, v1
	v_lshl_add_u64 v[192:193], v[106:107], 0, v[192:193]
	global_load_dwordx4 v[192:195], v[192:193], off offset:128
	v_or_b32_e32 v212, 8, v131
	v_lshlrev_b32_e32 v186, 11, v212
	v_mov_b32_e32 v187, v1
	v_lshl_add_u64 v[186:187], v[104:105], 0, v[186:187]
	global_load_dwordx2 v[186:187], v[186:187], off offset:64
	v_lshlrev_b32_e32 v200, 12, v212
	v_mov_b32_e32 v201, v1
	v_lshl_add_u64 v[200:201], v[106:107], 0, v[200:201]
	global_load_dwordx4 v[200:203], v[200:201], off offset:128
	v_or_b32_e32 v212, 16, v131
	v_lshlrev_b32_e32 v188, 11, v212
	v_mov_b32_e32 v189, v1
	v_lshl_add_u64 v[188:189], v[104:105], 0, v[188:189]
	global_load_dwordx2 v[188:189], v[188:189], off offset:64
	v_lshlrev_b32_e32 v204, 12, v212
	v_mov_b32_e32 v205, v1
	v_lshl_add_u64 v[204:205], v[106:107], 0, v[204:205]
	global_load_dwordx4 v[204:207], v[204:205], off offset:128
	v_or_b32_e32 v212, 24, v131
	v_lshlrev_b32_e32 v190, 11, v212
	v_mov_b32_e32 v191, v1
	v_lshl_add_u64 v[190:191], v[104:105], 0, v[190:191]
	global_load_dwordx2 v[190:191], v[190:191], off offset:64
	v_lshlrev_b32_e32 v208, 12, v212
	v_mov_b32_e32 v209, v1
	v_lshl_add_u64 v[208:209], v[106:107], 0, v[208:209]
	global_load_dwordx4 v[208:211], v[208:209], off offset:128
	s_waitcnt vmcnt(6)
	v_mov_b32_e32 v126, v184
	v_mov_b32_e32 v127, v185
	v_lshl_add_u64 v[112:113], v[106:107], 0, v[108:109]
	v_lshl_add_u64 v[128:129], v[102:103], 0, v[108:109]
	ds_read_b128 v[108:111], v0
	v_mov_b32_e32 v118, v180
	v_mov_b32_e32 v119, v181
	v_mov_b32_e32 v120, v182
	v_mov_b32_e32 v121, v183
	v_mov_b32_e32 v122, v192
	v_mov_b32_e32 v123, v193
	v_mov_b32_e32 v124, v194
	v_mov_b32_e32 v125, v195
	v_and_b32_e32 v113, 0xffff0000, v126
	v_lshlrev_b32_e32 v112, 16, v126
	v_pk_add_f32 v[112:113], v[122:123], v[112:113]
	s_waitcnt lgkmcnt(0)
	v_pk_fma_f32 v[108:109], v[108:109], v[118:119], v[112:113]
	v_and_b32_e32 v113, 0xffff0000, v127
	v_lshlrev_b32_e32 v112, 16, v127
	v_pk_add_f32 v[112:113], v[124:125], v[112:113]
	s_nop 0
	v_pk_fma_f32 v[110:111], v[110:111], v[120:121], v[112:113]
	global_store_dwordx4 v[128:129], v[108:111], off offset:128
	s_nop 1
	v_or_b32_e32 v110, 8, v131
	v_lshlrev_b32_e32 v108, 12, v110
	v_lshlrev_b32_e32 v110, 11, v110
	v_mov_b32_e32 v111, v1
	v_lshl_add_u64 v[110:111], v[104:105], 0, v[110:111]
	v_mov_b32_e32 v109, v1
	s_waitcnt vmcnt(5)
	v_mov_b32_e32 v126, v186
	v_mov_b32_e32 v127, v187
	v_lshl_add_u64 v[112:113], v[106:107], 0, v[108:109]
	v_lshl_add_u64 v[128:129], v[102:103], 0, v[108:109]
	ds_read_b128 v[108:111], v0 offset:1152
	v_mov_b32_e32 v118, v180
	v_mov_b32_e32 v119, v181
	v_mov_b32_e32 v120, v182
	v_mov_b32_e32 v121, v183
	v_mov_b32_e32 v122, v200
	v_mov_b32_e32 v123, v201
	v_mov_b32_e32 v124, v202
	v_mov_b32_e32 v125, v203
	v_and_b32_e32 v113, 0xffff0000, v126
	v_lshlrev_b32_e32 v112, 16, v126
	v_pk_add_f32 v[112:113], v[122:123], v[112:113]
	s_waitcnt lgkmcnt(0)
	v_pk_fma_f32 v[108:109], v[108:109], v[118:119], v[112:113]
	v_and_b32_e32 v113, 0xffff0000, v127
	v_lshlrev_b32_e32 v112, 16, v127
	v_pk_add_f32 v[112:113], v[124:125], v[112:113]
	s_nop 0
	v_pk_fma_f32 v[110:111], v[110:111], v[120:121], v[112:113]
	global_store_dwordx4 v[128:129], v[108:111], off offset:128
	s_nop 1
	v_or_b32_e32 v110, 16, v131
	v_lshlrev_b32_e32 v108, 12, v110
	v_lshlrev_b32_e32 v110, 11, v110
	v_mov_b32_e32 v111, v1
	v_lshl_add_u64 v[110:111], v[104:105], 0, v[110:111]
	v_mov_b32_e32 v109, v1
	s_waitcnt vmcnt(4)
	v_mov_b32_e32 v126, v188
	v_mov_b32_e32 v127, v189
	v_lshl_add_u64 v[112:113], v[106:107], 0, v[108:109]
	v_lshl_add_u64 v[128:129], v[102:103], 0, v[108:109]
	ds_read_b128 v[108:111], v0 offset:2304
	v_mov_b32_e32 v118, v180
	v_mov_b32_e32 v119, v181
	v_mov_b32_e32 v120, v182
	v_mov_b32_e32 v121, v183
	v_mov_b32_e32 v122, v204
	v_mov_b32_e32 v123, v205
	v_mov_b32_e32 v124, v206
	v_mov_b32_e32 v125, v207
	v_and_b32_e32 v113, 0xffff0000, v126
	v_lshlrev_b32_e32 v112, 16, v126
	v_pk_add_f32 v[112:113], v[122:123], v[112:113]
	s_waitcnt lgkmcnt(0)
	v_pk_fma_f32 v[108:109], v[108:109], v[118:119], v[112:113]
	v_and_b32_e32 v113, 0xffff0000, v127
	v_lshlrev_b32_e32 v112, 16, v127
	v_pk_add_f32 v[112:113], v[124:125], v[112:113]
	s_nop 0
	v_pk_fma_f32 v[110:111], v[110:111], v[120:121], v[112:113]
	v_or_b32_e32 v112, 24, v131
	global_store_dwordx4 v[128:129], v[108:111], off offset:128
	s_nop 1
	v_lshlrev_b32_e32 v108, 12, v112
	v_mov_b32_e32 v109, v1
	v_lshl_add_u64 v[110:111], v[106:107], 0, v[108:109]
	v_lshlrev_b32_e32 v106, 11, v112
	v_mov_b32_e32 v107, v1
	v_lshl_add_u64 v[104:105], v[104:105], 0, v[106:107]
	s_waitcnt vmcnt(3)
	v_mov_b32_e32 v118, v190
	v_mov_b32_e32 v119, v191
	v_lshl_add_u64 v[120:121], v[102:103], 0, v[108:109]
	ds_read_b128 v[102:105], v0 offset:3456
	v_mov_b32_e32 v106, v180
	v_mov_b32_e32 v107, v181
	v_mov_b32_e32 v108, v182
	v_mov_b32_e32 v109, v183
	s_nop 0
	v_mov_b32_e32 v110, v208
	v_mov_b32_e32 v111, v209
	v_mov_b32_e32 v112, v210
	v_mov_b32_e32 v113, v211
	v_and_b32_e32 v101, 0xffff0000, v118
	v_lshlrev_b32_e32 v100, 16, v118
	v_pk_add_f32 v[100:101], v[110:111], v[100:101]
	s_waitcnt lgkmcnt(0)
	v_pk_fma_f32 v[100:101], v[102:103], v[106:107], v[100:101]
	v_and_b32_e32 v103, 0xffff0000, v119
	v_lshlrev_b32_e32 v102, 16, v119
	v_pk_add_f32 v[102:103], v[112:113], v[102:103]
	s_nop 0
	v_pk_fma_f32 v[102:103], v[104:105], v[108:109], v[102:103]
	global_store_dwordx4 v[120:121], v[100:103], off offset:128
	s_nop 1
	v_or_b32_e32 v100, 32, v130
	v_add_u32_e32 v0, v100, v155
	v_ashrrev_i32_e32 v0, 14, v0
	v_mul_i32_i24_e32 v101, 0x4000, v0
	v_sub_u32_e32 v101, v100, v101
	v_add_u32_e32 v106, 0x100, v101
	v_mul_i32_i24_e32 v102, 0xc00, v0
	v_mul_hi_i32_i24_e32 v105, 0x4100, v0
	v_mul_i32_i24_e32 v104, 0x4100, v0
	v_ashrrev_i32_e32 v107, 31, v106
	v_mov_b32_e32 v0, v179
	v_lshl_add_u64 v[104:105], v[104:105], 0, v[106:107]
	v_ashrrev_i32_e32 v103, 31, v102
	v_and_b32_e32 v106, 31, v0
	v_bfe_u32 v107, v0, 5, 1
	v_mul_u32_u24_e32 v107, 0x240, v107
	v_lshlrev_b32_e32 v106, 2, v106
	v_add3_u32 v106, v151, v107, v106
	ds_write2_b32 v106, v82, v83 offset1:36
	ds_write2_b32 v106, v84, v85 offset0:72 offset1:108
	v_add_u32_e32 v82, 0x400, v106
	ds_write2_b32 v82, v86, v87 offset0:32 offset1:68
	ds_write2_b32 v82, v88, v89 offset0:104 offset1:140
	v_add_u32_e32 v82, 0x800, v106
	ds_write2_b32 v82, v90, v91 offset0:64 offset1:100
	ds_write2_b32 v82, v92, v93 offset0:136 offset1:172
	v_add_u32_e32 v82, 0xc00, v106
	v_lshlrev_b64 v[104:105], 11, v[104:105]
	v_ashrrev_i32_e32 v101, 31, v100
	ds_write2_b32 v82, v94, v95 offset0:96 offset1:132
	ds_write2_b32 v82, v96, v97 offset0:168 offset1:204
	v_lshl_add_u64 v[82:83], v[102:103], 2, s[54:55]
	v_lshlrev_b32_e32 v92, 2, v0
	v_lshl_add_u64 v[86:87], v[82:83], 0, s[2:3]
	v_lshl_add_u64 v[82:83], s[0:1], 0, v[104:105]
	v_lshlrev_b64 v[84:85], 12, v[100:101]
	v_and_b32_e32 v92, 28, v92
	v_lshl_add_u64 v[82:83], v[82:83], 0, v[116:117]
	v_lshl_add_u64 v[88:89], s[36:37], 0, v[84:85]
	v_lshl_add_u64 v[84:85], s[52:53], 0, v[84:85]
	v_lshlrev_b32_e32 v100, 2, v92
	v_lshlrev_b32_e32 v92, 1, v92
	v_mov_b32_e32 v93, v1
	v_bfe_u32 v122, v0, 3, 3
	v_lshl_add_u64 v[90:91], v[86:87], 0, v[114:115]
	v_lshl_add_u64 v[88:89], v[88:89], 0, v[114:115]
	v_lshl_add_u64 v[84:85], v[84:85], 0, v[114:115]
	v_mov_b32_e32 v101, v1
	v_lshl_add_u64 v[94:95], v[82:83], 0, v[92:93]
	v_mul_u32_u24_e32 v0, 0x90, v122
	v_lshlrev_b32_e32 v102, 11, v122
	v_mov_b32_e32 v103, v1
	s_waitcnt lgkmcnt(0)
	v_lshl_add_u64 v[90:91], v[90:91], 0, v[100:101]
	v_lshl_add_u64 v[96:97], v[88:89], 0, v[100:101]
	v_lshl_add_u64 v[92:93], v[84:85], 0, v[100:101]
	v_add3_u32 v0, v151, v100, v0
	v_lshlrev_b32_e32 v100, 12, v122
	v_lshl_add_u64 v[102:103], v[94:95], 0, v[102:103]
	v_lshl_add_u64 v[108:109], v[96:97], 0, v[100:101]
	global_load_dwordx4 v[180:183], v[90:91], off
	v_mov_b32_e32 v212, v122
	v_lshlrev_b32_e32 v184, 11, v212
	v_mov_b32_e32 v185, v1
	v_lshl_add_u64 v[184:185], v[94:95], 0, v[184:185]
	global_load_dwordx2 v[184:185], v[184:185], off
	v_lshlrev_b32_e32 v192, 12, v212
	v_mov_b32_e32 v193, v1
	v_lshl_add_u64 v[192:193], v[96:97], 0, v[192:193]
	global_load_dwordx4 v[192:195], v[192:193], off
	v_or_b32_e32 v212, 8, v122
	v_lshlrev_b32_e32 v186, 11, v212
	v_mov_b32_e32 v187, v1
	v_lshl_add_u64 v[186:187], v[94:95], 0, v[186:187]
	global_load_dwordx2 v[186:187], v[186:187], off
	v_lshlrev_b32_e32 v200, 12, v212
	v_mov_b32_e32 v201, v1
	v_lshl_add_u64 v[200:201], v[96:97], 0, v[200:201]
	global_load_dwordx4 v[200:203], v[200:201], off
	v_or_b32_e32 v212, 16, v122
	v_lshlrev_b32_e32 v188, 11, v212
	v_mov_b32_e32 v189, v1
	v_lshl_add_u64 v[188:189], v[94:95], 0, v[188:189]
	global_load_dwordx2 v[188:189], v[188:189], off
	v_lshlrev_b32_e32 v204, 12, v212
	v_mov_b32_e32 v205, v1
	v_lshl_add_u64 v[204:205], v[96:97], 0, v[204:205]
	global_load_dwordx4 v[204:207], v[204:205], off
	v_or_b32_e32 v212, 24, v122
	v_lshlrev_b32_e32 v190, 11, v212
	v_mov_b32_e32 v191, v1
	v_lshl_add_u64 v[190:191], v[94:95], 0, v[190:191]
	global_load_dwordx2 v[190:191], v[190:191], off
	v_lshlrev_b32_e32 v208, 12, v212
	v_mov_b32_e32 v209, v1
	v_lshl_add_u64 v[208:209], v[96:97], 0, v[208:209]
	global_load_dwordx4 v[208:211], v[208:209], off
	s_waitcnt vmcnt(6)
	v_mov_b32_e32 v112, v184
	v_mov_b32_e32 v113, v185
	v_lshl_add_u64 v[118:119], v[92:93], 0, v[100:101]
	ds_read_b128 v[100:103], v0
	v_mov_b32_e32 v104, v180
	v_mov_b32_e32 v105, v181
	v_mov_b32_e32 v106, v182
	v_mov_b32_e32 v107, v183
	s_nop 0
	v_mov_b32_e32 v108, v192
	v_mov_b32_e32 v109, v193
	v_mov_b32_e32 v110, v194
	v_mov_b32_e32 v111, v195
	v_and_b32_e32 v121, 0xffff0000, v112
	v_lshlrev_b32_e32 v120, 16, v112
	v_pk_add_f32 v[108:109], v[108:109], v[120:121]
	s_waitcnt lgkmcnt(0)
	v_pk_fma_f32 v[100:101], v[100:101], v[104:105], v[108:109]
	v_and_b32_e32 v105, 0xffff0000, v113
	v_lshlrev_b32_e32 v104, 16, v113
	v_pk_add_f32 v[104:105], v[110:111], v[104:105]
	s_nop 0
	v_pk_fma_f32 v[102:103], v[102:103], v[106:107], v[104:105]
	global_store_dwordx4 v[118:119], v[100:103], off
	s_nop 1
	v_or_b32_e32 v102, 8, v122
	v_lshlrev_b32_e32 v100, 12, v102
	v_lshlrev_b32_e32 v102, 11, v102
	v_mov_b32_e32 v103, v1
	v_mov_b32_e32 v101, v1
	v_lshl_add_u64 v[102:103], v[94:95], 0, v[102:103]
	v_lshl_add_u64 v[108:109], v[96:97], 0, v[100:101]
	s_waitcnt vmcnt(5)
	v_mov_b32_e32 v112, v186
	v_mov_b32_e32 v113, v187
	v_lshl_add_u64 v[118:119], v[92:93], 0, v[100:101]
	ds_read_b128 v[100:103], v0 offset:1152
	v_mov_b32_e32 v104, v180
	v_mov_b32_e32 v105, v181
	v_mov_b32_e32 v106, v182
	v_mov_b32_e32 v107, v183
	s_nop 0
	v_mov_b32_e32 v108, v200
	v_mov_b32_e32 v109, v201
	v_mov_b32_e32 v110, v202
	v_mov_b32_e32 v111, v203
	v_and_b32_e32 v121, 0xffff0000, v112
	v_lshlrev_b32_e32 v120, 16, v112
	v_pk_add_f32 v[108:109], v[108:109], v[120:121]
	s_waitcnt lgkmcnt(0)
	v_pk_fma_f32 v[100:101], v[100:101], v[104:105], v[108:109]
	v_and_b32_e32 v105, 0xffff0000, v113
	v_lshlrev_b32_e32 v104, 16, v113
	v_pk_add_f32 v[104:105], v[110:111], v[104:105]
	s_nop 0
	v_pk_fma_f32 v[102:103], v[102:103], v[106:107], v[104:105]
	global_store_dwordx4 v[118:119], v[100:103], off
	s_nop 1
	v_or_b32_e32 v102, 16, v122
	v_lshlrev_b32_e32 v100, 12, v102
	v_lshlrev_b32_e32 v102, 11, v102
	v_mov_b32_e32 v103, v1
	v_mov_b32_e32 v101, v1
	v_lshl_add_u64 v[102:103], v[94:95], 0, v[102:103]
	v_lshl_add_u64 v[108:109], v[96:97], 0, v[100:101]
	s_waitcnt vmcnt(4)
	v_mov_b32_e32 v112, v188
	v_mov_b32_e32 v113, v189
	v_lshl_add_u64 v[118:119], v[92:93], 0, v[100:101]
	ds_read_b128 v[100:103], v0 offset:2304
	v_mov_b32_e32 v104, v180
	v_mov_b32_e32 v105, v181
	v_mov_b32_e32 v106, v182
	v_mov_b32_e32 v107, v183
	s_nop 0
	v_mov_b32_e32 v108, v204
	v_mov_b32_e32 v109, v205
	v_mov_b32_e32 v110, v206
	v_mov_b32_e32 v111, v207
	v_and_b32_e32 v121, 0xffff0000, v112
	v_lshlrev_b32_e32 v120, 16, v112
	v_pk_add_f32 v[108:109], v[108:109], v[120:121]
	s_waitcnt lgkmcnt(0)
	v_pk_fma_f32 v[100:101], v[100:101], v[104:105], v[108:109]
	v_and_b32_e32 v105, 0xffff0000, v113
	v_lshlrev_b32_e32 v104, 16, v113
	v_pk_add_f32 v[104:105], v[110:111], v[104:105]
	s_nop 0
	v_pk_fma_f32 v[102:103], v[102:103], v[106:107], v[104:105]
	global_store_dwordx4 v[118:119], v[100:103], off
	s_nop 1
	v_or_b32_e32 v102, 24, v122
	v_lshlrev_b32_e32 v100, 12, v102
	v_lshlrev_b32_e32 v102, 11, v102
	v_mov_b32_e32 v103, v1
	v_lshl_add_u64 v[94:95], v[94:95], 0, v[102:103]
	v_mov_b32_e32 v101, v1
	s_waitcnt vmcnt(3)
	v_mov_b32_e32 v108, v190
	v_mov_b32_e32 v109, v191
	v_lshl_add_u64 v[96:97], v[96:97], 0, v[100:101]
	v_lshl_add_u64 v[110:111], v[92:93], 0, v[100:101]
	ds_read_b128 v[92:95], v0 offset:3456
	v_mov_b32_e32 v100, v180
	v_mov_b32_e32 v101, v181
	v_mov_b32_e32 v102, v182
	v_mov_b32_e32 v103, v183
	v_mov_b32_e32 v104, v208
	v_mov_b32_e32 v105, v209
	v_mov_b32_e32 v106, v210
	v_mov_b32_e32 v107, v211
	v_and_b32_e32 v91, 0xffff0000, v108
	v_lshlrev_b32_e32 v90, 16, v108
	v_pk_add_f32 v[90:91], v[104:105], v[90:91]
	s_waitcnt lgkmcnt(0)
	v_pk_fma_f32 v[90:91], v[92:93], v[100:101], v[90:91]
	v_and_b32_e32 v93, 0xffff0000, v109
	v_lshlrev_b32_e32 v92, 16, v109
	v_pk_add_f32 v[92:93], v[106:107], v[92:93]
	s_nop 0
	v_pk_fma_f32 v[92:93], v[94:95], v[102:103], v[92:93]
	global_store_dwordx4 v[110:111], v[90:93], off
	v_mov_b32_e32 v0, v179
	s_nop 0
	v_and_b32_e32 v90, 31, v0
	v_bfe_u32 v91, v0, 5, 1
	v_mul_u32_u24_e32 v91, 0x240, v91
	v_lshlrev_b32_e32 v90, 2, v90
	v_add3_u32 v90, v151, v91, v90
	ds_write2_b32 v90, v66, v67 offset1:36
	ds_write2_b32 v90, v68, v69 offset0:72 offset1:108
	v_add_u32_e32 v66, 0x400, v90
	ds_write2_b32 v66, v70, v71 offset0:32 offset1:68
	ds_write2_b32 v66, v72, v73 offset0:104 offset1:140
	v_add_u32_e32 v66, 0x800, v90
	ds_write2_b32 v66, v74, v75 offset0:64 offset1:100
	ds_write2_b32 v66, v76, v77 offset0:136 offset1:172
	v_add_u32_e32 v66, 0xc00, v90
	ds_write2_b32 v66, v78, v79 offset0:96 offset1:132
	ds_write2_b32 v66, v80, v81 offset0:168 offset1:204
	v_lshlrev_b32_e32 v66, 2, v0
	v_and_b32_e32 v68, 28, v66
	v_lshlrev_b32_e32 v74, 2, v68
	v_lshlrev_b32_e32 v68, 1, v68
	v_mov_b32_e32 v69, v1
	v_bfe_u32 v92, v0, 3, 3
	v_mov_b32_e32 v75, v1
	v_lshl_add_u64 v[70:71], v[82:83], 0, v[68:69]
	v_mul_u32_u24_e32 v0, 0x90, v92
	v_lshlrev_b32_e32 v76, 11, v92
	v_mov_b32_e32 v77, v1
	s_waitcnt lgkmcnt(0)
	v_lshl_add_u64 v[66:67], v[86:87], 0, v[74:75]
	v_lshl_add_u64 v[72:73], v[88:89], 0, v[74:75]
	v_lshl_add_u64 v[68:69], v[84:85], 0, v[74:75]
	v_add3_u32 v0, v151, v74, v0
	v_lshlrev_b32_e32 v74, 12, v92
	v_lshl_add_u64 v[76:77], v[70:71], 0, v[76:77]
	v_lshl_add_u64 v[66:67], v[66:67], 0, v[98:99]
	v_lshl_add_u64 v[82:83], v[72:73], 0, v[74:75]
	global_load_dwordx4 v[180:183], v[66:67], off
	v_mov_b32_e32 v212, v92
	v_lshlrev_b32_e32 v184, 11, v212
	v_mov_b32_e32 v185, v1
	v_lshl_add_u64 v[184:185], v[70:71], 0, v[184:185]
	global_load_dwordx2 v[184:185], v[184:185], off offset:64
	v_lshlrev_b32_e32 v192, 12, v212
	v_mov_b32_e32 v193, v1
	v_lshl_add_u64 v[192:193], v[72:73], 0, v[192:193]
	global_load_dwordx4 v[192:195], v[192:193], off offset:128
	v_or_b32_e32 v212, 8, v92
	v_lshlrev_b32_e32 v186, 11, v212
	v_mov_b32_e32 v187, v1
	v_lshl_add_u64 v[186:187], v[70:71], 0, v[186:187]
	global_load_dwordx2 v[186:187], v[186:187], off offset:64
	v_lshlrev_b32_e32 v200, 12, v212
	v_mov_b32_e32 v201, v1
	v_lshl_add_u64 v[200:201], v[72:73], 0, v[200:201]
	global_load_dwordx4 v[200:203], v[200:201], off offset:128
	v_or_b32_e32 v212, 16, v92
	v_lshlrev_b32_e32 v188, 11, v212
	v_mov_b32_e32 v189, v1
	v_lshl_add_u64 v[188:189], v[70:71], 0, v[188:189]
	global_load_dwordx2 v[188:189], v[188:189], off offset:64
	v_lshlrev_b32_e32 v204, 12, v212
	v_mov_b32_e32 v205, v1
	v_lshl_add_u64 v[204:205], v[72:73], 0, v[204:205]
	global_load_dwordx4 v[204:207], v[204:205], off offset:128
	v_or_b32_e32 v212, 24, v92
	v_lshlrev_b32_e32 v190, 11, v212
	v_mov_b32_e32 v191, v1
	v_lshl_add_u64 v[190:191], v[70:71], 0, v[190:191]
	global_load_dwordx2 v[190:191], v[190:191], off offset:64
	v_lshlrev_b32_e32 v208, 12, v212
	v_mov_b32_e32 v209, v1
	v_lshl_add_u64 v[208:209], v[72:73], 0, v[208:209]
	global_load_dwordx4 v[208:211], v[208:209], off offset:128
	s_waitcnt vmcnt(6)
	v_mov_b32_e32 v86, v184
	v_mov_b32_e32 v87, v185
	v_lshl_add_u64 v[88:89], v[68:69], 0, v[74:75]
	ds_read_b128 v[74:77], v0
	v_mov_b32_e32 v78, v180
	v_mov_b32_e32 v79, v181
	v_mov_b32_e32 v80, v182
	v_mov_b32_e32 v81, v183
	s_nop 0
	v_mov_b32_e32 v82, v192
	v_mov_b32_e32 v83, v193
	v_mov_b32_e32 v84, v194
	v_mov_b32_e32 v85, v195
	v_and_b32_e32 v91, 0xffff0000, v86
	v_lshlrev_b32_e32 v90, 16, v86
	v_pk_add_f32 v[82:83], v[82:83], v[90:91]
	s_waitcnt lgkmcnt(0)
	v_pk_fma_f32 v[74:75], v[74:75], v[78:79], v[82:83]
	v_and_b32_e32 v79, 0xffff0000, v87
	v_lshlrev_b32_e32 v78, 16, v87
	v_pk_add_f32 v[78:79], v[84:85], v[78:79]
	s_nop 0
	v_pk_fma_f32 v[76:77], v[76:77], v[80:81], v[78:79]
	global_store_dwordx4 v[88:89], v[74:77], off offset:128
	s_nop 1
	v_or_b32_e32 v76, 8, v92
	v_lshlrev_b32_e32 v74, 12, v76
	v_lshlrev_b32_e32 v76, 11, v76
	v_mov_b32_e32 v77, v1
	v_mov_b32_e32 v75, v1
	v_lshl_add_u64 v[76:77], v[70:71], 0, v[76:77]
	v_lshl_add_u64 v[82:83], v[72:73], 0, v[74:75]
	s_waitcnt vmcnt(5)
	v_mov_b32_e32 v86, v186
	v_mov_b32_e32 v87, v187
	v_lshl_add_u64 v[88:89], v[68:69], 0, v[74:75]
	ds_read_b128 v[74:77], v0 offset:1152
	v_mov_b32_e32 v78, v180
	v_mov_b32_e32 v79, v181
	v_mov_b32_e32 v80, v182
	v_mov_b32_e32 v81, v183
	s_nop 0
	v_mov_b32_e32 v82, v200
	v_mov_b32_e32 v83, v201
	v_mov_b32_e32 v84, v202
	v_mov_b32_e32 v85, v203
	v_and_b32_e32 v91, 0xffff0000, v86
	v_lshlrev_b32_e32 v90, 16, v86
	v_pk_add_f32 v[82:83], v[82:83], v[90:91]
	s_waitcnt lgkmcnt(0)
	v_pk_fma_f32 v[74:75], v[74:75], v[78:79], v[82:83]
	v_and_b32_e32 v79, 0xffff0000, v87
	v_lshlrev_b32_e32 v78, 16, v87
	v_pk_add_f32 v[78:79], v[84:85], v[78:79]
	s_nop 0
	v_pk_fma_f32 v[76:77], v[76:77], v[80:81], v[78:79]
	global_store_dwordx4 v[88:89], v[74:77], off offset:128
	s_nop 1
	v_or_b32_e32 v76, 16, v92
	v_lshlrev_b32_e32 v74, 12, v76
	v_lshlrev_b32_e32 v76, 11, v76
	v_mov_b32_e32 v77, v1
	v_mov_b32_e32 v75, v1
	v_lshl_add_u64 v[76:77], v[70:71], 0, v[76:77]
	v_lshl_add_u64 v[82:83], v[72:73], 0, v[74:75]
	s_waitcnt vmcnt(4)
	v_mov_b32_e32 v86, v188
	v_mov_b32_e32 v87, v189
	v_lshl_add_u64 v[88:89], v[68:69], 0, v[74:75]
	ds_read_b128 v[74:77], v0 offset:2304
	v_mov_b32_e32 v78, v180
	v_mov_b32_e32 v79, v181
	v_mov_b32_e32 v80, v182
	v_mov_b32_e32 v81, v183
	s_nop 0
	v_mov_b32_e32 v82, v204
	v_mov_b32_e32 v83, v205
	v_mov_b32_e32 v84, v206
	v_mov_b32_e32 v85, v207
	v_and_b32_e32 v91, 0xffff0000, v86
	v_lshlrev_b32_e32 v90, 16, v86
	v_pk_add_f32 v[82:83], v[82:83], v[90:91]
	s_waitcnt lgkmcnt(0)
	v_pk_fma_f32 v[74:75], v[74:75], v[78:79], v[82:83]
	v_and_b32_e32 v79, 0xffff0000, v87
	v_lshlrev_b32_e32 v78, 16, v87
	v_pk_add_f32 v[78:79], v[84:85], v[78:79]
	s_nop 0
	v_pk_fma_f32 v[76:77], v[76:77], v[80:81], v[78:79]
	v_or_b32_e32 v78, 24, v92
	global_store_dwordx4 v[88:89], v[74:77], off offset:128
	s_nop 1
	v_lshlrev_b32_e32 v74, 12, v78
	v_mov_b32_e32 v75, v1
	v_lshl_add_u64 v[76:77], v[72:73], 0, v[74:75]
	v_lshlrev_b32_e32 v72, 11, v78
	v_mov_b32_e32 v73, v1
	v_lshl_add_u64 v[70:71], v[70:71], 0, v[72:73]
	s_waitcnt vmcnt(3)
	v_mov_b32_e32 v80, v190
	v_mov_b32_e32 v81, v191
	v_lshl_add_u64 v[82:83], v[68:69], 0, v[74:75]
	ds_read_b128 v[68:71], v0 offset:3456
	v_mov_b32_e32 v72, v180
	v_mov_b32_e32 v73, v181
	v_mov_b32_e32 v74, v182
	v_mov_b32_e32 v75, v183
	s_nop 0
	v_mov_b32_e32 v76, v208
	v_mov_b32_e32 v77, v209
	v_mov_b32_e32 v78, v210
	v_mov_b32_e32 v79, v211
	v_and_b32_e32 v67, 0xffff0000, v80
	v_lshlrev_b32_e32 v66, 16, v80
	v_pk_add_f32 v[66:67], v[76:77], v[66:67]
	s_waitcnt lgkmcnt(0)
	v_pk_fma_f32 v[66:67], v[68:69], v[72:73], v[66:67]
	v_and_b32_e32 v69, 0xffff0000, v81
	v_lshlrev_b32_e32 v68, 16, v81
	v_pk_add_f32 v[68:69], v[78:79], v[68:69]
	s_nop 0
	v_pk_fma_f32 v[68:69], v[70:71], v[74:75], v[68:69]
	global_store_dwordx4 v[82:83], v[66:69], off offset:128
	s_nop 1
	v_or_b32_e32 v66, 64, v130
	v_add_u32_e32 v0, v66, v155
	v_ashrrev_i32_e32 v0, 14, v0
	v_mul_i32_i24_e32 v67, 0x4000, v0
	v_sub_u32_e32 v67, v66, v67
	v_add_u32_e32 v72, 0x100, v67
	v_mul_i32_i24_e32 v68, 0xc00, v0
	v_mul_hi_i32_i24_e32 v71, 0x4100, v0
	v_mul_i32_i24_e32 v70, 0x4100, v0
	v_ashrrev_i32_e32 v73, 31, v72
	v_mov_b32_e32 v0, v179
	v_lshl_add_u64 v[70:71], v[70:71], 0, v[72:73]
	v_ashrrev_i32_e32 v69, 31, v68
	v_and_b32_e32 v72, 31, v0
	v_bfe_u32 v73, v0, 5, 1
	v_mul_u32_u24_e32 v73, 0x240, v73
	v_lshlrev_b32_e32 v72, 2, v72
	v_add3_u32 v72, v151, v73, v72
	ds_write2_b32 v72, v50, v51 offset1:36
	ds_write2_b32 v72, v52, v53 offset0:72 offset1:108
	v_add_u32_e32 v50, 0x400, v72
	ds_write2_b32 v50, v54, v55 offset0:32 offset1:68
	ds_write2_b32 v50, v56, v57 offset0:104 offset1:140
	v_add_u32_e32 v50, 0x800, v72
	ds_write2_b32 v50, v58, v59 offset0:64 offset1:100
	ds_write2_b32 v50, v60, v61 offset0:136 offset1:172
	v_add_u32_e32 v50, 0xc00, v72
	v_lshlrev_b64 v[70:71], 11, v[70:71]
	v_ashrrev_i32_e32 v67, 31, v66
	ds_write2_b32 v50, v62, v63 offset0:96 offset1:132
	ds_write2_b32 v50, v64, v65 offset0:168 offset1:204
	v_lshl_add_u64 v[50:51], v[68:69], 2, s[54:55]
	v_lshlrev_b32_e32 v60, 2, v0
	v_lshl_add_u64 v[54:55], v[50:51], 0, s[2:3]
	v_lshl_add_u64 v[50:51], s[0:1], 0, v[70:71]
	v_lshlrev_b64 v[52:53], 12, v[66:67]
	v_and_b32_e32 v60, 28, v60
	v_lshl_add_u64 v[50:51], v[50:51], 0, v[116:117]
	v_lshl_add_u64 v[56:57], s[36:37], 0, v[52:53]
	v_lshl_add_u64 v[52:53], s[52:53], 0, v[52:53]
	v_lshlrev_b32_e32 v66, 2, v60
	v_lshlrev_b32_e32 v60, 1, v60
	v_mov_b32_e32 v61, v1
	v_bfe_u32 v84, v0, 3, 3
	v_lshl_add_u64 v[58:59], v[54:55], 0, v[114:115]
	v_lshl_add_u64 v[56:57], v[56:57], 0, v[114:115]
	v_lshl_add_u64 v[52:53], v[52:53], 0, v[114:115]
	v_mov_b32_e32 v67, v1
	v_lshl_add_u64 v[62:63], v[50:51], 0, v[60:61]
	v_mul_u32_u24_e32 v0, 0x90, v84
	v_lshlrev_b32_e32 v68, 11, v84
	v_mov_b32_e32 v69, v1
	s_waitcnt lgkmcnt(0)
	v_lshl_add_u64 v[58:59], v[58:59], 0, v[66:67]
	v_lshl_add_u64 v[64:65], v[56:57], 0, v[66:67]
	v_lshl_add_u64 v[60:61], v[52:53], 0, v[66:67]
	v_add3_u32 v0, v151, v66, v0
	v_lshlrev_b32_e32 v66, 12, v84
	v_lshl_add_u64 v[68:69], v[62:63], 0, v[68:69]
	v_lshl_add_u64 v[74:75], v[64:65], 0, v[66:67]
	global_load_dwordx4 v[180:183], v[58:59], off
	v_mov_b32_e32 v212, v84
	v_lshlrev_b32_e32 v184, 11, v212
	v_mov_b32_e32 v185, v1
	v_lshl_add_u64 v[184:185], v[62:63], 0, v[184:185]
	global_load_dwordx2 v[184:185], v[184:185], off
	v_lshlrev_b32_e32 v192, 12, v212
	v_mov_b32_e32 v193, v1
	v_lshl_add_u64 v[192:193], v[64:65], 0, v[192:193]
	global_load_dwordx4 v[192:195], v[192:193], off
	v_or_b32_e32 v212, 8, v84
	v_lshlrev_b32_e32 v186, 11, v212
	v_mov_b32_e32 v187, v1
	v_lshl_add_u64 v[186:187], v[62:63], 0, v[186:187]
	global_load_dwordx2 v[186:187], v[186:187], off
	v_lshlrev_b32_e32 v200, 12, v212
	v_mov_b32_e32 v201, v1
	v_lshl_add_u64 v[200:201], v[64:65], 0, v[200:201]
	global_load_dwordx4 v[200:203], v[200:201], off
	v_or_b32_e32 v212, 16, v84
	v_lshlrev_b32_e32 v188, 11, v212
	v_mov_b32_e32 v189, v1
	v_lshl_add_u64 v[188:189], v[62:63], 0, v[188:189]
	global_load_dwordx2 v[188:189], v[188:189], off
	v_lshlrev_b32_e32 v204, 12, v212
	v_mov_b32_e32 v205, v1
	v_lshl_add_u64 v[204:205], v[64:65], 0, v[204:205]
	global_load_dwordx4 v[204:207], v[204:205], off
	v_or_b32_e32 v212, 24, v84
	v_lshlrev_b32_e32 v190, 11, v212
	v_mov_b32_e32 v191, v1
	v_lshl_add_u64 v[190:191], v[62:63], 0, v[190:191]
	global_load_dwordx2 v[190:191], v[190:191], off
	v_lshlrev_b32_e32 v208, 12, v212
	v_mov_b32_e32 v209, v1
	v_lshl_add_u64 v[208:209], v[64:65], 0, v[208:209]
	global_load_dwordx4 v[208:211], v[208:209], off
	s_waitcnt vmcnt(6)
	v_mov_b32_e32 v78, v184
	v_mov_b32_e32 v79, v185
	v_lshl_add_u64 v[80:81], v[60:61], 0, v[66:67]
	ds_read_b128 v[66:69], v0
	v_mov_b32_e32 v70, v180
	v_mov_b32_e32 v71, v181
	v_mov_b32_e32 v72, v182
	v_mov_b32_e32 v73, v183
	s_nop 0
	v_mov_b32_e32 v74, v192
	v_mov_b32_e32 v75, v193
	v_mov_b32_e32 v76, v194
	v_mov_b32_e32 v77, v195
	v_and_b32_e32 v83, 0xffff0000, v78
	v_lshlrev_b32_e32 v82, 16, v78
	v_pk_add_f32 v[74:75], v[74:75], v[82:83]
	s_waitcnt lgkmcnt(0)
	v_pk_fma_f32 v[66:67], v[66:67], v[70:71], v[74:75]
	v_and_b32_e32 v71, 0xffff0000, v79
	v_lshlrev_b32_e32 v70, 16, v79
	v_pk_add_f32 v[70:71], v[76:77], v[70:71]
	s_nop 0
	v_pk_fma_f32 v[68:69], v[68:69], v[72:73], v[70:71]
	global_store_dwordx4 v[80:81], v[66:69], off
	s_nop 1
	v_or_b32_e32 v68, 8, v84
	v_lshlrev_b32_e32 v66, 12, v68
	v_lshlrev_b32_e32 v68, 11, v68
	v_mov_b32_e32 v69, v1
	v_mov_b32_e32 v67, v1
	v_lshl_add_u64 v[68:69], v[62:63], 0, v[68:69]
	v_lshl_add_u64 v[74:75], v[64:65], 0, v[66:67]
	s_waitcnt vmcnt(5)
	v_mov_b32_e32 v78, v186
	v_mov_b32_e32 v79, v187
	v_lshl_add_u64 v[80:81], v[60:61], 0, v[66:67]
	ds_read_b128 v[66:69], v0 offset:1152
	v_mov_b32_e32 v70, v180
	v_mov_b32_e32 v71, v181
	v_mov_b32_e32 v72, v182
	v_mov_b32_e32 v73, v183
	s_nop 0
	v_mov_b32_e32 v74, v200
	v_mov_b32_e32 v75, v201
	v_mov_b32_e32 v76, v202
	v_mov_b32_e32 v77, v203
	v_and_b32_e32 v83, 0xffff0000, v78
	v_lshlrev_b32_e32 v82, 16, v78
	v_pk_add_f32 v[74:75], v[74:75], v[82:83]
	s_waitcnt lgkmcnt(0)
	v_pk_fma_f32 v[66:67], v[66:67], v[70:71], v[74:75]
	v_and_b32_e32 v71, 0xffff0000, v79
	v_lshlrev_b32_e32 v70, 16, v79
	v_pk_add_f32 v[70:71], v[76:77], v[70:71]
	s_nop 0
	v_pk_fma_f32 v[68:69], v[68:69], v[72:73], v[70:71]
	global_store_dwordx4 v[80:81], v[66:69], off
	s_nop 1
	v_or_b32_e32 v68, 16, v84
	v_lshlrev_b32_e32 v66, 12, v68
	v_lshlrev_b32_e32 v68, 11, v68
	v_mov_b32_e32 v69, v1
	v_mov_b32_e32 v67, v1
	v_lshl_add_u64 v[68:69], v[62:63], 0, v[68:69]
	v_lshl_add_u64 v[74:75], v[64:65], 0, v[66:67]
	s_waitcnt vmcnt(4)
	v_mov_b32_e32 v78, v188
	v_mov_b32_e32 v79, v189
	v_lshl_add_u64 v[80:81], v[60:61], 0, v[66:67]
	ds_read_b128 v[66:69], v0 offset:2304
	v_mov_b32_e32 v70, v180
	v_mov_b32_e32 v71, v181
	v_mov_b32_e32 v72, v182
	v_mov_b32_e32 v73, v183
	s_nop 0
	v_mov_b32_e32 v74, v204
	v_mov_b32_e32 v75, v205
	v_mov_b32_e32 v76, v206
	v_mov_b32_e32 v77, v207
	v_and_b32_e32 v83, 0xffff0000, v78
	v_lshlrev_b32_e32 v82, 16, v78
	v_pk_add_f32 v[74:75], v[74:75], v[82:83]
	s_waitcnt lgkmcnt(0)
	v_pk_fma_f32 v[66:67], v[66:67], v[70:71], v[74:75]
	v_and_b32_e32 v71, 0xffff0000, v79
	v_lshlrev_b32_e32 v70, 16, v79
	v_pk_add_f32 v[70:71], v[76:77], v[70:71]
	s_nop 0
	v_pk_fma_f32 v[68:69], v[68:69], v[72:73], v[70:71]
	v_or_b32_e32 v70, 24, v84
	global_store_dwordx4 v[80:81], v[66:69], off
	s_nop 1
	v_lshlrev_b32_e32 v66, 12, v70
	v_mov_b32_e32 v67, v1
	v_lshl_add_u64 v[68:69], v[64:65], 0, v[66:67]
	v_lshlrev_b32_e32 v64, 11, v70
	v_mov_b32_e32 v65, v1
	v_lshl_add_u64 v[62:63], v[62:63], 0, v[64:65]
	s_waitcnt vmcnt(3)
	v_mov_b32_e32 v72, v190
	v_mov_b32_e32 v73, v191
	v_lshl_add_u64 v[74:75], v[60:61], 0, v[66:67]
	ds_read_b128 v[60:63], v0 offset:3456
	v_mov_b32_e32 v64, v180
	v_mov_b32_e32 v65, v181
	v_mov_b32_e32 v66, v182
	v_mov_b32_e32 v67, v183
	s_nop 0
	v_mov_b32_e32 v68, v208
	v_mov_b32_e32 v69, v209
	v_mov_b32_e32 v70, v210
	v_mov_b32_e32 v71, v211
	v_and_b32_e32 v59, 0xffff0000, v72
	v_lshlrev_b32_e32 v58, 16, v72
	v_pk_add_f32 v[58:59], v[68:69], v[58:59]
	s_waitcnt lgkmcnt(0)
	v_pk_fma_f32 v[58:59], v[60:61], v[64:65], v[58:59]
	v_and_b32_e32 v61, 0xffff0000, v73
	v_lshlrev_b32_e32 v60, 16, v73
	v_pk_add_f32 v[60:61], v[70:71], v[60:61]
	s_nop 0
	v_pk_fma_f32 v[60:61], v[62:63], v[66:67], v[60:61]
	global_store_dwordx4 v[74:75], v[58:61], off
	v_mov_b32_e32 v0, v179
	s_nop 0
	v_and_b32_e32 v58, 31, v0
	v_bfe_u32 v59, v0, 5, 1
	v_mul_u32_u24_e32 v59, 0x240, v59
	v_lshlrev_b32_e32 v58, 2, v58
	v_add3_u32 v58, v151, v59, v58
	ds_write2_b32 v58, v34, v35 offset1:36
	ds_write2_b32 v58, v36, v37 offset0:72 offset1:108
	v_add_u32_e32 v34, 0x400, v58
	ds_write2_b32 v34, v38, v39 offset0:32 offset1:68
	ds_write2_b32 v34, v40, v41 offset0:104 offset1:140
	v_add_u32_e32 v34, 0x800, v58
	ds_write2_b32 v34, v42, v43 offset0:64 offset1:100
	ds_write2_b32 v34, v44, v45 offset0:136 offset1:172
	v_add_u32_e32 v34, 0xc00, v58
	ds_write2_b32 v34, v46, v47 offset0:96 offset1:132
	ds_write2_b32 v34, v48, v49 offset0:168 offset1:204
	v_lshlrev_b32_e32 v34, 2, v0
	v_and_b32_e32 v36, 28, v34
	v_lshlrev_b32_e32 v42, 2, v36
	v_lshlrev_b32_e32 v36, 1, v36
	v_mov_b32_e32 v37, v1
	v_bfe_u32 v60, v0, 3, 3
	v_mov_b32_e32 v43, v1
	v_lshl_add_u64 v[38:39], v[50:51], 0, v[36:37]
	v_mul_u32_u24_e32 v0, 0x90, v60
	v_lshlrev_b32_e32 v44, 11, v60
	v_mov_b32_e32 v45, v1
	s_waitcnt lgkmcnt(0)
	v_lshl_add_u64 v[34:35], v[54:55], 0, v[42:43]
	v_lshl_add_u64 v[40:41], v[56:57], 0, v[42:43]
	v_lshl_add_u64 v[36:37], v[52:53], 0, v[42:43]
	v_add3_u32 v0, v151, v42, v0
	v_lshlrev_b32_e32 v42, 12, v60
	v_lshl_add_u64 v[44:45], v[38:39], 0, v[44:45]
	v_lshl_add_u64 v[34:35], v[34:35], 0, v[98:99]
	v_lshl_add_u64 v[50:51], v[40:41], 0, v[42:43]
	global_load_dwordx4 v[180:183], v[34:35], off
	v_mov_b32_e32 v212, v60
	v_lshlrev_b32_e32 v184, 11, v212
	v_mov_b32_e32 v185, v1
	v_lshl_add_u64 v[184:185], v[38:39], 0, v[184:185]
	global_load_dwordx2 v[184:185], v[184:185], off offset:64
	v_lshlrev_b32_e32 v192, 12, v212
	v_mov_b32_e32 v193, v1
	v_lshl_add_u64 v[192:193], v[40:41], 0, v[192:193]
	global_load_dwordx4 v[192:195], v[192:193], off offset:128
	v_or_b32_e32 v212, 8, v60
	v_lshlrev_b32_e32 v186, 11, v212
	v_mov_b32_e32 v187, v1
	v_lshl_add_u64 v[186:187], v[38:39], 0, v[186:187]
	global_load_dwordx2 v[186:187], v[186:187], off offset:64
	v_lshlrev_b32_e32 v200, 12, v212
	v_mov_b32_e32 v201, v1
	v_lshl_add_u64 v[200:201], v[40:41], 0, v[200:201]
	global_load_dwordx4 v[200:203], v[200:201], off offset:128
	v_or_b32_e32 v212, 16, v60
	v_lshlrev_b32_e32 v188, 11, v212
	v_mov_b32_e32 v189, v1
	v_lshl_add_u64 v[188:189], v[38:39], 0, v[188:189]
	global_load_dwordx2 v[188:189], v[188:189], off offset:64
	v_lshlrev_b32_e32 v204, 12, v212
	v_mov_b32_e32 v205, v1
	v_lshl_add_u64 v[204:205], v[40:41], 0, v[204:205]
	global_load_dwordx4 v[204:207], v[204:205], off offset:128
	v_or_b32_e32 v212, 24, v60
	v_lshlrev_b32_e32 v190, 11, v212
	v_mov_b32_e32 v191, v1
	v_lshl_add_u64 v[190:191], v[38:39], 0, v[190:191]
	global_load_dwordx2 v[190:191], v[190:191], off offset:64
	v_lshlrev_b32_e32 v208, 12, v212
	v_mov_b32_e32 v209, v1
	v_lshl_add_u64 v[208:209], v[40:41], 0, v[208:209]
	global_load_dwordx4 v[208:211], v[208:209], off offset:128
	s_waitcnt vmcnt(6)
	v_mov_b32_e32 v54, v184
	v_mov_b32_e32 v55, v185
	v_lshl_add_u64 v[56:57], v[36:37], 0, v[42:43]
	ds_read_b128 v[42:45], v0
	v_mov_b32_e32 v46, v180
	v_mov_b32_e32 v47, v181
	v_mov_b32_e32 v48, v182
	v_mov_b32_e32 v49, v183
	s_nop 0
	v_mov_b32_e32 v50, v192
	v_mov_b32_e32 v51, v193
	v_mov_b32_e32 v52, v194
	v_mov_b32_e32 v53, v195
	v_and_b32_e32 v59, 0xffff0000, v54
	v_lshlrev_b32_e32 v58, 16, v54
	v_pk_add_f32 v[50:51], v[50:51], v[58:59]
	s_waitcnt lgkmcnt(0)
	v_pk_fma_f32 v[42:43], v[42:43], v[46:47], v[50:51]
	v_and_b32_e32 v47, 0xffff0000, v55
	v_lshlrev_b32_e32 v46, 16, v55
	v_pk_add_f32 v[46:47], v[52:53], v[46:47]
	s_nop 0
	v_pk_fma_f32 v[44:45], v[44:45], v[48:49], v[46:47]
	global_store_dwordx4 v[56:57], v[42:45], off offset:128
	s_nop 1
	v_or_b32_e32 v44, 8, v60
	v_lshlrev_b32_e32 v42, 12, v44
	v_lshlrev_b32_e32 v44, 11, v44
	v_mov_b32_e32 v45, v1
	v_mov_b32_e32 v43, v1
	v_lshl_add_u64 v[44:45], v[38:39], 0, v[44:45]
	v_lshl_add_u64 v[50:51], v[40:41], 0, v[42:43]
	s_waitcnt vmcnt(5)
	v_mov_b32_e32 v54, v186
	v_mov_b32_e32 v55, v187
	v_lshl_add_u64 v[56:57], v[36:37], 0, v[42:43]
	ds_read_b128 v[42:45], v0 offset:1152
	v_mov_b32_e32 v46, v180
	v_mov_b32_e32 v47, v181
	v_mov_b32_e32 v48, v182
	v_mov_b32_e32 v49, v183
	s_nop 0
	v_mov_b32_e32 v50, v200
	v_mov_b32_e32 v51, v201
	v_mov_b32_e32 v52, v202
	v_mov_b32_e32 v53, v203
	v_and_b32_e32 v59, 0xffff0000, v54
	v_lshlrev_b32_e32 v58, 16, v54
	v_pk_add_f32 v[50:51], v[50:51], v[58:59]
	s_waitcnt lgkmcnt(0)
	v_pk_fma_f32 v[42:43], v[42:43], v[46:47], v[50:51]
	v_and_b32_e32 v47, 0xffff0000, v55
	v_lshlrev_b32_e32 v46, 16, v55
	v_pk_add_f32 v[46:47], v[52:53], v[46:47]
	s_nop 0
	v_pk_fma_f32 v[44:45], v[44:45], v[48:49], v[46:47]
	global_store_dwordx4 v[56:57], v[42:45], off offset:128
	s_nop 1
	v_or_b32_e32 v44, 16, v60
	v_lshlrev_b32_e32 v42, 12, v44
	v_lshlrev_b32_e32 v44, 11, v44
	v_mov_b32_e32 v45, v1
	v_mov_b32_e32 v43, v1
	v_lshl_add_u64 v[44:45], v[38:39], 0, v[44:45]
	v_lshl_add_u64 v[50:51], v[40:41], 0, v[42:43]
	s_waitcnt vmcnt(4)
	v_mov_b32_e32 v54, v188
	v_mov_b32_e32 v55, v189
	v_lshl_add_u64 v[56:57], v[36:37], 0, v[42:43]
	ds_read_b128 v[42:45], v0 offset:2304
	v_mov_b32_e32 v46, v180
	v_mov_b32_e32 v47, v181
	v_mov_b32_e32 v48, v182
	v_mov_b32_e32 v49, v183
	s_nop 0
	v_mov_b32_e32 v50, v204
	v_mov_b32_e32 v51, v205
	v_mov_b32_e32 v52, v206
	v_mov_b32_e32 v53, v207
	v_and_b32_e32 v59, 0xffff0000, v54
	v_lshlrev_b32_e32 v58, 16, v54
	v_pk_add_f32 v[50:51], v[50:51], v[58:59]
	s_waitcnt lgkmcnt(0)
	v_pk_fma_f32 v[42:43], v[42:43], v[46:47], v[50:51]
	v_and_b32_e32 v47, 0xffff0000, v55
	v_lshlrev_b32_e32 v46, 16, v55
	v_pk_add_f32 v[46:47], v[52:53], v[46:47]
	s_nop 0
	v_pk_fma_f32 v[44:45], v[44:45], v[48:49], v[46:47]
	v_or_b32_e32 v46, 24, v60
	global_store_dwordx4 v[56:57], v[42:45], off offset:128
	s_nop 1
	v_lshlrev_b32_e32 v42, 12, v46
	v_mov_b32_e32 v43, v1
	v_lshl_add_u64 v[44:45], v[40:41], 0, v[42:43]
	v_lshlrev_b32_e32 v40, 11, v46
	v_mov_b32_e32 v41, v1
	v_lshl_add_u64 v[38:39], v[38:39], 0, v[40:41]
	s_waitcnt vmcnt(3)
	v_mov_b32_e32 v48, v190
	v_mov_b32_e32 v49, v191
	v_lshl_add_u64 v[50:51], v[36:37], 0, v[42:43]
	ds_read_b128 v[36:39], v0 offset:3456
	v_mov_b32_e32 v40, v180
	v_mov_b32_e32 v41, v181
	v_mov_b32_e32 v42, v182
	v_mov_b32_e32 v43, v183
	s_nop 0
	v_mov_b32_e32 v44, v208
	v_mov_b32_e32 v45, v209
	v_mov_b32_e32 v46, v210
	v_mov_b32_e32 v47, v211
	v_and_b32_e32 v35, 0xffff0000, v48
	v_lshlrev_b32_e32 v34, 16, v48
	v_pk_add_f32 v[34:35], v[44:45], v[34:35]
	s_waitcnt lgkmcnt(0)
	v_pk_fma_f32 v[34:35], v[36:37], v[40:41], v[34:35]
	v_and_b32_e32 v37, 0xffff0000, v49
	v_lshlrev_b32_e32 v36, 16, v49
	v_pk_add_f32 v[36:37], v[46:47], v[36:37]
	s_nop 0
	v_pk_fma_f32 v[36:37], v[38:39], v[42:43], v[36:37]
	global_store_dwordx4 v[50:51], v[34:37], off offset:128
	s_nop 1
	v_or_b32_e32 v34, 0x60, v130
	v_add_u32_e32 v0, v34, v155
	v_ashrrev_i32_e32 v0, 14, v0
	v_mul_i32_i24_e32 v35, 0x4000, v0
	v_sub_u32_e32 v35, v34, v35
	v_add_u32_e32 v40, 0x100, v35
	v_mul_i32_i24_e32 v36, 0xc00, v0
	v_mul_hi_i32_i24_e32 v39, 0x4100, v0
	v_mul_i32_i24_e32 v38, 0x4100, v0
	v_ashrrev_i32_e32 v41, 31, v40
	v_mov_b32_e32 v0, v179
	v_lshl_add_u64 v[38:39], v[38:39], 0, v[40:41]
	v_ashrrev_i32_e32 v37, 31, v36
	v_and_b32_e32 v40, 31, v0
	v_bfe_u32 v41, v0, 5, 1
	v_mul_u32_u24_e32 v41, 0x240, v41
	v_lshlrev_b32_e32 v40, 2, v40
	v_add3_u32 v40, v151, v41, v40
	ds_write2_b32 v40, v18, v19 offset1:36
	ds_write2_b32 v40, v20, v21 offset0:72 offset1:108
	v_add_u32_e32 v18, 0x400, v40
	ds_write2_b32 v18, v22, v23 offset0:32 offset1:68
	ds_write2_b32 v18, v24, v25 offset0:104 offset1:140
	v_add_u32_e32 v18, 0x800, v40
	ds_write2_b32 v18, v26, v27 offset0:64 offset1:100
	ds_write2_b32 v18, v28, v29 offset0:136 offset1:172
	v_add_u32_e32 v18, 0xc00, v40
	v_lshlrev_b64 v[38:39], 11, v[38:39]
	v_ashrrev_i32_e32 v35, 31, v34
	ds_write2_b32 v18, v30, v31 offset0:96 offset1:132
	ds_write2_b32 v18, v32, v33 offset0:168 offset1:204
	v_lshl_add_u64 v[18:19], v[36:37], 2, s[54:55]
	v_lshlrev_b32_e32 v28, 2, v0
	v_lshl_add_u64 v[20:21], v[18:19], 0, s[2:3]
	v_lshl_add_u64 v[18:19], s[0:1], 0, v[38:39]
	v_lshlrev_b64 v[22:23], 12, v[34:35]
	v_and_b32_e32 v28, 28, v28
	v_lshl_add_u64 v[18:19], v[18:19], 0, v[116:117]
	v_lshl_add_u64 v[24:25], s[36:37], 0, v[22:23]
	v_lshl_add_u64 v[22:23], s[52:53], 0, v[22:23]
	v_lshlrev_b32_e32 v34, 2, v28
	v_lshlrev_b32_e32 v28, 1, v28
	v_mov_b32_e32 v29, v1
	v_bfe_u32 v52, v0, 3, 3
	v_lshl_add_u64 v[26:27], v[20:21], 0, v[114:115]
	v_lshl_add_u64 v[24:25], v[24:25], 0, v[114:115]
	v_lshl_add_u64 v[22:23], v[22:23], 0, v[114:115]
	v_mov_b32_e32 v35, v1
	v_lshl_add_u64 v[30:31], v[18:19], 0, v[28:29]
	v_mul_u32_u24_e32 v0, 0x90, v52
	v_lshlrev_b32_e32 v36, 11, v52
	v_mov_b32_e32 v37, v1
	s_waitcnt lgkmcnt(0)
	v_lshl_add_u64 v[26:27], v[26:27], 0, v[34:35]
	v_lshl_add_u64 v[32:33], v[24:25], 0, v[34:35]
	v_lshl_add_u64 v[28:29], v[22:23], 0, v[34:35]
	v_add3_u32 v0, v151, v34, v0
	v_lshlrev_b32_e32 v34, 12, v52
	v_lshl_add_u64 v[36:37], v[30:31], 0, v[36:37]
	v_lshl_add_u64 v[42:43], v[32:33], 0, v[34:35]
	global_load_dwordx4 v[180:183], v[26:27], off
	v_mov_b32_e32 v212, v52
	v_lshlrev_b32_e32 v184, 11, v212
	v_mov_b32_e32 v185, v1
	v_lshl_add_u64 v[184:185], v[30:31], 0, v[184:185]
	global_load_dwordx2 v[184:185], v[184:185], off
	v_lshlrev_b32_e32 v192, 12, v212
	v_mov_b32_e32 v193, v1
	v_lshl_add_u64 v[192:193], v[32:33], 0, v[192:193]
	global_load_dwordx4 v[192:195], v[192:193], off
	v_or_b32_e32 v212, 8, v52
	v_lshlrev_b32_e32 v186, 11, v212
	v_mov_b32_e32 v187, v1
	v_lshl_add_u64 v[186:187], v[30:31], 0, v[186:187]
	global_load_dwordx2 v[186:187], v[186:187], off
	v_lshlrev_b32_e32 v200, 12, v212
	v_mov_b32_e32 v201, v1
	v_lshl_add_u64 v[200:201], v[32:33], 0, v[200:201]
	global_load_dwordx4 v[200:203], v[200:201], off
	v_or_b32_e32 v212, 16, v52
	v_lshlrev_b32_e32 v188, 11, v212
	v_mov_b32_e32 v189, v1
	v_lshl_add_u64 v[188:189], v[30:31], 0, v[188:189]
	global_load_dwordx2 v[188:189], v[188:189], off
	v_lshlrev_b32_e32 v204, 12, v212
	v_mov_b32_e32 v205, v1
	v_lshl_add_u64 v[204:205], v[32:33], 0, v[204:205]
	global_load_dwordx4 v[204:207], v[204:205], off
	v_or_b32_e32 v212, 24, v52
	v_lshlrev_b32_e32 v190, 11, v212
	v_mov_b32_e32 v191, v1
	v_lshl_add_u64 v[190:191], v[30:31], 0, v[190:191]
	global_load_dwordx2 v[190:191], v[190:191], off
	v_lshlrev_b32_e32 v208, 12, v212
	v_mov_b32_e32 v209, v1
	v_lshl_add_u64 v[208:209], v[32:33], 0, v[208:209]
	global_load_dwordx4 v[208:211], v[208:209], off
	s_waitcnt vmcnt(6)
	v_mov_b32_e32 v46, v184
	v_mov_b32_e32 v47, v185
	v_lshl_add_u64 v[48:49], v[28:29], 0, v[34:35]
	ds_read_b128 v[34:37], v0
	v_mov_b32_e32 v38, v180
	v_mov_b32_e32 v39, v181
	v_mov_b32_e32 v40, v182
	v_mov_b32_e32 v41, v183
	s_nop 0
	v_mov_b32_e32 v42, v192
	v_mov_b32_e32 v43, v193
	v_mov_b32_e32 v44, v194
	v_mov_b32_e32 v45, v195
	v_and_b32_e32 v51, 0xffff0000, v46
	v_lshlrev_b32_e32 v50, 16, v46
	v_pk_add_f32 v[42:43], v[42:43], v[50:51]
	s_waitcnt lgkmcnt(0)
	v_pk_fma_f32 v[34:35], v[34:35], v[38:39], v[42:43]
	v_and_b32_e32 v39, 0xffff0000, v47
	v_lshlrev_b32_e32 v38, 16, v47
	v_pk_add_f32 v[38:39], v[44:45], v[38:39]
	s_nop 0
	v_pk_fma_f32 v[36:37], v[36:37], v[40:41], v[38:39]
	global_store_dwordx4 v[48:49], v[34:37], off
	s_nop 1
	v_or_b32_e32 v36, 8, v52
	v_lshlrev_b32_e32 v34, 12, v36
	v_lshlrev_b32_e32 v36, 11, v36
	v_mov_b32_e32 v37, v1
	v_mov_b32_e32 v35, v1
	v_lshl_add_u64 v[36:37], v[30:31], 0, v[36:37]
	v_lshl_add_u64 v[42:43], v[32:33], 0, v[34:35]
	s_waitcnt vmcnt(5)
	v_mov_b32_e32 v46, v186
	v_mov_b32_e32 v47, v187
	v_lshl_add_u64 v[48:49], v[28:29], 0, v[34:35]
	ds_read_b128 v[34:37], v0 offset:1152
	v_mov_b32_e32 v38, v180
	v_mov_b32_e32 v39, v181
	v_mov_b32_e32 v40, v182
	v_mov_b32_e32 v41, v183
	s_nop 0
	v_mov_b32_e32 v42, v200
	v_mov_b32_e32 v43, v201
	v_mov_b32_e32 v44, v202
	v_mov_b32_e32 v45, v203
	v_and_b32_e32 v51, 0xffff0000, v46
	v_lshlrev_b32_e32 v50, 16, v46
	v_pk_add_f32 v[42:43], v[42:43], v[50:51]
	s_waitcnt lgkmcnt(0)
	v_pk_fma_f32 v[34:35], v[34:35], v[38:39], v[42:43]
	v_and_b32_e32 v39, 0xffff0000, v47
	v_lshlrev_b32_e32 v38, 16, v47
	v_pk_add_f32 v[38:39], v[44:45], v[38:39]
	s_nop 0
	v_pk_fma_f32 v[36:37], v[36:37], v[40:41], v[38:39]
	global_store_dwordx4 v[48:49], v[34:37], off
	s_nop 1
	v_or_b32_e32 v36, 16, v52
	v_lshlrev_b32_e32 v34, 12, v36
	v_lshlrev_b32_e32 v36, 11, v36
	v_mov_b32_e32 v37, v1
	v_mov_b32_e32 v35, v1
	v_lshl_add_u64 v[36:37], v[30:31], 0, v[36:37]
	v_lshl_add_u64 v[42:43], v[32:33], 0, v[34:35]
	s_waitcnt vmcnt(4)
	v_mov_b32_e32 v46, v188
	v_mov_b32_e32 v47, v189
	v_lshl_add_u64 v[48:49], v[28:29], 0, v[34:35]
	ds_read_b128 v[34:37], v0 offset:2304
	v_mov_b32_e32 v38, v180
	v_mov_b32_e32 v39, v181
	v_mov_b32_e32 v40, v182
	v_mov_b32_e32 v41, v183
	s_nop 0
	v_mov_b32_e32 v42, v204
	v_mov_b32_e32 v43, v205
	v_mov_b32_e32 v44, v206
	v_mov_b32_e32 v45, v207
	v_and_b32_e32 v51, 0xffff0000, v46
	v_lshlrev_b32_e32 v50, 16, v46
	v_pk_add_f32 v[42:43], v[42:43], v[50:51]
	s_waitcnt lgkmcnt(0)
	v_pk_fma_f32 v[34:35], v[34:35], v[38:39], v[42:43]
	v_and_b32_e32 v39, 0xffff0000, v47
	v_lshlrev_b32_e32 v38, 16, v47
	v_pk_add_f32 v[38:39], v[44:45], v[38:39]
	s_nop 0
	v_pk_fma_f32 v[36:37], v[36:37], v[40:41], v[38:39]
	v_or_b32_e32 v38, 24, v52
	global_store_dwordx4 v[48:49], v[34:37], off
	s_nop 1
	v_lshlrev_b32_e32 v34, 12, v38
	v_mov_b32_e32 v35, v1
	v_lshl_add_u64 v[36:37], v[32:33], 0, v[34:35]
	v_lshlrev_b32_e32 v32, 11, v38
	v_mov_b32_e32 v33, v1
	v_lshl_add_u64 v[30:31], v[30:31], 0, v[32:33]
	s_waitcnt vmcnt(3)
	v_mov_b32_e32 v40, v190
	v_mov_b32_e32 v41, v191
	v_lshl_add_u64 v[42:43], v[28:29], 0, v[34:35]
	ds_read_b128 v[28:31], v0 offset:3456
	v_mov_b32_e32 v32, v180
	v_mov_b32_e32 v33, v181
	v_mov_b32_e32 v34, v182
	v_mov_b32_e32 v35, v183
	s_nop 0
	v_mov_b32_e32 v36, v208
	v_mov_b32_e32 v37, v209
	v_mov_b32_e32 v38, v210
	v_mov_b32_e32 v39, v211
	v_and_b32_e32 v27, 0xffff0000, v40
	v_lshlrev_b32_e32 v26, 16, v40
	v_pk_add_f32 v[26:27], v[36:37], v[26:27]
	s_waitcnt lgkmcnt(0)
	v_pk_fma_f32 v[26:27], v[28:29], v[32:33], v[26:27]
	v_and_b32_e32 v29, 0xffff0000, v41
	v_lshlrev_b32_e32 v28, 16, v41
	v_pk_add_f32 v[28:29], v[38:39], v[28:29]
	s_nop 0
	v_pk_fma_f32 v[28:29], v[30:31], v[34:35], v[28:29]
	global_store_dwordx4 v[42:43], v[26:29], off
	v_mov_b32_e32 v0, v179
	s_nop 0
	v_and_b32_e32 v26, 31, v0
	v_bfe_u32 v27, v0, 5, 1
	v_mul_u32_u24_e32 v27, 0x240, v27
	v_lshlrev_b32_e32 v26, 2, v26
	v_add3_u32 v26, v151, v27, v26
	ds_write2_b32 v26, v2, v3 offset1:36
	ds_write2_b32 v26, v4, v5 offset0:72 offset1:108
	v_add_u32_e32 v2, 0x400, v26
	ds_write2_b32 v2, v6, v7 offset0:32 offset1:68
	ds_write2_b32 v2, v8, v9 offset0:104 offset1:140
	v_add_u32_e32 v2, 0x800, v26
	ds_write2_b32 v2, v10, v11 offset0:64 offset1:100
	ds_write2_b32 v2, v12, v13 offset0:136 offset1:172
	v_add_u32_e32 v2, 0xc00, v26
	ds_write2_b32 v2, v14, v15 offset0:96 offset1:132
	ds_write2_b32 v2, v16, v17 offset0:168 offset1:204
	v_lshlrev_b32_e32 v2, 2, v0
	v_and_b32_e32 v4, 28, v2
	v_lshlrev_b32_e32 v10, 2, v4
	v_lshlrev_b32_e32 v4, 1, v4
	v_mov_b32_e32 v5, v1
	v_bfe_u32 v28, v0, 3, 3
	v_mov_b32_e32 v11, v1
	v_lshl_add_u64 v[6:7], v[18:19], 0, v[4:5]
	v_mul_u32_u24_e32 v0, 0x90, v28
	v_lshlrev_b32_e32 v12, 11, v28
	v_mov_b32_e32 v13, v1
	s_waitcnt lgkmcnt(0)
	v_lshl_add_u64 v[2:3], v[20:21], 0, v[10:11]
	v_lshl_add_u64 v[8:9], v[24:25], 0, v[10:11]
	v_lshl_add_u64 v[4:5], v[22:23], 0, v[10:11]
	v_add3_u32 v0, v151, v10, v0
	v_lshlrev_b32_e32 v10, 12, v28
	v_lshl_add_u64 v[12:13], v[6:7], 0, v[12:13]
	v_lshl_add_u64 v[2:3], v[2:3], 0, v[98:99]
	v_lshl_add_u64 v[18:19], v[8:9], 0, v[10:11]
	global_load_dwordx4 v[180:183], v[2:3], off
	v_mov_b32_e32 v212, v28
	v_lshlrev_b32_e32 v184, 11, v212
	v_mov_b32_e32 v185, v1
	v_lshl_add_u64 v[184:185], v[6:7], 0, v[184:185]
	global_load_dwordx2 v[184:185], v[184:185], off offset:64
	v_lshlrev_b32_e32 v192, 12, v212
	v_mov_b32_e32 v193, v1
	v_lshl_add_u64 v[192:193], v[8:9], 0, v[192:193]
	global_load_dwordx4 v[192:195], v[192:193], off offset:128
	v_or_b32_e32 v212, 8, v28
	v_lshlrev_b32_e32 v186, 11, v212
	v_mov_b32_e32 v187, v1
	v_lshl_add_u64 v[186:187], v[6:7], 0, v[186:187]
	global_load_dwordx2 v[186:187], v[186:187], off offset:64
	v_lshlrev_b32_e32 v200, 12, v212
	v_mov_b32_e32 v201, v1
	v_lshl_add_u64 v[200:201], v[8:9], 0, v[200:201]
	global_load_dwordx4 v[200:203], v[200:201], off offset:128
	v_or_b32_e32 v212, 16, v28
	v_lshlrev_b32_e32 v188, 11, v212
	v_mov_b32_e32 v189, v1
	v_lshl_add_u64 v[188:189], v[6:7], 0, v[188:189]
	global_load_dwordx2 v[188:189], v[188:189], off offset:64
	v_lshlrev_b32_e32 v204, 12, v212
	v_mov_b32_e32 v205, v1
	v_lshl_add_u64 v[204:205], v[8:9], 0, v[204:205]
	global_load_dwordx4 v[204:207], v[204:205], off offset:128
	v_or_b32_e32 v212, 24, v28
	v_lshlrev_b32_e32 v190, 11, v212
	v_mov_b32_e32 v191, v1
	v_lshl_add_u64 v[190:191], v[6:7], 0, v[190:191]
	global_load_dwordx2 v[190:191], v[190:191], off offset:64
	v_lshlrev_b32_e32 v208, 12, v212
	v_mov_b32_e32 v209, v1
	v_lshl_add_u64 v[208:209], v[8:9], 0, v[208:209]
	global_load_dwordx4 v[208:211], v[208:209], off offset:128
	s_waitcnt vmcnt(6)
	v_mov_b32_e32 v22, v184
	v_mov_b32_e32 v23, v185
	v_lshl_add_u64 v[24:25], v[4:5], 0, v[10:11]
	ds_read_b128 v[10:13], v0
	v_mov_b32_e32 v14, v180
	v_mov_b32_e32 v15, v181
	v_mov_b32_e32 v16, v182
	v_mov_b32_e32 v17, v183
	s_nop 0
	v_mov_b32_e32 v18, v192
	v_mov_b32_e32 v19, v193
	v_mov_b32_e32 v20, v194
	v_mov_b32_e32 v21, v195
	v_and_b32_e32 v27, 0xffff0000, v22
	v_lshlrev_b32_e32 v26, 16, v22
	v_pk_add_f32 v[18:19], v[18:19], v[26:27]
	s_waitcnt lgkmcnt(0)
	v_pk_fma_f32 v[10:11], v[10:11], v[14:15], v[18:19]
	v_and_b32_e32 v15, 0xffff0000, v23
	v_lshlrev_b32_e32 v14, 16, v23
	v_pk_add_f32 v[14:15], v[20:21], v[14:15]
	s_nop 0
	v_pk_fma_f32 v[12:13], v[12:13], v[16:17], v[14:15]
	global_store_dwordx4 v[24:25], v[10:13], off offset:128
	s_nop 1
	v_or_b32_e32 v12, 8, v28
	v_lshlrev_b32_e32 v10, 12, v12
	v_lshlrev_b32_e32 v12, 11, v12
	v_mov_b32_e32 v13, v1
	v_mov_b32_e32 v11, v1
	v_lshl_add_u64 v[12:13], v[6:7], 0, v[12:13]
	v_lshl_add_u64 v[18:19], v[8:9], 0, v[10:11]
	s_waitcnt vmcnt(5)
	v_mov_b32_e32 v22, v186
	v_mov_b32_e32 v23, v187
	v_lshl_add_u64 v[24:25], v[4:5], 0, v[10:11]
	ds_read_b128 v[10:13], v0 offset:1152
	v_mov_b32_e32 v14, v180
	v_mov_b32_e32 v15, v181
	v_mov_b32_e32 v16, v182
	v_mov_b32_e32 v17, v183
	s_nop 0
	v_mov_b32_e32 v18, v200
	v_mov_b32_e32 v19, v201
	v_mov_b32_e32 v20, v202
	v_mov_b32_e32 v21, v203
	v_and_b32_e32 v27, 0xffff0000, v22
	v_lshlrev_b32_e32 v26, 16, v22
	v_pk_add_f32 v[18:19], v[18:19], v[26:27]
	s_waitcnt lgkmcnt(0)
	v_pk_fma_f32 v[10:11], v[10:11], v[14:15], v[18:19]
	v_and_b32_e32 v15, 0xffff0000, v23
	v_lshlrev_b32_e32 v14, 16, v23
	v_pk_add_f32 v[14:15], v[20:21], v[14:15]
	s_nop 0
	v_pk_fma_f32 v[12:13], v[12:13], v[16:17], v[14:15]
	global_store_dwordx4 v[24:25], v[10:13], off offset:128
	s_nop 1
	v_or_b32_e32 v12, 16, v28
	v_lshlrev_b32_e32 v10, 12, v12
	v_lshlrev_b32_e32 v12, 11, v12
	v_mov_b32_e32 v13, v1
	v_mov_b32_e32 v11, v1
	v_lshl_add_u64 v[12:13], v[6:7], 0, v[12:13]
	v_lshl_add_u64 v[18:19], v[8:9], 0, v[10:11]
	s_waitcnt vmcnt(4)
	v_mov_b32_e32 v22, v188
	v_mov_b32_e32 v23, v189
	v_lshl_add_u64 v[24:25], v[4:5], 0, v[10:11]
	ds_read_b128 v[10:13], v0 offset:2304
	v_mov_b32_e32 v14, v180
	v_mov_b32_e32 v15, v181
	v_mov_b32_e32 v16, v182
	v_mov_b32_e32 v17, v183
	s_nop 0
	v_mov_b32_e32 v18, v204
	v_mov_b32_e32 v19, v205
	v_mov_b32_e32 v20, v206
	v_mov_b32_e32 v21, v207
	v_and_b32_e32 v27, 0xffff0000, v22
	v_lshlrev_b32_e32 v26, 16, v22
	v_pk_add_f32 v[18:19], v[18:19], v[26:27]
	s_waitcnt lgkmcnt(0)
	v_pk_fma_f32 v[10:11], v[10:11], v[14:15], v[18:19]
	v_and_b32_e32 v15, 0xffff0000, v23
	v_lshlrev_b32_e32 v14, 16, v23
	v_pk_add_f32 v[14:15], v[20:21], v[14:15]
	s_nop 0
	v_pk_fma_f32 v[12:13], v[12:13], v[16:17], v[14:15]
	v_or_b32_e32 v14, 24, v28
	global_store_dwordx4 v[24:25], v[10:13], off offset:128
	s_nop 1
	v_lshlrev_b32_e32 v10, 12, v14
	v_mov_b32_e32 v11, v1
	v_lshl_add_u64 v[12:13], v[8:9], 0, v[10:11]
	v_lshlrev_b32_e32 v8, 11, v14
	v_mov_b32_e32 v9, v1
	v_lshl_add_u64 v[6:7], v[6:7], 0, v[8:9]
	s_waitcnt vmcnt(3)
	v_mov_b32_e32 v16, v190
	v_mov_b32_e32 v17, v191
	v_lshl_add_u64 v[18:19], v[4:5], 0, v[10:11]
	ds_read_b128 v[4:7], v0 offset:3456
	v_mov_b32_e32 v8, v180
	v_mov_b32_e32 v9, v181
	v_mov_b32_e32 v10, v182
	v_mov_b32_e32 v11, v183
	s_nop 0
	v_mov_b32_e32 v12, v208
	v_mov_b32_e32 v13, v209
	v_mov_b32_e32 v14, v210
	v_mov_b32_e32 v15, v211
	v_and_b32_e32 v3, 0xffff0000, v16
	v_lshlrev_b32_e32 v2, 16, v16
	v_pk_add_f32 v[2:3], v[12:13], v[2:3]
	s_waitcnt lgkmcnt(0)
	v_pk_fma_f32 v[2:3], v[4:5], v[8:9], v[2:3]
	v_and_b32_e32 v5, 0xffff0000, v17
	v_lshlrev_b32_e32 v4, 16, v17
	v_pk_add_f32 v[4:5], v[14:15], v[4:5]
	s_nop 0
	v_pk_fma_f32 v[4:5], v[6:7], v[10:11], v[4:5]
	global_store_dwordx4 v[18:19], v[2:5], off offset:128
	s_add_i32 s7, s7, s6
	s_cmpk_gt_i32 s7, 0x1ff
	v_readlane_b32 s64, v254, 55
	v_readlane_b32 s38, v254, 57
	v_readlane_b32 s42, v254, 59
	s_cselect_b64 s[0:1], -1, 0
	v_readlane_b32 s65, v254, 56
	v_readlane_b32 s39, v254, 58
	v_readlane_b32 s43, v254, 60
	s_mov_b32 s51, s27
	s_movk_i32 s37, 0x1000
	s_movk_i32 s36, 0x1ff
	s_mov_b32 s47, 0x7f800000
	s_mov_b32 s49, 0x20000
	s_mov_b32 s46, 0x4081e0d3
	s_mov_b32 s48, 0xc09de9e6
	s_mov_b64 s[44:45], 0x800
	s_branch .LBB0_21

.LBB0_293:
	s_add_i32 s2, s11, s12
	s_cmpk_gt_i32 s2, 0xcb1
	s_mov_b64 s[0:1], -1
	s_cbranch_scc1 .LBB0_292
	s_mul_hi_i32 s0, s2, 0x51eb851f
	s_lshr_b32 s1, s0, 31
	s_ashr_i32 s0, s0, 6
	s_add_i32 s0, s0, s1
	s_lshl_b32 s1, s0, 3
	s_sub_i32 s3, 0x82, s1
	s_min_u32 s3, s3, 8
	v_cvt_f32_ubyte0_e32 v0, s3
	v_rcp_iflag_f32_e32 v0, v0
	s_sub_i32 s5, 0, s3
	s_mulk_i32 s0, 0xff38
	s_add_i32 s0, s0, s2
	v_mul_f32_e32 v0, 0x4f7ffffe, v0
	v_cvt_u32_f32_e32 v0, v0
	s_abs_i32 s4, s0
	s_ashr_i32 s2, s0, 31
	v_readlane_b32 s16, v251, 2
	v_readfirstlane_b32 s7, v0
	s_mul_i32 s5, s5, s7
	s_mul_hi_u32 s5, s7, s5
	s_add_i32 s7, s7, s5
	s_mul_hi_u32 s5, s4, s7
	s_mul_i32 s7, s5, s3
	s_sub_i32 s4, s4, s7
	s_add_i32 s7, s5, 1
	s_sub_i32 s8, s4, s3
	s_cmp_ge_u32 s4, s3
	s_cselect_b32 s5, s7, s5
	s_cselect_b32 s4, s8, s4
	s_add_i32 s7, s5, 1
	s_cmp_ge_u32 s4, s3
	s_cselect_b32 s4, s7, s5
	s_xor_b32 s4, s4, s2
	s_sub_i32 s4, s4, s2
	s_mul_i32 s2, s4, s3
	s_sub_i32 s0, s0, s2
	s_add_i32 s0, s0, s1
	s_lshl_b32 s0, s0, 8
	s_lshl_b32 s4, s4, 8
	s_ashr_i32 s1, s0, 31
	s_ashr_i32 s5, s4, 31
	s_lshl_b64 s[2:3], s[0:1], 11
	s_lshl_b64 s[8:9], s[4:5], 11
	v_readlane_b32 s28, v251, 14
	v_readlane_b32 s29, v251, 15
	s_add_u32 s14, s28, s2
	v_mov_b32_e32 v0, v142
	s_addc_u32 s15, s29, s3
	s_waitcnt vmcnt(63) expcnt(7) lgkmcnt(15)
	s_barrier
	v_readlane_b32 s17, v251, 3
	v_lshl_add_u64 v[2:3], v[0:1], 1, s[14:15]
	v_add_u32_e32 v0, 32, v143
	v_readlane_b32 s16, v251, 42
	v_readfirstlane_b32 s1, v0
	s_mov_b32 m0, s1
	v_mov_b32_e32 v0, v144
	global_load_lds_dwordx4 v[2:3], off
	v_readlane_b32 s17, v251, 43
	v_lshl_add_u64 v[2:3], v[0:1], 1, s[14:15]
	v_add_u32_e32 v0, 32, v145
	s_add_u32 s16, s16, s8
	v_readfirstlane_b32 s1, v0
	s_mov_b32 m0, s1
	v_mov_b32_e32 v0, v146
	global_load_lds_dwordx4 v[2:3], off
	s_addc_u32 s17, s17, s9
	v_lshl_add_u64 v[2:3], v[0:1], 1, s[14:15]
	v_add_u32_e32 v0, 32, v147
	v_readlane_b32 s5, v254, 3
	v_readfirstlane_b32 s1, v0
	s_mov_b32 m0, s1
	v_mov_b32_e32 v0, v148
	global_load_lds_dwordx4 v[2:3], off
	s_mov_b32 s6, 0
	v_lshl_add_u64 v[2:3], v[0:1], 1, s[14:15]
	v_add_u32_e32 v0, 32, v149
	v_readlane_b32 s18, v251, 4
	v_readfirstlane_b32 s1, v0
	s_mov_b32 m0, s1
	v_mov_b32_e32 v0, v142
	global_load_lds_dwordx4 v[2:3], off
	v_readlane_b32 s19, v251, 5
	v_lshl_add_u64 v[2:3], v[0:1], 1, s[16:17]
	v_add_u32_e32 v0, s5, v143
	v_readlane_b32 s20, v251, 6
	v_readfirstlane_b32 s1, v0
	s_mov_b32 m0, s1
	v_mov_b32_e32 v0, v144
	global_load_lds_dwordx4 v[2:3], off
	v_readlane_b32 s21, v251, 7
	v_lshl_add_u64 v[2:3], v[0:1], 1, s[16:17]
	v_add_u32_e32 v0, s5, v145
	v_readlane_b32 s22, v251, 8
	v_readfirstlane_b32 s1, v0
	s_mov_b32 m0, s1
	v_mov_b32_e32 v0, v146
	global_load_lds_dwordx4 v[2:3], off
	v_readlane_b32 s23, v251, 9
	v_lshl_add_u64 v[2:3], v[0:1], 1, s[16:17]
	v_add_u32_e32 v0, s5, v147
	v_readlane_b32 s24, v251, 10
	v_readfirstlane_b32 s1, v0
	s_mov_b32 m0, s1
	v_mov_b32_e32 v0, v148
	global_load_lds_dwordx4 v[2:3], off
	v_readlane_b32 s25, v251, 11
	v_lshl_add_u64 v[2:3], v[0:1], 1, s[16:17]
	v_add_u32_e32 v0, s5, v149
	v_readlane_b32 s26, v251, 12
	v_readfirstlane_b32 s1, v0
	s_mov_b32 m0, s1
	v_readlane_b32 s1, v253, 29
	global_load_lds_dwordx4 v[2:3], off
	s_add_u32 s1, s1, s2
	v_readlane_b32 s2, v253, 30
	s_waitcnt vmcnt(0)
	s_addc_u32 s5, s2, s3
	v_readlane_b32 s2, v253, 31
	s_add_u32 s7, s2, s8
	v_readlane_b32 s2, v253, 32
	v_mov_b32_e32 v2, 0
	s_addc_u32 s8, s2, s9
	s_mov_b64 s[2:3], 0
	v_mov_b32_e32 v3, v2
	v_mov_b32_e32 v4, v2
	v_mov_b32_e32 v5, v2
	v_mov_b32_e32 v6, v2
	v_mov_b32_e32 v7, v2
	v_mov_b32_e32 v8, v2
	v_mov_b32_e32 v9, v2
	v_mov_b32_e32 v10, v2
	v_mov_b32_e32 v11, v2
	v_mov_b32_e32 v12, v2
	v_mov_b32_e32 v13, v2
	s_waitcnt vmcnt(0)
	v_mov_b32_e32 v14, v2
	v_mov_b32_e32 v15, v2
	v_mov_b32_e32 v16, v2
	v_mov_b32_e32 v17, v2
	v_mov_b32_e32 v18, v2
	v_mov_b32_e32 v19, v2
	v_mov_b32_e32 v20, v2
	v_mov_b32_e32 v21, v2
	v_mov_b32_e32 v22, v2
	v_mov_b32_e32 v23, v2
	v_mov_b32_e32 v24, v2
	v_mov_b32_e32 v25, v2
	v_mov_b32_e32 v26, v2
	v_mov_b32_e32 v27, v2
	v_mov_b32_e32 v28, v2
	v_mov_b32_e32 v29, v2
	v_mov_b32_e32 v30, v2
	v_mov_b32_e32 v31, v2
	v_mov_b32_e32 v32, v2
	v_mov_b32_e32 v33, v2
	v_mov_b32_e32 v34, v2
	v_mov_b32_e32 v35, v2
	v_mov_b32_e32 v36, v2
	v_mov_b32_e32 v37, v2
	v_mov_b32_e32 v38, v2
	v_mov_b32_e32 v39, v2
	v_mov_b32_e32 v40, v2
	v_mov_b32_e32 v41, v2
	v_mov_b32_e32 v42, v2
	v_mov_b32_e32 v43, v2
	v_mov_b32_e32 v44, v2
	v_mov_b32_e32 v45, v2
	v_mov_b32_e32 v46, v2
	v_mov_b32_e32 v47, v2
	v_mov_b32_e32 v48, v2
	v_mov_b32_e32 v49, v2
	v_mov_b32_e32 v50, v2
	v_mov_b32_e32 v51, v2
	v_mov_b32_e32 v52, v2
	v_mov_b32_e32 v53, v2
	v_mov_b32_e32 v54, v2
	v_mov_b32_e32 v55, v2
	v_mov_b32_e32 v56, v2
	v_mov_b32_e32 v57, v2
	v_mov_b32_e32 v58, v2
	v_mov_b32_e32 v59, v2
	v_mov_b32_e32 v60, v2
	v_mov_b32_e32 v61, v2
	v_mov_b32_e32 v62, v2
	v_mov_b32_e32 v63, v2
	v_mov_b32_e32 v64, v2
	v_mov_b32_e32 v65, v2
	v_mov_b32_e32 v66, v2
	v_mov_b32_e32 v67, v2
	v_mov_b32_e32 v68, v2
	v_mov_b32_e32 v69, v2
	v_mov_b32_e32 v70, v2
	v_mov_b32_e32 v71, v2
	v_mov_b32_e32 v72, v2
	v_mov_b32_e32 v73, v2
	v_mov_b32_e32 v74, v2
	v_mov_b32_e32 v75, v2
	v_mov_b32_e32 v76, v2
	v_mov_b32_e32 v77, v2
	v_mov_b32_e32 v78, v2
	v_mov_b32_e32 v79, v2
	v_mov_b32_e32 v80, v2
	v_mov_b32_e32 v81, v2
	v_mov_b32_e32 v82, v2
	v_mov_b32_e32 v83, v2
	v_mov_b32_e32 v84, v2
	v_mov_b32_e32 v85, v2
	v_mov_b32_e32 v86, v2
	v_mov_b32_e32 v87, v2
	v_mov_b32_e32 v88, v2
	v_mov_b32_e32 v89, v2
	v_mov_b32_e32 v90, v2
	v_mov_b32_e32 v91, v2
	v_mov_b32_e32 v92, v2
	v_mov_b32_e32 v93, v2
	v_mov_b32_e32 v94, v2
	v_mov_b32_e32 v95, v2
	v_mov_b32_e32 v96, v2
	v_mov_b32_e32 v97, v2
	v_mov_b32_e32 v98, v2
	v_mov_b32_e32 v99, v2
	v_mov_b32_e32 v100, v2
	v_mov_b32_e32 v101, v2
	v_mov_b32_e32 v102, v2
	v_mov_b32_e32 v103, v2
	v_mov_b32_e32 v104, v2
	v_mov_b32_e32 v105, v2
	v_mov_b32_e32 v106, v2
	v_mov_b32_e32 v107, v2
	v_mov_b32_e32 v108, v2
	v_mov_b32_e32 v109, v2
	v_mov_b32_e32 v110, v2
	v_mov_b32_e32 v111, v2
	v_mov_b32_e32 v112, v2
	v_mov_b32_e32 v113, v2
	v_mov_b32_e32 v114, v2
	v_mov_b32_e32 v115, v2
	v_mov_b32_e32 v116, v2
	v_mov_b32_e32 v117, v2
	v_mov_b32_e32 v118, v2
	v_mov_b32_e32 v119, v2
	v_mov_b32_e32 v120, v2
	v_mov_b32_e32 v121, v2
	v_mov_b32_e32 v122, v2
	v_mov_b32_e32 v123, v2
	v_mov_b32_e32 v124, v2
	v_mov_b32_e32 v125, v2
	v_mov_b32_e32 v126, v2
	v_mov_b32_e32 v127, v2
	v_mov_b32_e32 v128, v2
	v_mov_b32_e32 v129, v2
	v_readlane_b32 s27, v251, 13
	v_readlane_b32 s30, v251, 16
	v_readlane_b32 s31, v251, 17
	s_waitcnt lgkmcnt(0)
	s_barrier
	v_readfirstlane_b32 s66, v179
	s_cmp_lt_u32 s66, 0x100
	s_cbranch_scc0 .Lgl295_entry
	s_setprio 1
	v_lshlrev_b32_e32 v159, 1, v142
	v_readfirstlane_b32 s9, v143
	v_add_u32_e32 v177, v150, v152
	v_add_u32_e32 v207, v151, v152
	v_add_u32_e32 v204, v150, v156
	v_add_u32_e32 v208, v151, v156
	v_add_u32_e32 v205, v150, v157
	v_add_u32_e32 v209, v151, v157
	v_add_u32_e32 v206, v150, v158
	v_add_u32_e32 v210, v151, v158
	s_mov_b32 s6, 7
	s_add_u32 m0, s9, 0x8020
	s_add_u32 s14, s1, s2
	s_addc_u32 s15, s5, s3
	global_load_lds_dwordx4 v159, s[14:15]
	s_add_u32 m0, s9, 0x9020
	s_add_u32 s68, s14, 0x10000
	s_addc_u32 s69, s15, 0
	global_load_lds_dwordx4 v159, s[68:69]
	s_add_u32 m0, s9, 0xa020
	s_add_u32 s14, s14, 0x20000
	s_addc_u32 s15, s15, 0
	global_load_lds_dwordx4 v159, s[14:15]
	s_add_u32 m0, s9, 0xb020
	s_add_u32 s68, s14, 0x10000
	s_addc_u32 s69, s15, 0
	global_load_lds_dwordx4 v159, s[68:69]
	s_add_u32 m0, s9, 0xc020
	s_add_u32 s14, s14, 0x20000
	s_addc_u32 s15, s15, 0
	global_load_lds_dwordx4 v159, s[14:15]
	s_add_u32 m0, s9, 0xd020
	s_add_u32 s68, s14, 0x10000
	s_addc_u32 s69, s15, 0
	global_load_lds_dwordx4 v159, s[68:69]
	s_add_u32 m0, s9, 0xe020
	s_add_u32 s14, s14, 0x20000
	s_addc_u32 s15, s15, 0
	global_load_lds_dwordx4 v159, s[14:15]
	s_add_u32 m0, s9, 0xf020
	s_add_u32 s68, s14, 0x10000
	s_addc_u32 s69, s15, 0
	global_load_lds_dwordx4 v159, s[68:69]
	s_add_u32 m0, s9, 0x18020
	s_add_u32 s14, s7, s2
	s_addc_u32 s15, s8, s3
	global_load_lds_dwordx4 v159, s[14:15]
	s_add_u32 m0, s9, 0x19020
	s_add_u32 s68, s14, 0x10000
	s_addc_u32 s69, s15, 0
	global_load_lds_dwordx4 v159, s[68:69]
	ds_read_b128 v[130:133], v177 offset:0
	ds_read_b128 v[164:167], v207 offset:0
	ds_read_b128 v[168:171], v207 offset:4096
	ds_read_b128 v[134:137], v177 offset:4096
	ds_read_b128 v[138:141], v177 offset:8192
	ds_read_b128 v[160:163], v177 offset:12288
.Lg295_loop:
	s_waitcnt lgkmcnt(4)
	v_mfma_f32_32x32x16_bf16 v[114:129], v[130:133], v[164:167], v[114:129]
	ds_read_b128 v[172:175], v204 offset:0
	s_waitcnt lgkmcnt(4)
	v_mfma_f32_32x32x16_bf16 v[98:113], v[130:133], v[168:171], v[98:113]
	ds_read_b128 v[192:195], v208 offset:0
	s_add_u32 m0, s9, 0x1a020
	s_add_u32 s14, s14, 0x20000
	s_addc_u32 s15, s15, 0
	global_load_lds_dwordx4 v159, s[14:15]
	s_add_u32 m0, s9, 0x1b020
	s_add_u32 s68, s14, 0x10000
	s_addc_u32 s69, s15, 0
	global_load_lds_dwordx4 v159, s[68:69]
	s_waitcnt lgkmcnt(4)
	v_mfma_f32_32x32x16_bf16 v[82:97], v[134:137], v[164:167], v[82:97]
	ds_read_b128 v[200:203], v208 offset:4096
	v_mfma_f32_32x32x16_bf16 v[66:81], v[134:137], v[168:171], v[66:81]
	ds_read_b128 v[180:183], v204 offset:4096
	s_add_u32 m0, s9, 0x1c020
	s_add_u32 s14, s14, 0x20000
	s_addc_u32 s15, s15, 0
	global_load_lds_dwordx4 v159, s[14:15]
	s_add_u32 m0, s9, 0x1d020
	s_add_u32 s68, s14, 0x10000
	s_addc_u32 s69, s15, 0
	global_load_lds_dwordx4 v159, s[68:69]
	s_waitcnt lgkmcnt(5)
	v_mfma_f32_32x32x16_bf16 v[50:65], v[138:141], v[164:167], v[50:65]
	ds_read_b128 v[184:187], v204 offset:8192
	v_mfma_f32_32x32x16_bf16 v[34:49], v[138:141], v[168:171], v[34:49]
	ds_read_b128 v[188:191], v204 offset:12288
	s_add_u32 m0, s9, 0x1e020
	s_add_u32 s14, s14, 0x20000
	s_addc_u32 s15, s15, 0
	global_load_lds_dwordx4 v159, s[14:15]
	s_add_u32 m0, s9, 0x1f020
	s_add_u32 s68, s14, 0x10000
	s_addc_u32 s69, s15, 0
	global_load_lds_dwordx4 v159, s[68:69]
	s_add_u32 s2, s2, 0x80
	s_addc_u32 s3, s3, 0
	s_waitcnt lgkmcnt(6)
	v_mfma_f32_32x32x16_bf16 v[18:33], v[160:163], v[164:167], v[18:33]
	v_mfma_f32_32x32x16_bf16 v[2:17], v[160:163], v[168:171], v[2:17]
	s_waitcnt lgkmcnt(4)
	v_mfma_f32_32x32x16_bf16 v[114:129], v[172:175], v[192:195], v[114:129]
	ds_read_b128 v[130:133], v205 offset:0
	s_waitcnt lgkmcnt(4)
	v_mfma_f32_32x32x16_bf16 v[98:113], v[172:175], v[200:203], v[98:113]
	ds_read_b128 v[164:167], v209 offset:0
	s_waitcnt lgkmcnt(4)
	v_mfma_f32_32x32x16_bf16 v[82:97], v[180:183], v[192:195], v[82:97]
	ds_read_b128 v[168:171], v209 offset:4096
	v_mfma_f32_32x32x16_bf16 v[66:81], v[180:183], v[200:203], v[66:81]
	ds_read_b128 v[134:137], v205 offset:4096
	s_waitcnt lgkmcnt(5)
	v_mfma_f32_32x32x16_bf16 v[50:65], v[184:187], v[192:195], v[50:65]
	ds_read_b128 v[138:141], v205 offset:8192
	v_mfma_f32_32x32x16_bf16 v[34:49], v[184:187], v[200:203], v[34:49]
	ds_read_b128 v[160:163], v205 offset:12288
	s_waitcnt lgkmcnt(6)
	v_mfma_f32_32x32x16_bf16 v[18:33], v[188:191], v[192:195], v[18:33]
	v_mfma_f32_32x32x16_bf16 v[2:17], v[188:191], v[200:203], v[2:17]
	s_waitcnt lgkmcnt(4)
	v_mfma_f32_32x32x16_bf16 v[114:129], v[130:133], v[164:167], v[114:129]
	ds_read_b128 v[172:175], v206 offset:0
	ds_read_b128 v[192:195], v210 offset:0
	s_waitcnt lgkmcnt(5)
	v_mfma_f32_32x32x16_bf16 v[98:113], v[130:133], v[168:171], v[98:113]
	ds_read_b128 v[200:203], v210 offset:4096
	ds_read_b128 v[180:183], v206 offset:4096
	s_waitcnt lgkmcnt(6)
	v_mfma_f32_32x32x16_bf16 v[82:97], v[134:137], v[164:167], v[82:97]
	ds_read_b128 v[184:187], v206 offset:8192
	ds_read_b128 v[188:191], v206 offset:12288
	v_mfma_f32_32x32x16_bf16 v[66:81], v[134:137], v[168:171], v[66:81]
	s_waitcnt lgkmcnt(7)
	v_mfma_f32_32x32x16_bf16 v[50:65], v[138:141], v[164:167], v[50:65]
	v_mfma_f32_32x32x16_bf16 v[34:49], v[138:141], v[168:171], v[34:49]
	s_waitcnt lgkmcnt(6)
	v_mfma_f32_32x32x16_bf16 v[18:33], v[160:163], v[164:167], v[18:33]
	v_mfma_f32_32x32x16_bf16 v[2:17], v[160:163], v[168:171], v[2:17]
	s_waitcnt vmcnt(0) lgkmcnt(0)
	s_barrier
	v_mfma_f32_32x32x16_bf16 v[114:129], v[172:175], v[192:195], v[114:129]
	ds_read_b128 v[130:133], v177 offset:32768
	s_add_u32 m0, s9, 0x20
	s_add_u32 s14, s1, s2
	s_addc_u32 s15, s5, s3
	global_load_lds_dwordx4 v159, s[14:15]
	s_add_u32 m0, s9, 0x1020
	s_add_u32 s68, s14, 0x10000
	s_addc_u32 s69, s15, 0
	global_load_lds_dwordx4 v159, s[68:69]
	v_mfma_f32_32x32x16_bf16 v[98:113], v[172:175], v[200:203], v[98:113]
	ds_read_b128 v[164:167], v207 offset:32768
	s_add_u32 m0, s9, 0x2020
	s_add_u32 s14, s14, 0x20000
	s_addc_u32 s15, s15, 0
	global_load_lds_dwordx4 v159, s[14:15]
	s_add_u32 m0, s9, 0x3020
	s_add_u32 s68, s14, 0x10000
	s_addc_u32 s69, s15, 0
	global_load_lds_dwordx4 v159, s[68:69]
	v_mfma_f32_32x32x16_bf16 v[82:97], v[180:183], v[192:195], v[82:97]
	ds_read_b128 v[168:171], v207 offset:36864
	s_add_u32 m0, s9, 0x4020
	s_add_u32 s14, s14, 0x20000
	s_addc_u32 s15, s15, 0
	global_load_lds_dwordx4 v159, s[14:15]
	s_add_u32 m0, s9, 0x5020
	s_add_u32 s68, s14, 0x10000
	s_addc_u32 s69, s15, 0
	global_load_lds_dwordx4 v159, s[68:69]
	v_mfma_f32_32x32x16_bf16 v[66:81], v[180:183], v[200:203], v[66:81]
	ds_read_b128 v[134:137], v177 offset:36864
	s_add_u32 m0, s9, 0x6020
	s_add_u32 s14, s14, 0x20000
	s_addc_u32 s15, s15, 0
	global_load_lds_dwordx4 v159, s[14:15]
	s_add_u32 m0, s9, 0x7020
	s_add_u32 s68, s14, 0x10000
	s_addc_u32 s69, s15, 0
	global_load_lds_dwordx4 v159, s[68:69]
	v_mfma_f32_32x32x16_bf16 v[50:65], v[184:187], v[192:195], v[50:65]
	ds_read_b128 v[138:141], v177 offset:40960
	s_add_u32 m0, s9, 0x10020
	s_add_u32 s14, s7, s2
	s_addc_u32 s15, s8, s3
	global_load_lds_dwordx4 v159, s[14:15]
	s_add_u32 m0, s9, 0x11020
	s_add_u32 s68, s14, 0x10000
	s_addc_u32 s69, s15, 0
	global_load_lds_dwordx4 v159, s[68:69]
	v_mfma_f32_32x32x16_bf16 v[34:49], v[184:187], v[200:203], v[34:49]
	ds_read_b128 v[160:163], v177 offset:45056
	v_mfma_f32_32x32x16_bf16 v[18:33], v[188:191], v[192:195], v[18:33]
	v_mfma_f32_32x32x16_bf16 v[2:17], v[188:191], v[200:203], v[2:17]
	s_waitcnt lgkmcnt(4)
	v_mfma_f32_32x32x16_bf16 v[114:129], v[130:133], v[164:167], v[114:129]
	ds_read_b128 v[172:175], v204 offset:32768
	s_waitcnt lgkmcnt(4)
	v_mfma_f32_32x32x16_bf16 v[98:113], v[130:133], v[168:171], v[98:113]
	ds_read_b128 v[192:195], v208 offset:32768
	s_add_u32 m0, s9, 0x12020
	s_add_u32 s14, s14, 0x20000
	s_addc_u32 s15, s15, 0
	global_load_lds_dwordx4 v159, s[14:15]
	s_add_u32 m0, s9, 0x13020
	s_add_u32 s68, s14, 0x10000
	s_addc_u32 s69, s15, 0
	global_load_lds_dwordx4 v159, s[68:69]
	s_waitcnt lgkmcnt(4)
	v_mfma_f32_32x32x16_bf16 v[82:97], v[134:137], v[164:167], v[82:97]
	ds_read_b128 v[200:203], v208 offset:36864
	v_mfma_f32_32x32x16_bf16 v[66:81], v[134:137], v[168:171], v[66:81]
	ds_read_b128 v[180:183], v204 offset:36864
	s_add_u32 m0, s9, 0x14020
	s_add_u32 s14, s14, 0x20000
	s_addc_u32 s15, s15, 0
	global_load_lds_dwordx4 v159, s[14:15]
	s_add_u32 m0, s9, 0x15020
	s_add_u32 s68, s14, 0x10000
	s_addc_u32 s69, s15, 0
	global_load_lds_dwordx4 v159, s[68:69]
	s_waitcnt lgkmcnt(5)
	v_mfma_f32_32x32x16_bf16 v[50:65], v[138:141], v[164:167], v[50:65]
	ds_read_b128 v[184:187], v204 offset:40960
	v_mfma_f32_32x32x16_bf16 v[34:49], v[138:141], v[168:171], v[34:49]
	ds_read_b128 v[188:191], v204 offset:45056
	s_add_u32 m0, s9, 0x16020
	s_add_u32 s14, s14, 0x20000
	s_addc_u32 s15, s15, 0
	global_load_lds_dwordx4 v159, s[14:15]
	s_add_u32 m0, s9, 0x17020
	s_add_u32 s68, s14, 0x10000
	s_addc_u32 s69, s15, 0
	global_load_lds_dwordx4 v159, s[68:69]
	s_add_u32 s2, s2, 0x80
	s_addc_u32 s3, s3, 0
	s_waitcnt lgkmcnt(6)
	v_mfma_f32_32x32x16_bf16 v[18:33], v[160:163], v[164:167], v[18:33]
	v_mfma_f32_32x32x16_bf16 v[2:17], v[160:163], v[168:171], v[2:17]
	s_waitcnt lgkmcnt(4)
	v_mfma_f32_32x32x16_bf16 v[114:129], v[172:175], v[192:195], v[114:129]
	ds_read_b128 v[130:133], v205 offset:32768
	s_waitcnt lgkmcnt(4)
	v_mfma_f32_32x32x16_bf16 v[98:113], v[172:175], v[200:203], v[98:113]
	ds_read_b128 v[164:167], v209 offset:32768
	s_waitcnt lgkmcnt(4)
	v_mfma_f32_32x32x16_bf16 v[82:97], v[180:183], v[192:195], v[82:97]
	ds_read_b128 v[168:171], v209 offset:36864
	v_mfma_f32_32x32x16_bf16 v[66:81], v[180:183], v[200:203], v[66:81]
	ds_read_b128 v[134:137], v205 offset:36864
	s_waitcnt lgkmcnt(5)
	v_mfma_f32_32x32x16_bf16 v[50:65], v[184:187], v[192:195], v[50:65]
	ds_read_b128 v[138:141], v205 offset:40960
	v_mfma_f32_32x32x16_bf16 v[34:49], v[184:187], v[200:203], v[34:49]
	ds_read_b128 v[160:163], v205 offset:45056
	s_waitcnt lgkmcnt(6)
	v_mfma_f32_32x32x16_bf16 v[18:33], v[188:191], v[192:195], v[18:33]
	v_mfma_f32_32x32x16_bf16 v[2:17], v[188:191], v[200:203], v[2:17]
	s_waitcnt lgkmcnt(4)
	v_mfma_f32_32x32x16_bf16 v[114:129], v[130:133], v[164:167], v[114:129]
	ds_read_b128 v[172:175], v206 offset:32768
	ds_read_b128 v[192:195], v210 offset:32768
	s_waitcnt lgkmcnt(5)
	v_mfma_f32_32x32x16_bf16 v[98:113], v[130:133], v[168:171], v[98:113]
	ds_read_b128 v[200:203], v210 offset:36864
	ds_read_b128 v[180:183], v206 offset:36864
	s_waitcnt lgkmcnt(6)
	v_mfma_f32_32x32x16_bf16 v[82:97], v[134:137], v[164:167], v[82:97]
	ds_read_b128 v[184:187], v206 offset:40960
	ds_read_b128 v[188:191], v206 offset:45056
	v_mfma_f32_32x32x16_bf16 v[66:81], v[134:137], v[168:171], v[66:81]
	s_waitcnt lgkmcnt(7)
	v_mfma_f32_32x32x16_bf16 v[50:65], v[138:141], v[164:167], v[50:65]
	v_mfma_f32_32x32x16_bf16 v[34:49], v[138:141], v[168:171], v[34:49]
	s_waitcnt lgkmcnt(6)
	v_mfma_f32_32x32x16_bf16 v[18:33], v[160:163], v[164:167], v[18:33]
	v_mfma_f32_32x32x16_bf16 v[2:17], v[160:163], v[168:171], v[2:17]
	s_waitcnt vmcnt(0) lgkmcnt(0)
	s_barrier
	v_mfma_f32_32x32x16_bf16 v[114:129], v[172:175], v[192:195], v[114:129]
	ds_read_b128 v[130:133], v177 offset:0
	s_add_u32 m0, s9, 0x8020
	s_add_u32 s14, s1, s2
	s_addc_u32 s15, s5, s3
	global_load_lds_dwordx4 v159, s[14:15]
	s_add_u32 m0, s9, 0x9020
	s_add_u32 s68, s14, 0x10000
	s_addc_u32 s69, s15, 0
	global_load_lds_dwordx4 v159, s[68:69]
	v_mfma_f32_32x32x16_bf16 v[98:113], v[172:175], v[200:203], v[98:113]
	ds_read_b128 v[164:167], v207 offset:0
	s_add_u32 m0, s9, 0xa020
	s_add_u32 s14, s14, 0x20000
	s_addc_u32 s15, s15, 0
	global_load_lds_dwordx4 v159, s[14:15]
	s_add_u32 m0, s9, 0xb020
	s_add_u32 s68, s14, 0x10000
	s_addc_u32 s69, s15, 0
	global_load_lds_dwordx4 v159, s[68:69]
	v_mfma_f32_32x32x16_bf16 v[82:97], v[180:183], v[192:195], v[82:97]
	ds_read_b128 v[168:171], v207 offset:4096
	s_add_u32 m0, s9, 0xc020
	s_add_u32 s14, s14, 0x20000
	s_addc_u32 s15, s15, 0
	global_load_lds_dwordx4 v159, s[14:15]
	s_add_u32 m0, s9, 0xd020
	s_add_u32 s68, s14, 0x10000
	s_addc_u32 s69, s15, 0
	global_load_lds_dwordx4 v159, s[68:69]
	v_mfma_f32_32x32x16_bf16 v[66:81], v[180:183], v[200:203], v[66:81]
	ds_read_b128 v[134:137], v177 offset:4096
	s_add_u32 m0, s9, 0xe020
	s_add_u32 s14, s14, 0x20000
	s_addc_u32 s15, s15, 0
	global_load_lds_dwordx4 v159, s[14:15]
	s_add_u32 m0, s9, 0xf020
	s_add_u32 s68, s14, 0x10000
	s_addc_u32 s69, s15, 0
	global_load_lds_dwordx4 v159, s[68:69]
	v_mfma_f32_32x32x16_bf16 v[50:65], v[184:187], v[192:195], v[50:65]
	ds_read_b128 v[138:141], v177 offset:8192
	s_add_u32 m0, s9, 0x18020
	s_add_u32 s14, s7, s2
	s_addc_u32 s15, s8, s3
	global_load_lds_dwordx4 v159, s[14:15]
	s_add_u32 m0, s9, 0x19020
	s_add_u32 s68, s14, 0x10000
	s_addc_u32 s69, s15, 0
	global_load_lds_dwordx4 v159, s[68:69]
	v_mfma_f32_32x32x16_bf16 v[34:49], v[184:187], v[200:203], v[34:49]
	ds_read_b128 v[160:163], v177 offset:12288
	v_mfma_f32_32x32x16_bf16 v[18:33], v[188:191], v[192:195], v[18:33]
	v_mfma_f32_32x32x16_bf16 v[2:17], v[188:191], v[200:203], v[2:17]
	s_sub_u32 s6, s6, 1
	s_cmp_lg_u32 s6, 0
	s_cbranch_scc1 .Lg295_loop
	s_waitcnt lgkmcnt(4)
	v_mfma_f32_32x32x16_bf16 v[114:129], v[130:133], v[164:167], v[114:129]
	ds_read_b128 v[172:175], v204 offset:0
	s_waitcnt lgkmcnt(4)
	v_mfma_f32_32x32x16_bf16 v[98:113], v[130:133], v[168:171], v[98:113]
	ds_read_b128 v[192:195], v208 offset:0
	s_add_u32 m0, s9, 0x1a020
	s_add_u32 s14, s14, 0x20000
	s_addc_u32 s15, s15, 0
	global_load_lds_dwordx4 v159, s[14:15]
	s_add_u32 m0, s9, 0x1b020
	s_add_u32 s68, s14, 0x10000
	s_addc_u32 s69, s15, 0
	global_load_lds_dwordx4 v159, s[68:69]
	s_waitcnt lgkmcnt(4)
	v_mfma_f32_32x32x16_bf16 v[82:97], v[134:137], v[164:167], v[82:97]
	ds_read_b128 v[200:203], v208 offset:4096
	v_mfma_f32_32x32x16_bf16 v[66:81], v[134:137], v[168:171], v[66:81]
	ds_read_b128 v[180:183], v204 offset:4096
	s_add_u32 m0, s9, 0x1c020
	s_add_u32 s14, s14, 0x20000
	s_addc_u32 s15, s15, 0
	global_load_lds_dwordx4 v159, s[14:15]
	s_add_u32 m0, s9, 0x1d020
	s_add_u32 s68, s14, 0x10000
	s_addc_u32 s69, s15, 0
	global_load_lds_dwordx4 v159, s[68:69]
	s_waitcnt lgkmcnt(5)
	v_mfma_f32_32x32x16_bf16 v[50:65], v[138:141], v[164:167], v[50:65]
	ds_read_b128 v[184:187], v204 offset:8192
	v_mfma_f32_32x32x16_bf16 v[34:49], v[138:141], v[168:171], v[34:49]
	ds_read_b128 v[188:191], v204 offset:12288
	s_add_u32 m0, s9, 0x1e020
	s_add_u32 s14, s14, 0x20000
	s_addc_u32 s15, s15, 0
	global_load_lds_dwordx4 v159, s[14:15]
	s_add_u32 m0, s9, 0x1f020
	s_add_u32 s68, s14, 0x10000
	s_addc_u32 s69, s15, 0
	global_load_lds_dwordx4 v159, s[68:69]
	s_add_u32 s2, s2, 0x80
	s_addc_u32 s3, s3, 0
	s_waitcnt lgkmcnt(6)
	v_mfma_f32_32x32x16_bf16 v[18:33], v[160:163], v[164:167], v[18:33]
	v_mfma_f32_32x32x16_bf16 v[2:17], v[160:163], v[168:171], v[2:17]
	s_waitcnt lgkmcnt(4)
	v_mfma_f32_32x32x16_bf16 v[114:129], v[172:175], v[192:195], v[114:129]
	ds_read_b128 v[130:133], v205 offset:0
	s_waitcnt lgkmcnt(4)
	v_mfma_f32_32x32x16_bf16 v[98:113], v[172:175], v[200:203], v[98:113]
	ds_read_b128 v[164:167], v209 offset:0
	s_waitcnt lgkmcnt(4)
	v_mfma_f32_32x32x16_bf16 v[82:97], v[180:183], v[192:195], v[82:97]
	ds_read_b128 v[168:171], v209 offset:4096
	v_mfma_f32_32x32x16_bf16 v[66:81], v[180:183], v[200:203], v[66:81]
	ds_read_b128 v[134:137], v205 offset:4096
	s_waitcnt lgkmcnt(5)
	v_mfma_f32_32x32x16_bf16 v[50:65], v[184:187], v[192:195], v[50:65]
	ds_read_b128 v[138:141], v205 offset:8192
	v_mfma_f32_32x32x16_bf16 v[34:49], v[184:187], v[200:203], v[34:49]
	ds_read_b128 v[160:163], v205 offset:12288
	s_waitcnt lgkmcnt(6)
	v_mfma_f32_32x32x16_bf16 v[18:33], v[188:191], v[192:195], v[18:33]
	v_mfma_f32_32x32x16_bf16 v[2:17], v[188:191], v[200:203], v[2:17]
	s_waitcnt lgkmcnt(4)
	v_mfma_f32_32x32x16_bf16 v[114:129], v[130:133], v[164:167], v[114:129]
	ds_read_b128 v[172:175], v206 offset:0
	ds_read_b128 v[192:195], v210 offset:0
	s_waitcnt lgkmcnt(5)
	v_mfma_f32_32x32x16_bf16 v[98:113], v[130:133], v[168:171], v[98:113]
	ds_read_b128 v[200:203], v210 offset:4096
	ds_read_b128 v[180:183], v206 offset:4096
	s_waitcnt lgkmcnt(6)
	v_mfma_f32_32x32x16_bf16 v[82:97], v[134:137], v[164:167], v[82:97]
	ds_read_b128 v[184:187], v206 offset:8192
	ds_read_b128 v[188:191], v206 offset:12288
	v_mfma_f32_32x32x16_bf16 v[66:81], v[134:137], v[168:171], v[66:81]
	s_waitcnt lgkmcnt(7)
	v_mfma_f32_32x32x16_bf16 v[50:65], v[138:141], v[164:167], v[50:65]
	v_mfma_f32_32x32x16_bf16 v[34:49], v[138:141], v[168:171], v[34:49]
	s_waitcnt lgkmcnt(6)
	v_mfma_f32_32x32x16_bf16 v[18:33], v[160:163], v[164:167], v[18:33]
	v_mfma_f32_32x32x16_bf16 v[2:17], v[160:163], v[168:171], v[2:17]
	s_waitcnt vmcnt(0) lgkmcnt(0)
	s_barrier
	v_mfma_f32_32x32x16_bf16 v[114:129], v[172:175], v[192:195], v[114:129]
	ds_read_b128 v[130:133], v177 offset:32768
	v_mfma_f32_32x32x16_bf16 v[98:113], v[172:175], v[200:203], v[98:113]
	ds_read_b128 v[164:167], v207 offset:32768
	v_mfma_f32_32x32x16_bf16 v[82:97], v[180:183], v[192:195], v[82:97]
	ds_read_b128 v[168:171], v207 offset:36864
	v_mfma_f32_32x32x16_bf16 v[66:81], v[180:183], v[200:203], v[66:81]
	ds_read_b128 v[134:137], v177 offset:36864
	v_mfma_f32_32x32x16_bf16 v[50:65], v[184:187], v[192:195], v[50:65]
	ds_read_b128 v[138:141], v177 offset:40960
	v_mfma_f32_32x32x16_bf16 v[34:49], v[184:187], v[200:203], v[34:49]
	ds_read_b128 v[160:163], v177 offset:45056
	v_mfma_f32_32x32x16_bf16 v[18:33], v[188:191], v[192:195], v[18:33]
	v_mfma_f32_32x32x16_bf16 v[2:17], v[188:191], v[200:203], v[2:17]
	s_waitcnt lgkmcnt(4)
	v_mfma_f32_32x32x16_bf16 v[114:129], v[130:133], v[164:167], v[114:129]
	ds_read_b128 v[172:175], v204 offset:32768
	s_waitcnt lgkmcnt(4)
	v_mfma_f32_32x32x16_bf16 v[98:113], v[130:133], v[168:171], v[98:113]
	ds_read_b128 v[192:195], v208 offset:32768
	s_waitcnt lgkmcnt(4)
	v_mfma_f32_32x32x16_bf16 v[82:97], v[134:137], v[164:167], v[82:97]
	ds_read_b128 v[200:203], v208 offset:36864
	v_mfma_f32_32x32x16_bf16 v[66:81], v[134:137], v[168:171], v[66:81]
	ds_read_b128 v[180:183], v204 offset:36864
	s_waitcnt lgkmcnt(5)
	v_mfma_f32_32x32x16_bf16 v[50:65], v[138:141], v[164:167], v[50:65]
	ds_read_b128 v[184:187], v204 offset:40960
	v_mfma_f32_32x32x16_bf16 v[34:49], v[138:141], v[168:171], v[34:49]
	ds_read_b128 v[188:191], v204 offset:45056
	s_waitcnt lgkmcnt(6)
	v_mfma_f32_32x32x16_bf16 v[18:33], v[160:163], v[164:167], v[18:33]
	v_mfma_f32_32x32x16_bf16 v[2:17], v[160:163], v[168:171], v[2:17]
	s_waitcnt lgkmcnt(4)
	v_mfma_f32_32x32x16_bf16 v[114:129], v[172:175], v[192:195], v[114:129]
	ds_read_b128 v[130:133], v205 offset:32768
	s_waitcnt lgkmcnt(4)
	v_mfma_f32_32x32x16_bf16 v[98:113], v[172:175], v[200:203], v[98:113]
	ds_read_b128 v[164:167], v209 offset:32768
	s_waitcnt lgkmcnt(4)
	v_mfma_f32_32x32x16_bf16 v[82:97], v[180:183], v[192:195], v[82:97]
	ds_read_b128 v[168:171], v209 offset:36864
	v_mfma_f32_32x32x16_bf16 v[66:81], v[180:183], v[200:203], v[66:81]
	ds_read_b128 v[134:137], v205 offset:36864
	s_waitcnt lgkmcnt(5)
	v_mfma_f32_32x32x16_bf16 v[50:65], v[184:187], v[192:195], v[50:65]
	ds_read_b128 v[138:141], v205 offset:40960
	v_mfma_f32_32x32x16_bf16 v[34:49], v[184:187], v[200:203], v[34:49]
	ds_read_b128 v[160:163], v205 offset:45056
	s_waitcnt lgkmcnt(6)
	v_mfma_f32_32x32x16_bf16 v[18:33], v[188:191], v[192:195], v[18:33]
	v_mfma_f32_32x32x16_bf16 v[2:17], v[188:191], v[200:203], v[2:17]
	s_waitcnt lgkmcnt(4)
	v_mfma_f32_32x32x16_bf16 v[114:129], v[130:133], v[164:167], v[114:129]
	ds_read_b128 v[172:175], v206 offset:32768
	ds_read_b128 v[192:195], v210 offset:32768
	s_waitcnt lgkmcnt(5)
	v_mfma_f32_32x32x16_bf16 v[98:113], v[130:133], v[168:171], v[98:113]
	ds_read_b128 v[200:203], v210 offset:36864
	ds_read_b128 v[180:183], v206 offset:36864
	s_waitcnt lgkmcnt(6)
	v_mfma_f32_32x32x16_bf16 v[82:97], v[134:137], v[164:167], v[82:97]
	ds_read_b128 v[184:187], v206 offset:40960
	ds_read_b128 v[188:191], v206 offset:45056
	v_mfma_f32_32x32x16_bf16 v[66:81], v[134:137], v[168:171], v[66:81]
	s_waitcnt lgkmcnt(7)
	v_mfma_f32_32x32x16_bf16 v[50:65], v[138:141], v[164:167], v[50:65]
	v_mfma_f32_32x32x16_bf16 v[34:49], v[138:141], v[168:171], v[34:49]
	s_waitcnt lgkmcnt(6)
	v_mfma_f32_32x32x16_bf16 v[18:33], v[160:163], v[164:167], v[18:33]
	v_mfma_f32_32x32x16_bf16 v[2:17], v[160:163], v[168:171], v[2:17]
	s_waitcnt vmcnt(0) lgkmcnt(0)
	s_barrier
	v_mfma_f32_32x32x16_bf16 v[114:129], v[172:175], v[192:195], v[114:129]
	v_mfma_f32_32x32x16_bf16 v[98:113], v[172:175], v[200:203], v[98:113]
	v_mfma_f32_32x32x16_bf16 v[82:97], v[180:183], v[192:195], v[82:97]
	v_mfma_f32_32x32x16_bf16 v[66:81], v[180:183], v[200:203], v[66:81]
	v_mfma_f32_32x32x16_bf16 v[50:65], v[184:187], v[192:195], v[50:65]
	v_mfma_f32_32x32x16_bf16 v[34:49], v[184:187], v[200:203], v[34:49]
	v_mfma_f32_32x32x16_bf16 v[18:33], v[188:191], v[192:195], v[18:33]
	v_mfma_f32_32x32x16_bf16 v[2:17], v[188:191], v[200:203], v[2:17]
	s_branch .Lg295_end
.Lgl295_entry:
	v_lshlrev_b32_e32 v159, 1, v142
	v_readfirstlane_b32 s9, v143
	v_add_u32_e32 v177, v150, v152
	v_add_u32_e32 v207, v151, v152
	v_add_u32_e32 v204, v150, v156
	v_add_u32_e32 v208, v151, v156
	v_add_u32_e32 v205, v150, v157
	v_add_u32_e32 v209, v151, v157
	v_add_u32_e32 v206, v150, v158
	v_add_u32_e32 v210, v151, v158
	s_mov_b32 s6, 7
	ds_read_b128 v[130:133], v177 offset:0
	ds_read_b128 v[164:167], v207 offset:0
	ds_read_b128 v[168:171], v207 offset:4096
	ds_read_b128 v[134:137], v177 offset:4096
	ds_read_b128 v[138:141], v177 offset:8192
	ds_read_b128 v[160:163], v177 offset:12288
.Lgl295_loop:
	s_waitcnt lgkmcnt(4)
	v_mfma_f32_32x32x16_bf16 v[114:129], v[130:133], v[164:167], v[114:129]
	ds_read_b128 v[172:175], v204 offset:0
	s_waitcnt lgkmcnt(4)
	v_mfma_f32_32x32x16_bf16 v[98:113], v[130:133], v[168:171], v[98:113]
	ds_read_b128 v[192:195], v208 offset:0
	s_waitcnt lgkmcnt(4)
	v_mfma_f32_32x32x16_bf16 v[82:97], v[134:137], v[164:167], v[82:97]
	ds_read_b128 v[200:203], v208 offset:4096
	v_mfma_f32_32x32x16_bf16 v[66:81], v[134:137], v[168:171], v[66:81]
	ds_read_b128 v[180:183], v204 offset:4096
	s_waitcnt lgkmcnt(5)
	v_mfma_f32_32x32x16_bf16 v[50:65], v[138:141], v[164:167], v[50:65]
	ds_read_b128 v[184:187], v204 offset:8192
	v_mfma_f32_32x32x16_bf16 v[34:49], v[138:141], v[168:171], v[34:49]
	ds_read_b128 v[188:191], v204 offset:12288
	s_add_u32 s2, s2, 0x80
	s_addc_u32 s3, s3, 0
	s_waitcnt lgkmcnt(6)
	v_mfma_f32_32x32x16_bf16 v[18:33], v[160:163], v[164:167], v[18:33]
	v_mfma_f32_32x32x16_bf16 v[2:17], v[160:163], v[168:171], v[2:17]
	s_waitcnt lgkmcnt(4)
	v_mfma_f32_32x32x16_bf16 v[114:129], v[172:175], v[192:195], v[114:129]
	ds_read_b128 v[130:133], v205 offset:0
	s_waitcnt lgkmcnt(4)
	v_mfma_f32_32x32x16_bf16 v[98:113], v[172:175], v[200:203], v[98:113]
	ds_read_b128 v[164:167], v209 offset:0
	s_waitcnt lgkmcnt(4)
	v_mfma_f32_32x32x16_bf16 v[82:97], v[180:183], v[192:195], v[82:97]
	ds_read_b128 v[168:171], v209 offset:4096
	v_mfma_f32_32x32x16_bf16 v[66:81], v[180:183], v[200:203], v[66:81]
	ds_read_b128 v[134:137], v205 offset:4096
	s_waitcnt lgkmcnt(5)
	v_mfma_f32_32x32x16_bf16 v[50:65], v[184:187], v[192:195], v[50:65]
	ds_read_b128 v[138:141], v205 offset:8192
	v_mfma_f32_32x32x16_bf16 v[34:49], v[184:187], v[200:203], v[34:49]
	ds_read_b128 v[160:163], v205 offset:12288
	s_waitcnt lgkmcnt(6)
	v_mfma_f32_32x32x16_bf16 v[18:33], v[188:191], v[192:195], v[18:33]
	v_mfma_f32_32x32x16_bf16 v[2:17], v[188:191], v[200:203], v[2:17]
	s_waitcnt lgkmcnt(4)
	v_mfma_f32_32x32x16_bf16 v[114:129], v[130:133], v[164:167], v[114:129]
	ds_read_b128 v[172:175], v206 offset:0
	ds_read_b128 v[192:195], v210 offset:0
	s_waitcnt lgkmcnt(5)
	v_mfma_f32_32x32x16_bf16 v[98:113], v[130:133], v[168:171], v[98:113]
	ds_read_b128 v[200:203], v210 offset:4096
	ds_read_b128 v[180:183], v206 offset:4096
	s_waitcnt lgkmcnt(6)
	v_mfma_f32_32x32x16_bf16 v[82:97], v[134:137], v[164:167], v[82:97]
	ds_read_b128 v[184:187], v206 offset:8192
	ds_read_b128 v[188:191], v206 offset:12288
	v_mfma_f32_32x32x16_bf16 v[66:81], v[134:137], v[168:171], v[66:81]
	s_waitcnt lgkmcnt(7)
	v_mfma_f32_32x32x16_bf16 v[50:65], v[138:141], v[164:167], v[50:65]
	v_mfma_f32_32x32x16_bf16 v[34:49], v[138:141], v[168:171], v[34:49]
	s_waitcnt lgkmcnt(6)
	v_mfma_f32_32x32x16_bf16 v[18:33], v[160:163], v[164:167], v[18:33]
	v_mfma_f32_32x32x16_bf16 v[2:17], v[160:163], v[168:171], v[2:17]
	s_waitcnt vmcnt(0) lgkmcnt(0)
	s_barrier
	v_mfma_f32_32x32x16_bf16 v[114:129], v[172:175], v[192:195], v[114:129]
	ds_read_b128 v[130:133], v177 offset:32768
	v_mfma_f32_32x32x16_bf16 v[98:113], v[172:175], v[200:203], v[98:113]
	ds_read_b128 v[164:167], v207 offset:32768
	v_mfma_f32_32x32x16_bf16 v[82:97], v[180:183], v[192:195], v[82:97]
	ds_read_b128 v[168:171], v207 offset:36864
	v_mfma_f32_32x32x16_bf16 v[66:81], v[180:183], v[200:203], v[66:81]
	ds_read_b128 v[134:137], v177 offset:36864
	v_mfma_f32_32x32x16_bf16 v[50:65], v[184:187], v[192:195], v[50:65]
	ds_read_b128 v[138:141], v177 offset:40960
	v_mfma_f32_32x32x16_bf16 v[34:49], v[184:187], v[200:203], v[34:49]
	ds_read_b128 v[160:163], v177 offset:45056
	v_mfma_f32_32x32x16_bf16 v[18:33], v[188:191], v[192:195], v[18:33]
	v_mfma_f32_32x32x16_bf16 v[2:17], v[188:191], v[200:203], v[2:17]
	s_waitcnt lgkmcnt(4)
	v_mfma_f32_32x32x16_bf16 v[114:129], v[130:133], v[164:167], v[114:129]
	ds_read_b128 v[172:175], v204 offset:32768
	s_waitcnt lgkmcnt(4)
	v_mfma_f32_32x32x16_bf16 v[98:113], v[130:133], v[168:171], v[98:113]
	ds_read_b128 v[192:195], v208 offset:32768
	s_waitcnt lgkmcnt(4)
	v_mfma_f32_32x32x16_bf16 v[82:97], v[134:137], v[164:167], v[82:97]
	ds_read_b128 v[200:203], v208 offset:36864
	v_mfma_f32_32x32x16_bf16 v[66:81], v[134:137], v[168:171], v[66:81]
	ds_read_b128 v[180:183], v204 offset:36864
	s_waitcnt lgkmcnt(5)
	v_mfma_f32_32x32x16_bf16 v[50:65], v[138:141], v[164:167], v[50:65]
	ds_read_b128 v[184:187], v204 offset:40960
	v_mfma_f32_32x32x16_bf16 v[34:49], v[138:141], v[168:171], v[34:49]
	ds_read_b128 v[188:191], v204 offset:45056
	s_add_u32 s2, s2, 0x80
	s_addc_u32 s3, s3, 0
	s_waitcnt lgkmcnt(6)
	v_mfma_f32_32x32x16_bf16 v[18:33], v[160:163], v[164:167], v[18:33]
	v_mfma_f32_32x32x16_bf16 v[2:17], v[160:163], v[168:171], v[2:17]
	s_waitcnt lgkmcnt(4)
	v_mfma_f32_32x32x16_bf16 v[114:129], v[172:175], v[192:195], v[114:129]
	ds_read_b128 v[130:133], v205 offset:32768
	s_waitcnt lgkmcnt(4)
	v_mfma_f32_32x32x16_bf16 v[98:113], v[172:175], v[200:203], v[98:113]
	ds_read_b128 v[164:167], v209 offset:32768
	s_waitcnt lgkmcnt(4)
	v_mfma_f32_32x32x16_bf16 v[82:97], v[180:183], v[192:195], v[82:97]
	ds_read_b128 v[168:171], v209 offset:36864
	v_mfma_f32_32x32x16_bf16 v[66:81], v[180:183], v[200:203], v[66:81]
	ds_read_b128 v[134:137], v205 offset:36864
	s_waitcnt lgkmcnt(5)
	v_mfma_f32_32x32x16_bf16 v[50:65], v[184:187], v[192:195], v[50:65]
	ds_read_b128 v[138:141], v205 offset:40960
	v_mfma_f32_32x32x16_bf16 v[34:49], v[184:187], v[200:203], v[34:49]
	ds_read_b128 v[160:163], v205 offset:45056
	s_waitcnt lgkmcnt(6)
	v_mfma_f32_32x32x16_bf16 v[18:33], v[188:191], v[192:195], v[18:33]
	v_mfma_f32_32x32x16_bf16 v[2:17], v[188:191], v[200:203], v[2:17]
	s_waitcnt lgkmcnt(4)
	v_mfma_f32_32x32x16_bf16 v[114:129], v[130:133], v[164:167], v[114:129]
	ds_read_b128 v[172:175], v206 offset:32768
	ds_read_b128 v[192:195], v210 offset:32768
	s_waitcnt lgkmcnt(5)
	v_mfma_f32_32x32x16_bf16 v[98:113], v[130:133], v[168:171], v[98:113]
	ds_read_b128 v[200:203], v210 offset:36864
	ds_read_b128 v[180:183], v206 offset:36864
	s_waitcnt lgkmcnt(6)
	v_mfma_f32_32x32x16_bf16 v[82:97], v[134:137], v[164:167], v[82:97]
	ds_read_b128 v[184:187], v206 offset:40960
	ds_read_b128 v[188:191], v206 offset:45056
	v_mfma_f32_32x32x16_bf16 v[66:81], v[134:137], v[168:171], v[66:81]
	s_waitcnt lgkmcnt(7)
	v_mfma_f32_32x32x16_bf16 v[50:65], v[138:141], v[164:167], v[50:65]
	v_mfma_f32_32x32x16_bf16 v[34:49], v[138:141], v[168:171], v[34:49]
	s_waitcnt lgkmcnt(6)
	v_mfma_f32_32x32x16_bf16 v[18:33], v[160:163], v[164:167], v[18:33]
	v_mfma_f32_32x32x16_bf16 v[2:17], v[160:163], v[168:171], v[2:17]
	s_waitcnt vmcnt(0) lgkmcnt(0)
	s_barrier
	v_mfma_f32_32x32x16_bf16 v[114:129], v[172:175], v[192:195], v[114:129]
	ds_read_b128 v[130:133], v177 offset:0
	v_mfma_f32_32x32x16_bf16 v[98:113], v[172:175], v[200:203], v[98:113]
	ds_read_b128 v[164:167], v207 offset:0
	v_mfma_f32_32x32x16_bf16 v[82:97], v[180:183], v[192:195], v[82:97]
	ds_read_b128 v[168:171], v207 offset:4096
	v_mfma_f32_32x32x16_bf16 v[66:81], v[180:183], v[200:203], v[66:81]
	ds_read_b128 v[134:137], v177 offset:4096
	v_mfma_f32_32x32x16_bf16 v[50:65], v[184:187], v[192:195], v[50:65]
	ds_read_b128 v[138:141], v177 offset:8192
	v_mfma_f32_32x32x16_bf16 v[34:49], v[184:187], v[200:203], v[34:49]
	ds_read_b128 v[160:163], v177 offset:12288
	v_mfma_f32_32x32x16_bf16 v[18:33], v[188:191], v[192:195], v[18:33]
	v_mfma_f32_32x32x16_bf16 v[2:17], v[188:191], v[200:203], v[2:17]
	s_sub_u32 s6, s6, 1
	s_cmp_lg_u32 s6, 0
	s_cbranch_scc1 .Lgl295_loop
	s_waitcnt lgkmcnt(4)
	v_mfma_f32_32x32x16_bf16 v[114:129], v[130:133], v[164:167], v[114:129]
	ds_read_b128 v[172:175], v204 offset:0
	s_waitcnt lgkmcnt(4)
	v_mfma_f32_32x32x16_bf16 v[98:113], v[130:133], v[168:171], v[98:113]
	ds_read_b128 v[192:195], v208 offset:0
	s_waitcnt lgkmcnt(4)
	v_mfma_f32_32x32x16_bf16 v[82:97], v[134:137], v[164:167], v[82:97]
	ds_read_b128 v[200:203], v208 offset:4096
	v_mfma_f32_32x32x16_bf16 v[66:81], v[134:137], v[168:171], v[66:81]
	ds_read_b128 v[180:183], v204 offset:4096
	s_waitcnt lgkmcnt(5)
	v_mfma_f32_32x32x16_bf16 v[50:65], v[138:141], v[164:167], v[50:65]
	ds_read_b128 v[184:187], v204 offset:8192
	v_mfma_f32_32x32x16_bf16 v[34:49], v[138:141], v[168:171], v[34:49]
	ds_read_b128 v[188:191], v204 offset:12288
	s_add_u32 s2, s2, 0x80
	s_addc_u32 s3, s3, 0
	s_waitcnt lgkmcnt(6)
	v_mfma_f32_32x32x16_bf16 v[18:33], v[160:163], v[164:167], v[18:33]
	v_mfma_f32_32x32x16_bf16 v[2:17], v[160:163], v[168:171], v[2:17]
	s_waitcnt lgkmcnt(4)
	v_mfma_f32_32x32x16_bf16 v[114:129], v[172:175], v[192:195], v[114:129]
	ds_read_b128 v[130:133], v205 offset:0
	s_waitcnt lgkmcnt(4)
	v_mfma_f32_32x32x16_bf16 v[98:113], v[172:175], v[200:203], v[98:113]
	ds_read_b128 v[164:167], v209 offset:0
	s_waitcnt lgkmcnt(4)
	v_mfma_f32_32x32x16_bf16 v[82:97], v[180:183], v[192:195], v[82:97]
	ds_read_b128 v[168:171], v209 offset:4096
	v_mfma_f32_32x32x16_bf16 v[66:81], v[180:183], v[200:203], v[66:81]
	ds_read_b128 v[134:137], v205 offset:4096
	s_waitcnt lgkmcnt(5)
	v_mfma_f32_32x32x16_bf16 v[50:65], v[184:187], v[192:195], v[50:65]
	ds_read_b128 v[138:141], v205 offset:8192
	v_mfma_f32_32x32x16_bf16 v[34:49], v[184:187], v[200:203], v[34:49]
	ds_read_b128 v[160:163], v205 offset:12288
	s_waitcnt lgkmcnt(6)
	v_mfma_f32_32x32x16_bf16 v[18:33], v[188:191], v[192:195], v[18:33]
	v_mfma_f32_32x32x16_bf16 v[2:17], v[188:191], v[200:203], v[2:17]
	s_waitcnt lgkmcnt(4)
	v_mfma_f32_32x32x16_bf16 v[114:129], v[130:133], v[164:167], v[114:129]
	ds_read_b128 v[172:175], v206 offset:0
	ds_read_b128 v[192:195], v210 offset:0
	s_waitcnt lgkmcnt(5)
	v_mfma_f32_32x32x16_bf16 v[98:113], v[130:133], v[168:171], v[98:113]
	ds_read_b128 v[200:203], v210 offset:4096
	ds_read_b128 v[180:183], v206 offset:4096
	s_waitcnt lgkmcnt(6)
	v_mfma_f32_32x32x16_bf16 v[82:97], v[134:137], v[164:167], v[82:97]
	ds_read_b128 v[184:187], v206 offset:8192
	ds_read_b128 v[188:191], v206 offset:12288
	v_mfma_f32_32x32x16_bf16 v[66:81], v[134:137], v[168:171], v[66:81]
	s_waitcnt lgkmcnt(7)
	v_mfma_f32_32x32x16_bf16 v[50:65], v[138:141], v[164:167], v[50:65]
	v_mfma_f32_32x32x16_bf16 v[34:49], v[138:141], v[168:171], v[34:49]
	s_waitcnt lgkmcnt(6)
	v_mfma_f32_32x32x16_bf16 v[18:33], v[160:163], v[164:167], v[18:33]
	v_mfma_f32_32x32x16_bf16 v[2:17], v[160:163], v[168:171], v[2:17]
	s_waitcnt vmcnt(0) lgkmcnt(0)
	s_barrier
	v_mfma_f32_32x32x16_bf16 v[114:129], v[172:175], v[192:195], v[114:129]
	ds_read_b128 v[130:133], v177 offset:32768
	v_mfma_f32_32x32x16_bf16 v[98:113], v[172:175], v[200:203], v[98:113]
	ds_read_b128 v[164:167], v207 offset:32768
	v_mfma_f32_32x32x16_bf16 v[82:97], v[180:183], v[192:195], v[82:97]
	ds_read_b128 v[168:171], v207 offset:36864
	v_mfma_f32_32x32x16_bf16 v[66:81], v[180:183], v[200:203], v[66:81]
	ds_read_b128 v[134:137], v177 offset:36864
	v_mfma_f32_32x32x16_bf16 v[50:65], v[184:187], v[192:195], v[50:65]
	ds_read_b128 v[138:141], v177 offset:40960
	v_mfma_f32_32x32x16_bf16 v[34:49], v[184:187], v[200:203], v[34:49]
	ds_read_b128 v[160:163], v177 offset:45056
	v_mfma_f32_32x32x16_bf16 v[18:33], v[188:191], v[192:195], v[18:33]
	v_mfma_f32_32x32x16_bf16 v[2:17], v[188:191], v[200:203], v[2:17]
	s_waitcnt lgkmcnt(4)
	v_mfma_f32_32x32x16_bf16 v[114:129], v[130:133], v[164:167], v[114:129]
	ds_read_b128 v[172:175], v204 offset:32768
	s_waitcnt lgkmcnt(4)
	v_mfma_f32_32x32x16_bf16 v[98:113], v[130:133], v[168:171], v[98:113]
	ds_read_b128 v[192:195], v208 offset:32768
	s_waitcnt lgkmcnt(4)
	v_mfma_f32_32x32x16_bf16 v[82:97], v[134:137], v[164:167], v[82:97]
	ds_read_b128 v[200:203], v208 offset:36864
	v_mfma_f32_32x32x16_bf16 v[66:81], v[134:137], v[168:171], v[66:81]
	ds_read_b128 v[180:183], v204 offset:36864
	s_waitcnt lgkmcnt(5)
	v_mfma_f32_32x32x16_bf16 v[50:65], v[138:141], v[164:167], v[50:65]
	ds_read_b128 v[184:187], v204 offset:40960
	v_mfma_f32_32x32x16_bf16 v[34:49], v[138:141], v[168:171], v[34:49]
	ds_read_b128 v[188:191], v204 offset:45056
	s_waitcnt lgkmcnt(6)
	v_mfma_f32_32x32x16_bf16 v[18:33], v[160:163], v[164:167], v[18:33]
	v_mfma_f32_32x32x16_bf16 v[2:17], v[160:163], v[168:171], v[2:17]
	s_waitcnt lgkmcnt(4)
	v_mfma_f32_32x32x16_bf16 v[114:129], v[172:175], v[192:195], v[114:129]
	ds_read_b128 v[130:133], v205 offset:32768
	s_waitcnt lgkmcnt(4)
	v_mfma_f32_32x32x16_bf16 v[98:113], v[172:175], v[200:203], v[98:113]
	ds_read_b128 v[164:167], v209 offset:32768
	s_waitcnt lgkmcnt(4)
	v_mfma_f32_32x32x16_bf16 v[82:97], v[180:183], v[192:195], v[82:97]
	ds_read_b128 v[168:171], v209 offset:36864
	v_mfma_f32_32x32x16_bf16 v[66:81], v[180:183], v[200:203], v[66:81]
	ds_read_b128 v[134:137], v205 offset:36864
	s_waitcnt lgkmcnt(5)
	v_mfma_f32_32x32x16_bf16 v[50:65], v[184:187], v[192:195], v[50:65]
	ds_read_b128 v[138:141], v205 offset:40960
	v_mfma_f32_32x32x16_bf16 v[34:49], v[184:187], v[200:203], v[34:49]
	ds_read_b128 v[160:163], v205 offset:45056
	s_waitcnt lgkmcnt(6)
	v_mfma_f32_32x32x16_bf16 v[18:33], v[188:191], v[192:195], v[18:33]
	v_mfma_f32_32x32x16_bf16 v[2:17], v[188:191], v[200:203], v[2:17]
	s_waitcnt lgkmcnt(4)
	v_mfma_f32_32x32x16_bf16 v[114:129], v[130:133], v[164:167], v[114:129]
	ds_read_b128 v[172:175], v206 offset:32768
	ds_read_b128 v[192:195], v210 offset:32768
	s_waitcnt lgkmcnt(5)
	v_mfma_f32_32x32x16_bf16 v[98:113], v[130:133], v[168:171], v[98:113]
	ds_read_b128 v[200:203], v210 offset:36864
	ds_read_b128 v[180:183], v206 offset:36864
	s_waitcnt lgkmcnt(6)
	v_mfma_f32_32x32x16_bf16 v[82:97], v[134:137], v[164:167], v[82:97]
	ds_read_b128 v[184:187], v206 offset:40960
	ds_read_b128 v[188:191], v206 offset:45056
	v_mfma_f32_32x32x16_bf16 v[66:81], v[134:137], v[168:171], v[66:81]
	s_waitcnt lgkmcnt(7)
	v_mfma_f32_32x32x16_bf16 v[50:65], v[138:141], v[164:167], v[50:65]
	v_mfma_f32_32x32x16_bf16 v[34:49], v[138:141], v[168:171], v[34:49]
	s_waitcnt lgkmcnt(6)
	v_mfma_f32_32x32x16_bf16 v[18:33], v[160:163], v[164:167], v[18:33]
	v_mfma_f32_32x32x16_bf16 v[2:17], v[160:163], v[168:171], v[2:17]
	s_waitcnt vmcnt(0) lgkmcnt(0)
	s_barrier
	v_mfma_f32_32x32x16_bf16 v[114:129], v[172:175], v[192:195], v[114:129]
	v_mfma_f32_32x32x16_bf16 v[98:113], v[172:175], v[200:203], v[98:113]
	v_mfma_f32_32x32x16_bf16 v[82:97], v[180:183], v[192:195], v[82:97]
	v_mfma_f32_32x32x16_bf16 v[66:81], v[180:183], v[200:203], v[66:81]
	v_mfma_f32_32x32x16_bf16 v[50:65], v[184:187], v[192:195], v[50:65]
	v_mfma_f32_32x32x16_bf16 v[34:49], v[184:187], v[200:203], v[34:49]
	v_mfma_f32_32x32x16_bf16 v[18:33], v[188:191], v[192:195], v[18:33]
	v_mfma_f32_32x32x16_bf16 v[2:17], v[188:191], v[200:203], v[2:17]
.Lg295_end:
	s_setprio 0
	v_add_u32_e32 v159, s0, v153
	s_mov_b32 s0, 0x7e07e07f
	v_mul_hi_i32 v0, v159, s0
	v_lshrrev_b32_e32 v133, 31, v0
	v_ashrrev_i32_e32 v0, 13, v0
	v_add_u32_e32 v134, v0, v133
	v_mul_i32_i24_e32 v0, 0x4100, v134
	v_sub_u32_e32 v136, v159, v0
	s_movk_i32 s0, 0x100
	v_cmp_gt_i32_e64 s[56:57], s0, v136
	v_ashrrev_i32_e32 v137, 31, v136
	s_mov_b32 s0, 0xfff00000
	s_waitcnt vmcnt(0)
	v_ashrrev_i32_e32 v130, 7, v159
	v_lshlrev_b64 v[136:137], 12, v[136:137]
	s_mov_b32 s1, -1
	v_or_b32_e32 v132, s4, v154
	v_ashrrev_i32_e32 v131, 31, v130
	v_ashrrev_i32_e32 v135, 31, v134
	v_lshl_add_u64 v[136:137], v[136:137], 0, s[0:1]
	s_movk_i32 s0, 0x1840
	v_lshlrev_b64 v[130:131], 14, v[130:131]
	v_lshlrev_b64 v[134:135], 26, v[134:135]
	v_mov_b32_e32 v161, v179
	v_cmp_gt_i32_e64 s[54:55], s0, v132
	s_barrier
	s_and_saveexec_b64 s[2:3], s[54:55]
	s_cbranch_execz .LBB0_371
	s_movk_i32 s0, 0x7ff
	v_cmp_lt_i32_e32 vcc, s0, v132
	s_xor_b64 s[0:1], s[56:57], -1
	s_or_b64 s[0:1], vcc, s[0:1]
	s_and_b64 exec, exec, s[0:1]
	s_cbranch_execz .LBB0_371
	v_bfe_u32 v0, v161, 5, 1
	v_mul_u32_u24_e32 v0, 0x90, v0
	v_lshlrev_b32_e32 v133, 2, v161
	v_lshlrev_b32_e32 v0, 2, v0
	v_and_b32_e32 v133, 0x7c, v133
	v_add3_u32 v138, v155, v0, v133
	v_add3_u32 v0, v155, v133, v0
	ds_write_b32 v138, v114
	v_add_u32_e32 v114, 0x100, v0
	ds_write2_b32 v114, v117, v118 offset0:44 offset1:224
	v_add_u32_e32 v114, 0x400, v0
	ds_write2_b32 v114, v119, v120 offset0:68 offset1:104
	v_add_u32_e32 v114, 0x600, v0
	ds_write2_b32 v114, v121, v122 offset0:12 offset1:192
	v_add_u32_e32 v114, 0x800, v0
	ds_write2_b32 v114, v123, v124 offset0:100 offset1:136
	v_add_u32_e32 v114, 0xa00, v0
	ds_write2_b32 v114, v125, v126 offset0:44 offset1:224
	v_add_u32_e32 v114, 0xc00, v0
	ds_write2_b32 v0, v115, v116 offset0:36 offset1:72
	ds_write2_b32 v114, v127, v128 offset0:132 offset1:168
	ds_write_b32 v0, v129 offset:3888
	s_waitcnt lgkmcnt(0)
	v_and_b32_e32 v160, 63, v161
	s_and_saveexec_b64 s[0:1], vcc
	s_xor_b64 s[6:7], exec, s[0:1]
	s_cbranch_execz .LBB0_369
	s_cmpk_gt_u32 s4, 0x17ff
	s_mov_b64 s[0:1], -1
	s_cbranch_scc0 .LBB0_365
	v_readlane_b32 s16, v251, 2
	v_lshlrev_b32_e32 v116, 3, v161
	v_add_u32_e32 v0, 0xffffe800, v132
	v_readlane_b32 s17, v251, 3
	v_and_b32_e32 v116, 24, v116
	v_lshlrev_b32_e32 v140, 2, v116
	v_lshl_add_u64 v[114:115], v[0:1], 2, s[16:17]
	v_mov_b32_e32 v141, v1
	v_lshl_add_u64 v[138:139], v[114:115], 0, v[140:141]
	global_load_dwordx4 v[122:125], v[138:139], off
	global_load_dwordx4 v[114:117], v[138:139], off offset:16
	v_add_u32_e32 v162, v155, v140
	v_lshrrev_b32_e32 v133, 2, v160
	s_movk_i32 s0, 0x90
	v_mad_u32_u24 v118, v133, s0, v162
	ds_read_b128 v[126:129], v118
	ds_read_b128 v[118:121], v118 offset:16
	s_mov_b32 s0, 0xbfb8aa3b
	v_readlane_b32 s18, v251, 4
	v_readlane_b32 s19, v251, 5
	v_readlane_b32 s20, v251, 6
	v_readlane_b32 s21, v251, 7
	v_readlane_b32 s22, v251, 8
	v_readlane_b32 s23, v251, 9
	v_readlane_b32 s24, v251, 10
	v_readlane_b32 s25, v251, 11
	v_readlane_b32 s26, v251, 12
	v_readlane_b32 s27, v251, 13
	v_readlane_b32 s28, v251, 14
	v_readlane_b32 s29, v251, 15
	v_readlane_b32 s30, v251, 16
	v_readlane_b32 s31, v251, 17
	s_waitcnt vmcnt(1) lgkmcnt(1)
	v_add_f32_e32 v122, v126, v122
	v_mul_f32_e64 v126, |v122|, s0
	v_exp_f32_e32 v141, v126
	s_mov_b32 s0, 0x3c23d70a
	v_cmp_ngt_f32_e32 vcc, s0, v141
	s_and_saveexec_b64 s[0:1], vcc
	s_xor_b64 s[8:9], exec, s[0:1]
	s_cbranch_execz .LBB0_302
	v_add_f32_e32 v126, 1.0, v141
	s_mov_b32 s0, 0x800000
	v_cmp_gt_f32_e32 vcc, s0, v126
	s_mov_b32 s0, 0x3f317217
	s_nop 0
	v_cndmask_b32_e64 v141, 0, 32, vcc
	v_ldexp_f32 v126, v126, v141
	v_log_f32_e32 v126, v126
	s_nop 0
	v_mul_f32_e32 v141, 0x3f317217, v126
	v_fma_f32 v141, v126, s0, -v141
	v_fmac_f32_e32 v141, 0x3377d1cf, v126
	v_fmac_f32_e32 v141, 0x3f317217, v126
	v_cmp_lt_f32_e64 s[0:1], |v126|, s47
	s_nop 1
	v_cndmask_b32_e64 v126, v126, v141, s[0:1]
	v_cndmask_b32_e32 v141, 0, v238, vcc
	v_sub_f32_e32 v126, v126, v141

.LBB0_908:
	s_add_i32 s2, s7, s8
	s_cmpk_gt_i32 s2, 0x207
	s_mov_b64 s[0:1], -1
	s_cbranch_scc1 .LBB0_907
	s_ashr_i32 s0, s2, 31
	s_lshr_b32 s0, s0, 27
	s_add_i32 s0, s2, s0
	s_ashr_i32 s1, s0, 5
	s_lshl_b32 s1, s1, 3
	s_sub_i32 s3, 0x82, s1
	s_min_u32 s3, s3, 8
	v_cvt_f32_ubyte0_e32 v0, s3
	v_rcp_iflag_f32_e32 v0, v0
	s_sub_i32 s5, 0, s3
	s_andn2_b32 s0, s0, 31
	s_sub_i32 s0, s2, s0
	v_mul_f32_e32 v0, 0x4f7ffffe, v0
	v_cvt_u32_f32_e32 v0, v0
	s_abs_i32 s4, s0
	s_ashr_i32 s2, s0, 31
	s_waitcnt vmcnt(63) expcnt(7) lgkmcnt(15)
	v_readfirstlane_b32 s10, v0
	s_mul_i32 s5, s5, s10
	s_mul_hi_u32 s5, s10, s5
	s_add_i32 s10, s10, s5
	s_mul_hi_u32 s5, s4, s10
	s_mul_i32 s10, s5, s3
	s_sub_i32 s4, s4, s10
	s_add_i32 s10, s5, 1
	s_sub_i32 s11, s4, s3
	s_cmp_ge_u32 s4, s3
	s_cselect_b32 s5, s10, s5
	s_cselect_b32 s4, s11, s4
	s_add_i32 s10, s5, 1
	s_cmp_ge_u32 s4, s3
	s_cselect_b32 s4, s10, s5
	s_xor_b32 s4, s4, s2
	s_sub_i32 s2, s4, s2
	s_mul_i32 s3, s2, s3
	s_sub_i32 s0, s0, s3
	s_add_i32 s0, s0, s1
	s_lshl_b32 s0, s0, 8
	s_lshl_b32 s2, s2, 8
	s_ashr_i32 s1, s0, 31
	s_ashr_i32 s3, s2, 31
	s_lshl_b64 s[4:5], s[0:1], 11
	s_lshl_b64 s[10:11], s[2:3], 11
	s_add_u32 s12, s64, s4
	v_mov_b32_e32 v0, v132
	s_addc_u32 s13, s65, s5
	s_barrier
	v_readlane_b32 s14, v251, 50
	v_lshl_add_u64 v[2:3], v[0:1], 1, s[12:13]
	v_add_u32_e32 v0, 32, v133
	v_readlane_b32 s15, v251, 51
	v_readfirstlane_b32 s1, v0
	s_mov_b32 m0, s1
	v_mov_b32_e32 v0, v134
	global_load_lds_dwordx4 v[2:3], off
	s_add_u32 s14, s14, s10
	v_lshl_add_u64 v[2:3], v[0:1], 1, s[12:13]
	v_add_u32_e32 v0, 32, v135
	s_addc_u32 s15, s15, s11
	v_readfirstlane_b32 s1, v0
	s_mov_b32 m0, s1
	v_mov_b32_e32 v0, v136
	global_load_lds_dwordx4 v[2:3], off
	v_readlane_b32 s3, v254, 3
	v_lshl_add_u64 v[2:3], v[0:1], 1, s[12:13]
	v_add_u32_e32 v0, 32, v137
	s_mov_b32 s9, 0
	v_readfirstlane_b32 s1, v0
	s_mov_b32 m0, s1
	v_mov_b32_e32 v0, v138
	global_load_lds_dwordx4 v[2:3], off
	s_nop 0
	v_lshl_add_u64 v[2:3], v[0:1], 1, s[12:13]
	v_add_u32_e32 v0, 32, v139
	s_nop 0
	v_readfirstlane_b32 s1, v0
	s_mov_b32 m0, s1
	v_mov_b32_e32 v0, v132
	global_load_lds_dwordx4 v[2:3], off
	s_nop 0
	v_lshl_add_u64 v[2:3], v[0:1], 1, s[14:15]
	v_add_u32_e32 v0, s3, v133
	s_nop 0
	v_readfirstlane_b32 s1, v0
	s_mov_b32 m0, s1
	v_mov_b32_e32 v0, v134
	global_load_lds_dwordx4 v[2:3], off
	s_nop 0
	v_lshl_add_u64 v[2:3], v[0:1], 1, s[14:15]
	v_add_u32_e32 v0, s3, v135
	s_nop 0
	v_readfirstlane_b32 s1, v0
	s_mov_b32 m0, s1
	v_mov_b32_e32 v0, v136
	global_load_lds_dwordx4 v[2:3], off
	s_nop 0
	v_lshl_add_u64 v[2:3], v[0:1], 1, s[14:15]
	v_add_u32_e32 v0, s3, v137
	s_nop 0
	v_readfirstlane_b32 s1, v0
	s_mov_b32 m0, s1
	v_mov_b32_e32 v0, v138
	global_load_lds_dwordx4 v[2:3], off
	s_nop 0
	v_lshl_add_u64 v[2:3], v[0:1], 1, s[14:15]
	v_add_u32_e32 v0, s3, v139
	v_readlane_b32 s3, v253, 26
	v_readfirstlane_b32 s1, v0
	s_mov_b32 m0, s1
	v_readlane_b32 s1, v253, 25
	global_load_lds_dwordx4 v[2:3], off
	s_add_u32 s1, s1, s4
	s_waitcnt vmcnt(0)
	s_addc_u32 s3, s3, s5
	v_readlane_b32 s4, v253, 34
	s_add_u32 s10, s4, s10
	v_readlane_b32 s4, v253, 35
	v_mov_b32_e32 v2, 0
	s_addc_u32 s11, s4, s11
	s_mov_b64 s[4:5], 0
	v_mov_b32_e32 v3, v2
	v_mov_b32_e32 v4, v2
	v_mov_b32_e32 v5, v2
	v_mov_b32_e32 v6, v2
	v_mov_b32_e32 v7, v2
	v_mov_b32_e32 v8, v2
	v_mov_b32_e32 v9, v2
	v_mov_b32_e32 v10, v2
	v_mov_b32_e32 v11, v2
	v_mov_b32_e32 v12, v2
	v_mov_b32_e32 v13, v2
	s_waitcnt vmcnt(0)
	v_mov_b32_e32 v14, v2
	v_mov_b32_e32 v15, v2
	v_mov_b32_e32 v16, v2
	v_mov_b32_e32 v17, v2
	v_mov_b32_e32 v18, v2
	v_mov_b32_e32 v19, v2
	v_mov_b32_e32 v20, v2
	v_mov_b32_e32 v21, v2
	v_mov_b32_e32 v22, v2
	v_mov_b32_e32 v23, v2
	v_mov_b32_e32 v24, v2
	v_mov_b32_e32 v25, v2
	v_mov_b32_e32 v26, v2
	v_mov_b32_e32 v27, v2
	v_mov_b32_e32 v28, v2
	v_mov_b32_e32 v29, v2
	v_mov_b32_e32 v30, v2
	v_mov_b32_e32 v31, v2
	v_mov_b32_e32 v32, v2
	v_mov_b32_e32 v33, v2
	v_mov_b32_e32 v34, v2
	v_mov_b32_e32 v35, v2
	v_mov_b32_e32 v36, v2
	v_mov_b32_e32 v37, v2
	v_mov_b32_e32 v38, v2
	v_mov_b32_e32 v39, v2
	v_mov_b32_e32 v40, v2
	v_mov_b32_e32 v41, v2
	v_mov_b32_e32 v42, v2
	v_mov_b32_e32 v43, v2
	v_mov_b32_e32 v44, v2
	v_mov_b32_e32 v45, v2
	v_mov_b32_e32 v46, v2
	v_mov_b32_e32 v47, v2
	v_mov_b32_e32 v48, v2
	v_mov_b32_e32 v49, v2
	v_mov_b32_e32 v50, v2
	v_mov_b32_e32 v51, v2
	v_mov_b32_e32 v52, v2
	v_mov_b32_e32 v53, v2
	v_mov_b32_e32 v54, v2
	v_mov_b32_e32 v55, v2
	v_mov_b32_e32 v56, v2
	v_mov_b32_e32 v57, v2
	v_mov_b32_e32 v58, v2
	v_mov_b32_e32 v59, v2
	v_mov_b32_e32 v60, v2
	v_mov_b32_e32 v61, v2
	v_mov_b32_e32 v62, v2
	v_mov_b32_e32 v63, v2
	v_mov_b32_e32 v64, v2
	v_mov_b32_e32 v65, v2
	v_mov_b32_e32 v66, v2
	v_mov_b32_e32 v67, v2
	v_mov_b32_e32 v68, v2
	v_mov_b32_e32 v69, v2
	v_mov_b32_e32 v70, v2
	v_mov_b32_e32 v71, v2
	v_mov_b32_e32 v72, v2
	v_mov_b32_e32 v73, v2
	v_mov_b32_e32 v74, v2
	v_mov_b32_e32 v75, v2
	v_mov_b32_e32 v76, v2
	v_mov_b32_e32 v77, v2
	v_mov_b32_e32 v78, v2
	v_mov_b32_e32 v79, v2
	v_mov_b32_e32 v80, v2
	v_mov_b32_e32 v81, v2
	v_mov_b32_e32 v82, v2
	v_mov_b32_e32 v83, v2
	v_mov_b32_e32 v84, v2
	v_mov_b32_e32 v85, v2
	v_mov_b32_e32 v86, v2
	v_mov_b32_e32 v87, v2
	v_mov_b32_e32 v88, v2
	v_mov_b32_e32 v89, v2
	v_mov_b32_e32 v90, v2
	v_mov_b32_e32 v91, v2
	v_mov_b32_e32 v92, v2
	v_mov_b32_e32 v93, v2
	v_mov_b32_e32 v94, v2
	v_mov_b32_e32 v95, v2
	v_mov_b32_e32 v96, v2
	v_mov_b32_e32 v97, v2
	v_mov_b32_e32 v98, v2
	v_mov_b32_e32 v99, v2
	v_mov_b32_e32 v100, v2
	v_mov_b32_e32 v101, v2
	v_mov_b32_e32 v102, v2
	v_mov_b32_e32 v103, v2
	v_mov_b32_e32 v104, v2
	v_mov_b32_e32 v105, v2
	v_mov_b32_e32 v106, v2
	v_mov_b32_e32 v107, v2
	v_mov_b32_e32 v108, v2
	v_mov_b32_e32 v109, v2
	v_mov_b32_e32 v110, v2
	v_mov_b32_e32 v111, v2
	v_mov_b32_e32 v112, v2
	v_mov_b32_e32 v113, v2
	v_mov_b32_e32 v114, v2
	v_mov_b32_e32 v115, v2
	v_mov_b32_e32 v116, v2
	v_mov_b32_e32 v117, v2
	v_mov_b32_e32 v118, v2
	v_mov_b32_e32 v119, v2
	v_mov_b32_e32 v120, v2
	v_mov_b32_e32 v121, v2
	v_mov_b32_e32 v122, v2
	v_mov_b32_e32 v123, v2
	v_mov_b32_e32 v124, v2
	v_mov_b32_e32 v125, v2
	v_mov_b32_e32 v126, v2
	v_mov_b32_e32 v127, v2
	v_mov_b32_e32 v128, v2
	v_mov_b32_e32 v129, v2
	s_waitcnt lgkmcnt(0)
	s_barrier
	v_readfirstlane_b32 s66, v179
	s_cmp_lt_u32 s66, 0x100
	s_cbranch_scc0 .Lgl910_entry
	s_setprio 1
	v_lshlrev_b32_e32 v149, 1, v132
	v_readfirstlane_b32 s14, v133
	v_add_u32_e32 v205, v140, v142
	v_add_u32_e32 v209, v141, v142
	v_add_u32_e32 v206, v140, v146
	v_add_u32_e32 v210, v141, v146
	v_add_u32_e32 v207, v140, v147
	v_add_u32_e32 v211, v141, v147
	v_add_u32_e32 v208, v140, v148
	v_add_u32_e32 v212, v141, v148
	s_mov_b32 s9, 7
	s_add_u32 m0, s14, 0x8020
	s_add_u32 s12, s1, s4
	s_addc_u32 s13, s3, s5
	global_load_lds_dwordx4 v149, s[12:13]
	s_add_u32 m0, s14, 0x9020
	s_add_u32 s68, s12, 0x10000
	s_addc_u32 s69, s13, 0
	global_load_lds_dwordx4 v149, s[68:69]
	s_add_u32 m0, s14, 0xa020
	s_add_u32 s12, s12, 0x20000
	s_addc_u32 s13, s13, 0
	global_load_lds_dwordx4 v149, s[12:13]
	s_add_u32 m0, s14, 0xb020
	s_add_u32 s68, s12, 0x10000
	s_addc_u32 s69, s13, 0
	global_load_lds_dwordx4 v149, s[68:69]
	s_add_u32 m0, s14, 0xc020
	s_add_u32 s12, s12, 0x20000
	s_addc_u32 s13, s13, 0
	global_load_lds_dwordx4 v149, s[12:13]
	s_add_u32 m0, s14, 0xd020
	s_add_u32 s68, s12, 0x10000
	s_addc_u32 s69, s13, 0
	global_load_lds_dwordx4 v149, s[68:69]
	s_add_u32 m0, s14, 0xe020
	s_add_u32 s12, s12, 0x20000
	s_addc_u32 s13, s13, 0
	global_load_lds_dwordx4 v149, s[12:13]
	s_add_u32 m0, s14, 0xf020
	s_add_u32 s68, s12, 0x10000
	s_addc_u32 s69, s13, 0
	global_load_lds_dwordx4 v149, s[68:69]
	s_add_u32 m0, s14, 0x18020
	s_add_u32 s12, s10, s4
	s_addc_u32 s13, s11, s5
	global_load_lds_dwordx4 v149, s[12:13]
	s_add_u32 m0, s14, 0x19020
	s_add_u32 s68, s12, 0x10000
	s_addc_u32 s69, s13, 0
	global_load_lds_dwordx4 v149, s[68:69]
	ds_read_b128 v[150:153], v205 offset:0
	ds_read_b128 v[166:169], v209 offset:0
	ds_read_b128 v[170:173], v209 offset:4096
	ds_read_b128 v[154:157], v205 offset:4096
	ds_read_b128 v[158:161], v205 offset:8192
	ds_read_b128 v[162:165], v205 offset:12288
.Lg910_loop:
	s_waitcnt lgkmcnt(4)
	v_mfma_f32_32x32x16_bf16 v[114:129], v[150:153], v[166:169], v[114:129]
	ds_read_b128 v[174:177], v206 offset:0
	s_waitcnt lgkmcnt(4)
	v_mfma_f32_32x32x16_bf16 v[98:113], v[150:153], v[170:173], v[98:113]
	ds_read_b128 v[192:195], v210 offset:0
	s_add_u32 m0, s14, 0x1a020
	s_add_u32 s12, s12, 0x20000
	s_addc_u32 s13, s13, 0
	global_load_lds_dwordx4 v149, s[12:13]
	s_add_u32 m0, s14, 0x1b020
	s_add_u32 s68, s12, 0x10000
	s_addc_u32 s69, s13, 0
	global_load_lds_dwordx4 v149, s[68:69]
	s_waitcnt lgkmcnt(4)
	v_mfma_f32_32x32x16_bf16 v[82:97], v[154:157], v[166:169], v[82:97]
	ds_read_b128 v[200:203], v210 offset:4096
	v_mfma_f32_32x32x16_bf16 v[66:81], v[154:157], v[170:173], v[66:81]
	ds_read_b128 v[180:183], v206 offset:4096
	s_add_u32 m0, s14, 0x1c020
	s_add_u32 s12, s12, 0x20000
	s_addc_u32 s13, s13, 0
	global_load_lds_dwordx4 v149, s[12:13]
	s_add_u32 m0, s14, 0x1d020
	s_add_u32 s68, s12, 0x10000
	s_addc_u32 s69, s13, 0
	global_load_lds_dwordx4 v149, s[68:69]
	s_waitcnt lgkmcnt(5)
	v_mfma_f32_32x32x16_bf16 v[50:65], v[158:161], v[166:169], v[50:65]
	ds_read_b128 v[184:187], v206 offset:8192
	v_mfma_f32_32x32x16_bf16 v[34:49], v[158:161], v[170:173], v[34:49]
	ds_read_b128 v[188:191], v206 offset:12288
	s_add_u32 m0, s14, 0x1e020
	s_add_u32 s12, s12, 0x20000
	s_addc_u32 s13, s13, 0
	global_load_lds_dwordx4 v149, s[12:13]
	s_add_u32 m0, s14, 0x1f020
	s_add_u32 s68, s12, 0x10000
	s_addc_u32 s69, s13, 0
	global_load_lds_dwordx4 v149, s[68:69]
	s_add_u32 s4, s4, 0x80
	s_addc_u32 s5, s5, 0
	s_waitcnt lgkmcnt(6)
	v_mfma_f32_32x32x16_bf16 v[18:33], v[162:165], v[166:169], v[18:33]
	v_mfma_f32_32x32x16_bf16 v[2:17], v[162:165], v[170:173], v[2:17]
	s_waitcnt lgkmcnt(4)
	v_mfma_f32_32x32x16_bf16 v[114:129], v[174:177], v[192:195], v[114:129]
	ds_read_b128 v[150:153], v207 offset:0
	s_waitcnt lgkmcnt(4)
	v_mfma_f32_32x32x16_bf16 v[98:113], v[174:177], v[200:203], v[98:113]
	ds_read_b128 v[166:169], v211 offset:0
	s_waitcnt lgkmcnt(4)
	v_mfma_f32_32x32x16_bf16 v[82:97], v[180:183], v[192:195], v[82:97]
	ds_read_b128 v[170:173], v211 offset:4096
	v_mfma_f32_32x32x16_bf16 v[66:81], v[180:183], v[200:203], v[66:81]
	ds_read_b128 v[154:157], v207 offset:4096
	s_waitcnt lgkmcnt(5)
	v_mfma_f32_32x32x16_bf16 v[50:65], v[184:187], v[192:195], v[50:65]
	ds_read_b128 v[158:161], v207 offset:8192
	v_mfma_f32_32x32x16_bf16 v[34:49], v[184:187], v[200:203], v[34:49]
	ds_read_b128 v[162:165], v207 offset:12288
	s_waitcnt lgkmcnt(6)
	v_mfma_f32_32x32x16_bf16 v[18:33], v[188:191], v[192:195], v[18:33]
	v_mfma_f32_32x32x16_bf16 v[2:17], v[188:191], v[200:203], v[2:17]
	s_waitcnt lgkmcnt(4)
	v_mfma_f32_32x32x16_bf16 v[114:129], v[150:153], v[166:169], v[114:129]
	ds_read_b128 v[174:177], v208 offset:0
	ds_read_b128 v[192:195], v212 offset:0
	s_waitcnt lgkmcnt(5)
	v_mfma_f32_32x32x16_bf16 v[98:113], v[150:153], v[170:173], v[98:113]
	ds_read_b128 v[200:203], v212 offset:4096
	ds_read_b128 v[180:183], v208 offset:4096
	s_waitcnt lgkmcnt(6)
	v_mfma_f32_32x32x16_bf16 v[82:97], v[154:157], v[166:169], v[82:97]
	ds_read_b128 v[184:187], v208 offset:8192
	ds_read_b128 v[188:191], v208 offset:12288
	v_mfma_f32_32x32x16_bf16 v[66:81], v[154:157], v[170:173], v[66:81]
	s_waitcnt lgkmcnt(7)
	v_mfma_f32_32x32x16_bf16 v[50:65], v[158:161], v[166:169], v[50:65]
	v_mfma_f32_32x32x16_bf16 v[34:49], v[158:161], v[170:173], v[34:49]
	s_waitcnt lgkmcnt(6)
	v_mfma_f32_32x32x16_bf16 v[18:33], v[162:165], v[166:169], v[18:33]
	v_mfma_f32_32x32x16_bf16 v[2:17], v[162:165], v[170:173], v[2:17]
	s_waitcnt vmcnt(0) lgkmcnt(0)
	s_barrier
	v_mfma_f32_32x32x16_bf16 v[114:129], v[174:177], v[192:195], v[114:129]
	ds_read_b128 v[150:153], v205 offset:32768
	s_add_u32 m0, s14, 0x20
	s_add_u32 s12, s1, s4
	s_addc_u32 s13, s3, s5
	global_load_lds_dwordx4 v149, s[12:13]
	s_add_u32 m0, s14, 0x1020
	s_add_u32 s68, s12, 0x10000
	s_addc_u32 s69, s13, 0
	global_load_lds_dwordx4 v149, s[68:69]
	v_mfma_f32_32x32x16_bf16 v[98:113], v[174:177], v[200:203], v[98:113]
	ds_read_b128 v[166:169], v209 offset:32768
	s_add_u32 m0, s14, 0x2020
	s_add_u32 s12, s12, 0x20000
	s_addc_u32 s13, s13, 0
	global_load_lds_dwordx4 v149, s[12:13]
	s_add_u32 m0, s14, 0x3020
	s_add_u32 s68, s12, 0x10000
	s_addc_u32 s69, s13, 0
	global_load_lds_dwordx4 v149, s[68:69]
	v_mfma_f32_32x32x16_bf16 v[82:97], v[180:183], v[192:195], v[82:97]
	ds_read_b128 v[170:173], v209 offset:36864
	s_add_u32 m0, s14, 0x4020
	s_add_u32 s12, s12, 0x20000
	s_addc_u32 s13, s13, 0
	global_load_lds_dwordx4 v149, s[12:13]
	s_add_u32 m0, s14, 0x5020
	s_add_u32 s68, s12, 0x10000
	s_addc_u32 s69, s13, 0
	global_load_lds_dwordx4 v149, s[68:69]
	v_mfma_f32_32x32x16_bf16 v[66:81], v[180:183], v[200:203], v[66:81]
	ds_read_b128 v[154:157], v205 offset:36864
	s_add_u32 m0, s14, 0x6020
	s_add_u32 s12, s12, 0x20000
	s_addc_u32 s13, s13, 0
	global_load_lds_dwordx4 v149, s[12:13]
	s_add_u32 m0, s14, 0x7020
	s_add_u32 s68, s12, 0x10000
	s_addc_u32 s69, s13, 0
	global_load_lds_dwordx4 v149, s[68:69]
	v_mfma_f32_32x32x16_bf16 v[50:65], v[184:187], v[192:195], v[50:65]
	ds_read_b128 v[158:161], v205 offset:40960
	s_add_u32 m0, s14, 0x10020
	s_add_u32 s12, s10, s4
	s_addc_u32 s13, s11, s5
	global_load_lds_dwordx4 v149, s[12:13]
	s_add_u32 m0, s14, 0x11020
	s_add_u32 s68, s12, 0x10000
	s_addc_u32 s69, s13, 0
	global_load_lds_dwordx4 v149, s[68:69]
	v_mfma_f32_32x32x16_bf16 v[34:49], v[184:187], v[200:203], v[34:49]
	ds_read_b128 v[162:165], v205 offset:45056
	v_mfma_f32_32x32x16_bf16 v[18:33], v[188:191], v[192:195], v[18:33]
	v_mfma_f32_32x32x16_bf16 v[2:17], v[188:191], v[200:203], v[2:17]
	s_waitcnt lgkmcnt(4)
	v_mfma_f32_32x32x16_bf16 v[114:129], v[150:153], v[166:169], v[114:129]
	ds_read_b128 v[174:177], v206 offset:32768
	s_waitcnt lgkmcnt(4)
	v_mfma_f32_32x32x16_bf16 v[98:113], v[150:153], v[170:173], v[98:113]
	ds_read_b128 v[192:195], v210 offset:32768
	s_add_u32 m0, s14, 0x12020
	s_add_u32 s12, s12, 0x20000
	s_addc_u32 s13, s13, 0
	global_load_lds_dwordx4 v149, s[12:13]
	s_add_u32 m0, s14, 0x13020
	s_add_u32 s68, s12, 0x10000
	s_addc_u32 s69, s13, 0
	global_load_lds_dwordx4 v149, s[68:69]
	s_waitcnt lgkmcnt(4)
	v_mfma_f32_32x32x16_bf16 v[82:97], v[154:157], v[166:169], v[82:97]
	ds_read_b128 v[200:203], v210 offset:36864
	v_mfma_f32_32x32x16_bf16 v[66:81], v[154:157], v[170:173], v[66:81]
	ds_read_b128 v[180:183], v206 offset:36864
	s_add_u32 m0, s14, 0x14020
	s_add_u32 s12, s12, 0x20000
	s_addc_u32 s13, s13, 0
	global_load_lds_dwordx4 v149, s[12:13]
	s_add_u32 m0, s14, 0x15020
	s_add_u32 s68, s12, 0x10000
	s_addc_u32 s69, s13, 0
	global_load_lds_dwordx4 v149, s[68:69]
	s_waitcnt lgkmcnt(5)
	v_mfma_f32_32x32x16_bf16 v[50:65], v[158:161], v[166:169], v[50:65]
	ds_read_b128 v[184:187], v206 offset:40960
	v_mfma_f32_32x32x16_bf16 v[34:49], v[158:161], v[170:173], v[34:49]
	ds_read_b128 v[188:191], v206 offset:45056
	s_add_u32 m0, s14, 0x16020
	s_add_u32 s12, s12, 0x20000
	s_addc_u32 s13, s13, 0
	global_load_lds_dwordx4 v149, s[12:13]
	s_add_u32 m0, s14, 0x17020
	s_add_u32 s68, s12, 0x10000
	s_addc_u32 s69, s13, 0
	global_load_lds_dwordx4 v149, s[68:69]
	s_add_u32 s4, s4, 0x80
	s_addc_u32 s5, s5, 0
	s_waitcnt lgkmcnt(6)
	v_mfma_f32_32x32x16_bf16 v[18:33], v[162:165], v[166:169], v[18:33]
	v_mfma_f32_32x32x16_bf16 v[2:17], v[162:165], v[170:173], v[2:17]
	s_waitcnt lgkmcnt(4)
	v_mfma_f32_32x32x16_bf16 v[114:129], v[174:177], v[192:195], v[114:129]
	ds_read_b128 v[150:153], v207 offset:32768
	s_waitcnt lgkmcnt(4)
	v_mfma_f32_32x32x16_bf16 v[98:113], v[174:177], v[200:203], v[98:113]
	ds_read_b128 v[166:169], v211 offset:32768
	s_waitcnt lgkmcnt(4)
	v_mfma_f32_32x32x16_bf16 v[82:97], v[180:183], v[192:195], v[82:97]
	ds_read_b128 v[170:173], v211 offset:36864
	v_mfma_f32_32x32x16_bf16 v[66:81], v[180:183], v[200:203], v[66:81]
	ds_read_b128 v[154:157], v207 offset:36864
	s_waitcnt lgkmcnt(5)
	v_mfma_f32_32x32x16_bf16 v[50:65], v[184:187], v[192:195], v[50:65]
	ds_read_b128 v[158:161], v207 offset:40960
	v_mfma_f32_32x32x16_bf16 v[34:49], v[184:187], v[200:203], v[34:49]
	ds_read_b128 v[162:165], v207 offset:45056
	s_waitcnt lgkmcnt(6)
	v_mfma_f32_32x32x16_bf16 v[18:33], v[188:191], v[192:195], v[18:33]
	v_mfma_f32_32x32x16_bf16 v[2:17], v[188:191], v[200:203], v[2:17]
	s_waitcnt lgkmcnt(4)
	v_mfma_f32_32x32x16_bf16 v[114:129], v[150:153], v[166:169], v[114:129]
	ds_read_b128 v[174:177], v208 offset:32768
	ds_read_b128 v[192:195], v212 offset:32768
	s_waitcnt lgkmcnt(5)
	v_mfma_f32_32x32x16_bf16 v[98:113], v[150:153], v[170:173], v[98:113]
	ds_read_b128 v[200:203], v212 offset:36864
	ds_read_b128 v[180:183], v208 offset:36864
	s_waitcnt lgkmcnt(6)
	v_mfma_f32_32x32x16_bf16 v[82:97], v[154:157], v[166:169], v[82:97]
	ds_read_b128 v[184:187], v208 offset:40960
	ds_read_b128 v[188:191], v208 offset:45056
	v_mfma_f32_32x32x16_bf16 v[66:81], v[154:157], v[170:173], v[66:81]
	s_waitcnt lgkmcnt(7)
	v_mfma_f32_32x32x16_bf16 v[50:65], v[158:161], v[166:169], v[50:65]
	v_mfma_f32_32x32x16_bf16 v[34:49], v[158:161], v[170:173], v[34:49]
	s_waitcnt lgkmcnt(6)
	v_mfma_f32_32x32x16_bf16 v[18:33], v[162:165], v[166:169], v[18:33]
	v_mfma_f32_32x32x16_bf16 v[2:17], v[162:165], v[170:173], v[2:17]
	s_waitcnt vmcnt(0) lgkmcnt(0)
	s_barrier
	v_mfma_f32_32x32x16_bf16 v[114:129], v[174:177], v[192:195], v[114:129]
	ds_read_b128 v[150:153], v205 offset:0
	s_add_u32 m0, s14, 0x8020
	s_add_u32 s12, s1, s4
	s_addc_u32 s13, s3, s5
	global_load_lds_dwordx4 v149, s[12:13]
	s_add_u32 m0, s14, 0x9020
	s_add_u32 s68, s12, 0x10000
	s_addc_u32 s69, s13, 0
	global_load_lds_dwordx4 v149, s[68:69]
	v_mfma_f32_32x32x16_bf16 v[98:113], v[174:177], v[200:203], v[98:113]
	ds_read_b128 v[166:169], v209 offset:0
	s_add_u32 m0, s14, 0xa020
	s_add_u32 s12, s12, 0x20000
	s_addc_u32 s13, s13, 0
	global_load_lds_dwordx4 v149, s[12:13]
	s_add_u32 m0, s14, 0xb020
	s_add_u32 s68, s12, 0x10000
	s_addc_u32 s69, s13, 0
	global_load_lds_dwordx4 v149, s[68:69]
	v_mfma_f32_32x32x16_bf16 v[82:97], v[180:183], v[192:195], v[82:97]
	ds_read_b128 v[170:173], v209 offset:4096
	s_add_u32 m0, s14, 0xc020
	s_add_u32 s12, s12, 0x20000
	s_addc_u32 s13, s13, 0
	global_load_lds_dwordx4 v149, s[12:13]
	s_add_u32 m0, s14, 0xd020
	s_add_u32 s68, s12, 0x10000
	s_addc_u32 s69, s13, 0
	global_load_lds_dwordx4 v149, s[68:69]
	v_mfma_f32_32x32x16_bf16 v[66:81], v[180:183], v[200:203], v[66:81]
	ds_read_b128 v[154:157], v205 offset:4096
	s_add_u32 m0, s14, 0xe020
	s_add_u32 s12, s12, 0x20000
	s_addc_u32 s13, s13, 0
	global_load_lds_dwordx4 v149, s[12:13]
	s_add_u32 m0, s14, 0xf020
	s_add_u32 s68, s12, 0x10000
	s_addc_u32 s69, s13, 0
	global_load_lds_dwordx4 v149, s[68:69]
	v_mfma_f32_32x32x16_bf16 v[50:65], v[184:187], v[192:195], v[50:65]
	ds_read_b128 v[158:161], v205 offset:8192
	s_add_u32 m0, s14, 0x18020
	s_add_u32 s12, s10, s4
	s_addc_u32 s13, s11, s5
	global_load_lds_dwordx4 v149, s[12:13]
	s_add_u32 m0, s14, 0x19020
	s_add_u32 s68, s12, 0x10000
	s_addc_u32 s69, s13, 0
	global_load_lds_dwordx4 v149, s[68:69]
	v_mfma_f32_32x32x16_bf16 v[34:49], v[184:187], v[200:203], v[34:49]
	ds_read_b128 v[162:165], v205 offset:12288
	v_mfma_f32_32x32x16_bf16 v[18:33], v[188:191], v[192:195], v[18:33]
	v_mfma_f32_32x32x16_bf16 v[2:17], v[188:191], v[200:203], v[2:17]
	s_sub_u32 s9, s9, 1
	s_cmp_lg_u32 s9, 0
	s_cbranch_scc1 .Lg910_loop
	s_waitcnt lgkmcnt(4)
	v_mfma_f32_32x32x16_bf16 v[114:129], v[150:153], v[166:169], v[114:129]
	ds_read_b128 v[174:177], v206 offset:0
	s_waitcnt lgkmcnt(4)
	v_mfma_f32_32x32x16_bf16 v[98:113], v[150:153], v[170:173], v[98:113]
	ds_read_b128 v[192:195], v210 offset:0
	s_add_u32 m0, s14, 0x1a020
	s_add_u32 s12, s12, 0x20000
	s_addc_u32 s13, s13, 0
	global_load_lds_dwordx4 v149, s[12:13]
	s_add_u32 m0, s14, 0x1b020
	s_add_u32 s68, s12, 0x10000
	s_addc_u32 s69, s13, 0
	global_load_lds_dwordx4 v149, s[68:69]
	s_waitcnt lgkmcnt(4)
	v_mfma_f32_32x32x16_bf16 v[82:97], v[154:157], v[166:169], v[82:97]
	ds_read_b128 v[200:203], v210 offset:4096
	v_mfma_f32_32x32x16_bf16 v[66:81], v[154:157], v[170:173], v[66:81]
	ds_read_b128 v[180:183], v206 offset:4096
	s_add_u32 m0, s14, 0x1c020
	s_add_u32 s12, s12, 0x20000
	s_addc_u32 s13, s13, 0
	global_load_lds_dwordx4 v149, s[12:13]
	s_add_u32 m0, s14, 0x1d020
	s_add_u32 s68, s12, 0x10000
	s_addc_u32 s69, s13, 0
	global_load_lds_dwordx4 v149, s[68:69]
	s_waitcnt lgkmcnt(5)
	v_mfma_f32_32x32x16_bf16 v[50:65], v[158:161], v[166:169], v[50:65]
	ds_read_b128 v[184:187], v206 offset:8192
	v_mfma_f32_32x32x16_bf16 v[34:49], v[158:161], v[170:173], v[34:49]
	ds_read_b128 v[188:191], v206 offset:12288
	s_add_u32 m0, s14, 0x1e020
	s_add_u32 s12, s12, 0x20000
	s_addc_u32 s13, s13, 0
	global_load_lds_dwordx4 v149, s[12:13]
	s_add_u32 m0, s14, 0x1f020
	s_add_u32 s68, s12, 0x10000
	s_addc_u32 s69, s13, 0
	global_load_lds_dwordx4 v149, s[68:69]
	s_add_u32 s4, s4, 0x80
	s_addc_u32 s5, s5, 0
	s_waitcnt lgkmcnt(6)
	v_mfma_f32_32x32x16_bf16 v[18:33], v[162:165], v[166:169], v[18:33]
	v_mfma_f32_32x32x16_bf16 v[2:17], v[162:165], v[170:173], v[2:17]
	s_waitcnt lgkmcnt(4)
	v_mfma_f32_32x32x16_bf16 v[114:129], v[174:177], v[192:195], v[114:129]
	ds_read_b128 v[150:153], v207 offset:0
	s_waitcnt lgkmcnt(4)
	v_mfma_f32_32x32x16_bf16 v[98:113], v[174:177], v[200:203], v[98:113]
	ds_read_b128 v[166:169], v211 offset:0
	s_waitcnt lgkmcnt(4)
	v_mfma_f32_32x32x16_bf16 v[82:97], v[180:183], v[192:195], v[82:97]
	ds_read_b128 v[170:173], v211 offset:4096
	v_mfma_f32_32x32x16_bf16 v[66:81], v[180:183], v[200:203], v[66:81]
	ds_read_b128 v[154:157], v207 offset:4096
	s_waitcnt lgkmcnt(5)
	v_mfma_f32_32x32x16_bf16 v[50:65], v[184:187], v[192:195], v[50:65]
	ds_read_b128 v[158:161], v207 offset:8192
	v_mfma_f32_32x32x16_bf16 v[34:49], v[184:187], v[200:203], v[34:49]
	ds_read_b128 v[162:165], v207 offset:12288
	s_waitcnt lgkmcnt(6)
	v_mfma_f32_32x32x16_bf16 v[18:33], v[188:191], v[192:195], v[18:33]
	v_mfma_f32_32x32x16_bf16 v[2:17], v[188:191], v[200:203], v[2:17]
	s_waitcnt lgkmcnt(4)
	v_mfma_f32_32x32x16_bf16 v[114:129], v[150:153], v[166:169], v[114:129]
	ds_read_b128 v[174:177], v208 offset:0
	ds_read_b128 v[192:195], v212 offset:0
	s_waitcnt lgkmcnt(5)
	v_mfma_f32_32x32x16_bf16 v[98:113], v[150:153], v[170:173], v[98:113]
	ds_read_b128 v[200:203], v212 offset:4096
	ds_read_b128 v[180:183], v208 offset:4096
	s_waitcnt lgkmcnt(6)
	v_mfma_f32_32x32x16_bf16 v[82:97], v[154:157], v[166:169], v[82:97]
	ds_read_b128 v[184:187], v208 offset:8192
	ds_read_b128 v[188:191], v208 offset:12288
	v_mfma_f32_32x32x16_bf16 v[66:81], v[154:157], v[170:173], v[66:81]
	s_waitcnt lgkmcnt(7)
	v_mfma_f32_32x32x16_bf16 v[50:65], v[158:161], v[166:169], v[50:65]
	v_mfma_f32_32x32x16_bf16 v[34:49], v[158:161], v[170:173], v[34:49]
	s_waitcnt lgkmcnt(6)
	v_mfma_f32_32x32x16_bf16 v[18:33], v[162:165], v[166:169], v[18:33]
	v_mfma_f32_32x32x16_bf16 v[2:17], v[162:165], v[170:173], v[2:17]
	s_waitcnt vmcnt(0) lgkmcnt(0)
	s_barrier
	v_mfma_f32_32x32x16_bf16 v[114:129], v[174:177], v[192:195], v[114:129]
	ds_read_b128 v[150:153], v205 offset:32768
	v_mfma_f32_32x32x16_bf16 v[98:113], v[174:177], v[200:203], v[98:113]
	ds_read_b128 v[166:169], v209 offset:32768
	v_mfma_f32_32x32x16_bf16 v[82:97], v[180:183], v[192:195], v[82:97]
	ds_read_b128 v[170:173], v209 offset:36864
	v_mfma_f32_32x32x16_bf16 v[66:81], v[180:183], v[200:203], v[66:81]
	ds_read_b128 v[154:157], v205 offset:36864
	v_mfma_f32_32x32x16_bf16 v[50:65], v[184:187], v[192:195], v[50:65]
	ds_read_b128 v[158:161], v205 offset:40960
	v_mfma_f32_32x32x16_bf16 v[34:49], v[184:187], v[200:203], v[34:49]
	ds_read_b128 v[162:165], v205 offset:45056
	v_mfma_f32_32x32x16_bf16 v[18:33], v[188:191], v[192:195], v[18:33]
	v_mfma_f32_32x32x16_bf16 v[2:17], v[188:191], v[200:203], v[2:17]
	s_waitcnt lgkmcnt(4)
	v_mfma_f32_32x32x16_bf16 v[114:129], v[150:153], v[166:169], v[114:129]
	ds_read_b128 v[174:177], v206 offset:32768
	s_waitcnt lgkmcnt(4)
	v_mfma_f32_32x32x16_bf16 v[98:113], v[150:153], v[170:173], v[98:113]
	ds_read_b128 v[192:195], v210 offset:32768
	s_waitcnt lgkmcnt(4)
	v_mfma_f32_32x32x16_bf16 v[82:97], v[154:157], v[166:169], v[82:97]
	ds_read_b128 v[200:203], v210 offset:36864
	v_mfma_f32_32x32x16_bf16 v[66:81], v[154:157], v[170:173], v[66:81]
	ds_read_b128 v[180:183], v206 offset:36864
	s_waitcnt lgkmcnt(5)
	v_mfma_f32_32x32x16_bf16 v[50:65], v[158:161], v[166:169], v[50:65]
	ds_read_b128 v[184:187], v206 offset:40960
	v_mfma_f32_32x32x16_bf16 v[34:49], v[158:161], v[170:173], v[34:49]
	ds_read_b128 v[188:191], v206 offset:45056
	s_waitcnt lgkmcnt(6)
	v_mfma_f32_32x32x16_bf16 v[18:33], v[162:165], v[166:169], v[18:33]
	v_mfma_f32_32x32x16_bf16 v[2:17], v[162:165], v[170:173], v[2:17]
	s_waitcnt lgkmcnt(4)
	v_mfma_f32_32x32x16_bf16 v[114:129], v[174:177], v[192:195], v[114:129]
	ds_read_b128 v[150:153], v207 offset:32768
	s_waitcnt lgkmcnt(4)
	v_mfma_f32_32x32x16_bf16 v[98:113], v[174:177], v[200:203], v[98:113]
	ds_read_b128 v[166:169], v211 offset:32768
	s_waitcnt lgkmcnt(4)
	v_mfma_f32_32x32x16_bf16 v[82:97], v[180:183], v[192:195], v[82:97]
	ds_read_b128 v[170:173], v211 offset:36864
	v_mfma_f32_32x32x16_bf16 v[66:81], v[180:183], v[200:203], v[66:81]
	ds_read_b128 v[154:157], v207 offset:36864
	s_waitcnt lgkmcnt(5)
	v_mfma_f32_32x32x16_bf16 v[50:65], v[184:187], v[192:195], v[50:65]
	ds_read_b128 v[158:161], v207 offset:40960
	v_mfma_f32_32x32x16_bf16 v[34:49], v[184:187], v[200:203], v[34:49]
	ds_read_b128 v[162:165], v207 offset:45056
	s_waitcnt lgkmcnt(6)
	v_mfma_f32_32x32x16_bf16 v[18:33], v[188:191], v[192:195], v[18:33]
	v_mfma_f32_32x32x16_bf16 v[2:17], v[188:191], v[200:203], v[2:17]
	s_waitcnt lgkmcnt(4)
	v_mfma_f32_32x32x16_bf16 v[114:129], v[150:153], v[166:169], v[114:129]
	ds_read_b128 v[174:177], v208 offset:32768
	ds_read_b128 v[192:195], v212 offset:32768
	s_waitcnt lgkmcnt(5)
	v_mfma_f32_32x32x16_bf16 v[98:113], v[150:153], v[170:173], v[98:113]
	ds_read_b128 v[200:203], v212 offset:36864
	ds_read_b128 v[180:183], v208 offset:36864
	s_waitcnt lgkmcnt(6)
	v_mfma_f32_32x32x16_bf16 v[82:97], v[154:157], v[166:169], v[82:97]
	ds_read_b128 v[184:187], v208 offset:40960
	ds_read_b128 v[188:191], v208 offset:45056
	v_mfma_f32_32x32x16_bf16 v[66:81], v[154:157], v[170:173], v[66:81]
	s_waitcnt lgkmcnt(7)
	v_mfma_f32_32x32x16_bf16 v[50:65], v[158:161], v[166:169], v[50:65]
	v_mfma_f32_32x32x16_bf16 v[34:49], v[158:161], v[170:173], v[34:49]
	s_waitcnt lgkmcnt(6)
	v_mfma_f32_32x32x16_bf16 v[18:33], v[162:165], v[166:169], v[18:33]
	v_mfma_f32_32x32x16_bf16 v[2:17], v[162:165], v[170:173], v[2:17]
	s_waitcnt vmcnt(0) lgkmcnt(0)
	s_barrier
	v_mfma_f32_32x32x16_bf16 v[114:129], v[174:177], v[192:195], v[114:129]
	v_mfma_f32_32x32x16_bf16 v[98:113], v[174:177], v[200:203], v[98:113]
	v_mfma_f32_32x32x16_bf16 v[82:97], v[180:183], v[192:195], v[82:97]
	v_mfma_f32_32x32x16_bf16 v[66:81], v[180:183], v[200:203], v[66:81]
	v_mfma_f32_32x32x16_bf16 v[50:65], v[184:187], v[192:195], v[50:65]
	v_mfma_f32_32x32x16_bf16 v[34:49], v[184:187], v[200:203], v[34:49]
	v_mfma_f32_32x32x16_bf16 v[18:33], v[188:191], v[192:195], v[18:33]
	v_mfma_f32_32x32x16_bf16 v[2:17], v[188:191], v[200:203], v[2:17]
	s_branch .Lg910_end
.Lgl910_entry:
	v_lshlrev_b32_e32 v149, 1, v132
	v_readfirstlane_b32 s14, v133
	v_add_u32_e32 v205, v140, v142
	v_add_u32_e32 v209, v141, v142
	v_add_u32_e32 v206, v140, v146
	v_add_u32_e32 v210, v141, v146
	v_add_u32_e32 v207, v140, v147
	v_add_u32_e32 v211, v141, v147
	v_add_u32_e32 v208, v140, v148
	v_add_u32_e32 v212, v141, v148
	s_mov_b32 s9, 7
	ds_read_b128 v[150:153], v205 offset:0
	ds_read_b128 v[166:169], v209 offset:0
	ds_read_b128 v[170:173], v209 offset:4096
	ds_read_b128 v[154:157], v205 offset:4096
	ds_read_b128 v[158:161], v205 offset:8192
	ds_read_b128 v[162:165], v205 offset:12288
.Lgl910_loop:
	s_waitcnt lgkmcnt(4)
	v_mfma_f32_32x32x16_bf16 v[114:129], v[150:153], v[166:169], v[114:129]
	ds_read_b128 v[174:177], v206 offset:0
	s_waitcnt lgkmcnt(4)
	v_mfma_f32_32x32x16_bf16 v[98:113], v[150:153], v[170:173], v[98:113]
	ds_read_b128 v[192:195], v210 offset:0
	s_waitcnt lgkmcnt(4)
	v_mfma_f32_32x32x16_bf16 v[82:97], v[154:157], v[166:169], v[82:97]
	ds_read_b128 v[200:203], v210 offset:4096
	v_mfma_f32_32x32x16_bf16 v[66:81], v[154:157], v[170:173], v[66:81]
	ds_read_b128 v[180:183], v206 offset:4096
	s_waitcnt lgkmcnt(5)
	v_mfma_f32_32x32x16_bf16 v[50:65], v[158:161], v[166:169], v[50:65]
	ds_read_b128 v[184:187], v206 offset:8192
	v_mfma_f32_32x32x16_bf16 v[34:49], v[158:161], v[170:173], v[34:49]
	ds_read_b128 v[188:191], v206 offset:12288
	s_add_u32 s4, s4, 0x80
	s_addc_u32 s5, s5, 0
	s_waitcnt lgkmcnt(6)
	v_mfma_f32_32x32x16_bf16 v[18:33], v[162:165], v[166:169], v[18:33]
	v_mfma_f32_32x32x16_bf16 v[2:17], v[162:165], v[170:173], v[2:17]
	s_waitcnt lgkmcnt(4)
	v_mfma_f32_32x32x16_bf16 v[114:129], v[174:177], v[192:195], v[114:129]
	ds_read_b128 v[150:153], v207 offset:0
	s_waitcnt lgkmcnt(4)
	v_mfma_f32_32x32x16_bf16 v[98:113], v[174:177], v[200:203], v[98:113]
	ds_read_b128 v[166:169], v211 offset:0
	s_waitcnt lgkmcnt(4)
	v_mfma_f32_32x32x16_bf16 v[82:97], v[180:183], v[192:195], v[82:97]
	ds_read_b128 v[170:173], v211 offset:4096
	v_mfma_f32_32x32x16_bf16 v[66:81], v[180:183], v[200:203], v[66:81]
	ds_read_b128 v[154:157], v207 offset:4096
	s_waitcnt lgkmcnt(5)
	v_mfma_f32_32x32x16_bf16 v[50:65], v[184:187], v[192:195], v[50:65]
	ds_read_b128 v[158:161], v207 offset:8192
	v_mfma_f32_32x32x16_bf16 v[34:49], v[184:187], v[200:203], v[34:49]
	ds_read_b128 v[162:165], v207 offset:12288
	s_waitcnt lgkmcnt(6)
	v_mfma_f32_32x32x16_bf16 v[18:33], v[188:191], v[192:195], v[18:33]
	v_mfma_f32_32x32x16_bf16 v[2:17], v[188:191], v[200:203], v[2:17]
	s_waitcnt lgkmcnt(4)
	v_mfma_f32_32x32x16_bf16 v[114:129], v[150:153], v[166:169], v[114:129]
	ds_read_b128 v[174:177], v208 offset:0
	ds_read_b128 v[192:195], v212 offset:0
	s_waitcnt lgkmcnt(5)
	v_mfma_f32_32x32x16_bf16 v[98:113], v[150:153], v[170:173], v[98:113]
	ds_read_b128 v[200:203], v212 offset:4096
	ds_read_b128 v[180:183], v208 offset:4096
	s_waitcnt lgkmcnt(6)
	v_mfma_f32_32x32x16_bf16 v[82:97], v[154:157], v[166:169], v[82:97]
	ds_read_b128 v[184:187], v208 offset:8192
	ds_read_b128 v[188:191], v208 offset:12288
	v_mfma_f32_32x32x16_bf16 v[66:81], v[154:157], v[170:173], v[66:81]
	s_waitcnt lgkmcnt(7)
	v_mfma_f32_32x32x16_bf16 v[50:65], v[158:161], v[166:169], v[50:65]
	v_mfma_f32_32x32x16_bf16 v[34:49], v[158:161], v[170:173], v[34:49]
	s_waitcnt lgkmcnt(6)
	v_mfma_f32_32x32x16_bf16 v[18:33], v[162:165], v[166:169], v[18:33]
	v_mfma_f32_32x32x16_bf16 v[2:17], v[162:165], v[170:173], v[2:17]
	s_waitcnt vmcnt(0) lgkmcnt(0)
	s_barrier
	v_mfma_f32_32x32x16_bf16 v[114:129], v[174:177], v[192:195], v[114:129]
	ds_read_b128 v[150:153], v205 offset:32768
	v_mfma_f32_32x32x16_bf16 v[98:113], v[174:177], v[200:203], v[98:113]
	ds_read_b128 v[166:169], v209 offset:32768
	v_mfma_f32_32x32x16_bf16 v[82:97], v[180:183], v[192:195], v[82:97]
	ds_read_b128 v[170:173], v209 offset:36864
	v_mfma_f32_32x32x16_bf16 v[66:81], v[180:183], v[200:203], v[66:81]
	ds_read_b128 v[154:157], v205 offset:36864
	v_mfma_f32_32x32x16_bf16 v[50:65], v[184:187], v[192:195], v[50:65]
	ds_read_b128 v[158:161], v205 offset:40960
	v_mfma_f32_32x32x16_bf16 v[34:49], v[184:187], v[200:203], v[34:49]
	ds_read_b128 v[162:165], v205 offset:45056
	v_mfma_f32_32x32x16_bf16 v[18:33], v[188:191], v[192:195], v[18:33]
	v_mfma_f32_32x32x16_bf16 v[2:17], v[188:191], v[200:203], v[2:17]
	s_waitcnt lgkmcnt(4)
	v_mfma_f32_32x32x16_bf16 v[114:129], v[150:153], v[166:169], v[114:129]
	ds_read_b128 v[174:177], v206 offset:32768
	s_waitcnt lgkmcnt(4)
	v_mfma_f32_32x32x16_bf16 v[98:113], v[150:153], v[170:173], v[98:113]
	ds_read_b128 v[192:195], v210 offset:32768
	s_waitcnt lgkmcnt(4)
	v_mfma_f32_32x32x16_bf16 v[82:97], v[154:157], v[166:169], v[82:97]
	ds_read_b128 v[200:203], v210 offset:36864
	v_mfma_f32_32x32x16_bf16 v[66:81], v[154:157], v[170:173], v[66:81]
	ds_read_b128 v[180:183], v206 offset:36864
	s_waitcnt lgkmcnt(5)
	v_mfma_f32_32x32x16_bf16 v[50:65], v[158:161], v[166:169], v[50:65]
	ds_read_b128 v[184:187], v206 offset:40960
	v_mfma_f32_32x32x16_bf16 v[34:49], v[158:161], v[170:173], v[34:49]
	ds_read_b128 v[188:191], v206 offset:45056
	s_add_u32 s4, s4, 0x80
	s_addc_u32 s5, s5, 0
	s_waitcnt lgkmcnt(6)
	v_mfma_f32_32x32x16_bf16 v[18:33], v[162:165], v[166:169], v[18:33]
	v_mfma_f32_32x32x16_bf16 v[2:17], v[162:165], v[170:173], v[2:17]
	s_waitcnt lgkmcnt(4)
	v_mfma_f32_32x32x16_bf16 v[114:129], v[174:177], v[192:195], v[114:129]
	ds_read_b128 v[150:153], v207 offset:32768
	s_waitcnt lgkmcnt(4)
	v_mfma_f32_32x32x16_bf16 v[98:113], v[174:177], v[200:203], v[98:113]
	ds_read_b128 v[166:169], v211 offset:32768
	s_waitcnt lgkmcnt(4)
	v_mfma_f32_32x32x16_bf16 v[82:97], v[180:183], v[192:195], v[82:97]
	ds_read_b128 v[170:173], v211 offset:36864
	v_mfma_f32_32x32x16_bf16 v[66:81], v[180:183], v[200:203], v[66:81]
	ds_read_b128 v[154:157], v207 offset:36864
	s_waitcnt lgkmcnt(5)
	v_mfma_f32_32x32x16_bf16 v[50:65], v[184:187], v[192:195], v[50:65]
	ds_read_b128 v[158:161], v207 offset:40960
	v_mfma_f32_32x32x16_bf16 v[34:49], v[184:187], v[200:203], v[34:49]
	ds_read_b128 v[162:165], v207 offset:45056
	s_waitcnt lgkmcnt(6)
	v_mfma_f32_32x32x16_bf16 v[18:33], v[188:191], v[192:195], v[18:33]
	v_mfma_f32_32x32x16_bf16 v[2:17], v[188:191], v[200:203], v[2:17]
	s_waitcnt lgkmcnt(4)
	v_mfma_f32_32x32x16_bf16 v[114:129], v[150:153], v[166:169], v[114:129]
	ds_read_b128 v[174:177], v208 offset:32768
	ds_read_b128 v[192:195], v212 offset:32768
	s_waitcnt lgkmcnt(5)
	v_mfma_f32_32x32x16_bf16 v[98:113], v[150:153], v[170:173], v[98:113]
	ds_read_b128 v[200:203], v212 offset:36864
	ds_read_b128 v[180:183], v208 offset:36864
	s_waitcnt lgkmcnt(6)
	v_mfma_f32_32x32x16_bf16 v[82:97], v[154:157], v[166:169], v[82:97]
	ds_read_b128 v[184:187], v208 offset:40960
	ds_read_b128 v[188:191], v208 offset:45056
	v_mfma_f32_32x32x16_bf16 v[66:81], v[154:157], v[170:173], v[66:81]
	s_waitcnt lgkmcnt(7)
	v_mfma_f32_32x32x16_bf16 v[50:65], v[158:161], v[166:169], v[50:65]
	v_mfma_f32_32x32x16_bf16 v[34:49], v[158:161], v[170:173], v[34:49]
	s_waitcnt lgkmcnt(6)
	v_mfma_f32_32x32x16_bf16 v[18:33], v[162:165], v[166:169], v[18:33]
	v_mfma_f32_32x32x16_bf16 v[2:17], v[162:165], v[170:173], v[2:17]
	s_waitcnt vmcnt(0) lgkmcnt(0)
	s_barrier
	v_mfma_f32_32x32x16_bf16 v[114:129], v[174:177], v[192:195], v[114:129]
	ds_read_b128 v[150:153], v205 offset:0
	v_mfma_f32_32x32x16_bf16 v[98:113], v[174:177], v[200:203], v[98:113]
	ds_read_b128 v[166:169], v209 offset:0
	v_mfma_f32_32x32x16_bf16 v[82:97], v[180:183], v[192:195], v[82:97]
	ds_read_b128 v[170:173], v209 offset:4096
	v_mfma_f32_32x32x16_bf16 v[66:81], v[180:183], v[200:203], v[66:81]
	ds_read_b128 v[154:157], v205 offset:4096
	v_mfma_f32_32x32x16_bf16 v[50:65], v[184:187], v[192:195], v[50:65]
	ds_read_b128 v[158:161], v205 offset:8192
	v_mfma_f32_32x32x16_bf16 v[34:49], v[184:187], v[200:203], v[34:49]
	ds_read_b128 v[162:165], v205 offset:12288
	v_mfma_f32_32x32x16_bf16 v[18:33], v[188:191], v[192:195], v[18:33]
	v_mfma_f32_32x32x16_bf16 v[2:17], v[188:191], v[200:203], v[2:17]
	s_sub_u32 s9, s9, 1
	s_cmp_lg_u32 s9, 0
	s_cbranch_scc1 .Lgl910_loop
	s_waitcnt lgkmcnt(4)
	v_mfma_f32_32x32x16_bf16 v[114:129], v[150:153], v[166:169], v[114:129]
	ds_read_b128 v[174:177], v206 offset:0
	s_waitcnt lgkmcnt(4)
	v_mfma_f32_32x32x16_bf16 v[98:113], v[150:153], v[170:173], v[98:113]
	ds_read_b128 v[192:195], v210 offset:0
	s_waitcnt lgkmcnt(4)
	v_mfma_f32_32x32x16_bf16 v[82:97], v[154:157], v[166:169], v[82:97]
	ds_read_b128 v[200:203], v210 offset:4096
	v_mfma_f32_32x32x16_bf16 v[66:81], v[154:157], v[170:173], v[66:81]
	ds_read_b128 v[180:183], v206 offset:4096
	s_waitcnt lgkmcnt(5)
	v_mfma_f32_32x32x16_bf16 v[50:65], v[158:161], v[166:169], v[50:65]
	ds_read_b128 v[184:187], v206 offset:8192
	v_mfma_f32_32x32x16_bf16 v[34:49], v[158:161], v[170:173], v[34:49]
	ds_read_b128 v[188:191], v206 offset:12288
	s_add_u32 s4, s4, 0x80
	s_addc_u32 s5, s5, 0
	s_waitcnt lgkmcnt(6)
	v_mfma_f32_32x32x16_bf16 v[18:33], v[162:165], v[166:169], v[18:33]
	v_mfma_f32_32x32x16_bf16 v[2:17], v[162:165], v[170:173], v[2:17]
	s_waitcnt lgkmcnt(4)
	v_mfma_f32_32x32x16_bf16 v[114:129], v[174:177], v[192:195], v[114:129]
	ds_read_b128 v[150:153], v207 offset:0
	s_waitcnt lgkmcnt(4)
	v_mfma_f32_32x32x16_bf16 v[98:113], v[174:177], v[200:203], v[98:113]
	ds_read_b128 v[166:169], v211 offset:0
	s_waitcnt lgkmcnt(4)
	v_mfma_f32_32x32x16_bf16 v[82:97], v[180:183], v[192:195], v[82:97]
	ds_read_b128 v[170:173], v211 offset:4096
	v_mfma_f32_32x32x16_bf16 v[66:81], v[180:183], v[200:203], v[66:81]
	ds_read_b128 v[154:157], v207 offset:4096
	s_waitcnt lgkmcnt(5)
	v_mfma_f32_32x32x16_bf16 v[50:65], v[184:187], v[192:195], v[50:65]
	ds_read_b128 v[158:161], v207 offset:8192
	v_mfma_f32_32x32x16_bf16 v[34:49], v[184:187], v[200:203], v[34:49]
	ds_read_b128 v[162:165], v207 offset:12288
	s_waitcnt lgkmcnt(6)
	v_mfma_f32_32x32x16_bf16 v[18:33], v[188:191], v[192:195], v[18:33]
	v_mfma_f32_32x32x16_bf16 v[2:17], v[188:191], v[200:203], v[2:17]
	s_waitcnt lgkmcnt(4)
	v_mfma_f32_32x32x16_bf16 v[114:129], v[150:153], v[166:169], v[114:129]
	ds_read_b128 v[174:177], v208 offset:0
	ds_read_b128 v[192:195], v212 offset:0
	s_waitcnt lgkmcnt(5)
	v_mfma_f32_32x32x16_bf16 v[98:113], v[150:153], v[170:173], v[98:113]
	ds_read_b128 v[200:203], v212 offset:4096
	ds_read_b128 v[180:183], v208 offset:4096
	s_waitcnt lgkmcnt(6)
	v_mfma_f32_32x32x16_bf16 v[82:97], v[154:157], v[166:169], v[82:97]
	ds_read_b128 v[184:187], v208 offset:8192
	ds_read_b128 v[188:191], v208 offset:12288
	v_mfma_f32_32x32x16_bf16 v[66:81], v[154:157], v[170:173], v[66:81]
	s_waitcnt lgkmcnt(7)
	v_mfma_f32_32x32x16_bf16 v[50:65], v[158:161], v[166:169], v[50:65]
	v_mfma_f32_32x32x16_bf16 v[34:49], v[158:161], v[170:173], v[34:49]
	s_waitcnt lgkmcnt(6)
	v_mfma_f32_32x32x16_bf16 v[18:33], v[162:165], v[166:169], v[18:33]
	v_mfma_f32_32x32x16_bf16 v[2:17], v[162:165], v[170:173], v[2:17]
	s_waitcnt vmcnt(0) lgkmcnt(0)
	s_barrier
	v_mfma_f32_32x32x16_bf16 v[114:129], v[174:177], v[192:195], v[114:129]
	ds_read_b128 v[150:153], v205 offset:32768
	v_mfma_f32_32x32x16_bf16 v[98:113], v[174:177], v[200:203], v[98:113]
	ds_read_b128 v[166:169], v209 offset:32768
	v_mfma_f32_32x32x16_bf16 v[82:97], v[180:183], v[192:195], v[82:97]
	ds_read_b128 v[170:173], v209 offset:36864
	v_mfma_f32_32x32x16_bf16 v[66:81], v[180:183], v[200:203], v[66:81]
	ds_read_b128 v[154:157], v205 offset:36864
	v_mfma_f32_32x32x16_bf16 v[50:65], v[184:187], v[192:195], v[50:65]
	ds_read_b128 v[158:161], v205 offset:40960
	v_mfma_f32_32x32x16_bf16 v[34:49], v[184:187], v[200:203], v[34:49]
	ds_read_b128 v[162:165], v205 offset:45056
	v_mfma_f32_32x32x16_bf16 v[18:33], v[188:191], v[192:195], v[18:33]
	v_mfma_f32_32x32x16_bf16 v[2:17], v[188:191], v[200:203], v[2:17]
	s_waitcnt lgkmcnt(4)
	v_mfma_f32_32x32x16_bf16 v[114:129], v[150:153], v[166:169], v[114:129]
	ds_read_b128 v[174:177], v206 offset:32768
	s_waitcnt lgkmcnt(4)
	v_mfma_f32_32x32x16_bf16 v[98:113], v[150:153], v[170:173], v[98:113]
	ds_read_b128 v[192:195], v210 offset:32768
	s_waitcnt lgkmcnt(4)
	v_mfma_f32_32x32x16_bf16 v[82:97], v[154:157], v[166:169], v[82:97]
	ds_read_b128 v[200:203], v210 offset:36864
	v_mfma_f32_32x32x16_bf16 v[66:81], v[154:157], v[170:173], v[66:81]
	ds_read_b128 v[180:183], v206 offset:36864
	s_waitcnt lgkmcnt(5)
	v_mfma_f32_32x32x16_bf16 v[50:65], v[158:161], v[166:169], v[50:65]
	ds_read_b128 v[184:187], v206 offset:40960
	v_mfma_f32_32x32x16_bf16 v[34:49], v[158:161], v[170:173], v[34:49]
	ds_read_b128 v[188:191], v206 offset:45056
	s_waitcnt lgkmcnt(6)
	v_mfma_f32_32x32x16_bf16 v[18:33], v[162:165], v[166:169], v[18:33]
	v_mfma_f32_32x32x16_bf16 v[2:17], v[162:165], v[170:173], v[2:17]
	s_waitcnt lgkmcnt(4)
	v_mfma_f32_32x32x16_bf16 v[114:129], v[174:177], v[192:195], v[114:129]
	ds_read_b128 v[150:153], v207 offset:32768
	s_waitcnt lgkmcnt(4)
	v_mfma_f32_32x32x16_bf16 v[98:113], v[174:177], v[200:203], v[98:113]
	ds_read_b128 v[166:169], v211 offset:32768
	s_waitcnt lgkmcnt(4)
	v_mfma_f32_32x32x16_bf16 v[82:97], v[180:183], v[192:195], v[82:97]
	ds_read_b128 v[170:173], v211 offset:36864
	v_mfma_f32_32x32x16_bf16 v[66:81], v[180:183], v[200:203], v[66:81]
	ds_read_b128 v[154:157], v207 offset:36864
	s_waitcnt lgkmcnt(5)
	v_mfma_f32_32x32x16_bf16 v[50:65], v[184:187], v[192:195], v[50:65]
	ds_read_b128 v[158:161], v207 offset:40960
	v_mfma_f32_32x32x16_bf16 v[34:49], v[184:187], v[200:203], v[34:49]
	ds_read_b128 v[162:165], v207 offset:45056
	s_waitcnt lgkmcnt(6)
	v_mfma_f32_32x32x16_bf16 v[18:33], v[188:191], v[192:195], v[18:33]
	v_mfma_f32_32x32x16_bf16 v[2:17], v[188:191], v[200:203], v[2:17]
	s_waitcnt lgkmcnt(4)
	v_mfma_f32_32x32x16_bf16 v[114:129], v[150:153], v[166:169], v[114:129]
	ds_read_b128 v[174:177], v208 offset:32768
	ds_read_b128 v[192:195], v212 offset:32768
	s_waitcnt lgkmcnt(5)
	v_mfma_f32_32x32x16_bf16 v[98:113], v[150:153], v[170:173], v[98:113]
	ds_read_b128 v[200:203], v212 offset:36864
	ds_read_b128 v[180:183], v208 offset:36864
	s_waitcnt lgkmcnt(6)
	v_mfma_f32_32x32x16_bf16 v[82:97], v[154:157], v[166:169], v[82:97]
	ds_read_b128 v[184:187], v208 offset:40960
	ds_read_b128 v[188:191], v208 offset:45056
	v_mfma_f32_32x32x16_bf16 v[66:81], v[154:157], v[170:173], v[66:81]
	s_waitcnt lgkmcnt(7)
	v_mfma_f32_32x32x16_bf16 v[50:65], v[158:161], v[166:169], v[50:65]
	v_mfma_f32_32x32x16_bf16 v[34:49], v[158:161], v[170:173], v[34:49]
	s_waitcnt lgkmcnt(6)
	v_mfma_f32_32x32x16_bf16 v[18:33], v[162:165], v[166:169], v[18:33]
	v_mfma_f32_32x32x16_bf16 v[2:17], v[162:165], v[170:173], v[2:17]
	s_waitcnt vmcnt(0) lgkmcnt(0)
	s_barrier
	v_mfma_f32_32x32x16_bf16 v[114:129], v[174:177], v[192:195], v[114:129]
	v_mfma_f32_32x32x16_bf16 v[98:113], v[174:177], v[200:203], v[98:113]
	v_mfma_f32_32x32x16_bf16 v[82:97], v[180:183], v[192:195], v[82:97]
	v_mfma_f32_32x32x16_bf16 v[66:81], v[180:183], v[200:203], v[66:81]
	v_mfma_f32_32x32x16_bf16 v[50:65], v[184:187], v[192:195], v[50:65]
	v_mfma_f32_32x32x16_bf16 v[34:49], v[184:187], v[200:203], v[34:49]
	v_mfma_f32_32x32x16_bf16 v[18:33], v[188:191], v[192:195], v[18:33]
	v_mfma_f32_32x32x16_bf16 v[2:17], v[188:191], v[200:203], v[2:17]
.Lg910_end:
	s_setprio 0
	v_add_u32_e32 v149, s0, v143
	v_or_b32_e32 v130, s2, v144
	s_mov_b32 s2, 0x7e07e07f
	v_mul_hi_i32 v0, v149, s2
	v_lshrrev_b32_e32 v131, 31, v0
	v_ashrrev_i32_e32 v0, 13, v0
	v_add_u32_e32 v0, v0, v131
	v_mul_i32_i24_e32 v131, 0x4100, v0
	v_sub_u32_e32 v131, v149, v131
	s_movk_i32 s3, 0xff
	v_mul_i32_i24_e32 v0, 0xc00, v0
	v_cmp_lt_i32_e32 vcc, s3, v131
	v_mov_b32_e32 v162, 0x1800
	v_mov_b32_e32 v152, v179
	s_waitcnt vmcnt(0)
	s_barrier
	v_cndmask_b32_e32 v150, v162, v0, vcc
	v_readlane_b32 s12, v251, 2
	v_and_b32_e32 v0, 31, v152
	v_bfe_u32 v131, v152, 5, 1
	v_mul_u32_u24_e32 v131, 0x240, v131
	v_lshlrev_b32_e32 v0, 2, v0
	v_add3_u32 v0, v145, v131, v0
	ds_write2_b32 v0, v114, v115 offset1:36
	ds_write2_b32 v0, v116, v117 offset0:72 offset1:108
	v_add_u32_e32 v114, 0x400, v0
	v_ashrrev_i32_e32 v151, 31, v150
	ds_write2_b32 v114, v118, v119 offset0:32 offset1:68
	ds_write2_b32 v114, v120, v121 offset0:104 offset1:140
	v_add_u32_e32 v114, 0x800, v0
	v_add_u32_e32 v0, 0xc00, v0
	v_readlane_b32 s26, v251, 16
	v_readlane_b32 s27, v251, 17
	ds_write2_b32 v114, v122, v123 offset0:64 offset1:100
	ds_write2_b32 v114, v124, v125 offset0:136 offset1:172
	ds_write2_b32 v0, v126, v127 offset0:96 offset1:132
	ds_write2_b32 v0, v128, v129 offset0:168 offset1:204
	v_lshl_add_u64 v[114:115], v[150:151], 2, s[26:27]
	s_mov_b64 s[4:5], 0x1b02000
	v_ashrrev_i32_e32 v131, 31, v130
	v_readlane_b32 s0, v251, 26
	v_lshlrev_b32_e32 v0, 3, v152
	v_lshl_add_u64 v[118:119], v[114:115], 0, s[4:5]
	v_lshlrev_b64 v[116:117], 2, v[130:131]
	v_readlane_b32 s1, v251, 27
	v_and_b32_e32 v122, 24, v0
	v_lshl_add_u64 v[120:121], v[118:119], 0, v[116:117]
	v_lshl_add_u64 v[114:115], v[130:131], 1, s[0:1]
	v_lshlrev_b32_e32 v0, 2, v122
	v_bfe_u32 v131, v152, 2, 4
	v_lshl_add_u64 v[158:159], v[120:121], 0, v[0:1]
	v_lshlrev_b32_e32 v120, 1, v122
	v_mul_u32_u24_e32 v122, 0x90, v131
	s_waitcnt lgkmcnt(0)
	v_add3_u32 v0, v145, v0, v122
	ds_read_b128 v[122:125], v0
	ds_read_b128 v[126:129], v0 offset:16
	global_load_dwordx4 v[150:153], v[158:159], off offset:16
	global_load_dwordx4 v[154:157], v[158:159], off
	v_or_b32_e32 v160, v131, v149
	v_mov_b32_e32 v121, v1
	v_ashrrev_i32_e32 v161, 31, v160
	v_lshl_add_u64 v[120:121], v[114:115], 0, v[120:121]
	v_readlane_b32 s13, v251, 3
	v_readlane_b32 s14, v251, 4
	v_readlane_b32 s15, v251, 5
	v_readlane_b32 s16, v251, 6
	v_readlane_b32 s17, v251, 7
	v_readlane_b32 s18, v251, 8
	v_readlane_b32 s19, v251, 9
	v_readlane_b32 s20, v251, 10
	v_readlane_b32 s21, v251, 11
	v_readlane_b32 s22, v251, 12
	v_readlane_b32 s23, v251, 13
	v_readlane_b32 s24, v251, 14
	v_readlane_b32 s25, v251, 15
	s_waitcnt vmcnt(1) lgkmcnt(0)
	v_pk_mul_f32 v[126:127], v[126:127], v[150:151]
	s_waitcnt vmcnt(0)
	v_pk_mul_f32 v[122:123], v[122:123], v[154:155]
	v_pk_mul_f32 v[124:125], v[124:125], v[156:157]
	v_pk_mul_f32 v[128:129], v[128:129], v[152:153]
	v_cvt_pk_bf16_f32 v122, v122, v123
	v_cvt_pk_bf16_f32 v123, v124, v125
	v_cvt_pk_bf16_f32 v124, v126, v127
	v_lshlrev_b64 v[126:127], 11, v[160:161]
	v_cvt_pk_bf16_f32 v125, v128, v129
	v_lshl_add_u64 v[126:127], v[120:121], 0, v[126:127]
	global_store_dwordx4 v[126:127], v[122:125], off
	ds_read_b128 v[122:125], v0 offset:2304
	ds_read_b128 v[126:129], v0 offset:2320
	global_load_dwordx4 v[150:153], v[158:159], off offset:16
	global_load_dwordx4 v[154:157], v[158:159], off
	s_waitcnt vmcnt(1) lgkmcnt(0)
	v_pk_mul_f32 v[126:127], v[126:127], v[150:151]
	s_waitcnt vmcnt(0)
	v_pk_mul_f32 v[122:123], v[122:123], v[154:155]
	v_pk_mul_f32 v[124:125], v[124:125], v[156:157]
	v_cvt_pk_bf16_f32 v122, v122, v123
	v_cvt_pk_bf16_f32 v123, v124, v125
	v_cvt_pk_bf16_f32 v124, v126, v127
	v_or_b32_e32 v126, 16, v160
	v_ashrrev_i32_e32 v127, 31, v126
	v_pk_mul_f32 v[128:129], v[128:129], v[152:153]
	v_lshlrev_b64 v[126:127], 11, v[126:127]
	v_cvt_pk_bf16_f32 v125, v128, v129
	v_lshl_add_u64 v[120:121], v[120:121], 0, v[126:127]
	global_store_dwordx4 v[120:121], v[122:125], off
	v_mov_b32_e32 v120, v179
	v_or_b32_e32 v126, 32, v130
	v_and_b32_e32 v0, 31, v120
	v_bfe_u32 v121, v120, 5, 1
	v_mul_u32_u24_e32 v121, 0x240, v121
	v_lshlrev_b32_e32 v0, 2, v0
	v_add3_u32 v0, v145, v121, v0
	ds_write2_b32 v0, v98, v99 offset1:36
	ds_write2_b32 v0, v100, v101 offset0:72 offset1:108
	v_add_u32_e32 v98, 0x400, v0
	ds_write2_b32 v98, v102, v103 offset0:32 offset1:68
	ds_write2_b32 v98, v104, v105 offset0:104 offset1:140
	v_add_u32_e32 v98, 0x800, v0
	v_add_u32_e32 v0, 0xc00, v0
	ds_write2_b32 v98, v106, v107 offset0:64 offset1:100
	ds_write2_b32 v98, v108, v109 offset0:136 offset1:172
	ds_write2_b32 v0, v110, v111 offset0:96 offset1:132
	ds_write2_b32 v0, v112, v113 offset0:168 offset1:204
	v_lshlrev_b32_e32 v0, 3, v120
	v_and_b32_e32 v102, 24, v0
	v_ashrrev_i32_e32 v127, 31, v126
	v_lshlrev_b32_e32 v0, 2, v102
	v_lshl_add_u64 v[98:99], v[118:119], 0, v[0:1]
	v_lshlrev_b64 v[100:101], 2, v[126:127]
	v_lshl_add_u64 v[112:113], v[98:99], 0, v[100:101]
	v_lshlrev_b32_e32 v98, 1, v102
	v_mov_b32_e32 v99, v1
	v_bfe_u32 v128, v120, 2, 4
	v_lshl_add_u64 v[102:103], s[0:1], 0, v[98:99]
	v_mul_u32_u24_e32 v98, 0x90, v128
	s_waitcnt lgkmcnt(0)
	v_add3_u32 v0, v145, v0, v98
	ds_read_b128 v[104:107], v0
	ds_read_b128 v[108:111], v0 offset:16
	global_load_dwordx4 v[118:121], v[112:113], off offset:16
	global_load_dwordx4 v[122:125], v[112:113], off
	v_or_b32_e32 v128, v128, v149
	v_ashrrev_i32_e32 v129, 31, v128
	s_waitcnt vmcnt(1) lgkmcnt(0)
	v_pk_mul_f32 v[108:109], v[108:109], v[118:119]
	s_waitcnt vmcnt(0)
	v_pk_mul_f32 v[98:99], v[104:105], v[122:123]
	v_pk_mul_f32 v[106:107], v[106:107], v[124:125]
	v_cvt_pk_bf16_f32 v104, v98, v99
	v_lshlrev_b64 v[98:99], 11, v[128:129]
	v_pk_mul_f32 v[110:111], v[110:111], v[120:121]
	v_cvt_pk_bf16_f32 v105, v106, v107
	v_cvt_pk_bf16_f32 v106, v108, v109
	v_lshl_add_u64 v[108:109], v[102:103], 0, v[98:99]
	v_lshlrev_b64 v[98:99], 1, v[126:127]
	v_cvt_pk_bf16_f32 v107, v110, v111
	v_lshl_add_u64 v[108:109], v[108:109], 0, v[98:99]
	global_store_dwordx4 v[108:109], v[104:107], off
	ds_read_b128 v[104:107], v0 offset:2304
	ds_read_b128 v[108:111], v0 offset:2320
	global_load_dwordx4 v[118:121], v[112:113], off offset:16
	global_load_dwordx4 v[122:125], v[112:113], off
	s_waitcnt vmcnt(1) lgkmcnt(0)
	v_pk_mul_f32 v[108:109], v[108:109], v[118:119]
	s_waitcnt vmcnt(0)
	v_pk_mul_f32 v[104:105], v[104:105], v[122:123]
	v_pk_mul_f32 v[106:107], v[106:107], v[124:125]
	v_cvt_pk_bf16_f32 v104, v104, v105
	v_cvt_pk_bf16_f32 v105, v106, v107
	v_cvt_pk_bf16_f32 v106, v108, v109
	v_or_b32_e32 v108, 16, v128
	v_ashrrev_i32_e32 v109, 31, v108
	v_lshlrev_b64 v[108:109], 11, v[108:109]
	v_pk_mul_f32 v[110:111], v[110:111], v[120:121]
	v_lshl_add_u64 v[102:103], v[102:103], 0, v[108:109]
	v_cvt_pk_bf16_f32 v107, v110, v111
	v_lshl_add_u64 v[102:103], v[102:103], 0, v[98:99]
	global_store_dwordx4 v[102:103], v[104:107], off
	v_or_b32_e32 v110, 32, v149
	v_mul_hi_i32 v0, v110, s2
	v_lshrrev_b32_e32 v102, 31, v0
	v_ashrrev_i32_e32 v0, 13, v0
	v_add_u32_e32 v0, v0, v102
	v_mul_i32_i24_e32 v102, 0x4100, v0
	v_sub_u32_e32 v102, v110, v102
	v_mul_i32_i24_e32 v0, 0xc00, v0
	v_cmp_lt_i32_e32 vcc, s3, v102
	v_mov_b32_e32 v104, v179
	s_nop 0
	v_cndmask_b32_e32 v102, v162, v0, vcc
	v_and_b32_e32 v0, 31, v104
	v_bfe_u32 v105, v104, 5, 1
	v_mul_u32_u24_e32 v105, 0x240, v105
	v_lshlrev_b32_e32 v0, 2, v0
	v_add3_u32 v0, v145, v105, v0
	ds_write2_b32 v0, v82, v83 offset1:36
	ds_write2_b32 v0, v84, v85 offset0:72 offset1:108
	v_add_u32_e32 v82, 0x400, v0
	v_ashrrev_i32_e32 v103, 31, v102
	ds_write2_b32 v82, v86, v87 offset0:32 offset1:68
	ds_write2_b32 v82, v88, v89 offset0:104 offset1:140
	v_add_u32_e32 v82, 0x800, v0
	v_add_u32_e32 v0, 0xc00, v0
	ds_write2_b32 v82, v90, v91 offset0:64 offset1:100
	ds_write2_b32 v82, v92, v93 offset0:136 offset1:172
	ds_write2_b32 v0, v94, v95 offset0:96 offset1:132
	ds_write2_b32 v0, v96, v97 offset0:168 offset1:204
	v_lshl_add_u64 v[82:83], v[102:103], 2, s[26:27]
	v_lshlrev_b32_e32 v0, 3, v104
	v_lshl_add_u64 v[82:83], v[82:83], 0, s[4:5]
	v_and_b32_e32 v86, 24, v0
	v_lshl_add_u64 v[84:85], v[82:83], 0, v[116:117]
	v_lshlrev_b32_e32 v0, 2, v86
	v_bfe_u32 v108, v104, 2, 4
	v_lshl_add_u64 v[106:107], v[84:85], 0, v[0:1]
	v_lshlrev_b32_e32 v84, 1, v86
	v_mul_u32_u24_e32 v86, 0x90, v108
	s_waitcnt lgkmcnt(0)
	v_add3_u32 v0, v145, v0, v86
	ds_read_b128 v[86:89], v0
	ds_read_b128 v[90:93], v0 offset:16
	global_load_dwordx4 v[94:97], v[106:107], off offset:16
	global_load_dwordx4 v[102:105], v[106:107], off
	v_or_b32_e32 v108, v108, v110
	v_mov_b32_e32 v85, v1
	v_ashrrev_i32_e32 v109, 31, v108
	v_lshl_add_u64 v[84:85], v[114:115], 0, v[84:85]
	s_waitcnt vmcnt(1) lgkmcnt(0)
	v_pk_mul_f32 v[90:91], v[90:91], v[94:95]
	s_waitcnt vmcnt(0)
	v_pk_mul_f32 v[86:87], v[86:87], v[102:103]
	v_pk_mul_f32 v[88:89], v[88:89], v[104:105]
	v_pk_mul_f32 v[92:93], v[92:93], v[96:97]
	v_cvt_pk_bf16_f32 v86, v86, v87
	v_cvt_pk_bf16_f32 v87, v88, v89
	v_cvt_pk_bf16_f32 v88, v90, v91
	v_lshlrev_b64 v[90:91], 11, v[108:109]
	v_cvt_pk_bf16_f32 v89, v92, v93
	v_lshl_add_u64 v[90:91], v[84:85], 0, v[90:91]
	global_store_dwordx4 v[90:91], v[86:89], off
	ds_read_b128 v[86:89], v0 offset:2304
	ds_read_b128 v[90:93], v0 offset:2320
	global_load_dwordx4 v[94:97], v[106:107], off offset:16
	global_load_dwordx4 v[102:105], v[106:107], off
	s_waitcnt vmcnt(1) lgkmcnt(0)
	v_pk_mul_f32 v[90:91], v[90:91], v[94:95]
	s_waitcnt vmcnt(0)
	v_pk_mul_f32 v[86:87], v[86:87], v[102:103]
	v_pk_mul_f32 v[88:89], v[88:89], v[104:105]
	v_cvt_pk_bf16_f32 v86, v86, v87
	v_cvt_pk_bf16_f32 v87, v88, v89
	v_cvt_pk_bf16_f32 v88, v90, v91
	v_or_b32_e32 v90, 16, v108
	v_ashrrev_i32_e32 v91, 31, v90
	v_pk_mul_f32 v[92:93], v[92:93], v[96:97]
	v_lshlrev_b64 v[90:91], 11, v[90:91]
	v_cvt_pk_bf16_f32 v89, v92, v93
	v_lshl_add_u64 v[84:85], v[84:85], 0, v[90:91]
	global_store_dwordx4 v[84:85], v[86:89], off
	s_nop 1
	v_mov_b32_e32 v86, v179
	s_nop 0
	v_and_b32_e32 v0, 31, v86
	v_bfe_u32 v84, v86, 5, 1
	v_mul_u32_u24_e32 v84, 0x240, v84
	v_lshlrev_b32_e32 v0, 2, v0
	v_add3_u32 v0, v145, v84, v0
	ds_write2_b32 v0, v66, v67 offset1:36
	ds_write2_b32 v0, v68, v69 offset0:72 offset1:108
	v_add_u32_e32 v66, 0x400, v0
	ds_write2_b32 v66, v70, v71 offset0:32 offset1:68
	ds_write2_b32 v66, v72, v73 offset0:104 offset1:140
	v_add_u32_e32 v66, 0x800, v0
	v_add_u32_e32 v0, 0xc00, v0
	ds_write2_b32 v66, v74, v75 offset0:64 offset1:100
	ds_write2_b32 v66, v76, v77 offset0:136 offset1:172
	ds_write2_b32 v0, v78, v79 offset0:96 offset1:132
	ds_write2_b32 v0, v80, v81 offset0:168 offset1:204
	v_lshlrev_b32_e32 v0, 3, v86
	v_and_b32_e32 v68, 24, v0
	v_lshlrev_b32_e32 v0, 2, v68
	v_lshl_add_u64 v[66:67], v[82:83], 0, v[0:1]
	v_bfe_u32 v86, v86, 2, 4
	v_lshl_add_u64 v[84:85], v[66:67], 0, v[100:101]
	v_lshlrev_b32_e32 v66, 1, v68
	v_mul_u32_u24_e32 v68, 0x90, v86
	s_waitcnt lgkmcnt(0)
	v_add3_u32 v0, v145, v0, v68
	ds_read_b128 v[68:71], v0
	ds_read_b128 v[72:75], v0 offset:16
	global_load_dwordx4 v[76:79], v[84:85], off offset:16
	global_load_dwordx4 v[80:83], v[84:85], off
	v_or_b32_e32 v86, v86, v110
	v_mov_b32_e32 v67, v1
	v_ashrrev_i32_e32 v87, 31, v86
	v_lshl_add_u64 v[66:67], s[0:1], 0, v[66:67]
	s_waitcnt vmcnt(1) lgkmcnt(0)
	v_pk_mul_f32 v[72:73], v[72:73], v[76:77]
	s_waitcnt vmcnt(0)
	v_pk_mul_f32 v[68:69], v[68:69], v[80:81]
	v_pk_mul_f32 v[70:71], v[70:71], v[82:83]
	v_cvt_pk_bf16_f32 v68, v68, v69
	v_cvt_pk_bf16_f32 v69, v70, v71
	v_cvt_pk_bf16_f32 v70, v72, v73
	v_lshlrev_b64 v[72:73], 11, v[86:87]
	v_pk_mul_f32 v[74:75], v[74:75], v[78:79]
	v_lshl_add_u64 v[72:73], v[66:67], 0, v[72:73]
	v_cvt_pk_bf16_f32 v71, v74, v75
	v_lshl_add_u64 v[72:73], v[72:73], 0, v[98:99]
	global_store_dwordx4 v[72:73], v[68:71], off
	ds_read_b128 v[68:71], v0 offset:2304
	ds_read_b128 v[72:75], v0 offset:2320
	global_load_dwordx4 v[76:79], v[84:85], off offset:16
	global_load_dwordx4 v[80:83], v[84:85], off
	s_waitcnt vmcnt(1) lgkmcnt(0)
	v_pk_mul_f32 v[72:73], v[72:73], v[76:77]
	s_waitcnt vmcnt(0)
	v_pk_mul_f32 v[68:69], v[68:69], v[80:81]
	v_pk_mul_f32 v[70:71], v[70:71], v[82:83]
	v_cvt_pk_bf16_f32 v68, v68, v69
	v_cvt_pk_bf16_f32 v69, v70, v71
	v_cvt_pk_bf16_f32 v70, v72, v73
	v_or_b32_e32 v72, 16, v86
	v_ashrrev_i32_e32 v73, 31, v72
	v_lshlrev_b64 v[72:73], 11, v[72:73]
	v_pk_mul_f32 v[74:75], v[74:75], v[78:79]
	v_lshl_add_u64 v[66:67], v[66:67], 0, v[72:73]
	v_cvt_pk_bf16_f32 v71, v74, v75
	v_lshl_add_u64 v[66:67], v[66:67], 0, v[98:99]
	global_store_dwordx4 v[66:67], v[68:71], off
	v_or_b32_e32 v74, 64, v149
	v_mul_hi_i32 v0, v74, s2
	v_lshrrev_b32_e32 v66, 31, v0
	v_ashrrev_i32_e32 v0, 13, v0
	v_add_u32_e32 v0, v0, v66
	v_mul_i32_i24_e32 v66, 0x4100, v0
	v_sub_u32_e32 v66, v74, v66
	v_mul_i32_i24_e32 v0, 0xc00, v0
	v_cmp_lt_i32_e32 vcc, s3, v66
	v_mov_b32_e32 v68, v179
	s_nop 0
	v_cndmask_b32_e32 v66, v162, v0, vcc
	v_and_b32_e32 v0, 31, v68
	v_bfe_u32 v69, v68, 5, 1
	v_mul_u32_u24_e32 v69, 0x240, v69
	v_lshlrev_b32_e32 v0, 2, v0
	v_add3_u32 v0, v145, v69, v0
	ds_write2_b32 v0, v50, v51 offset1:36
	ds_write2_b32 v0, v52, v53 offset0:72 offset1:108
	v_add_u32_e32 v50, 0x400, v0
	v_ashrrev_i32_e32 v67, 31, v66
	ds_write2_b32 v50, v54, v55 offset0:32 offset1:68
	ds_write2_b32 v50, v56, v57 offset0:104 offset1:140
	v_add_u32_e32 v50, 0x800, v0
	v_add_u32_e32 v0, 0xc00, v0
	ds_write2_b32 v50, v58, v59 offset0:64 offset1:100
	ds_write2_b32 v50, v60, v61 offset0:136 offset1:172
	ds_write2_b32 v0, v62, v63 offset0:96 offset1:132
	ds_write2_b32 v0, v64, v65 offset0:168 offset1:204
	v_lshl_add_u64 v[50:51], v[66:67], 2, s[26:27]
	v_lshlrev_b32_e32 v0, 3, v68
	v_lshl_add_u64 v[50:51], v[50:51], 0, s[4:5]
	v_and_b32_e32 v54, 24, v0
	v_lshl_add_u64 v[52:53], v[50:51], 0, v[116:117]
	v_lshlrev_b32_e32 v0, 2, v54
	v_bfe_u32 v72, v68, 2, 4
	v_lshl_add_u64 v[70:71], v[52:53], 0, v[0:1]
	v_lshlrev_b32_e32 v52, 1, v54
	v_mul_u32_u24_e32 v54, 0x90, v72
	s_waitcnt lgkmcnt(0)
	v_add3_u32 v0, v145, v0, v54
	ds_read_b128 v[54:57], v0
	ds_read_b128 v[58:61], v0 offset:16
	global_load_dwordx4 v[62:65], v[70:71], off offset:16
	global_load_dwordx4 v[66:69], v[70:71], off
	v_or_b32_e32 v72, v72, v74
	v_mov_b32_e32 v53, v1
	v_ashrrev_i32_e32 v73, 31, v72
	v_lshl_add_u64 v[52:53], v[114:115], 0, v[52:53]
	s_waitcnt vmcnt(1) lgkmcnt(0)
	v_pk_mul_f32 v[58:59], v[58:59], v[62:63]
	s_waitcnt vmcnt(0)
	v_pk_mul_f32 v[54:55], v[54:55], v[66:67]
	v_pk_mul_f32 v[56:57], v[56:57], v[68:69]
	v_pk_mul_f32 v[60:61], v[60:61], v[64:65]
	v_cvt_pk_bf16_f32 v54, v54, v55
	v_cvt_pk_bf16_f32 v55, v56, v57
	v_cvt_pk_bf16_f32 v56, v58, v59
	v_lshlrev_b64 v[58:59], 11, v[72:73]
	v_cvt_pk_bf16_f32 v57, v60, v61
	v_lshl_add_u64 v[58:59], v[52:53], 0, v[58:59]
	global_store_dwordx4 v[58:59], v[54:57], off
	ds_read_b128 v[54:57], v0 offset:2304
	ds_read_b128 v[58:61], v0 offset:2320
	global_load_dwordx4 v[62:65], v[70:71], off offset:16
	global_load_dwordx4 v[66:69], v[70:71], off
	s_waitcnt vmcnt(1) lgkmcnt(0)
	v_pk_mul_f32 v[58:59], v[58:59], v[62:63]
	s_waitcnt vmcnt(0)
	v_pk_mul_f32 v[54:55], v[54:55], v[66:67]
	v_pk_mul_f32 v[56:57], v[56:57], v[68:69]
	v_cvt_pk_bf16_f32 v54, v54, v55
	v_cvt_pk_bf16_f32 v55, v56, v57
	v_cvt_pk_bf16_f32 v56, v58, v59
	v_or_b32_e32 v58, 16, v72
	v_ashrrev_i32_e32 v59, 31, v58
	v_pk_mul_f32 v[60:61], v[60:61], v[64:65]
	v_lshlrev_b64 v[58:59], 11, v[58:59]
	v_cvt_pk_bf16_f32 v57, v60, v61
	v_lshl_add_u64 v[52:53], v[52:53], 0, v[58:59]
	global_store_dwordx4 v[52:53], v[54:57], off
	s_nop 1
	v_mov_b32_e32 v54, v179
	s_nop 0
	v_and_b32_e32 v0, 31, v54
	v_bfe_u32 v52, v54, 5, 1
	v_mul_u32_u24_e32 v52, 0x240, v52
	v_lshlrev_b32_e32 v0, 2, v0
	v_add3_u32 v0, v145, v52, v0
	ds_write2_b32 v0, v34, v35 offset1:36
	ds_write2_b32 v0, v36, v37 offset0:72 offset1:108
	v_add_u32_e32 v34, 0x400, v0
	ds_write2_b32 v34, v38, v39 offset0:32 offset1:68
	ds_write2_b32 v34, v40, v41 offset0:104 offset1:140
	v_add_u32_e32 v34, 0x800, v0
	v_add_u32_e32 v0, 0xc00, v0
	ds_write2_b32 v34, v42, v43 offset0:64 offset1:100
	ds_write2_b32 v34, v44, v45 offset0:136 offset1:172
	ds_write2_b32 v0, v46, v47 offset0:96 offset1:132
	ds_write2_b32 v0, v48, v49 offset0:168 offset1:204
	v_lshlrev_b32_e32 v0, 3, v54
	v_and_b32_e32 v36, 24, v0
	v_lshlrev_b32_e32 v0, 2, v36
	v_lshl_add_u64 v[34:35], v[50:51], 0, v[0:1]
	v_bfe_u32 v54, v54, 2, 4
	v_lshl_add_u64 v[52:53], v[34:35], 0, v[100:101]
	v_lshlrev_b32_e32 v34, 1, v36
	v_mul_u32_u24_e32 v36, 0x90, v54
	s_waitcnt lgkmcnt(0)
	v_add3_u32 v0, v145, v0, v36
	ds_read_b128 v[36:39], v0
	ds_read_b128 v[40:43], v0 offset:16
	global_load_dwordx4 v[44:47], v[52:53], off offset:16
	global_load_dwordx4 v[48:51], v[52:53], off
	v_or_b32_e32 v54, v54, v74
	v_mov_b32_e32 v35, v1
	v_ashrrev_i32_e32 v55, 31, v54
	v_lshl_add_u64 v[34:35], s[0:1], 0, v[34:35]
	s_waitcnt vmcnt(1) lgkmcnt(0)
	v_pk_mul_f32 v[40:41], v[40:41], v[44:45]
	s_waitcnt vmcnt(0)
	v_pk_mul_f32 v[36:37], v[36:37], v[48:49]
	v_pk_mul_f32 v[38:39], v[38:39], v[50:51]
	v_cvt_pk_bf16_f32 v36, v36, v37
	v_cvt_pk_bf16_f32 v37, v38, v39
	v_cvt_pk_bf16_f32 v38, v40, v41
	v_lshlrev_b64 v[40:41], 11, v[54:55]
	v_pk_mul_f32 v[42:43], v[42:43], v[46:47]
	v_lshl_add_u64 v[40:41], v[34:35], 0, v[40:41]
	v_cvt_pk_bf16_f32 v39, v42, v43
	v_lshl_add_u64 v[40:41], v[40:41], 0, v[98:99]
	global_store_dwordx4 v[40:41], v[36:39], off
	ds_read_b128 v[36:39], v0 offset:2304
	ds_read_b128 v[40:43], v0 offset:2320
	global_load_dwordx4 v[44:47], v[52:53], off offset:16
	global_load_dwordx4 v[48:51], v[52:53], off
	s_waitcnt vmcnt(1) lgkmcnt(0)
	v_pk_mul_f32 v[40:41], v[40:41], v[44:45]
	s_waitcnt vmcnt(0)
	v_pk_mul_f32 v[36:37], v[36:37], v[48:49]
	v_pk_mul_f32 v[38:39], v[38:39], v[50:51]
	v_cvt_pk_bf16_f32 v36, v36, v37
	v_cvt_pk_bf16_f32 v37, v38, v39
	v_cvt_pk_bf16_f32 v38, v40, v41
	v_or_b32_e32 v40, 16, v54
	v_ashrrev_i32_e32 v41, 31, v40
	v_lshlrev_b64 v[40:41], 11, v[40:41]
	v_pk_mul_f32 v[42:43], v[42:43], v[46:47]
	v_lshl_add_u64 v[34:35], v[34:35], 0, v[40:41]
	v_cvt_pk_bf16_f32 v39, v42, v43
	v_lshl_add_u64 v[34:35], v[34:35], 0, v[98:99]
	global_store_dwordx4 v[34:35], v[36:39], off
	v_or_b32_e32 v42, 0x60, v149
	v_mul_hi_i32 v0, v42, s2
	v_lshrrev_b32_e32 v34, 31, v0
	v_ashrrev_i32_e32 v0, 13, v0
	v_add_u32_e32 v0, v0, v34
	v_mul_i32_i24_e32 v34, 0x4100, v0
	v_sub_u32_e32 v34, v42, v34
	v_mul_i32_i24_e32 v0, 0xc00, v0
	v_cmp_lt_i32_e32 vcc, s3, v34
	v_mov_b32_e32 v36, v179
	s_nop 0
	v_cndmask_b32_e32 v34, v162, v0, vcc
	v_and_b32_e32 v0, 31, v36
	v_bfe_u32 v37, v36, 5, 1
	v_mul_u32_u24_e32 v37, 0x240, v37
	v_lshlrev_b32_e32 v0, 2, v0
	v_add3_u32 v0, v145, v37, v0
	ds_write2_b32 v0, v18, v19 offset1:36
	ds_write2_b32 v0, v20, v21 offset0:72 offset1:108
	v_add_u32_e32 v18, 0x400, v0
	v_ashrrev_i32_e32 v35, 31, v34
	ds_write2_b32 v18, v22, v23 offset0:32 offset1:68
	ds_write2_b32 v18, v24, v25 offset0:104 offset1:140
	v_add_u32_e32 v18, 0x800, v0
	v_add_u32_e32 v0, 0xc00, v0
	ds_write2_b32 v18, v26, v27 offset0:64 offset1:100
	ds_write2_b32 v18, v28, v29 offset0:136 offset1:172
	ds_write2_b32 v0, v30, v31 offset0:96 offset1:132
	ds_write2_b32 v0, v32, v33 offset0:168 offset1:204
	v_lshl_add_u64 v[18:19], v[34:35], 2, s[26:27]
	v_lshlrev_b32_e32 v0, 3, v36
	v_lshl_add_u64 v[18:19], v[18:19], 0, s[4:5]
	v_and_b32_e32 v22, 24, v0
	v_lshl_add_u64 v[20:21], v[18:19], 0, v[116:117]
	v_lshlrev_b32_e32 v0, 2, v22
	v_bfe_u32 v40, v36, 2, 4
	v_lshl_add_u64 v[38:39], v[20:21], 0, v[0:1]
	v_lshlrev_b32_e32 v20, 1, v22
	v_mul_u32_u24_e32 v22, 0x90, v40
	s_waitcnt lgkmcnt(0)
	v_add3_u32 v0, v145, v0, v22
	ds_read_b128 v[22:25], v0
	ds_read_b128 v[26:29], v0 offset:16
	global_load_dwordx4 v[30:33], v[38:39], off offset:16
	global_load_dwordx4 v[34:37], v[38:39], off
	v_or_b32_e32 v40, v40, v42
	v_mov_b32_e32 v21, v1
	v_ashrrev_i32_e32 v41, 31, v40
	v_lshl_add_u64 v[20:21], v[114:115], 0, v[20:21]
	s_waitcnt vmcnt(1) lgkmcnt(0)
	v_pk_mul_f32 v[26:27], v[26:27], v[30:31]
	s_waitcnt vmcnt(0)
	v_pk_mul_f32 v[22:23], v[22:23], v[34:35]
	v_pk_mul_f32 v[24:25], v[24:25], v[36:37]
	v_pk_mul_f32 v[28:29], v[28:29], v[32:33]
	v_cvt_pk_bf16_f32 v22, v22, v23
	v_cvt_pk_bf16_f32 v23, v24, v25
	v_cvt_pk_bf16_f32 v24, v26, v27
	v_lshlrev_b64 v[26:27], 11, v[40:41]
	v_cvt_pk_bf16_f32 v25, v28, v29
	v_lshl_add_u64 v[26:27], v[20:21], 0, v[26:27]
	global_store_dwordx4 v[26:27], v[22:25], off
	ds_read_b128 v[22:25], v0 offset:2304
	ds_read_b128 v[26:29], v0 offset:2320
	global_load_dwordx4 v[30:33], v[38:39], off offset:16
	global_load_dwordx4 v[34:37], v[38:39], off
	s_waitcnt vmcnt(1) lgkmcnt(0)
	v_pk_mul_f32 v[26:27], v[26:27], v[30:31]
	s_waitcnt vmcnt(0)
	v_pk_mul_f32 v[22:23], v[22:23], v[34:35]
	v_pk_mul_f32 v[24:25], v[24:25], v[36:37]
	v_cvt_pk_bf16_f32 v22, v22, v23
	v_cvt_pk_bf16_f32 v23, v24, v25
	v_cvt_pk_bf16_f32 v24, v26, v27
	v_or_b32_e32 v26, 16, v40
	v_ashrrev_i32_e32 v27, 31, v26
	v_pk_mul_f32 v[28:29], v[28:29], v[32:33]
	v_lshlrev_b64 v[26:27], 11, v[26:27]
	v_cvt_pk_bf16_f32 v25, v28, v29
	v_lshl_add_u64 v[20:21], v[20:21], 0, v[26:27]
	global_store_dwordx4 v[20:21], v[22:25], off
	s_nop 1
	v_mov_b32_e32 v22, v179
	s_nop 0
	v_and_b32_e32 v0, 31, v22
	v_bfe_u32 v20, v22, 5, 1
	v_mul_u32_u24_e32 v20, 0x240, v20
	v_lshlrev_b32_e32 v0, 2, v0
	v_add3_u32 v0, v145, v20, v0
	ds_write2_b32 v0, v2, v3 offset1:36
	ds_write2_b32 v0, v4, v5 offset0:72 offset1:108
	v_add_u32_e32 v2, 0x400, v0
	ds_write2_b32 v2, v6, v7 offset0:32 offset1:68
	ds_write2_b32 v2, v8, v9 offset0:104 offset1:140
	v_add_u32_e32 v2, 0x800, v0
	v_add_u32_e32 v0, 0xc00, v0
	ds_write2_b32 v2, v10, v11 offset0:64 offset1:100
	ds_write2_b32 v2, v12, v13 offset0:136 offset1:172
	ds_write2_b32 v0, v14, v15 offset0:96 offset1:132
	ds_write2_b32 v0, v16, v17 offset0:168 offset1:204
	v_lshlrev_b32_e32 v0, 3, v22
	v_and_b32_e32 v4, 24, v0
	v_lshlrev_b32_e32 v0, 2, v4
	v_lshl_add_u64 v[2:3], v[18:19], 0, v[0:1]
	v_bfe_u32 v22, v22, 2, 4
	v_lshl_add_u64 v[20:21], v[2:3], 0, v[100:101]
	v_lshlrev_b32_e32 v2, 1, v4
	v_mul_u32_u24_e32 v4, 0x90, v22
	s_waitcnt lgkmcnt(0)
	v_add3_u32 v0, v145, v0, v4
	ds_read_b128 v[4:7], v0
	ds_read_b128 v[8:11], v0 offset:16
	global_load_dwordx4 v[12:15], v[20:21], off offset:16
	global_load_dwordx4 v[16:19], v[20:21], off
	v_or_b32_e32 v22, v22, v42
	v_mov_b32_e32 v3, v1
	v_ashrrev_i32_e32 v23, 31, v22
	v_lshl_add_u64 v[2:3], s[0:1], 0, v[2:3]
	s_waitcnt vmcnt(1) lgkmcnt(0)
	v_pk_mul_f32 v[8:9], v[8:9], v[12:13]
	s_waitcnt vmcnt(0)
	v_pk_mul_f32 v[4:5], v[4:5], v[16:17]
	v_pk_mul_f32 v[6:7], v[6:7], v[18:19]
	v_cvt_pk_bf16_f32 v4, v4, v5
	v_cvt_pk_bf16_f32 v5, v6, v7
	v_cvt_pk_bf16_f32 v6, v8, v9
	v_lshlrev_b64 v[8:9], 11, v[22:23]
	v_pk_mul_f32 v[10:11], v[10:11], v[14:15]
	v_lshl_add_u64 v[8:9], v[2:3], 0, v[8:9]
	v_cvt_pk_bf16_f32 v7, v10, v11
	v_lshl_add_u64 v[8:9], v[8:9], 0, v[98:99]
	global_store_dwordx4 v[8:9], v[4:7], off
	ds_read_b128 v[4:7], v0 offset:2304
	ds_read_b128 v[8:11], v0 offset:2320
	global_load_dwordx4 v[12:15], v[20:21], off offset:16
	global_load_dwordx4 v[16:19], v[20:21], off
	s_waitcnt vmcnt(1) lgkmcnt(0)
	v_pk_mul_f32 v[8:9], v[8:9], v[12:13]
	s_waitcnt vmcnt(0)
	v_pk_mul_f32 v[4:5], v[4:5], v[16:17]
	v_pk_mul_f32 v[6:7], v[6:7], v[18:19]
	v_cvt_pk_bf16_f32 v4, v4, v5
	v_cvt_pk_bf16_f32 v5, v6, v7
	v_cvt_pk_bf16_f32 v6, v8, v9
	v_or_b32_e32 v8, 16, v22
	v_ashrrev_i32_e32 v9, 31, v8
	v_lshlrev_b64 v[8:9], 11, v[8:9]
	v_pk_mul_f32 v[10:11], v[10:11], v[14:15]
	v_lshl_add_u64 v[2:3], v[2:3], 0, v[8:9]
	v_cvt_pk_bf16_f32 v7, v10, v11
	v_lshl_add_u64 v[2:3], v[2:3], 0, v[98:99]
	global_store_dwordx4 v[2:3], v[4:7], off
	s_add_i32 s7, s7, s6
	s_cmpk_gt_i32 s7, 0x207
	s_cselect_b64 s[0:1], -1, 0
	s_branch .LBB0_907

.LBB0_1120:
	s_add_i32 s2, s13, s14
	s_cmpk_gt_i32 s2, 0x81f
	s_mov_b64 s[0:1], -1
	s_cbranch_scc1 .LBB0_1119
	s_ashr_i32 s0, s2, 31
	s_lshr_b32 s0, s0, 25
	s_add_i32 s0, s2, s0
	s_ashr_i32 s1, s0, 7
	s_lshl_b32 s1, s1, 3
	s_sub_i32 s3, 0x82, s1
	s_min_u32 s3, s3, 8
	v_cvt_f32_ubyte0_e32 v0, s3
	v_rcp_iflag_f32_e32 v0, v0
	s_sub_i32 s6, 0, s3
	s_and_b32 s0, s0, 0xffffff80
	s_sub_i32 s0, s2, s0
	v_mul_f32_e32 v0, 0x4f7ffffe, v0
	v_cvt_u32_f32_e32 v0, v0
	s_abs_i32 s4, s0
	s_ashr_i32 s2, s0, 31
	s_waitcnt vmcnt(63) expcnt(7) lgkmcnt(15)
	v_readfirstlane_b32 s7, v0
	s_mul_i32 s6, s6, s7
	s_mul_hi_u32 s6, s7, s6
	s_add_i32 s7, s7, s6
	s_mul_hi_u32 s6, s4, s7
	s_mul_i32 s7, s6, s3
	s_sub_i32 s4, s4, s7
	s_add_i32 s7, s6, 1
	s_sub_i32 s8, s4, s3
	s_cmp_ge_u32 s4, s3
	s_cselect_b32 s6, s7, s6
	s_cselect_b32 s4, s8, s4
	s_add_i32 s7, s6, 1
	s_cmp_ge_u32 s4, s3
	s_cselect_b32 s4, s7, s6
	s_xor_b32 s4, s4, s2
	s_sub_i32 s4, s4, s2
	s_mul_i32 s2, s4, s3
	s_sub_i32 s0, s0, s2
	s_add_i32 s0, s0, s1
	s_lshl_b32 s0, s0, 8
	s_lshl_b32 s6, s4, 8
	s_ashr_i32 s1, s0, 31
	s_ashr_i32 s7, s6, 31
	s_lshl_b64 s[2:3], s[0:1], 11
	s_lshl_b64 s[8:9], s[6:7], 11
	s_add_u32 s10, s64, s2
	v_mov_b32_e32 v0, v143
	s_addc_u32 s11, s65, s3
	s_barrier
	v_readlane_b32 s16, v251, 2
	v_lshl_add_u64 v[2:3], v[0:1], 1, s[10:11]
	v_add_u32_e32 v0, 32, v158
	v_readlane_b32 s30, v251, 16
	v_readfirstlane_b32 s1, v0
	s_mov_b32 m0, s1
	v_mov_b32_e32 v0, v159
	global_load_lds_dwordx4 v[2:3], off
	v_readlane_b32 s17, v251, 3
	v_lshl_add_u64 v[2:3], v[0:1], 1, s[10:11]
	v_add_u32_e32 v0, 32, v160
	v_readlane_b32 s31, v251, 17
	v_readfirstlane_b32 s1, v0
	s_mov_b32 m0, s1
	v_mov_b32_e32 v0, v161
	global_load_lds_dwordx4 v[2:3], off
	s_add_u32 s16, s30, s8
	v_lshl_add_u64 v[2:3], v[0:1], 1, s[10:11]
	v_add_u32_e32 v0, 32, v162
	s_addc_u32 s17, s31, s9
	v_readfirstlane_b32 s1, v0
	s_mov_b32 m0, s1
	v_mov_b32_e32 v0, v163
	global_load_lds_dwordx4 v[2:3], off
	v_readlane_b32 s7, v254, 3
	v_lshl_add_u64 v[2:3], v[0:1], 1, s[10:11]
	v_add_u32_e32 v0, 32, v164
	s_mov_b32 s5, 0
	v_readfirstlane_b32 s1, v0
	s_mov_b32 m0, s1
	v_mov_b32_e32 v0, v143
	global_load_lds_dwordx4 v[2:3], off
	v_readlane_b32 s18, v251, 4
	v_lshl_add_u64 v[2:3], v[0:1], 1, s[16:17]
	v_add_u32_e32 v0, s7, v158
	v_readlane_b32 s19, v251, 5
	v_readfirstlane_b32 s1, v0
	s_mov_b32 m0, s1
	v_mov_b32_e32 v0, v159
	global_load_lds_dwordx4 v[2:3], off
	v_readlane_b32 s20, v251, 6
	v_lshl_add_u64 v[2:3], v[0:1], 1, s[16:17]
	v_add_u32_e32 v0, s7, v160
	v_readlane_b32 s21, v251, 7
	v_readfirstlane_b32 s1, v0
	s_mov_b32 m0, s1
	v_mov_b32_e32 v0, v161
	global_load_lds_dwordx4 v[2:3], off
	v_readlane_b32 s22, v251, 8
	v_lshl_add_u64 v[2:3], v[0:1], 1, s[16:17]
	v_add_u32_e32 v0, s7, v162
	v_readlane_b32 s23, v251, 9
	v_readfirstlane_b32 s1, v0
	s_mov_b32 m0, s1
	v_mov_b32_e32 v0, v163
	global_load_lds_dwordx4 v[2:3], off
	v_readlane_b32 s24, v251, 10
	v_lshl_add_u64 v[2:3], v[0:1], 1, s[16:17]
	v_add_u32_e32 v0, s7, v164
	v_readlane_b32 s25, v251, 11
	v_readfirstlane_b32 s1, v0
	s_mov_b32 m0, s1
	v_readlane_b32 s1, v253, 25
	global_load_lds_dwordx4 v[2:3], off
	s_add_u32 s1, s1, s2
	v_readlane_b32 s2, v253, 26
	s_waitcnt vmcnt(0)
	s_addc_u32 s7, s2, s3
	v_readlane_b32 s2, v253, 45
	s_add_u32 s8, s2, s8
	v_readlane_b32 s2, v253, 46
	v_mov_b32_e32 v2, 0
	s_addc_u32 s9, s2, s9
	s_mov_b64 s[2:3], 0
	v_mov_b32_e32 v3, v2
	v_mov_b32_e32 v4, v2
	v_mov_b32_e32 v5, v2
	v_mov_b32_e32 v6, v2
	v_mov_b32_e32 v7, v2
	v_mov_b32_e32 v8, v2
	v_mov_b32_e32 v9, v2
	v_mov_b32_e32 v10, v2
	v_mov_b32_e32 v11, v2
	v_mov_b32_e32 v12, v2
	v_mov_b32_e32 v13, v2
	s_waitcnt vmcnt(0)
	v_mov_b32_e32 v14, v2
	v_mov_b32_e32 v15, v2
	v_mov_b32_e32 v16, v2
	v_mov_b32_e32 v17, v2
	v_mov_b32_e32 v18, v2
	v_mov_b32_e32 v19, v2
	v_mov_b32_e32 v20, v2
	v_mov_b32_e32 v21, v2
	v_mov_b32_e32 v22, v2
	v_mov_b32_e32 v23, v2
	v_mov_b32_e32 v24, v2
	v_mov_b32_e32 v25, v2
	v_mov_b32_e32 v26, v2
	v_mov_b32_e32 v27, v2
	v_mov_b32_e32 v28, v2
	v_mov_b32_e32 v29, v2
	v_mov_b32_e32 v30, v2
	v_mov_b32_e32 v31, v2
	v_mov_b32_e32 v32, v2
	v_mov_b32_e32 v33, v2
	v_mov_b32_e32 v34, v2
	v_mov_b32_e32 v35, v2
	v_mov_b32_e32 v36, v2
	v_mov_b32_e32 v37, v2
	v_mov_b32_e32 v38, v2
	v_mov_b32_e32 v39, v2
	v_mov_b32_e32 v40, v2
	v_mov_b32_e32 v41, v2
	v_mov_b32_e32 v42, v2
	v_mov_b32_e32 v43, v2
	v_mov_b32_e32 v44, v2
	v_mov_b32_e32 v45, v2
	v_mov_b32_e32 v46, v2
	v_mov_b32_e32 v47, v2
	v_mov_b32_e32 v48, v2
	v_mov_b32_e32 v49, v2
	v_mov_b32_e32 v50, v2
	v_mov_b32_e32 v51, v2
	v_mov_b32_e32 v52, v2
	v_mov_b32_e32 v53, v2
	v_mov_b32_e32 v54, v2
	v_mov_b32_e32 v55, v2
	v_mov_b32_e32 v56, v2
	v_mov_b32_e32 v57, v2
	v_mov_b32_e32 v58, v2
	v_mov_b32_e32 v59, v2
	v_mov_b32_e32 v60, v2
	v_mov_b32_e32 v61, v2
	v_mov_b32_e32 v62, v2
	v_mov_b32_e32 v63, v2
	v_mov_b32_e32 v64, v2
	v_mov_b32_e32 v65, v2
	v_mov_b32_e32 v66, v2
	v_mov_b32_e32 v67, v2
	v_mov_b32_e32 v68, v2
	v_mov_b32_e32 v69, v2
	v_mov_b32_e32 v70, v2
	v_mov_b32_e32 v71, v2
	v_mov_b32_e32 v72, v2
	v_mov_b32_e32 v73, v2
	v_mov_b32_e32 v74, v2
	v_mov_b32_e32 v75, v2
	v_mov_b32_e32 v76, v2
	v_mov_b32_e32 v77, v2
	v_mov_b32_e32 v78, v2
	v_mov_b32_e32 v79, v2
	v_mov_b32_e32 v80, v2
	v_mov_b32_e32 v81, v2
	v_mov_b32_e32 v82, v2
	v_mov_b32_e32 v83, v2
	v_mov_b32_e32 v84, v2
	v_mov_b32_e32 v85, v2
	v_mov_b32_e32 v86, v2
	v_mov_b32_e32 v87, v2
	v_mov_b32_e32 v88, v2
	v_mov_b32_e32 v89, v2
	v_mov_b32_e32 v90, v2
	v_mov_b32_e32 v91, v2
	v_mov_b32_e32 v92, v2
	v_mov_b32_e32 v93, v2
	v_mov_b32_e32 v94, v2
	v_mov_b32_e32 v95, v2
	v_mov_b32_e32 v96, v2
	v_mov_b32_e32 v97, v2
	v_mov_b32_e32 v98, v2
	v_mov_b32_e32 v99, v2
	v_mov_b32_e32 v100, v2
	v_mov_b32_e32 v101, v2
	v_mov_b32_e32 v102, v2
	v_mov_b32_e32 v103, v2
	v_mov_b32_e32 v104, v2
	v_mov_b32_e32 v105, v2
	v_mov_b32_e32 v106, v2
	v_mov_b32_e32 v107, v2
	v_mov_b32_e32 v108, v2
	v_mov_b32_e32 v109, v2
	v_mov_b32_e32 v110, v2
	v_mov_b32_e32 v111, v2
	v_mov_b32_e32 v112, v2
	v_mov_b32_e32 v113, v2
	v_mov_b32_e32 v114, v2
	v_mov_b32_e32 v115, v2
	v_mov_b32_e32 v116, v2
	v_mov_b32_e32 v117, v2
	v_mov_b32_e32 v118, v2
	v_mov_b32_e32 v119, v2
	v_mov_b32_e32 v120, v2
	v_mov_b32_e32 v121, v2
	v_mov_b32_e32 v122, v2
	v_mov_b32_e32 v123, v2
	v_mov_b32_e32 v124, v2
	v_mov_b32_e32 v125, v2
	v_mov_b32_e32 v126, v2
	v_mov_b32_e32 v127, v2
	v_mov_b32_e32 v128, v2
	v_mov_b32_e32 v129, v2
	v_readlane_b32 s26, v251, 12
	v_readlane_b32 s27, v251, 13
	v_readlane_b32 s28, v251, 14
	v_readlane_b32 s29, v251, 15
	s_waitcnt lgkmcnt(0)
	s_barrier
	v_readfirstlane_b32 s66, v179
	s_cmp_lt_u32 s66, 0x100
	s_cbranch_scc0 .Lgl1122_entry
	s_setprio 1
	v_lshlrev_b32_e32 v142, 1, v143
	v_readfirstlane_b32 s15, v158
	v_add_u32_e32 v156, v165, v167
	v_add_u32_e32 v195, v166, v167
	v_add_u32_e32 v157, v165, v172
	v_add_u32_e32 v200, v166, v172
	v_add_u32_e32 v193, v165, v173
	v_add_u32_e32 v201, v166, v173
	v_add_u32_e32 v194, v165, v174
	v_add_u32_e32 v202, v166, v174
	s_mov_b32 s5, 7
	s_add_u32 m0, s15, 0x8020
	s_add_u32 s10, s1, s2
	s_addc_u32 s11, s7, s3
	global_load_lds_dwordx4 v142, s[10:11]
	s_add_u32 m0, s15, 0x9020
	s_add_u32 s68, s10, 0x10000
	s_addc_u32 s69, s11, 0
	global_load_lds_dwordx4 v142, s[68:69]
	s_add_u32 m0, s15, 0xa020
	s_add_u32 s10, s10, 0x20000
	s_addc_u32 s11, s11, 0
	global_load_lds_dwordx4 v142, s[10:11]
	s_add_u32 m0, s15, 0xb020
	s_add_u32 s68, s10, 0x10000
	s_addc_u32 s69, s11, 0
	global_load_lds_dwordx4 v142, s[68:69]
	s_add_u32 m0, s15, 0xc020
	s_add_u32 s10, s10, 0x20000
	s_addc_u32 s11, s11, 0
	global_load_lds_dwordx4 v142, s[10:11]
	s_add_u32 m0, s15, 0xd020
	s_add_u32 s68, s10, 0x10000
	s_addc_u32 s69, s11, 0
	global_load_lds_dwordx4 v142, s[68:69]
	s_add_u32 m0, s15, 0xe020
	s_add_u32 s10, s10, 0x20000
	s_addc_u32 s11, s11, 0
	global_load_lds_dwordx4 v142, s[10:11]
	s_add_u32 m0, s15, 0xf020
	s_add_u32 s68, s10, 0x10000
	s_addc_u32 s69, s11, 0
	global_load_lds_dwordx4 v142, s[68:69]
	s_add_u32 m0, s15, 0x18020
	s_add_u32 s10, s8, s2
	s_addc_u32 s11, s9, s3
	global_load_lds_dwordx4 v142, s[10:11]
	s_add_u32 m0, s15, 0x19020
	s_add_u32 s68, s10, 0x10000
	s_addc_u32 s69, s11, 0
	global_load_lds_dwordx4 v142, s[68:69]
	ds_read_b128 v[130:133], v156 offset:0
	ds_read_b128 v[148:151], v195 offset:0
	ds_read_b128 v[152:155], v195 offset:4096
	ds_read_b128 v[134:137], v156 offset:4096
	ds_read_b128 v[138:141], v156 offset:8192
	ds_read_b128 v[144:147], v156 offset:12288
.Lg1122_loop:
	s_waitcnt lgkmcnt(4)
	v_mfma_f32_32x32x16_bf16 v[114:129], v[130:133], v[148:151], v[114:129]
	ds_read_b128 v[180:183], v157 offset:0
	s_waitcnt lgkmcnt(4)
	v_mfma_f32_32x32x16_bf16 v[98:113], v[130:133], v[152:155], v[98:113]
	ds_read_b128 v[226:229], v200 offset:0
	s_add_u32 m0, s15, 0x1a020
	s_add_u32 s10, s10, 0x20000
	s_addc_u32 s11, s11, 0
	global_load_lds_dwordx4 v142, s[10:11]
	s_add_u32 m0, s15, 0x1b020
	s_add_u32 s68, s10, 0x10000
	s_addc_u32 s69, s11, 0
	global_load_lds_dwordx4 v142, s[68:69]
	s_waitcnt lgkmcnt(4)
	v_mfma_f32_32x32x16_bf16 v[82:97], v[134:137], v[148:151], v[82:97]
	ds_read_b128 v[230:233], v200 offset:4096
	v_mfma_f32_32x32x16_bf16 v[66:81], v[134:137], v[152:155], v[66:81]
	ds_read_b128 v[184:187], v157 offset:4096
	s_add_u32 m0, s15, 0x1c020
	s_add_u32 s10, s10, 0x20000
	s_addc_u32 s11, s11, 0
	global_load_lds_dwordx4 v142, s[10:11]
	s_add_u32 m0, s15, 0x1d020
	s_add_u32 s68, s10, 0x10000
	s_addc_u32 s69, s11, 0
	global_load_lds_dwordx4 v142, s[68:69]
	s_waitcnt lgkmcnt(5)
	v_mfma_f32_32x32x16_bf16 v[50:65], v[138:141], v[148:151], v[50:65]
	ds_read_b128 v[188:191], v157 offset:8192
	v_mfma_f32_32x32x16_bf16 v[34:49], v[138:141], v[152:155], v[34:49]
	ds_read_b128 v[222:225], v157 offset:12288
	s_add_u32 m0, s15, 0x1e020
	s_add_u32 s10, s10, 0x20000
	s_addc_u32 s11, s11, 0
	global_load_lds_dwordx4 v142, s[10:11]
	s_add_u32 m0, s15, 0x1f020
	s_add_u32 s68, s10, 0x10000
	s_addc_u32 s69, s11, 0
	global_load_lds_dwordx4 v142, s[68:69]
	s_add_u32 s2, s2, 0x80
	s_addc_u32 s3, s3, 0
	s_waitcnt lgkmcnt(6)
	v_mfma_f32_32x32x16_bf16 v[18:33], v[144:147], v[148:151], v[18:33]
	v_mfma_f32_32x32x16_bf16 v[2:17], v[144:147], v[152:155], v[2:17]
	s_waitcnt lgkmcnt(4)
	v_mfma_f32_32x32x16_bf16 v[114:129], v[180:183], v[226:229], v[114:129]
	ds_read_b128 v[130:133], v193 offset:0
	s_waitcnt lgkmcnt(4)
	v_mfma_f32_32x32x16_bf16 v[98:113], v[180:183], v[230:233], v[98:113]
	ds_read_b128 v[148:151], v201 offset:0
	s_waitcnt lgkmcnt(4)
	v_mfma_f32_32x32x16_bf16 v[82:97], v[184:187], v[226:229], v[82:97]
	ds_read_b128 v[152:155], v201 offset:4096
	v_mfma_f32_32x32x16_bf16 v[66:81], v[184:187], v[230:233], v[66:81]
	ds_read_b128 v[134:137], v193 offset:4096
	s_waitcnt lgkmcnt(5)
	v_mfma_f32_32x32x16_bf16 v[50:65], v[188:191], v[226:229], v[50:65]
	ds_read_b128 v[138:141], v193 offset:8192
	v_mfma_f32_32x32x16_bf16 v[34:49], v[188:191], v[230:233], v[34:49]
	ds_read_b128 v[144:147], v193 offset:12288
	s_waitcnt lgkmcnt(6)
	v_mfma_f32_32x32x16_bf16 v[18:33], v[222:225], v[226:229], v[18:33]
	v_mfma_f32_32x32x16_bf16 v[2:17], v[222:225], v[230:233], v[2:17]
	s_waitcnt lgkmcnt(4)
	v_mfma_f32_32x32x16_bf16 v[114:129], v[130:133], v[148:151], v[114:129]
	ds_read_b128 v[180:183], v194 offset:0
	ds_read_b128 v[226:229], v202 offset:0
	s_waitcnt lgkmcnt(5)
	v_mfma_f32_32x32x16_bf16 v[98:113], v[130:133], v[152:155], v[98:113]
	ds_read_b128 v[230:233], v202 offset:4096
	ds_read_b128 v[184:187], v194 offset:4096
	s_waitcnt lgkmcnt(6)
	v_mfma_f32_32x32x16_bf16 v[82:97], v[134:137], v[148:151], v[82:97]
	ds_read_b128 v[188:191], v194 offset:8192
	ds_read_b128 v[222:225], v194 offset:12288
	v_mfma_f32_32x32x16_bf16 v[66:81], v[134:137], v[152:155], v[66:81]
	s_waitcnt lgkmcnt(7)
	v_mfma_f32_32x32x16_bf16 v[50:65], v[138:141], v[148:151], v[50:65]
	v_mfma_f32_32x32x16_bf16 v[34:49], v[138:141], v[152:155], v[34:49]
	s_waitcnt lgkmcnt(6)
	v_mfma_f32_32x32x16_bf16 v[18:33], v[144:147], v[148:151], v[18:33]
	v_mfma_f32_32x32x16_bf16 v[2:17], v[144:147], v[152:155], v[2:17]
	s_waitcnt vmcnt(0) lgkmcnt(0)
	s_barrier
	v_mfma_f32_32x32x16_bf16 v[114:129], v[180:183], v[226:229], v[114:129]
	ds_read_b128 v[130:133], v156 offset:32768
	s_add_u32 m0, s15, 0x20
	s_add_u32 s10, s1, s2
	s_addc_u32 s11, s7, s3
	global_load_lds_dwordx4 v142, s[10:11]
	s_add_u32 m0, s15, 0x1020
	s_add_u32 s68, s10, 0x10000
	s_addc_u32 s69, s11, 0
	global_load_lds_dwordx4 v142, s[68:69]
	v_mfma_f32_32x32x16_bf16 v[98:113], v[180:183], v[230:233], v[98:113]
	ds_read_b128 v[148:151], v195 offset:32768
	s_add_u32 m0, s15, 0x2020
	s_add_u32 s10, s10, 0x20000
	s_addc_u32 s11, s11, 0
	global_load_lds_dwordx4 v142, s[10:11]
	s_add_u32 m0, s15, 0x3020
	s_add_u32 s68, s10, 0x10000
	s_addc_u32 s69, s11, 0
	global_load_lds_dwordx4 v142, s[68:69]
	v_mfma_f32_32x32x16_bf16 v[82:97], v[184:187], v[226:229], v[82:97]
	ds_read_b128 v[152:155], v195 offset:36864
	s_add_u32 m0, s15, 0x4020
	s_add_u32 s10, s10, 0x20000
	s_addc_u32 s11, s11, 0
	global_load_lds_dwordx4 v142, s[10:11]
	s_add_u32 m0, s15, 0x5020
	s_add_u32 s68, s10, 0x10000
	s_addc_u32 s69, s11, 0
	global_load_lds_dwordx4 v142, s[68:69]
	v_mfma_f32_32x32x16_bf16 v[66:81], v[184:187], v[230:233], v[66:81]
	ds_read_b128 v[134:137], v156 offset:36864
	s_add_u32 m0, s15, 0x6020
	s_add_u32 s10, s10, 0x20000
	s_addc_u32 s11, s11, 0
	global_load_lds_dwordx4 v142, s[10:11]
	s_add_u32 m0, s15, 0x7020
	s_add_u32 s68, s10, 0x10000
	s_addc_u32 s69, s11, 0
	global_load_lds_dwordx4 v142, s[68:69]
	v_mfma_f32_32x32x16_bf16 v[50:65], v[188:191], v[226:229], v[50:65]
	ds_read_b128 v[138:141], v156 offset:40960
	s_add_u32 m0, s15, 0x10020
	s_add_u32 s10, s8, s2
	s_addc_u32 s11, s9, s3
	global_load_lds_dwordx4 v142, s[10:11]
	s_add_u32 m0, s15, 0x11020
	s_add_u32 s68, s10, 0x10000
	s_addc_u32 s69, s11, 0
	global_load_lds_dwordx4 v142, s[68:69]
	v_mfma_f32_32x32x16_bf16 v[34:49], v[188:191], v[230:233], v[34:49]
	ds_read_b128 v[144:147], v156 offset:45056
	v_mfma_f32_32x32x16_bf16 v[18:33], v[222:225], v[226:229], v[18:33]
	v_mfma_f32_32x32x16_bf16 v[2:17], v[222:225], v[230:233], v[2:17]
	s_waitcnt lgkmcnt(4)
	v_mfma_f32_32x32x16_bf16 v[114:129], v[130:133], v[148:151], v[114:129]
	ds_read_b128 v[180:183], v157 offset:32768
	s_waitcnt lgkmcnt(4)
	v_mfma_f32_32x32x16_bf16 v[98:113], v[130:133], v[152:155], v[98:113]
	ds_read_b128 v[226:229], v200 offset:32768
	s_add_u32 m0, s15, 0x12020
	s_add_u32 s10, s10, 0x20000
	s_addc_u32 s11, s11, 0
	global_load_lds_dwordx4 v142, s[10:11]
	s_add_u32 m0, s15, 0x13020
	s_add_u32 s68, s10, 0x10000
	s_addc_u32 s69, s11, 0
	global_load_lds_dwordx4 v142, s[68:69]
	s_waitcnt lgkmcnt(4)
	v_mfma_f32_32x32x16_bf16 v[82:97], v[134:137], v[148:151], v[82:97]
	ds_read_b128 v[230:233], v200 offset:36864
	v_mfma_f32_32x32x16_bf16 v[66:81], v[134:137], v[152:155], v[66:81]
	ds_read_b128 v[184:187], v157 offset:36864
	s_add_u32 m0, s15, 0x14020
	s_add_u32 s10, s10, 0x20000
	s_addc_u32 s11, s11, 0
	global_load_lds_dwordx4 v142, s[10:11]
	s_add_u32 m0, s15, 0x15020
	s_add_u32 s68, s10, 0x10000
	s_addc_u32 s69, s11, 0
	global_load_lds_dwordx4 v142, s[68:69]
	s_waitcnt lgkmcnt(5)
	v_mfma_f32_32x32x16_bf16 v[50:65], v[138:141], v[148:151], v[50:65]
	ds_read_b128 v[188:191], v157 offset:40960
	v_mfma_f32_32x32x16_bf16 v[34:49], v[138:141], v[152:155], v[34:49]
	ds_read_b128 v[222:225], v157 offset:45056
	s_add_u32 m0, s15, 0x16020
	s_add_u32 s10, s10, 0x20000
	s_addc_u32 s11, s11, 0
	global_load_lds_dwordx4 v142, s[10:11]
	s_add_u32 m0, s15, 0x17020
	s_add_u32 s68, s10, 0x10000
	s_addc_u32 s69, s11, 0
	global_load_lds_dwordx4 v142, s[68:69]
	s_add_u32 s2, s2, 0x80
	s_addc_u32 s3, s3, 0
	s_waitcnt lgkmcnt(6)
	v_mfma_f32_32x32x16_bf16 v[18:33], v[144:147], v[148:151], v[18:33]
	v_mfma_f32_32x32x16_bf16 v[2:17], v[144:147], v[152:155], v[2:17]
	s_waitcnt lgkmcnt(4)
	v_mfma_f32_32x32x16_bf16 v[114:129], v[180:183], v[226:229], v[114:129]
	ds_read_b128 v[130:133], v193 offset:32768
	s_waitcnt lgkmcnt(4)
	v_mfma_f32_32x32x16_bf16 v[98:113], v[180:183], v[230:233], v[98:113]
	ds_read_b128 v[148:151], v201 offset:32768
	s_waitcnt lgkmcnt(4)
	v_mfma_f32_32x32x16_bf16 v[82:97], v[184:187], v[226:229], v[82:97]
	ds_read_b128 v[152:155], v201 offset:36864
	v_mfma_f32_32x32x16_bf16 v[66:81], v[184:187], v[230:233], v[66:81]
	ds_read_b128 v[134:137], v193 offset:36864
	s_waitcnt lgkmcnt(5)
	v_mfma_f32_32x32x16_bf16 v[50:65], v[188:191], v[226:229], v[50:65]
	ds_read_b128 v[138:141], v193 offset:40960
	v_mfma_f32_32x32x16_bf16 v[34:49], v[188:191], v[230:233], v[34:49]
	ds_read_b128 v[144:147], v193 offset:45056
	s_waitcnt lgkmcnt(6)
	v_mfma_f32_32x32x16_bf16 v[18:33], v[222:225], v[226:229], v[18:33]
	v_mfma_f32_32x32x16_bf16 v[2:17], v[222:225], v[230:233], v[2:17]
	s_waitcnt lgkmcnt(4)
	v_mfma_f32_32x32x16_bf16 v[114:129], v[130:133], v[148:151], v[114:129]
	ds_read_b128 v[180:183], v194 offset:32768
	ds_read_b128 v[226:229], v202 offset:32768
	s_waitcnt lgkmcnt(5)
	v_mfma_f32_32x32x16_bf16 v[98:113], v[130:133], v[152:155], v[98:113]
	ds_read_b128 v[230:233], v202 offset:36864
	ds_read_b128 v[184:187], v194 offset:36864
	s_waitcnt lgkmcnt(6)
	v_mfma_f32_32x32x16_bf16 v[82:97], v[134:137], v[148:151], v[82:97]
	ds_read_b128 v[188:191], v194 offset:40960
	ds_read_b128 v[222:225], v194 offset:45056
	v_mfma_f32_32x32x16_bf16 v[66:81], v[134:137], v[152:155], v[66:81]
	s_waitcnt lgkmcnt(7)
	v_mfma_f32_32x32x16_bf16 v[50:65], v[138:141], v[148:151], v[50:65]
	v_mfma_f32_32x32x16_bf16 v[34:49], v[138:141], v[152:155], v[34:49]
	s_waitcnt lgkmcnt(6)
	v_mfma_f32_32x32x16_bf16 v[18:33], v[144:147], v[148:151], v[18:33]
	v_mfma_f32_32x32x16_bf16 v[2:17], v[144:147], v[152:155], v[2:17]
	s_waitcnt vmcnt(0) lgkmcnt(0)
	s_barrier
	v_mfma_f32_32x32x16_bf16 v[114:129], v[180:183], v[226:229], v[114:129]
	ds_read_b128 v[130:133], v156 offset:0
	s_add_u32 m0, s15, 0x8020
	s_add_u32 s10, s1, s2
	s_addc_u32 s11, s7, s3
	global_load_lds_dwordx4 v142, s[10:11]
	s_add_u32 m0, s15, 0x9020
	s_add_u32 s68, s10, 0x10000
	s_addc_u32 s69, s11, 0
	global_load_lds_dwordx4 v142, s[68:69]
	v_mfma_f32_32x32x16_bf16 v[98:113], v[180:183], v[230:233], v[98:113]
	ds_read_b128 v[148:151], v195 offset:0
	s_add_u32 m0, s15, 0xa020
	s_add_u32 s10, s10, 0x20000
	s_addc_u32 s11, s11, 0
	global_load_lds_dwordx4 v142, s[10:11]
	s_add_u32 m0, s15, 0xb020
	s_add_u32 s68, s10, 0x10000
	s_addc_u32 s69, s11, 0
	global_load_lds_dwordx4 v142, s[68:69]
	v_mfma_f32_32x32x16_bf16 v[82:97], v[184:187], v[226:229], v[82:97]
	ds_read_b128 v[152:155], v195 offset:4096
	s_add_u32 m0, s15, 0xc020
	s_add_u32 s10, s10, 0x20000
	s_addc_u32 s11, s11, 0
	global_load_lds_dwordx4 v142, s[10:11]
	s_add_u32 m0, s15, 0xd020
	s_add_u32 s68, s10, 0x10000
	s_addc_u32 s69, s11, 0
	global_load_lds_dwordx4 v142, s[68:69]
	v_mfma_f32_32x32x16_bf16 v[66:81], v[184:187], v[230:233], v[66:81]
	ds_read_b128 v[134:137], v156 offset:4096
	s_add_u32 m0, s15, 0xe020
	s_add_u32 s10, s10, 0x20000
	s_addc_u32 s11, s11, 0
	global_load_lds_dwordx4 v142, s[10:11]
	s_add_u32 m0, s15, 0xf020
	s_add_u32 s68, s10, 0x10000
	s_addc_u32 s69, s11, 0
	global_load_lds_dwordx4 v142, s[68:69]
	v_mfma_f32_32x32x16_bf16 v[50:65], v[188:191], v[226:229], v[50:65]
	ds_read_b128 v[138:141], v156 offset:8192
	s_add_u32 m0, s15, 0x18020
	s_add_u32 s10, s8, s2
	s_addc_u32 s11, s9, s3
	global_load_lds_dwordx4 v142, s[10:11]
	s_add_u32 m0, s15, 0x19020
	s_add_u32 s68, s10, 0x10000
	s_addc_u32 s69, s11, 0
	global_load_lds_dwordx4 v142, s[68:69]
	v_mfma_f32_32x32x16_bf16 v[34:49], v[188:191], v[230:233], v[34:49]
	ds_read_b128 v[144:147], v156 offset:12288
	v_mfma_f32_32x32x16_bf16 v[18:33], v[222:225], v[226:229], v[18:33]
	v_mfma_f32_32x32x16_bf16 v[2:17], v[222:225], v[230:233], v[2:17]
	s_sub_u32 s5, s5, 1
	s_cmp_lg_u32 s5, 0
	s_cbranch_scc1 .Lg1122_loop
	s_waitcnt lgkmcnt(4)
	v_mfma_f32_32x32x16_bf16 v[114:129], v[130:133], v[148:151], v[114:129]
	ds_read_b128 v[180:183], v157 offset:0
	s_waitcnt lgkmcnt(4)
	v_mfma_f32_32x32x16_bf16 v[98:113], v[130:133], v[152:155], v[98:113]
	ds_read_b128 v[226:229], v200 offset:0
	s_add_u32 m0, s15, 0x1a020
	s_add_u32 s10, s10, 0x20000
	s_addc_u32 s11, s11, 0
	global_load_lds_dwordx4 v142, s[10:11]
	s_add_u32 m0, s15, 0x1b020
	s_add_u32 s68, s10, 0x10000
	s_addc_u32 s69, s11, 0
	global_load_lds_dwordx4 v142, s[68:69]
	s_waitcnt lgkmcnt(4)
	v_mfma_f32_32x32x16_bf16 v[82:97], v[134:137], v[148:151], v[82:97]
	ds_read_b128 v[230:233], v200 offset:4096
	v_mfma_f32_32x32x16_bf16 v[66:81], v[134:137], v[152:155], v[66:81]
	ds_read_b128 v[184:187], v157 offset:4096
	s_add_u32 m0, s15, 0x1c020
	s_add_u32 s10, s10, 0x20000
	s_addc_u32 s11, s11, 0
	global_load_lds_dwordx4 v142, s[10:11]
	s_add_u32 m0, s15, 0x1d020
	s_add_u32 s68, s10, 0x10000
	s_addc_u32 s69, s11, 0
	global_load_lds_dwordx4 v142, s[68:69]
	s_waitcnt lgkmcnt(5)
	v_mfma_f32_32x32x16_bf16 v[50:65], v[138:141], v[148:151], v[50:65]
	ds_read_b128 v[188:191], v157 offset:8192
	v_mfma_f32_32x32x16_bf16 v[34:49], v[138:141], v[152:155], v[34:49]
	ds_read_b128 v[222:225], v157 offset:12288
	s_add_u32 m0, s15, 0x1e020
	s_add_u32 s10, s10, 0x20000
	s_addc_u32 s11, s11, 0
	global_load_lds_dwordx4 v142, s[10:11]
	s_add_u32 m0, s15, 0x1f020
	s_add_u32 s68, s10, 0x10000
	s_addc_u32 s69, s11, 0
	global_load_lds_dwordx4 v142, s[68:69]
	s_add_u32 s2, s2, 0x80
	s_addc_u32 s3, s3, 0
	s_waitcnt lgkmcnt(6)
	v_mfma_f32_32x32x16_bf16 v[18:33], v[144:147], v[148:151], v[18:33]
	v_mfma_f32_32x32x16_bf16 v[2:17], v[144:147], v[152:155], v[2:17]
	s_waitcnt lgkmcnt(4)
	v_mfma_f32_32x32x16_bf16 v[114:129], v[180:183], v[226:229], v[114:129]
	ds_read_b128 v[130:133], v193 offset:0
	s_waitcnt lgkmcnt(4)
	v_mfma_f32_32x32x16_bf16 v[98:113], v[180:183], v[230:233], v[98:113]
	ds_read_b128 v[148:151], v201 offset:0
	s_waitcnt lgkmcnt(4)
	v_mfma_f32_32x32x16_bf16 v[82:97], v[184:187], v[226:229], v[82:97]
	ds_read_b128 v[152:155], v201 offset:4096
	v_mfma_f32_32x32x16_bf16 v[66:81], v[184:187], v[230:233], v[66:81]
	ds_read_b128 v[134:137], v193 offset:4096
	s_waitcnt lgkmcnt(5)
	v_mfma_f32_32x32x16_bf16 v[50:65], v[188:191], v[226:229], v[50:65]
	ds_read_b128 v[138:141], v193 offset:8192
	v_mfma_f32_32x32x16_bf16 v[34:49], v[188:191], v[230:233], v[34:49]
	ds_read_b128 v[144:147], v193 offset:12288
	s_waitcnt lgkmcnt(6)
	v_mfma_f32_32x32x16_bf16 v[18:33], v[222:225], v[226:229], v[18:33]
	v_mfma_f32_32x32x16_bf16 v[2:17], v[222:225], v[230:233], v[2:17]
	s_waitcnt lgkmcnt(4)
	v_mfma_f32_32x32x16_bf16 v[114:129], v[130:133], v[148:151], v[114:129]
	ds_read_b128 v[180:183], v194 offset:0
	ds_read_b128 v[226:229], v202 offset:0
	s_waitcnt lgkmcnt(5)
	v_mfma_f32_32x32x16_bf16 v[98:113], v[130:133], v[152:155], v[98:113]
	ds_read_b128 v[230:233], v202 offset:4096
	ds_read_b128 v[184:187], v194 offset:4096
	s_waitcnt lgkmcnt(6)
	v_mfma_f32_32x32x16_bf16 v[82:97], v[134:137], v[148:151], v[82:97]
	ds_read_b128 v[188:191], v194 offset:8192
	ds_read_b128 v[222:225], v194 offset:12288
	v_mfma_f32_32x32x16_bf16 v[66:81], v[134:137], v[152:155], v[66:81]
	s_waitcnt lgkmcnt(7)
	v_mfma_f32_32x32x16_bf16 v[50:65], v[138:141], v[148:151], v[50:65]
	v_mfma_f32_32x32x16_bf16 v[34:49], v[138:141], v[152:155], v[34:49]
	s_waitcnt lgkmcnt(6)
	v_mfma_f32_32x32x16_bf16 v[18:33], v[144:147], v[148:151], v[18:33]
	v_mfma_f32_32x32x16_bf16 v[2:17], v[144:147], v[152:155], v[2:17]
	s_waitcnt vmcnt(0) lgkmcnt(0)
	s_barrier
	v_mfma_f32_32x32x16_bf16 v[114:129], v[180:183], v[226:229], v[114:129]
	ds_read_b128 v[130:133], v156 offset:32768
	v_mfma_f32_32x32x16_bf16 v[98:113], v[180:183], v[230:233], v[98:113]
	ds_read_b128 v[148:151], v195 offset:32768
	v_mfma_f32_32x32x16_bf16 v[82:97], v[184:187], v[226:229], v[82:97]
	ds_read_b128 v[152:155], v195 offset:36864
	v_mfma_f32_32x32x16_bf16 v[66:81], v[184:187], v[230:233], v[66:81]
	ds_read_b128 v[134:137], v156 offset:36864
	v_mfma_f32_32x32x16_bf16 v[50:65], v[188:191], v[226:229], v[50:65]
	ds_read_b128 v[138:141], v156 offset:40960
	v_mfma_f32_32x32x16_bf16 v[34:49], v[188:191], v[230:233], v[34:49]
	ds_read_b128 v[144:147], v156 offset:45056
	v_mfma_f32_32x32x16_bf16 v[18:33], v[222:225], v[226:229], v[18:33]
	v_mfma_f32_32x32x16_bf16 v[2:17], v[222:225], v[230:233], v[2:17]
	s_waitcnt lgkmcnt(4)
	v_mfma_f32_32x32x16_bf16 v[114:129], v[130:133], v[148:151], v[114:129]
	ds_read_b128 v[180:183], v157 offset:32768
	s_waitcnt lgkmcnt(4)
	v_mfma_f32_32x32x16_bf16 v[98:113], v[130:133], v[152:155], v[98:113]
	ds_read_b128 v[226:229], v200 offset:32768
	s_waitcnt lgkmcnt(4)
	v_mfma_f32_32x32x16_bf16 v[82:97], v[134:137], v[148:151], v[82:97]
	ds_read_b128 v[230:233], v200 offset:36864
	v_mfma_f32_32x32x16_bf16 v[66:81], v[134:137], v[152:155], v[66:81]
	ds_read_b128 v[184:187], v157 offset:36864
	s_waitcnt lgkmcnt(5)
	v_mfma_f32_32x32x16_bf16 v[50:65], v[138:141], v[148:151], v[50:65]
	ds_read_b128 v[188:191], v157 offset:40960
	v_mfma_f32_32x32x16_bf16 v[34:49], v[138:141], v[152:155], v[34:49]
	ds_read_b128 v[222:225], v157 offset:45056
	s_waitcnt lgkmcnt(6)
	v_mfma_f32_32x32x16_bf16 v[18:33], v[144:147], v[148:151], v[18:33]
	v_mfma_f32_32x32x16_bf16 v[2:17], v[144:147], v[152:155], v[2:17]
	s_waitcnt lgkmcnt(4)
	v_mfma_f32_32x32x16_bf16 v[114:129], v[180:183], v[226:229], v[114:129]
	ds_read_b128 v[130:133], v193 offset:32768
	s_waitcnt lgkmcnt(4)
	v_mfma_f32_32x32x16_bf16 v[98:113], v[180:183], v[230:233], v[98:113]
	ds_read_b128 v[148:151], v201 offset:32768
	s_waitcnt lgkmcnt(4)
	v_mfma_f32_32x32x16_bf16 v[82:97], v[184:187], v[226:229], v[82:97]
	ds_read_b128 v[152:155], v201 offset:36864
	v_mfma_f32_32x32x16_bf16 v[66:81], v[184:187], v[230:233], v[66:81]
	ds_read_b128 v[134:137], v193 offset:36864
	s_waitcnt lgkmcnt(5)
	v_mfma_f32_32x32x16_bf16 v[50:65], v[188:191], v[226:229], v[50:65]
	ds_read_b128 v[138:141], v193 offset:40960
	v_mfma_f32_32x32x16_bf16 v[34:49], v[188:191], v[230:233], v[34:49]
	ds_read_b128 v[144:147], v193 offset:45056
	s_waitcnt lgkmcnt(6)
	v_mfma_f32_32x32x16_bf16 v[18:33], v[222:225], v[226:229], v[18:33]
	v_mfma_f32_32x32x16_bf16 v[2:17], v[222:225], v[230:233], v[2:17]
	s_waitcnt lgkmcnt(4)
	v_mfma_f32_32x32x16_bf16 v[114:129], v[130:133], v[148:151], v[114:129]
	ds_read_b128 v[180:183], v194 offset:32768
	ds_read_b128 v[226:229], v202 offset:32768
	s_waitcnt lgkmcnt(5)
	v_mfma_f32_32x32x16_bf16 v[98:113], v[130:133], v[152:155], v[98:113]
	ds_read_b128 v[230:233], v202 offset:36864
	ds_read_b128 v[184:187], v194 offset:36864
	s_waitcnt lgkmcnt(6)
	v_mfma_f32_32x32x16_bf16 v[82:97], v[134:137], v[148:151], v[82:97]
	ds_read_b128 v[188:191], v194 offset:40960
	ds_read_b128 v[222:225], v194 offset:45056
	v_mfma_f32_32x32x16_bf16 v[66:81], v[134:137], v[152:155], v[66:81]
	s_waitcnt lgkmcnt(7)
	v_mfma_f32_32x32x16_bf16 v[50:65], v[138:141], v[148:151], v[50:65]
	v_mfma_f32_32x32x16_bf16 v[34:49], v[138:141], v[152:155], v[34:49]
	s_waitcnt lgkmcnt(6)
	v_mfma_f32_32x32x16_bf16 v[18:33], v[144:147], v[148:151], v[18:33]
	v_mfma_f32_32x32x16_bf16 v[2:17], v[144:147], v[152:155], v[2:17]
	s_waitcnt vmcnt(0) lgkmcnt(0)
	s_barrier
	v_mfma_f32_32x32x16_bf16 v[114:129], v[180:183], v[226:229], v[114:129]
	v_mfma_f32_32x32x16_bf16 v[98:113], v[180:183], v[230:233], v[98:113]
	v_mfma_f32_32x32x16_bf16 v[82:97], v[184:187], v[226:229], v[82:97]
	v_mfma_f32_32x32x16_bf16 v[66:81], v[184:187], v[230:233], v[66:81]
	v_mfma_f32_32x32x16_bf16 v[50:65], v[188:191], v[226:229], v[50:65]
	v_mfma_f32_32x32x16_bf16 v[34:49], v[188:191], v[230:233], v[34:49]
	v_mfma_f32_32x32x16_bf16 v[18:33], v[222:225], v[226:229], v[18:33]
	v_mfma_f32_32x32x16_bf16 v[2:17], v[222:225], v[230:233], v[2:17]
	s_branch .Lg1122_end
.Lgl1122_entry:
	v_lshlrev_b32_e32 v142, 1, v143
	v_readfirstlane_b32 s15, v158
	v_add_u32_e32 v156, v165, v167
	v_add_u32_e32 v195, v166, v167
	v_add_u32_e32 v157, v165, v172
	v_add_u32_e32 v200, v166, v172
	v_add_u32_e32 v193, v165, v173
	v_add_u32_e32 v201, v166, v173
	v_add_u32_e32 v194, v165, v174
	v_add_u32_e32 v202, v166, v174
	s_mov_b32 s5, 7
	ds_read_b128 v[130:133], v156 offset:0
	ds_read_b128 v[148:151], v195 offset:0
	ds_read_b128 v[152:155], v195 offset:4096
	ds_read_b128 v[134:137], v156 offset:4096
	ds_read_b128 v[138:141], v156 offset:8192
	ds_read_b128 v[144:147], v156 offset:12288
.Lgl1122_loop:
	s_waitcnt lgkmcnt(4)
	v_mfma_f32_32x32x16_bf16 v[114:129], v[130:133], v[148:151], v[114:129]
	ds_read_b128 v[180:183], v157 offset:0
	s_waitcnt lgkmcnt(4)
	v_mfma_f32_32x32x16_bf16 v[98:113], v[130:133], v[152:155], v[98:113]
	ds_read_b128 v[226:229], v200 offset:0
	s_waitcnt lgkmcnt(4)
	v_mfma_f32_32x32x16_bf16 v[82:97], v[134:137], v[148:151], v[82:97]
	ds_read_b128 v[230:233], v200 offset:4096
	v_mfma_f32_32x32x16_bf16 v[66:81], v[134:137], v[152:155], v[66:81]
	ds_read_b128 v[184:187], v157 offset:4096
	s_waitcnt lgkmcnt(5)
	v_mfma_f32_32x32x16_bf16 v[50:65], v[138:141], v[148:151], v[50:65]
	ds_read_b128 v[188:191], v157 offset:8192
	v_mfma_f32_32x32x16_bf16 v[34:49], v[138:141], v[152:155], v[34:49]
	ds_read_b128 v[222:225], v157 offset:12288
	s_add_u32 s2, s2, 0x80
	s_addc_u32 s3, s3, 0
	s_waitcnt lgkmcnt(6)
	v_mfma_f32_32x32x16_bf16 v[18:33], v[144:147], v[148:151], v[18:33]
	v_mfma_f32_32x32x16_bf16 v[2:17], v[144:147], v[152:155], v[2:17]
	s_waitcnt lgkmcnt(4)
	v_mfma_f32_32x32x16_bf16 v[114:129], v[180:183], v[226:229], v[114:129]
	ds_read_b128 v[130:133], v193 offset:0
	s_waitcnt lgkmcnt(4)
	v_mfma_f32_32x32x16_bf16 v[98:113], v[180:183], v[230:233], v[98:113]
	ds_read_b128 v[148:151], v201 offset:0
	s_waitcnt lgkmcnt(4)
	v_mfma_f32_32x32x16_bf16 v[82:97], v[184:187], v[226:229], v[82:97]
	ds_read_b128 v[152:155], v201 offset:4096
	v_mfma_f32_32x32x16_bf16 v[66:81], v[184:187], v[230:233], v[66:81]
	ds_read_b128 v[134:137], v193 offset:4096
	s_waitcnt lgkmcnt(5)
	v_mfma_f32_32x32x16_bf16 v[50:65], v[188:191], v[226:229], v[50:65]
	ds_read_b128 v[138:141], v193 offset:8192
	v_mfma_f32_32x32x16_bf16 v[34:49], v[188:191], v[230:233], v[34:49]
	ds_read_b128 v[144:147], v193 offset:12288
	s_waitcnt lgkmcnt(6)
	v_mfma_f32_32x32x16_bf16 v[18:33], v[222:225], v[226:229], v[18:33]
	v_mfma_f32_32x32x16_bf16 v[2:17], v[222:225], v[230:233], v[2:17]
	s_waitcnt lgkmcnt(4)
	v_mfma_f32_32x32x16_bf16 v[114:129], v[130:133], v[148:151], v[114:129]
	ds_read_b128 v[180:183], v194 offset:0
	ds_read_b128 v[226:229], v202 offset:0
	s_waitcnt lgkmcnt(5)
	v_mfma_f32_32x32x16_bf16 v[98:113], v[130:133], v[152:155], v[98:113]
	ds_read_b128 v[230:233], v202 offset:4096
	ds_read_b128 v[184:187], v194 offset:4096
	s_waitcnt lgkmcnt(6)
	v_mfma_f32_32x32x16_bf16 v[82:97], v[134:137], v[148:151], v[82:97]
	ds_read_b128 v[188:191], v194 offset:8192
	ds_read_b128 v[222:225], v194 offset:12288
	v_mfma_f32_32x32x16_bf16 v[66:81], v[134:137], v[152:155], v[66:81]
	s_waitcnt lgkmcnt(7)
	v_mfma_f32_32x32x16_bf16 v[50:65], v[138:141], v[148:151], v[50:65]
	v_mfma_f32_32x32x16_bf16 v[34:49], v[138:141], v[152:155], v[34:49]
	s_waitcnt lgkmcnt(6)
	v_mfma_f32_32x32x16_bf16 v[18:33], v[144:147], v[148:151], v[18:33]
	v_mfma_f32_32x32x16_bf16 v[2:17], v[144:147], v[152:155], v[2:17]
	s_waitcnt vmcnt(0) lgkmcnt(0)
	s_barrier
	v_mfma_f32_32x32x16_bf16 v[114:129], v[180:183], v[226:229], v[114:129]
	ds_read_b128 v[130:133], v156 offset:32768
	v_mfma_f32_32x32x16_bf16 v[98:113], v[180:183], v[230:233], v[98:113]
	ds_read_b128 v[148:151], v195 offset:32768
	v_mfma_f32_32x32x16_bf16 v[82:97], v[184:187], v[226:229], v[82:97]
	ds_read_b128 v[152:155], v195 offset:36864
	v_mfma_f32_32x32x16_bf16 v[66:81], v[184:187], v[230:233], v[66:81]
	ds_read_b128 v[134:137], v156 offset:36864
	v_mfma_f32_32x32x16_bf16 v[50:65], v[188:191], v[226:229], v[50:65]
	ds_read_b128 v[138:141], v156 offset:40960
	v_mfma_f32_32x32x16_bf16 v[34:49], v[188:191], v[230:233], v[34:49]
	ds_read_b128 v[144:147], v156 offset:45056
	v_mfma_f32_32x32x16_bf16 v[18:33], v[222:225], v[226:229], v[18:33]
	v_mfma_f32_32x32x16_bf16 v[2:17], v[222:225], v[230:233], v[2:17]
	s_waitcnt lgkmcnt(4)
	v_mfma_f32_32x32x16_bf16 v[114:129], v[130:133], v[148:151], v[114:129]
	ds_read_b128 v[180:183], v157 offset:32768
	s_waitcnt lgkmcnt(4)
	v_mfma_f32_32x32x16_bf16 v[98:113], v[130:133], v[152:155], v[98:113]
	ds_read_b128 v[226:229], v200 offset:32768
	s_waitcnt lgkmcnt(4)
	v_mfma_f32_32x32x16_bf16 v[82:97], v[134:137], v[148:151], v[82:97]
	ds_read_b128 v[230:233], v200 offset:36864
	v_mfma_f32_32x32x16_bf16 v[66:81], v[134:137], v[152:155], v[66:81]
	ds_read_b128 v[184:187], v157 offset:36864
	s_waitcnt lgkmcnt(5)
	v_mfma_f32_32x32x16_bf16 v[50:65], v[138:141], v[148:151], v[50:65]
	ds_read_b128 v[188:191], v157 offset:40960
	v_mfma_f32_32x32x16_bf16 v[34:49], v[138:141], v[152:155], v[34:49]
	ds_read_b128 v[222:225], v157 offset:45056
	s_add_u32 s2, s2, 0x80
	s_addc_u32 s3, s3, 0
	s_waitcnt lgkmcnt(6)
	v_mfma_f32_32x32x16_bf16 v[18:33], v[144:147], v[148:151], v[18:33]
	v_mfma_f32_32x32x16_bf16 v[2:17], v[144:147], v[152:155], v[2:17]
	s_waitcnt lgkmcnt(4)
	v_mfma_f32_32x32x16_bf16 v[114:129], v[180:183], v[226:229], v[114:129]
	ds_read_b128 v[130:133], v193 offset:32768
	s_waitcnt lgkmcnt(4)
	v_mfma_f32_32x32x16_bf16 v[98:113], v[180:183], v[230:233], v[98:113]
	ds_read_b128 v[148:151], v201 offset:32768
	s_waitcnt lgkmcnt(4)
	v_mfma_f32_32x32x16_bf16 v[82:97], v[184:187], v[226:229], v[82:97]
	ds_read_b128 v[152:155], v201 offset:36864
	v_mfma_f32_32x32x16_bf16 v[66:81], v[184:187], v[230:233], v[66:81]
	ds_read_b128 v[134:137], v193 offset:36864
	s_waitcnt lgkmcnt(5)
	v_mfma_f32_32x32x16_bf16 v[50:65], v[188:191], v[226:229], v[50:65]
	ds_read_b128 v[138:141], v193 offset:40960
	v_mfma_f32_32x32x16_bf16 v[34:49], v[188:191], v[230:233], v[34:49]
	ds_read_b128 v[144:147], v193 offset:45056
	s_waitcnt lgkmcnt(6)
	v_mfma_f32_32x32x16_bf16 v[18:33], v[222:225], v[226:229], v[18:33]
	v_mfma_f32_32x32x16_bf16 v[2:17], v[222:225], v[230:233], v[2:17]
	s_waitcnt lgkmcnt(4)
	v_mfma_f32_32x32x16_bf16 v[114:129], v[130:133], v[148:151], v[114:129]
	ds_read_b128 v[180:183], v194 offset:32768
	ds_read_b128 v[226:229], v202 offset:32768
	s_waitcnt lgkmcnt(5)
	v_mfma_f32_32x32x16_bf16 v[98:113], v[130:133], v[152:155], v[98:113]
	ds_read_b128 v[230:233], v202 offset:36864
	ds_read_b128 v[184:187], v194 offset:36864
	s_waitcnt lgkmcnt(6)
	v_mfma_f32_32x32x16_bf16 v[82:97], v[134:137], v[148:151], v[82:97]
	ds_read_b128 v[188:191], v194 offset:40960
	ds_read_b128 v[222:225], v194 offset:45056
	v_mfma_f32_32x32x16_bf16 v[66:81], v[134:137], v[152:155], v[66:81]
	s_waitcnt lgkmcnt(7)
	v_mfma_f32_32x32x16_bf16 v[50:65], v[138:141], v[148:151], v[50:65]
	v_mfma_f32_32x32x16_bf16 v[34:49], v[138:141], v[152:155], v[34:49]
	s_waitcnt lgkmcnt(6)
	v_mfma_f32_32x32x16_bf16 v[18:33], v[144:147], v[148:151], v[18:33]
	v_mfma_f32_32x32x16_bf16 v[2:17], v[144:147], v[152:155], v[2:17]
	s_waitcnt vmcnt(0) lgkmcnt(0)
	s_barrier
	v_mfma_f32_32x32x16_bf16 v[114:129], v[180:183], v[226:229], v[114:129]
	ds_read_b128 v[130:133], v156 offset:0
	v_mfma_f32_32x32x16_bf16 v[98:113], v[180:183], v[230:233], v[98:113]
	ds_read_b128 v[148:151], v195 offset:0
	v_mfma_f32_32x32x16_bf16 v[82:97], v[184:187], v[226:229], v[82:97]
	ds_read_b128 v[152:155], v195 offset:4096
	v_mfma_f32_32x32x16_bf16 v[66:81], v[184:187], v[230:233], v[66:81]
	ds_read_b128 v[134:137], v156 offset:4096
	v_mfma_f32_32x32x16_bf16 v[50:65], v[188:191], v[226:229], v[50:65]
	ds_read_b128 v[138:141], v156 offset:8192
	v_mfma_f32_32x32x16_bf16 v[34:49], v[188:191], v[230:233], v[34:49]
	ds_read_b128 v[144:147], v156 offset:12288
	v_mfma_f32_32x32x16_bf16 v[18:33], v[222:225], v[226:229], v[18:33]
	v_mfma_f32_32x32x16_bf16 v[2:17], v[222:225], v[230:233], v[2:17]
	s_sub_u32 s5, s5, 1
	s_cmp_lg_u32 s5, 0
	s_cbranch_scc1 .Lgl1122_loop
	s_waitcnt lgkmcnt(4)
	v_mfma_f32_32x32x16_bf16 v[114:129], v[130:133], v[148:151], v[114:129]
	ds_read_b128 v[180:183], v157 offset:0
	s_waitcnt lgkmcnt(4)
	v_mfma_f32_32x32x16_bf16 v[98:113], v[130:133], v[152:155], v[98:113]
	ds_read_b128 v[226:229], v200 offset:0
	s_waitcnt lgkmcnt(4)
	v_mfma_f32_32x32x16_bf16 v[82:97], v[134:137], v[148:151], v[82:97]
	ds_read_b128 v[230:233], v200 offset:4096
	v_mfma_f32_32x32x16_bf16 v[66:81], v[134:137], v[152:155], v[66:81]
	ds_read_b128 v[184:187], v157 offset:4096
	s_waitcnt lgkmcnt(5)
	v_mfma_f32_32x32x16_bf16 v[50:65], v[138:141], v[148:151], v[50:65]
	ds_read_b128 v[188:191], v157 offset:8192
	v_mfma_f32_32x32x16_bf16 v[34:49], v[138:141], v[152:155], v[34:49]
	ds_read_b128 v[222:225], v157 offset:12288
	s_add_u32 s2, s2, 0x80
	s_addc_u32 s3, s3, 0
	s_waitcnt lgkmcnt(6)
	v_mfma_f32_32x32x16_bf16 v[18:33], v[144:147], v[148:151], v[18:33]
	v_mfma_f32_32x32x16_bf16 v[2:17], v[144:147], v[152:155], v[2:17]
	s_waitcnt lgkmcnt(4)
	v_mfma_f32_32x32x16_bf16 v[114:129], v[180:183], v[226:229], v[114:129]
	ds_read_b128 v[130:133], v193 offset:0
	s_waitcnt lgkmcnt(4)
	v_mfma_f32_32x32x16_bf16 v[98:113], v[180:183], v[230:233], v[98:113]
	ds_read_b128 v[148:151], v201 offset:0
	s_waitcnt lgkmcnt(4)
	v_mfma_f32_32x32x16_bf16 v[82:97], v[184:187], v[226:229], v[82:97]
	ds_read_b128 v[152:155], v201 offset:4096
	v_mfma_f32_32x32x16_bf16 v[66:81], v[184:187], v[230:233], v[66:81]
	ds_read_b128 v[134:137], v193 offset:4096
	s_waitcnt lgkmcnt(5)
	v_mfma_f32_32x32x16_bf16 v[50:65], v[188:191], v[226:229], v[50:65]
	ds_read_b128 v[138:141], v193 offset:8192
	v_mfma_f32_32x32x16_bf16 v[34:49], v[188:191], v[230:233], v[34:49]
	ds_read_b128 v[144:147], v193 offset:12288
	s_waitcnt lgkmcnt(6)
	v_mfma_f32_32x32x16_bf16 v[18:33], v[222:225], v[226:229], v[18:33]
	v_mfma_f32_32x32x16_bf16 v[2:17], v[222:225], v[230:233], v[2:17]
	s_waitcnt lgkmcnt(4)
	v_mfma_f32_32x32x16_bf16 v[114:129], v[130:133], v[148:151], v[114:129]
	ds_read_b128 v[180:183], v194 offset:0
	ds_read_b128 v[226:229], v202 offset:0
	s_waitcnt lgkmcnt(5)
	v_mfma_f32_32x32x16_bf16 v[98:113], v[130:133], v[152:155], v[98:113]
	ds_read_b128 v[230:233], v202 offset:4096
	ds_read_b128 v[184:187], v194 offset:4096
	s_waitcnt lgkmcnt(6)
	v_mfma_f32_32x32x16_bf16 v[82:97], v[134:137], v[148:151], v[82:97]
	ds_read_b128 v[188:191], v194 offset:8192
	ds_read_b128 v[222:225], v194 offset:12288
	v_mfma_f32_32x32x16_bf16 v[66:81], v[134:137], v[152:155], v[66:81]
	s_waitcnt lgkmcnt(7)
	v_mfma_f32_32x32x16_bf16 v[50:65], v[138:141], v[148:151], v[50:65]
	v_mfma_f32_32x32x16_bf16 v[34:49], v[138:141], v[152:155], v[34:49]
	s_waitcnt lgkmcnt(6)
	v_mfma_f32_32x32x16_bf16 v[18:33], v[144:147], v[148:151], v[18:33]
	v_mfma_f32_32x32x16_bf16 v[2:17], v[144:147], v[152:155], v[2:17]
	s_waitcnt vmcnt(0) lgkmcnt(0)
	s_barrier
	v_mfma_f32_32x32x16_bf16 v[114:129], v[180:183], v[226:229], v[114:129]
	ds_read_b128 v[130:133], v156 offset:32768
	v_mfma_f32_32x32x16_bf16 v[98:113], v[180:183], v[230:233], v[98:113]
	ds_read_b128 v[148:151], v195 offset:32768
	v_mfma_f32_32x32x16_bf16 v[82:97], v[184:187], v[226:229], v[82:97]
	ds_read_b128 v[152:155], v195 offset:36864
	v_mfma_f32_32x32x16_bf16 v[66:81], v[184:187], v[230:233], v[66:81]
	ds_read_b128 v[134:137], v156 offset:36864
	v_mfma_f32_32x32x16_bf16 v[50:65], v[188:191], v[226:229], v[50:65]
	ds_read_b128 v[138:141], v156 offset:40960
	v_mfma_f32_32x32x16_bf16 v[34:49], v[188:191], v[230:233], v[34:49]
	ds_read_b128 v[144:147], v156 offset:45056
	v_mfma_f32_32x32x16_bf16 v[18:33], v[222:225], v[226:229], v[18:33]
	v_mfma_f32_32x32x16_bf16 v[2:17], v[222:225], v[230:233], v[2:17]
	s_waitcnt lgkmcnt(4)
	v_mfma_f32_32x32x16_bf16 v[114:129], v[130:133], v[148:151], v[114:129]
	ds_read_b128 v[180:183], v157 offset:32768
	s_waitcnt lgkmcnt(4)
	v_mfma_f32_32x32x16_bf16 v[98:113], v[130:133], v[152:155], v[98:113]
	ds_read_b128 v[226:229], v200 offset:32768
	s_waitcnt lgkmcnt(4)
	v_mfma_f32_32x32x16_bf16 v[82:97], v[134:137], v[148:151], v[82:97]
	ds_read_b128 v[230:233], v200 offset:36864
	v_mfma_f32_32x32x16_bf16 v[66:81], v[134:137], v[152:155], v[66:81]
	ds_read_b128 v[184:187], v157 offset:36864
	s_waitcnt lgkmcnt(5)
	v_mfma_f32_32x32x16_bf16 v[50:65], v[138:141], v[148:151], v[50:65]
	ds_read_b128 v[188:191], v157 offset:40960
	v_mfma_f32_32x32x16_bf16 v[34:49], v[138:141], v[152:155], v[34:49]
	ds_read_b128 v[222:225], v157 offset:45056
	s_waitcnt lgkmcnt(6)
	v_mfma_f32_32x32x16_bf16 v[18:33], v[144:147], v[148:151], v[18:33]
	v_mfma_f32_32x32x16_bf16 v[2:17], v[144:147], v[152:155], v[2:17]
	s_waitcnt lgkmcnt(4)
	v_mfma_f32_32x32x16_bf16 v[114:129], v[180:183], v[226:229], v[114:129]
	ds_read_b128 v[130:133], v193 offset:32768
	s_waitcnt lgkmcnt(4)
	v_mfma_f32_32x32x16_bf16 v[98:113], v[180:183], v[230:233], v[98:113]
	ds_read_b128 v[148:151], v201 offset:32768
	s_waitcnt lgkmcnt(4)
	v_mfma_f32_32x32x16_bf16 v[82:97], v[184:187], v[226:229], v[82:97]
	ds_read_b128 v[152:155], v201 offset:36864
	v_mfma_f32_32x32x16_bf16 v[66:81], v[184:187], v[230:233], v[66:81]
	ds_read_b128 v[134:137], v193 offset:36864
	s_waitcnt lgkmcnt(5)
	v_mfma_f32_32x32x16_bf16 v[50:65], v[188:191], v[226:229], v[50:65]
	ds_read_b128 v[138:141], v193 offset:40960
	v_mfma_f32_32x32x16_bf16 v[34:49], v[188:191], v[230:233], v[34:49]
	ds_read_b128 v[144:147], v193 offset:45056
	s_waitcnt lgkmcnt(6)
	v_mfma_f32_32x32x16_bf16 v[18:33], v[222:225], v[226:229], v[18:33]
	v_mfma_f32_32x32x16_bf16 v[2:17], v[222:225], v[230:233], v[2:17]
	s_waitcnt lgkmcnt(4)
	v_mfma_f32_32x32x16_bf16 v[114:129], v[130:133], v[148:151], v[114:129]
	ds_read_b128 v[180:183], v194 offset:32768
	ds_read_b128 v[226:229], v202 offset:32768
	s_waitcnt lgkmcnt(5)
	v_mfma_f32_32x32x16_bf16 v[98:113], v[130:133], v[152:155], v[98:113]
	ds_read_b128 v[230:233], v202 offset:36864
	ds_read_b128 v[184:187], v194 offset:36864
	s_waitcnt lgkmcnt(6)
	v_mfma_f32_32x32x16_bf16 v[82:97], v[134:137], v[148:151], v[82:97]
	ds_read_b128 v[188:191], v194 offset:40960
	ds_read_b128 v[222:225], v194 offset:45056
	v_mfma_f32_32x32x16_bf16 v[66:81], v[134:137], v[152:155], v[66:81]
	s_waitcnt lgkmcnt(7)
	v_mfma_f32_32x32x16_bf16 v[50:65], v[138:141], v[148:151], v[50:65]
	v_mfma_f32_32x32x16_bf16 v[34:49], v[138:141], v[152:155], v[34:49]
	s_waitcnt lgkmcnt(6)
	v_mfma_f32_32x32x16_bf16 v[18:33], v[144:147], v[148:151], v[18:33]
	v_mfma_f32_32x32x16_bf16 v[2:17], v[144:147], v[152:155], v[2:17]
	s_waitcnt vmcnt(0) lgkmcnt(0)
	s_barrier
	v_mfma_f32_32x32x16_bf16 v[114:129], v[180:183], v[226:229], v[114:129]
	v_mfma_f32_32x32x16_bf16 v[98:113], v[180:183], v[230:233], v[98:113]
	v_mfma_f32_32x32x16_bf16 v[82:97], v[184:187], v[226:229], v[82:97]
	v_mfma_f32_32x32x16_bf16 v[66:81], v[184:187], v[230:233], v[66:81]
	v_mfma_f32_32x32x16_bf16 v[50:65], v[188:191], v[226:229], v[50:65]
	v_mfma_f32_32x32x16_bf16 v[34:49], v[188:191], v[230:233], v[34:49]
	v_mfma_f32_32x32x16_bf16 v[18:33], v[222:225], v[226:229], v[18:33]
	v_mfma_f32_32x32x16_bf16 v[2:17], v[222:225], v[230:233], v[2:17]
.Lg1122_end:
	s_setprio 0
	v_add_u32_e32 v180, s0, v168
	s_and_b32 s0, s4, 0x7ffffe
	s_mov_b32 s4, 0x7e07e07f
	v_mul_hi_i32 v0, v180, s4
	v_lshrrev_b32_e32 v130, 31, v0
	v_ashrrev_i32_e32 v0, 13, v0
	s_cmp_eq_u32 s0, 12
	v_add_u32_e32 v182, v0, v130
	s_waitcnt vmcnt(0)
	s_cselect_b64 s[2:3], -1, 0
	s_cmp_lg_u32 s0, 12
	v_mul_i32_i24_e32 v0, 0x4100, v182
	v_or_b32_e32 v138, s6, v169
	s_movk_i32 s4, 0x5ff
	s_cselect_b64 s[0:1], -1, 0
	v_sub_u32_e32 v140, v180, v0
	v_mov_b32_e32 v184, v179
	v_cmp_lt_i32_e64 s[52:53], s4, v138
	s_barrier
	v_lshl_or_b32 v181, v182, 3, v171
	v_ashrrev_i32_e32 v141, 31, v140
	s_and_b64 s[10:11], s[0:1], s[52:53]
	v_and_b32_e32 v183, 63, v184
	v_and_b32_e32 v0, 31, v184
	v_bfe_u32 v133, v184, 5, 1
	s_and_saveexec_b64 s[0:1], s[10:11]
	s_xor_b64 s[8:9], exec, s[0:1]
	s_cbranch_execz .LBB0_1136
	s_add_i32 s4, s6, 0xfffff200
	v_mul_u32_u24_e32 v130, 0x90, v133
	s_mov_b64 s[0:1], -1
	s_cmp_gt_u32 s4, 0xfffff9ff
	v_lshlrev_b32_e32 v139, 2, v0
	v_lshlrev_b32_e32 v185, 2, v130
	s_cbranch_scc0 .LBB0_1134
	v_add3_u32 v0, v170, v185, v139
	ds_write_b32 v0, v114
	v_add3_u32 v0, v170, v139, v185
	v_add_u32_e32 v130, 0x100, v0
	ds_write2_b32 v130, v117, v118 offset0:44 offset1:224
	v_add_u32_e32 v130, 0x400, v0
	ds_write2_b32 v130, v119, v120 offset0:68 offset1:104
	v_add_u32_e32 v130, 0x600, v0
	ds_write2_b32 v130, v121, v122 offset0:12 offset1:192
	v_add_u32_e32 v130, 0x800, v0
	ds_write2_b32 v130, v123, v124 offset0:100 offset1:136
	v_add_u32_e32 v130, 0xa00, v0
	ds_write2_b32 v130, v125, v126 offset0:44 offset1:224
	v_add_u32_e32 v130, 0xc00, v0
	s_cmpk_lt_u32 s6, 0xa00
	ds_write2_b32 v0, v115, v116 offset0:36 offset1:72
	ds_write2_b32 v130, v127, v128 offset0:132 offset1:168
	ds_write_b32 v0, v129 offset:3888
	s_cselect_b64 s[0:1], -1, 0
	v_mov_b32_e32 v0, 0x3e38aa3b
	v_cndmask_b32_e64 v142, 1.0, v0, s[0:1]
	v_lshlrev_b32_e32 v0, 3, v184
	v_lshrrev_b32_e32 v188, 2, v183
	s_movk_i32 s4, 0x90
	v_and_b32_e32 v187, 24, v0
	v_mad_u32_u24 v147, v188, s4, v170
	s_waitcnt lgkmcnt(0)
	v_lshl_add_u32 v130, v187, 2, v147
	ds_read_b128 v[134:137], v130
	ds_read_b128 v[130:133], v130 offset:16
	v_and_b32_e32 v144, 2, v184
	v_or_b32_e32 v150, v188, v140
	s_movk_i32 s4, 0x100
	v_cmp_eq_u32_e32 vcc, 0, v144
	v_cmp_gt_i32_e64 s[4:5], s4, v150
	s_and_saveexec_b64 s[16:17], s[4:5]
	s_xor_b64 s[4:5], exec, s[16:17]
	s_cbranch_execz .LBB0_1127
	s_waitcnt lgkmcnt(1)
	v_pk_mul_f32 v[152:153], v[142:143], v[134:135] op_sel_hi:[0,1]
	v_pk_mul_f32 v[154:155], v[142:143], v[136:137] op_sel_hi:[0,1]
	s_waitcnt lgkmcnt(0)
	v_pk_mul_f32 v[156:157], v[142:143], v[130:131] op_sel_hi:[0,1]
	v_mul_f32_e32 v145, v142, v132
